# scan recurrence with chunk-local cumulative decay absorbed into operands (4 ops per state element instead of 5), f32 throughout
# speedup vs baseline: 1.0178x; 1.0178x over previous
.LBB0_127:
	s_andn2_b64 vcc, exec, s[10:11]
	s_cbranch_vccnz .LBB0_129
	v_mul_f32_e32 v4, 0xbf60028a, v4
	v_mul_f32_e32 v5, 0xbf60028a, v5
	v_exp_f32_e32 v4, v4
	v_exp_f32_e32 v5, v5
	v_mul_f32_e32 v6, 0xbf60028a, v6
	v_mul_f32_e32 v7, 0xbf60028a, v7
	v_exp_f32_e32 v6, v6
	v_exp_f32_e32 v7, v7
	v_mul_f32_e32 v8, 0xbf60028a, v8
	v_mul_f32_e32 v9, 0xbf60028a, v9
	v_exp_f32_e32 v8, v8
	v_exp_f32_e32 v9, v9
	v_mul_f32_e32 v10, 0xbf60028a, v10
	v_mul_f32_e32 v11, 0xbf60028a, v11
	v_exp_f32_e32 v10, v10
	v_exp_f32_e32 v11, v11
	s_nop 1
	v_mul_f32_e32 v198, v7, v6
	v_mul_f32_e32 v201, v11, v10
	v_mul_f32_e32 v199, v198, v5
	v_mul_f32_e32 v202, v201, v9
	v_mul_f32_e32 v200, v199, v4
	v_mul_f32_e32 v203, v202, v8
	v_mbcnt_lo_u32_b32 v204, -1, 0
	v_mbcnt_hi_u32_b32 v204, -1, v204
	v_and_b32_e32 v205, 15, v204
	v_lshlrev_b32_e32 v205, 2, v205
	v_add_u32_e32 v206, 64, v205
	v_add_u32_e32 v207, 128, v205
	v_add_u32_e32 v208, 192, v205
	v_mov_b32_e32 v217, 1.0
	ds_bpermute_b32 v209, v205, v200
	ds_bpermute_b32 v210, v206, v200
	ds_bpermute_b32 v211, v207, v200
	ds_bpermute_b32 v212, v208, v200
	ds_bpermute_b32 v213, v205, v203
	ds_bpermute_b32 v214, v206, v203
	ds_bpermute_b32 v215, v207, v203
	ds_bpermute_b32 v216, v208, v203
	s_waitcnt lgkmcnt(0)
	v_cmp_gt_u32_e32 vcc, 16, v204
	v_cndmask_b32_e32 v218, v217, v210, vcc
	v_cndmask_b32_e32 v221, v217, v214, vcc
	v_cmp_gt_u32_e32 vcc, 32, v204
	v_cndmask_b32_e32 v219, v217, v211, vcc
	v_cndmask_b32_e32 v222, v217, v215, vcc
	v_cmp_gt_u32_e32 vcc, 48, v204
	v_cndmask_b32_e32 v220, v217, v212, vcc
	v_cndmask_b32_e32 v223, v217, v216, vcc
	v_mul_f32_e32 v225, v221, v222
	v_mul_f32_e32 v224, v218, v219
	v_mul_f32_e32 v226, v213, v214
	v_mul_f32_e32 v225, v225, v223
	v_mul_f32_e32 v224, v224, v220
	v_mul_f32_e32 v226, v226, v215
	v_mul_f32_e32 v226, v226, v216
	v_mul_f32_e32 v224, v224, v226
	v_mul_f32_e32 v230, v200, v224
	v_mul_f32_e32 v231, v199, v224
	v_mul_f32_e32 v232, v198, v224
	v_mul_f32_e32 v233, v7, v224
	v_mul_f32_e32 v234, v203, v225
	v_mul_f32_e32 v235, v202, v225
	v_mul_f32_e32 v236, v201, v225
	v_mul_f32_e32 v237, v11, v225
	ds_write2st64_b32 v163, v230, v231 offset0:224 offset1:225
	ds_write2st64_b32 v163, v232, v233 offset0:226 offset1:227
	ds_write2st64_b32 v163, v234, v235 offset0:240 offset1:241
	ds_write2st64_b32 v163, v236, v237 offset0:242 offset1:243
	s_waitcnt lgkmcnt(7)
	v_mul_f32_e32 v15, v29, v4
	ds_write2st64_b32 v163, v4, v5 offset1:1
	s_waitcnt lgkmcnt(7)
	v_mul_f32_e32 v4, v28, v5
	ds_write2st64_b32 v163, v15, v4 offset0:128 offset1:129
	s_waitcnt lgkmcnt(7)
	v_mul_f32_e32 v4, v26, v6
	s_waitcnt lgkmcnt(6)
	v_mul_f32_e32 v5, v25, v7
	ds_write2st64_b32 v163, v4, v5 offset0:130 offset1:131
	s_waitcnt lgkmcnt(6)
	v_mul_f32_e32 v4, v24, v8
	s_waitcnt lgkmcnt(5)
	v_mul_f32_e32 v5, v14, v9
	ds_write2st64_b32 v163, v4, v5 offset0:144 offset1:145
	s_waitcnt lgkmcnt(5)
	v_mul_f32_e32 v4, v13, v10
	s_waitcnt lgkmcnt(4)
	v_mul_f32_e32 v5, v12, v11
	ds_write2st64_b32 v163, v6, v7 offset0:2 offset1:3
	ds_write2st64_b32 v163, v8, v9 offset0:16 offset1:17
	ds_write2st64_b32 v163, v10, v11 offset0:18 offset1:19
	ds_write2st64_b32 v163, v4, v5 offset0:146 offset1:147

.LBB0_131:
	s_or_b64 exec, exec, s[10:11]
	v_add_u32_e32 v227, 0x100, v156
	ds_read_b128 v[198:201], v156 offset:57344
	ds_read_b128 v[202:205], v227 offset:57344
	ds_read_b128 v[206:209], v156 offset:8192
	ds_read_b128 v[210:213], v156 offset:16384
	ds_read_b128 v[214:217], v156 offset:24576
	ds_read_b128 v[218:221], v156 offset:32768
	v_mov_b32_e32 v226, 1.0
	v_cmp_lt_u32_e32 vcc, 495, v134
	s_waitcnt lgkmcnt(4)
	v_rcp_f32_e32 v222, v198
	v_rcp_f32_e32 v223, v199
	v_rcp_f32_e32 v224, v200
	v_rcp_f32_e32 v225, v201
	v_cndmask_b32_e32 v202, v202, v226, vcc
	v_cndmask_b32_e32 v203, v203, v226, vcc
	v_cndmask_b32_e32 v204, v204, v226, vcc
	v_cndmask_b32_e32 v205, v205, v226, vcc
	s_waitcnt lgkmcnt(0)
	v_mul_f32_e32 v206, v206, v202
	v_mul_f32_e32 v207, v207, v203
	v_mul_f32_e32 v208, v208, v204
	v_mul_f32_e32 v209, v209, v205
	v_mul_f32_e32 v218, v218, v202
	v_mul_f32_e32 v219, v219, v203
	v_mul_f32_e32 v220, v220, v204
	v_mul_f32_e32 v221, v221, v205
	v_mul_f32_e32 v210, v210, v222
	v_mul_f32_e32 v211, v211, v223
	v_mul_f32_e32 v212, v212, v224
	v_mul_f32_e32 v213, v213, v225
	v_mul_f32_e32 v214, v214, v222
	v_mul_f32_e32 v215, v215, v223
	v_mul_f32_e32 v216, v216, v224
	v_mul_f32_e32 v217, v217, v225
	ds_write_b128 v156, v[206:209] offset:8192
	ds_write_b128 v156, v[218:221] offset:32768
	ds_write_b128 v156, v[210:213] offset:16384
	ds_write_b128 v156, v[214:217] offset:24576
	s_waitcnt lgkmcnt(0)
	s_barrier
	v_mbcnt_lo_u32_b32 v197, -1, 0
	v_mbcnt_hi_u32_b32 v197, -1, v197
	v_lshlrev_b32_e32 v197, 3, v197
	v_add_u32_e32 v197, 0xe000, v197
	v_cndmask_b32_e64 v196, v197, v161, s[8:9]
	v_add_u32_e32 v69, 0xffffe800, v185
	ds_read_b128 v[8:11], v152 offset:16128
	ds_read_b128 v[12:15], v152 offset:24320
	ds_read_b128 v[16:19], v152 offset:32512
	ds_read_b128 v[20:23], v152 offset:40704
	ds_read_b64 v[64:65], v69 offset:7936
	ds_read_b128 v[28:31], v152 offset:15872
	ds_read_b128 v[32:35], v152 offset:24064
	ds_read_b128 v[36:39], v152 offset:32256
	ds_read_b128 v[40:43], v152 offset:40448
	ds_read_b64 v[66:67], v69 offset:7680
	ds_read_b128 v[48:51], v152 offset:15616
	ds_read_b128 v[52:55], v152 offset:23808
	ds_read_b128 v[56:59], v152 offset:32000
	ds_read_b128 v[60:63], v152 offset:40192
	ds_read_b64 v[130:131], v69 offset:7424
	s_waitcnt lgkmcnt(10)
	v_mul_f32_e32 v194, v186, v8
	v_mul_f32_e32 v195, v190, v8
	v_mul_f32_e32 v132, v186, v20
	v_mul_f32_e32 v133, v190, v20
	v_fmac_f32_e32 v194, v187, v9
	v_fmac_f32_e32 v195, v191, v9
	v_fmac_f32_e32 v132, v187, v21
	v_fmac_f32_e32 v133, v191, v21
	v_fmac_f32_e32 v194, v188, v10
	v_fmac_f32_e32 v195, v192, v10
	v_fmac_f32_e32 v132, v188, v22
	v_fmac_f32_e32 v133, v192, v22
	v_fmac_f32_e32 v194, v189, v11
	v_fmac_f32_e32 v195, v193, v11
	v_fmac_f32_e32 v132, v189, v23
	v_fmac_f32_e32 v133, v193, v23
	v_add_f32_dpp v194, v194, v194 quad_perm:[1,0,3,2] row_mask:0xf bank_mask:0xf bound_ctrl:1
	v_add_f32_dpp v195, v195, v195 quad_perm:[1,0,3,2] row_mask:0xf bank_mask:0xf bound_ctrl:1
	v_add_f32_dpp v132, v132, v132 quad_perm:[1,0,3,2] row_mask:0xf bank_mask:0xf bound_ctrl:1
	v_add_f32_dpp v133, v133, v133 quad_perm:[1,0,3,2] row_mask:0xf bank_mask:0xf bound_ctrl:1
	v_add_f32_dpp v194, v194, v194 quad_perm:[2,3,0,1] row_mask:0xf bank_mask:0xf bound_ctrl:1
	v_add_f32_dpp v195, v195, v195 quad_perm:[2,3,0,1] row_mask:0xf bank_mask:0xf bound_ctrl:1
	v_add_f32_dpp v132, v132, v132 quad_perm:[2,3,0,1] row_mask:0xf bank_mask:0xf bound_ctrl:1
	v_add_f32_dpp v133, v133, v133 quad_perm:[2,3,0,1] row_mask:0xf bank_mask:0xf bound_ctrl:1
	v_add_f32_dpp v194, v194, v194 row_half_mirror row_mask:0xf bank_mask:0xf bound_ctrl:1
	v_add_f32_dpp v195, v195, v195 row_half_mirror row_mask:0xf bank_mask:0xf bound_ctrl:1
	v_add_f32_dpp v132, v132, v132 row_half_mirror row_mask:0xf bank_mask:0xf bound_ctrl:1
	v_add_f32_dpp v133, v133, v133 row_half_mirror row_mask:0xf bank_mask:0xf bound_ctrl:1
	v_add_f32_dpp v194, v194, v194 row_mirror row_mask:0xf bank_mask:0xf bound_ctrl:1
	v_add_f32_dpp v195, v195, v195 row_mirror row_mask:0xf bank_mask:0xf bound_ctrl:1
	v_fmac_f32_e32 v186, v64, v16
	v_fmac_f32_e32 v187, v64, v17
	v_fmac_f32_e32 v188, v64, v18
	v_fmac_f32_e32 v189, v64, v19
	v_fmac_f32_e32 v190, v65, v16
	v_fmac_f32_e32 v191, v65, v17
	v_fmac_f32_e32 v192, v65, v18
	v_fmac_f32_e32 v193, v65, v19
	v_fmac_f32_e32 v186, v194, v12
	v_fmac_f32_e32 v187, v194, v13
	v_fmac_f32_e32 v188, v194, v14
	v_fmac_f32_e32 v189, v194, v15
	v_fmac_f32_e32 v190, v195, v12
	v_fmac_f32_e32 v191, v195, v13
	v_fmac_f32_e32 v192, v195, v14
	v_fmac_f32_e32 v193, v195, v15
	s_mov_b64 exec, s[8:9]
	ds_write_b64 v161, v[132:133] offset:15872
	s_mov_b64 exec, -1
	ds_read_b128 v[8:11], v152 offset:15360
	ds_read_b128 v[12:15], v152 offset:23552
	ds_read_b128 v[16:19], v152 offset:31744
	ds_read_b128 v[20:23], v152 offset:39936
	ds_read_b64 v[64:65], v69 offset:7168
	s_waitcnt lgkmcnt(11)
	v_mul_f32_e32 v194, v186, v28
	v_mul_f32_e32 v195, v190, v28
	v_mul_f32_e32 v132, v186, v40
	v_mul_f32_e32 v133, v190, v40
	v_fmac_f32_e32 v194, v187, v29
	v_fmac_f32_e32 v195, v191, v29
	v_fmac_f32_e32 v132, v187, v41
	v_fmac_f32_e32 v133, v191, v41
	v_fmac_f32_e32 v194, v188, v30
	v_fmac_f32_e32 v195, v192, v30
	v_fmac_f32_e32 v132, v188, v42
	v_fmac_f32_e32 v133, v192, v42
	v_fmac_f32_e32 v194, v189, v31
	v_fmac_f32_e32 v195, v193, v31
	v_fmac_f32_e32 v132, v189, v43
	v_fmac_f32_e32 v133, v193, v43
	v_add_f32_dpp v194, v194, v194 quad_perm:[1,0,3,2] row_mask:0xf bank_mask:0xf bound_ctrl:1
	v_add_f32_dpp v195, v195, v195 quad_perm:[1,0,3,2] row_mask:0xf bank_mask:0xf bound_ctrl:1
	v_add_f32_dpp v132, v132, v132 quad_perm:[1,0,3,2] row_mask:0xf bank_mask:0xf bound_ctrl:1
	v_add_f32_dpp v133, v133, v133 quad_perm:[1,0,3,2] row_mask:0xf bank_mask:0xf bound_ctrl:1
	v_add_f32_dpp v194, v194, v194 quad_perm:[2,3,0,1] row_mask:0xf bank_mask:0xf bound_ctrl:1
	v_add_f32_dpp v195, v195, v195 quad_perm:[2,3,0,1] row_mask:0xf bank_mask:0xf bound_ctrl:1
	v_add_f32_dpp v132, v132, v132 quad_perm:[2,3,0,1] row_mask:0xf bank_mask:0xf bound_ctrl:1
	v_add_f32_dpp v133, v133, v133 quad_perm:[2,3,0,1] row_mask:0xf bank_mask:0xf bound_ctrl:1
	v_add_f32_dpp v194, v194, v194 row_half_mirror row_mask:0xf bank_mask:0xf bound_ctrl:1
	v_add_f32_dpp v195, v195, v195 row_half_mirror row_mask:0xf bank_mask:0xf bound_ctrl:1
	v_add_f32_dpp v132, v132, v132 row_half_mirror row_mask:0xf bank_mask:0xf bound_ctrl:1
	v_add_f32_dpp v133, v133, v133 row_half_mirror row_mask:0xf bank_mask:0xf bound_ctrl:1
	v_add_f32_dpp v194, v194, v194 row_mirror row_mask:0xf bank_mask:0xf bound_ctrl:1
	v_add_f32_dpp v195, v195, v195 row_mirror row_mask:0xf bank_mask:0xf bound_ctrl:1
	v_fmac_f32_e32 v186, v66, v36
	v_fmac_f32_e32 v187, v66, v37
	v_fmac_f32_e32 v188, v66, v38
	v_fmac_f32_e32 v189, v66, v39
	v_fmac_f32_e32 v190, v67, v36
	v_fmac_f32_e32 v191, v67, v37
	v_fmac_f32_e32 v192, v67, v38
	v_fmac_f32_e32 v193, v67, v39
	v_fmac_f32_e32 v186, v194, v32
	v_fmac_f32_e32 v187, v194, v33
	v_fmac_f32_e32 v188, v194, v34
	v_fmac_f32_e32 v189, v194, v35
	v_fmac_f32_e32 v190, v195, v32
	v_fmac_f32_e32 v191, v195, v33
	v_fmac_f32_e32 v192, v195, v34
	v_fmac_f32_e32 v193, v195, v35
	s_mov_b64 exec, s[8:9]
	ds_write_b64 v161, v[132:133] offset:15360
	s_mov_b64 exec, -1
	ds_read_b128 v[28:31], v152 offset:15104
	ds_read_b128 v[32:35], v152 offset:23296
	ds_read_b128 v[36:39], v152 offset:31488
	ds_read_b128 v[40:43], v152 offset:39680
	ds_read_b64 v[66:67], v69 offset:6912
	s_waitcnt lgkmcnt(12)
	v_mul_f32_e32 v194, v186, v48
	v_mul_f32_e32 v195, v190, v48
	v_mul_f32_e32 v132, v186, v60
	v_mul_f32_e32 v133, v190, v60
	v_fmac_f32_e32 v194, v187, v49
	v_fmac_f32_e32 v195, v191, v49
	v_fmac_f32_e32 v132, v187, v61
	v_fmac_f32_e32 v133, v191, v61
	v_fmac_f32_e32 v194, v188, v50
	v_fmac_f32_e32 v195, v192, v50
	v_fmac_f32_e32 v132, v188, v62
	v_fmac_f32_e32 v133, v192, v62
	v_fmac_f32_e32 v194, v189, v51
	v_fmac_f32_e32 v195, v193, v51
	v_fmac_f32_e32 v132, v189, v63
	v_fmac_f32_e32 v133, v193, v63
	v_add_f32_dpp v194, v194, v194 quad_perm:[1,0,3,2] row_mask:0xf bank_mask:0xf bound_ctrl:1
	v_add_f32_dpp v195, v195, v195 quad_perm:[1,0,3,2] row_mask:0xf bank_mask:0xf bound_ctrl:1
	v_add_f32_dpp v132, v132, v132 quad_perm:[1,0,3,2] row_mask:0xf bank_mask:0xf bound_ctrl:1
	v_add_f32_dpp v133, v133, v133 quad_perm:[1,0,3,2] row_mask:0xf bank_mask:0xf bound_ctrl:1
	v_add_f32_dpp v194, v194, v194 quad_perm:[2,3,0,1] row_mask:0xf bank_mask:0xf bound_ctrl:1
	v_add_f32_dpp v195, v195, v195 quad_perm:[2,3,0,1] row_mask:0xf bank_mask:0xf bound_ctrl:1
	v_add_f32_dpp v132, v132, v132 quad_perm:[2,3,0,1] row_mask:0xf bank_mask:0xf bound_ctrl:1
	v_add_f32_dpp v133, v133, v133 quad_perm:[2,3,0,1] row_mask:0xf bank_mask:0xf bound_ctrl:1
	v_add_f32_dpp v194, v194, v194 row_half_mirror row_mask:0xf bank_mask:0xf bound_ctrl:1
	v_add_f32_dpp v195, v195, v195 row_half_mirror row_mask:0xf bank_mask:0xf bound_ctrl:1
	v_add_f32_dpp v132, v132, v132 row_half_mirror row_mask:0xf bank_mask:0xf bound_ctrl:1
	v_add_f32_dpp v133, v133, v133 row_half_mirror row_mask:0xf bank_mask:0xf bound_ctrl:1
	v_add_f32_dpp v194, v194, v194 row_mirror row_mask:0xf bank_mask:0xf bound_ctrl:1
	v_add_f32_dpp v195, v195, v195 row_mirror row_mask:0xf bank_mask:0xf bound_ctrl:1
	v_fmac_f32_e32 v186, v130, v56
	v_fmac_f32_e32 v187, v130, v57
	v_fmac_f32_e32 v188, v130, v58
	v_fmac_f32_e32 v189, v130, v59
	v_fmac_f32_e32 v190, v131, v56
	v_fmac_f32_e32 v191, v131, v57
	v_fmac_f32_e32 v192, v131, v58
	v_fmac_f32_e32 v193, v131, v59
	v_fmac_f32_e32 v186, v194, v52
	v_fmac_f32_e32 v187, v194, v53
	v_fmac_f32_e32 v188, v194, v54
	v_fmac_f32_e32 v189, v194, v55
	v_fmac_f32_e32 v190, v195, v52
	v_fmac_f32_e32 v191, v195, v53
	v_fmac_f32_e32 v192, v195, v54
	v_fmac_f32_e32 v193, v195, v55
	s_mov_b64 exec, s[8:9]
	ds_write_b64 v161, v[132:133] offset:14848
	s_mov_b64 exec, -1
	ds_read_b128 v[48:51], v152 offset:14848
	ds_read_b128 v[52:55], v152 offset:23040
	ds_read_b128 v[56:59], v152 offset:31232
	ds_read_b128 v[60:63], v152 offset:39424
	ds_read_b64 v[130:131], v69 offset:6656
	s_waitcnt lgkmcnt(12)
	v_mul_f32_e32 v194, v186, v8
	v_mul_f32_e32 v195, v190, v8
	v_mul_f32_e32 v132, v186, v20
	v_mul_f32_e32 v133, v190, v20
	v_fmac_f32_e32 v194, v187, v9
	v_fmac_f32_e32 v195, v191, v9
	v_fmac_f32_e32 v132, v187, v21
	v_fmac_f32_e32 v133, v191, v21
	v_fmac_f32_e32 v194, v188, v10
	v_fmac_f32_e32 v195, v192, v10
	v_fmac_f32_e32 v132, v188, v22
	v_fmac_f32_e32 v133, v192, v22
	v_fmac_f32_e32 v194, v189, v11
	v_fmac_f32_e32 v195, v193, v11
	v_fmac_f32_e32 v132, v189, v23
	v_fmac_f32_e32 v133, v193, v23
	v_add_f32_dpp v194, v194, v194 quad_perm:[1,0,3,2] row_mask:0xf bank_mask:0xf bound_ctrl:1
	v_add_f32_dpp v195, v195, v195 quad_perm:[1,0,3,2] row_mask:0xf bank_mask:0xf bound_ctrl:1
	v_add_f32_dpp v132, v132, v132 quad_perm:[1,0,3,2] row_mask:0xf bank_mask:0xf bound_ctrl:1
	v_add_f32_dpp v133, v133, v133 quad_perm:[1,0,3,2] row_mask:0xf bank_mask:0xf bound_ctrl:1
	v_add_f32_dpp v194, v194, v194 quad_perm:[2,3,0,1] row_mask:0xf bank_mask:0xf bound_ctrl:1
	v_add_f32_dpp v195, v195, v195 quad_perm:[2,3,0,1] row_mask:0xf bank_mask:0xf bound_ctrl:1
	v_add_f32_dpp v132, v132, v132 quad_perm:[2,3,0,1] row_mask:0xf bank_mask:0xf bound_ctrl:1
	v_add_f32_dpp v133, v133, v133 quad_perm:[2,3,0,1] row_mask:0xf bank_mask:0xf bound_ctrl:1
	v_add_f32_dpp v194, v194, v194 row_half_mirror row_mask:0xf bank_mask:0xf bound_ctrl:1
	v_add_f32_dpp v195, v195, v195 row_half_mirror row_mask:0xf bank_mask:0xf bound_ctrl:1
	v_add_f32_dpp v132, v132, v132 row_half_mirror row_mask:0xf bank_mask:0xf bound_ctrl:1
	v_add_f32_dpp v133, v133, v133 row_half_mirror row_mask:0xf bank_mask:0xf bound_ctrl:1
	v_add_f32_dpp v194, v194, v194 row_mirror row_mask:0xf bank_mask:0xf bound_ctrl:1
	v_add_f32_dpp v195, v195, v195 row_mirror row_mask:0xf bank_mask:0xf bound_ctrl:1
	v_fmac_f32_e32 v186, v64, v16
	v_fmac_f32_e32 v187, v64, v17
	v_fmac_f32_e32 v188, v64, v18
	v_fmac_f32_e32 v189, v64, v19
	v_fmac_f32_e32 v190, v65, v16
	v_fmac_f32_e32 v191, v65, v17
	v_fmac_f32_e32 v192, v65, v18
	v_fmac_f32_e32 v193, v65, v19
	v_fmac_f32_e32 v186, v194, v12
	v_fmac_f32_e32 v187, v194, v13
	v_fmac_f32_e32 v188, v194, v14
	v_fmac_f32_e32 v189, v194, v15
	v_fmac_f32_e32 v190, v195, v12
	v_fmac_f32_e32 v191, v195, v13
	v_fmac_f32_e32 v192, v195, v14
	v_fmac_f32_e32 v193, v195, v15
	s_mov_b64 exec, s[8:9]
	ds_write_b64 v161, v[132:133] offset:14336
	s_mov_b64 exec, -1
	ds_read_b128 v[8:11], v152 offset:14592
	ds_read_b128 v[12:15], v152 offset:22784
	ds_read_b128 v[16:19], v152 offset:30976
	ds_read_b128 v[20:23], v152 offset:39168
	ds_read_b64 v[64:65], v69 offset:6400
	s_waitcnt lgkmcnt(12)
	v_mul_f32_e32 v194, v186, v28
	v_mul_f32_e32 v195, v190, v28
	v_mul_f32_e32 v132, v186, v40
	v_mul_f32_e32 v133, v190, v40
	v_fmac_f32_e32 v194, v187, v29
	v_fmac_f32_e32 v195, v191, v29
	v_fmac_f32_e32 v132, v187, v41
	v_fmac_f32_e32 v133, v191, v41
	v_fmac_f32_e32 v194, v188, v30
	v_fmac_f32_e32 v195, v192, v30
	v_fmac_f32_e32 v132, v188, v42
	v_fmac_f32_e32 v133, v192, v42
	v_fmac_f32_e32 v194, v189, v31
	v_fmac_f32_e32 v195, v193, v31
	v_fmac_f32_e32 v132, v189, v43
	v_fmac_f32_e32 v133, v193, v43
	v_add_f32_dpp v194, v194, v194 quad_perm:[1,0,3,2] row_mask:0xf bank_mask:0xf bound_ctrl:1
	v_add_f32_dpp v195, v195, v195 quad_perm:[1,0,3,2] row_mask:0xf bank_mask:0xf bound_ctrl:1
	v_add_f32_dpp v132, v132, v132 quad_perm:[1,0,3,2] row_mask:0xf bank_mask:0xf bound_ctrl:1
	v_add_f32_dpp v133, v133, v133 quad_perm:[1,0,3,2] row_mask:0xf bank_mask:0xf bound_ctrl:1
	v_add_f32_dpp v194, v194, v194 quad_perm:[2,3,0,1] row_mask:0xf bank_mask:0xf bound_ctrl:1
	v_add_f32_dpp v195, v195, v195 quad_perm:[2,3,0,1] row_mask:0xf bank_mask:0xf bound_ctrl:1
	v_add_f32_dpp v132, v132, v132 quad_perm:[2,3,0,1] row_mask:0xf bank_mask:0xf bound_ctrl:1
	v_add_f32_dpp v133, v133, v133 quad_perm:[2,3,0,1] row_mask:0xf bank_mask:0xf bound_ctrl:1
	v_add_f32_dpp v194, v194, v194 row_half_mirror row_mask:0xf bank_mask:0xf bound_ctrl:1
	v_add_f32_dpp v195, v195, v195 row_half_mirror row_mask:0xf bank_mask:0xf bound_ctrl:1
	v_add_f32_dpp v132, v132, v132 row_half_mirror row_mask:0xf bank_mask:0xf bound_ctrl:1
	v_add_f32_dpp v133, v133, v133 row_half_mirror row_mask:0xf bank_mask:0xf bound_ctrl:1
	v_add_f32_dpp v194, v194, v194 row_mirror row_mask:0xf bank_mask:0xf bound_ctrl:1
	v_add_f32_dpp v195, v195, v195 row_mirror row_mask:0xf bank_mask:0xf bound_ctrl:1
	v_fmac_f32_e32 v186, v66, v36
	v_fmac_f32_e32 v187, v66, v37
	v_fmac_f32_e32 v188, v66, v38
	v_fmac_f32_e32 v189, v66, v39
	v_fmac_f32_e32 v190, v67, v36
	v_fmac_f32_e32 v191, v67, v37
	v_fmac_f32_e32 v192, v67, v38
	v_fmac_f32_e32 v193, v67, v39
	v_fmac_f32_e32 v186, v194, v32
	v_fmac_f32_e32 v187, v194, v33
	v_fmac_f32_e32 v188, v194, v34
	v_fmac_f32_e32 v189, v194, v35
	v_fmac_f32_e32 v190, v195, v32
	v_fmac_f32_e32 v191, v195, v33
	v_fmac_f32_e32 v192, v195, v34
	v_fmac_f32_e32 v193, v195, v35
	s_mov_b64 exec, s[8:9]
	ds_write_b64 v161, v[132:133] offset:13824
	s_mov_b64 exec, -1
	ds_read_b128 v[28:31], v152 offset:14336
	ds_read_b128 v[32:35], v152 offset:22528
	ds_read_b128 v[36:39], v152 offset:30720
	ds_read_b128 v[40:43], v152 offset:38912
	ds_read_b64 v[66:67], v69 offset:6144
	s_waitcnt lgkmcnt(12)
	v_mul_f32_e32 v194, v186, v48
	v_mul_f32_e32 v195, v190, v48
	v_mul_f32_e32 v132, v186, v60
	v_mul_f32_e32 v133, v190, v60
	v_fmac_f32_e32 v194, v187, v49
	v_fmac_f32_e32 v195, v191, v49
	v_fmac_f32_e32 v132, v187, v61
	v_fmac_f32_e32 v133, v191, v61
	v_fmac_f32_e32 v194, v188, v50
	v_fmac_f32_e32 v195, v192, v50
	v_fmac_f32_e32 v132, v188, v62
	v_fmac_f32_e32 v133, v192, v62
	v_fmac_f32_e32 v194, v189, v51
	v_fmac_f32_e32 v195, v193, v51
	v_fmac_f32_e32 v132, v189, v63
	v_fmac_f32_e32 v133, v193, v63
	v_add_f32_dpp v194, v194, v194 quad_perm:[1,0,3,2] row_mask:0xf bank_mask:0xf bound_ctrl:1
	v_add_f32_dpp v195, v195, v195 quad_perm:[1,0,3,2] row_mask:0xf bank_mask:0xf bound_ctrl:1
	v_add_f32_dpp v132, v132, v132 quad_perm:[1,0,3,2] row_mask:0xf bank_mask:0xf bound_ctrl:1
	v_add_f32_dpp v133, v133, v133 quad_perm:[1,0,3,2] row_mask:0xf bank_mask:0xf bound_ctrl:1
	v_add_f32_dpp v194, v194, v194 quad_perm:[2,3,0,1] row_mask:0xf bank_mask:0xf bound_ctrl:1
	v_add_f32_dpp v195, v195, v195 quad_perm:[2,3,0,1] row_mask:0xf bank_mask:0xf bound_ctrl:1
	v_add_f32_dpp v132, v132, v132 quad_perm:[2,3,0,1] row_mask:0xf bank_mask:0xf bound_ctrl:1
	v_add_f32_dpp v133, v133, v133 quad_perm:[2,3,0,1] row_mask:0xf bank_mask:0xf bound_ctrl:1
	v_add_f32_dpp v194, v194, v194 row_half_mirror row_mask:0xf bank_mask:0xf bound_ctrl:1
	v_add_f32_dpp v195, v195, v195 row_half_mirror row_mask:0xf bank_mask:0xf bound_ctrl:1
	v_add_f32_dpp v132, v132, v132 row_half_mirror row_mask:0xf bank_mask:0xf bound_ctrl:1
	v_add_f32_dpp v133, v133, v133 row_half_mirror row_mask:0xf bank_mask:0xf bound_ctrl:1
	v_add_f32_dpp v194, v194, v194 row_mirror row_mask:0xf bank_mask:0xf bound_ctrl:1
	v_add_f32_dpp v195, v195, v195 row_mirror row_mask:0xf bank_mask:0xf bound_ctrl:1
	v_fmac_f32_e32 v186, v130, v56
	v_fmac_f32_e32 v187, v130, v57
	v_fmac_f32_e32 v188, v130, v58
	v_fmac_f32_e32 v189, v130, v59
	v_fmac_f32_e32 v190, v131, v56
	v_fmac_f32_e32 v191, v131, v57
	v_fmac_f32_e32 v192, v131, v58
	v_fmac_f32_e32 v193, v131, v59
	v_fmac_f32_e32 v186, v194, v52
	v_fmac_f32_e32 v187, v194, v53
	v_fmac_f32_e32 v188, v194, v54
	v_fmac_f32_e32 v189, v194, v55
	v_fmac_f32_e32 v190, v195, v52
	v_fmac_f32_e32 v191, v195, v53
	v_fmac_f32_e32 v192, v195, v54
	v_fmac_f32_e32 v193, v195, v55
	s_mov_b64 exec, s[8:9]
	ds_write_b64 v161, v[132:133] offset:13312
	s_mov_b64 exec, -1
	ds_read_b128 v[48:51], v152 offset:14080
	ds_read_b128 v[52:55], v152 offset:22272
	ds_read_b128 v[56:59], v152 offset:30464
	ds_read_b128 v[60:63], v152 offset:38656
	ds_read_b64 v[130:131], v69 offset:5888
	s_waitcnt lgkmcnt(12)
	v_mul_f32_e32 v194, v186, v8
	v_mul_f32_e32 v195, v190, v8
	v_mul_f32_e32 v132, v186, v20
	v_mul_f32_e32 v133, v190, v20
	v_fmac_f32_e32 v194, v187, v9
	v_fmac_f32_e32 v195, v191, v9
	v_fmac_f32_e32 v132, v187, v21
	v_fmac_f32_e32 v133, v191, v21
	v_fmac_f32_e32 v194, v188, v10
	v_fmac_f32_e32 v195, v192, v10
	v_fmac_f32_e32 v132, v188, v22
	v_fmac_f32_e32 v133, v192, v22
	v_fmac_f32_e32 v194, v189, v11
	v_fmac_f32_e32 v195, v193, v11
	v_fmac_f32_e32 v132, v189, v23
	v_fmac_f32_e32 v133, v193, v23
	v_add_f32_dpp v194, v194, v194 quad_perm:[1,0,3,2] row_mask:0xf bank_mask:0xf bound_ctrl:1
	v_add_f32_dpp v195, v195, v195 quad_perm:[1,0,3,2] row_mask:0xf bank_mask:0xf bound_ctrl:1
	v_add_f32_dpp v132, v132, v132 quad_perm:[1,0,3,2] row_mask:0xf bank_mask:0xf bound_ctrl:1
	v_add_f32_dpp v133, v133, v133 quad_perm:[1,0,3,2] row_mask:0xf bank_mask:0xf bound_ctrl:1
	v_add_f32_dpp v194, v194, v194 quad_perm:[2,3,0,1] row_mask:0xf bank_mask:0xf bound_ctrl:1
	v_add_f32_dpp v195, v195, v195 quad_perm:[2,3,0,1] row_mask:0xf bank_mask:0xf bound_ctrl:1
	v_add_f32_dpp v132, v132, v132 quad_perm:[2,3,0,1] row_mask:0xf bank_mask:0xf bound_ctrl:1
	v_add_f32_dpp v133, v133, v133 quad_perm:[2,3,0,1] row_mask:0xf bank_mask:0xf bound_ctrl:1
	v_add_f32_dpp v194, v194, v194 row_half_mirror row_mask:0xf bank_mask:0xf bound_ctrl:1
	v_add_f32_dpp v195, v195, v195 row_half_mirror row_mask:0xf bank_mask:0xf bound_ctrl:1
	v_add_f32_dpp v132, v132, v132 row_half_mirror row_mask:0xf bank_mask:0xf bound_ctrl:1
	v_add_f32_dpp v133, v133, v133 row_half_mirror row_mask:0xf bank_mask:0xf bound_ctrl:1
	v_add_f32_dpp v194, v194, v194 row_mirror row_mask:0xf bank_mask:0xf bound_ctrl:1
	v_add_f32_dpp v195, v195, v195 row_mirror row_mask:0xf bank_mask:0xf bound_ctrl:1
	v_fmac_f32_e32 v186, v64, v16
	v_fmac_f32_e32 v187, v64, v17
	v_fmac_f32_e32 v188, v64, v18
	v_fmac_f32_e32 v189, v64, v19
	v_fmac_f32_e32 v190, v65, v16
	v_fmac_f32_e32 v191, v65, v17
	v_fmac_f32_e32 v192, v65, v18
	v_fmac_f32_e32 v193, v65, v19
	v_fmac_f32_e32 v186, v194, v12
	v_fmac_f32_e32 v187, v194, v13
	v_fmac_f32_e32 v188, v194, v14
	v_fmac_f32_e32 v189, v194, v15
	v_fmac_f32_e32 v190, v195, v12
	v_fmac_f32_e32 v191, v195, v13
	v_fmac_f32_e32 v192, v195, v14
	v_fmac_f32_e32 v193, v195, v15
	s_mov_b64 exec, s[8:9]
	ds_write_b64 v161, v[132:133] offset:12800
	s_mov_b64 exec, -1
	ds_read_b128 v[8:11], v152 offset:13824
	ds_read_b128 v[12:15], v152 offset:22016
	ds_read_b128 v[16:19], v152 offset:30208
	ds_read_b128 v[20:23], v152 offset:38400
	ds_read_b64 v[64:65], v69 offset:5632
	s_waitcnt lgkmcnt(12)
	v_mul_f32_e32 v194, v186, v28
	v_mul_f32_e32 v195, v190, v28
	v_mul_f32_e32 v132, v186, v40
	v_mul_f32_e32 v133, v190, v40
	v_fmac_f32_e32 v194, v187, v29
	v_fmac_f32_e32 v195, v191, v29
	v_fmac_f32_e32 v132, v187, v41
	v_fmac_f32_e32 v133, v191, v41
	v_fmac_f32_e32 v194, v188, v30
	v_fmac_f32_e32 v195, v192, v30
	v_fmac_f32_e32 v132, v188, v42
	v_fmac_f32_e32 v133, v192, v42
	v_fmac_f32_e32 v194, v189, v31
	v_fmac_f32_e32 v195, v193, v31
	v_fmac_f32_e32 v132, v189, v43
	v_fmac_f32_e32 v133, v193, v43
	v_add_f32_dpp v194, v194, v194 quad_perm:[1,0,3,2] row_mask:0xf bank_mask:0xf bound_ctrl:1
	v_add_f32_dpp v195, v195, v195 quad_perm:[1,0,3,2] row_mask:0xf bank_mask:0xf bound_ctrl:1
	v_add_f32_dpp v132, v132, v132 quad_perm:[1,0,3,2] row_mask:0xf bank_mask:0xf bound_ctrl:1
	v_add_f32_dpp v133, v133, v133 quad_perm:[1,0,3,2] row_mask:0xf bank_mask:0xf bound_ctrl:1
	v_add_f32_dpp v194, v194, v194 quad_perm:[2,3,0,1] row_mask:0xf bank_mask:0xf bound_ctrl:1
	v_add_f32_dpp v195, v195, v195 quad_perm:[2,3,0,1] row_mask:0xf bank_mask:0xf bound_ctrl:1
	v_add_f32_dpp v132, v132, v132 quad_perm:[2,3,0,1] row_mask:0xf bank_mask:0xf bound_ctrl:1
	v_add_f32_dpp v133, v133, v133 quad_perm:[2,3,0,1] row_mask:0xf bank_mask:0xf bound_ctrl:1
	v_add_f32_dpp v194, v194, v194 row_half_mirror row_mask:0xf bank_mask:0xf bound_ctrl:1
	v_add_f32_dpp v195, v195, v195 row_half_mirror row_mask:0xf bank_mask:0xf bound_ctrl:1
	v_add_f32_dpp v132, v132, v132 row_half_mirror row_mask:0xf bank_mask:0xf bound_ctrl:1
	v_add_f32_dpp v133, v133, v133 row_half_mirror row_mask:0xf bank_mask:0xf bound_ctrl:1
	v_add_f32_dpp v194, v194, v194 row_mirror row_mask:0xf bank_mask:0xf bound_ctrl:1
	v_add_f32_dpp v195, v195, v195 row_mirror row_mask:0xf bank_mask:0xf bound_ctrl:1
	v_fmac_f32_e32 v186, v66, v36
	v_fmac_f32_e32 v187, v66, v37
	v_fmac_f32_e32 v188, v66, v38
	v_fmac_f32_e32 v189, v66, v39
	v_fmac_f32_e32 v190, v67, v36
	v_fmac_f32_e32 v191, v67, v37
	v_fmac_f32_e32 v192, v67, v38
	v_fmac_f32_e32 v193, v67, v39
	v_fmac_f32_e32 v186, v194, v32
	v_fmac_f32_e32 v187, v194, v33
	v_fmac_f32_e32 v188, v194, v34
	v_fmac_f32_e32 v189, v194, v35
	v_fmac_f32_e32 v190, v195, v32
	v_fmac_f32_e32 v191, v195, v33
	v_fmac_f32_e32 v192, v195, v34
	v_fmac_f32_e32 v193, v195, v35
	s_mov_b64 exec, s[8:9]
	ds_write_b64 v161, v[132:133] offset:12288
	s_mov_b64 exec, -1
	ds_read_b128 v[28:31], v152 offset:13568
	ds_read_b128 v[32:35], v152 offset:21760
	ds_read_b128 v[36:39], v152 offset:29952
	ds_read_b128 v[40:43], v152 offset:38144
	ds_read_b64 v[66:67], v69 offset:5376
	s_waitcnt lgkmcnt(12)
	v_mul_f32_e32 v194, v186, v48
	v_mul_f32_e32 v195, v190, v48
	v_mul_f32_e32 v132, v186, v60
	v_mul_f32_e32 v133, v190, v60
	v_fmac_f32_e32 v194, v187, v49
	v_fmac_f32_e32 v195, v191, v49
	v_fmac_f32_e32 v132, v187, v61
	v_fmac_f32_e32 v133, v191, v61
	v_fmac_f32_e32 v194, v188, v50
	v_fmac_f32_e32 v195, v192, v50
	v_fmac_f32_e32 v132, v188, v62
	v_fmac_f32_e32 v133, v192, v62
	v_fmac_f32_e32 v194, v189, v51
	v_fmac_f32_e32 v195, v193, v51
	v_fmac_f32_e32 v132, v189, v63
	v_fmac_f32_e32 v133, v193, v63
	v_add_f32_dpp v194, v194, v194 quad_perm:[1,0,3,2] row_mask:0xf bank_mask:0xf bound_ctrl:1
	v_add_f32_dpp v195, v195, v195 quad_perm:[1,0,3,2] row_mask:0xf bank_mask:0xf bound_ctrl:1
	v_add_f32_dpp v132, v132, v132 quad_perm:[1,0,3,2] row_mask:0xf bank_mask:0xf bound_ctrl:1
	v_add_f32_dpp v133, v133, v133 quad_perm:[1,0,3,2] row_mask:0xf bank_mask:0xf bound_ctrl:1
	v_add_f32_dpp v194, v194, v194 quad_perm:[2,3,0,1] row_mask:0xf bank_mask:0xf bound_ctrl:1
	v_add_f32_dpp v195, v195, v195 quad_perm:[2,3,0,1] row_mask:0xf bank_mask:0xf bound_ctrl:1
	v_add_f32_dpp v132, v132, v132 quad_perm:[2,3,0,1] row_mask:0xf bank_mask:0xf bound_ctrl:1
	v_add_f32_dpp v133, v133, v133 quad_perm:[2,3,0,1] row_mask:0xf bank_mask:0xf bound_ctrl:1
	v_add_f32_dpp v194, v194, v194 row_half_mirror row_mask:0xf bank_mask:0xf bound_ctrl:1
	v_add_f32_dpp v195, v195, v195 row_half_mirror row_mask:0xf bank_mask:0xf bound_ctrl:1
	v_add_f32_dpp v132, v132, v132 row_half_mirror row_mask:0xf bank_mask:0xf bound_ctrl:1
	v_add_f32_dpp v133, v133, v133 row_half_mirror row_mask:0xf bank_mask:0xf bound_ctrl:1
	v_add_f32_dpp v194, v194, v194 row_mirror row_mask:0xf bank_mask:0xf bound_ctrl:1
	v_add_f32_dpp v195, v195, v195 row_mirror row_mask:0xf bank_mask:0xf bound_ctrl:1
	v_fmac_f32_e32 v186, v130, v56
	v_fmac_f32_e32 v187, v130, v57
	v_fmac_f32_e32 v188, v130, v58
	v_fmac_f32_e32 v189, v130, v59
	v_fmac_f32_e32 v190, v131, v56
	v_fmac_f32_e32 v191, v131, v57
	v_fmac_f32_e32 v192, v131, v58
	v_fmac_f32_e32 v193, v131, v59
	v_fmac_f32_e32 v186, v194, v52
	v_fmac_f32_e32 v187, v194, v53
	v_fmac_f32_e32 v188, v194, v54
	v_fmac_f32_e32 v189, v194, v55
	v_fmac_f32_e32 v190, v195, v52
	v_fmac_f32_e32 v191, v195, v53
	v_fmac_f32_e32 v192, v195, v54
	v_fmac_f32_e32 v193, v195, v55
	s_mov_b64 exec, s[8:9]
	ds_write_b64 v161, v[132:133] offset:11776
	s_mov_b64 exec, -1
	ds_read_b128 v[48:51], v152 offset:13312
	ds_read_b128 v[52:55], v152 offset:21504
	ds_read_b128 v[56:59], v152 offset:29696
	ds_read_b128 v[60:63], v152 offset:37888
	ds_read_b64 v[130:131], v69 offset:5120
	s_waitcnt lgkmcnt(12)
	v_mul_f32_e32 v194, v186, v8
	v_mul_f32_e32 v195, v190, v8
	v_mul_f32_e32 v132, v186, v20
	v_mul_f32_e32 v133, v190, v20
	v_fmac_f32_e32 v194, v187, v9
	v_fmac_f32_e32 v195, v191, v9
	v_fmac_f32_e32 v132, v187, v21
	v_fmac_f32_e32 v133, v191, v21
	v_fmac_f32_e32 v194, v188, v10
	v_fmac_f32_e32 v195, v192, v10
	v_fmac_f32_e32 v132, v188, v22
	v_fmac_f32_e32 v133, v192, v22
	v_fmac_f32_e32 v194, v189, v11
	v_fmac_f32_e32 v195, v193, v11
	v_fmac_f32_e32 v132, v189, v23
	v_fmac_f32_e32 v133, v193, v23
	v_add_f32_dpp v194, v194, v194 quad_perm:[1,0,3,2] row_mask:0xf bank_mask:0xf bound_ctrl:1
	v_add_f32_dpp v195, v195, v195 quad_perm:[1,0,3,2] row_mask:0xf bank_mask:0xf bound_ctrl:1
	v_add_f32_dpp v132, v132, v132 quad_perm:[1,0,3,2] row_mask:0xf bank_mask:0xf bound_ctrl:1
	v_add_f32_dpp v133, v133, v133 quad_perm:[1,0,3,2] row_mask:0xf bank_mask:0xf bound_ctrl:1
	v_add_f32_dpp v194, v194, v194 quad_perm:[2,3,0,1] row_mask:0xf bank_mask:0xf bound_ctrl:1
	v_add_f32_dpp v195, v195, v195 quad_perm:[2,3,0,1] row_mask:0xf bank_mask:0xf bound_ctrl:1
	v_add_f32_dpp v132, v132, v132 quad_perm:[2,3,0,1] row_mask:0xf bank_mask:0xf bound_ctrl:1
	v_add_f32_dpp v133, v133, v133 quad_perm:[2,3,0,1] row_mask:0xf bank_mask:0xf bound_ctrl:1
	v_add_f32_dpp v194, v194, v194 row_half_mirror row_mask:0xf bank_mask:0xf bound_ctrl:1
	v_add_f32_dpp v195, v195, v195 row_half_mirror row_mask:0xf bank_mask:0xf bound_ctrl:1
	v_add_f32_dpp v132, v132, v132 row_half_mirror row_mask:0xf bank_mask:0xf bound_ctrl:1
	v_add_f32_dpp v133, v133, v133 row_half_mirror row_mask:0xf bank_mask:0xf bound_ctrl:1
	v_add_f32_dpp v194, v194, v194 row_mirror row_mask:0xf bank_mask:0xf bound_ctrl:1
	v_add_f32_dpp v195, v195, v195 row_mirror row_mask:0xf bank_mask:0xf bound_ctrl:1
	v_fmac_f32_e32 v186, v64, v16
	v_fmac_f32_e32 v187, v64, v17
	v_fmac_f32_e32 v188, v64, v18
	v_fmac_f32_e32 v189, v64, v19
	v_fmac_f32_e32 v190, v65, v16
	v_fmac_f32_e32 v191, v65, v17
	v_fmac_f32_e32 v192, v65, v18
	v_fmac_f32_e32 v193, v65, v19
	v_fmac_f32_e32 v186, v194, v12
	v_fmac_f32_e32 v187, v194, v13
	v_fmac_f32_e32 v188, v194, v14
	v_fmac_f32_e32 v189, v194, v15
	v_fmac_f32_e32 v190, v195, v12
	v_fmac_f32_e32 v191, v195, v13
	v_fmac_f32_e32 v192, v195, v14
	v_fmac_f32_e32 v193, v195, v15
	s_mov_b64 exec, s[8:9]
	ds_write_b64 v161, v[132:133] offset:11264
	s_mov_b64 exec, -1
	ds_read_b128 v[8:11], v152 offset:13056
	ds_read_b128 v[12:15], v152 offset:21248
	ds_read_b128 v[16:19], v152 offset:29440
	ds_read_b128 v[20:23], v152 offset:37632
	ds_read_b64 v[64:65], v69 offset:4864
	s_waitcnt lgkmcnt(12)
	v_mul_f32_e32 v194, v186, v28
	v_mul_f32_e32 v195, v190, v28
	v_mul_f32_e32 v132, v186, v40
	v_mul_f32_e32 v133, v190, v40
	v_fmac_f32_e32 v194, v187, v29
	v_fmac_f32_e32 v195, v191, v29
	v_fmac_f32_e32 v132, v187, v41
	v_fmac_f32_e32 v133, v191, v41
	v_fmac_f32_e32 v194, v188, v30
	v_fmac_f32_e32 v195, v192, v30
	v_fmac_f32_e32 v132, v188, v42
	v_fmac_f32_e32 v133, v192, v42
	v_fmac_f32_e32 v194, v189, v31
	v_fmac_f32_e32 v195, v193, v31
	v_fmac_f32_e32 v132, v189, v43
	v_fmac_f32_e32 v133, v193, v43
	v_add_f32_dpp v194, v194, v194 quad_perm:[1,0,3,2] row_mask:0xf bank_mask:0xf bound_ctrl:1
	v_add_f32_dpp v195, v195, v195 quad_perm:[1,0,3,2] row_mask:0xf bank_mask:0xf bound_ctrl:1
	v_add_f32_dpp v132, v132, v132 quad_perm:[1,0,3,2] row_mask:0xf bank_mask:0xf bound_ctrl:1
	v_add_f32_dpp v133, v133, v133 quad_perm:[1,0,3,2] row_mask:0xf bank_mask:0xf bound_ctrl:1
	v_add_f32_dpp v194, v194, v194 quad_perm:[2,3,0,1] row_mask:0xf bank_mask:0xf bound_ctrl:1
	v_add_f32_dpp v195, v195, v195 quad_perm:[2,3,0,1] row_mask:0xf bank_mask:0xf bound_ctrl:1
	v_add_f32_dpp v132, v132, v132 quad_perm:[2,3,0,1] row_mask:0xf bank_mask:0xf bound_ctrl:1
	v_add_f32_dpp v133, v133, v133 quad_perm:[2,3,0,1] row_mask:0xf bank_mask:0xf bound_ctrl:1
	v_add_f32_dpp v194, v194, v194 row_half_mirror row_mask:0xf bank_mask:0xf bound_ctrl:1
	v_add_f32_dpp v195, v195, v195 row_half_mirror row_mask:0xf bank_mask:0xf bound_ctrl:1
	v_add_f32_dpp v132, v132, v132 row_half_mirror row_mask:0xf bank_mask:0xf bound_ctrl:1
	v_add_f32_dpp v133, v133, v133 row_half_mirror row_mask:0xf bank_mask:0xf bound_ctrl:1
	v_add_f32_dpp v194, v194, v194 row_mirror row_mask:0xf bank_mask:0xf bound_ctrl:1
	v_add_f32_dpp v195, v195, v195 row_mirror row_mask:0xf bank_mask:0xf bound_ctrl:1
	v_fmac_f32_e32 v186, v66, v36
	v_fmac_f32_e32 v187, v66, v37
	v_fmac_f32_e32 v188, v66, v38
	v_fmac_f32_e32 v189, v66, v39
	v_fmac_f32_e32 v190, v67, v36
	v_fmac_f32_e32 v191, v67, v37
	v_fmac_f32_e32 v192, v67, v38
	v_fmac_f32_e32 v193, v67, v39
	v_fmac_f32_e32 v186, v194, v32
	v_fmac_f32_e32 v187, v194, v33
	v_fmac_f32_e32 v188, v194, v34
	v_fmac_f32_e32 v189, v194, v35
	v_fmac_f32_e32 v190, v195, v32
	v_fmac_f32_e32 v191, v195, v33
	v_fmac_f32_e32 v192, v195, v34
	v_fmac_f32_e32 v193, v195, v35
	s_mov_b64 exec, s[8:9]
	ds_write_b64 v161, v[132:133] offset:10752
	s_mov_b64 exec, -1
	ds_read_b128 v[28:31], v152 offset:12800
	ds_read_b128 v[32:35], v152 offset:20992
	ds_read_b128 v[36:39], v152 offset:29184
	ds_read_b128 v[40:43], v152 offset:37376
	ds_read_b64 v[66:67], v69 offset:4608
	s_waitcnt lgkmcnt(12)
	v_mul_f32_e32 v194, v186, v48
	v_mul_f32_e32 v195, v190, v48
	v_mul_f32_e32 v132, v186, v60
	v_mul_f32_e32 v133, v190, v60
	v_fmac_f32_e32 v194, v187, v49
	v_fmac_f32_e32 v195, v191, v49
	v_fmac_f32_e32 v132, v187, v61
	v_fmac_f32_e32 v133, v191, v61
	v_fmac_f32_e32 v194, v188, v50
	v_fmac_f32_e32 v195, v192, v50
	v_fmac_f32_e32 v132, v188, v62
	v_fmac_f32_e32 v133, v192, v62
	v_fmac_f32_e32 v194, v189, v51
	v_fmac_f32_e32 v195, v193, v51
	v_fmac_f32_e32 v132, v189, v63
	v_fmac_f32_e32 v133, v193, v63
	v_add_f32_dpp v194, v194, v194 quad_perm:[1,0,3,2] row_mask:0xf bank_mask:0xf bound_ctrl:1
	v_add_f32_dpp v195, v195, v195 quad_perm:[1,0,3,2] row_mask:0xf bank_mask:0xf bound_ctrl:1
	v_add_f32_dpp v132, v132, v132 quad_perm:[1,0,3,2] row_mask:0xf bank_mask:0xf bound_ctrl:1
	v_add_f32_dpp v133, v133, v133 quad_perm:[1,0,3,2] row_mask:0xf bank_mask:0xf bound_ctrl:1
	v_add_f32_dpp v194, v194, v194 quad_perm:[2,3,0,1] row_mask:0xf bank_mask:0xf bound_ctrl:1
	v_add_f32_dpp v195, v195, v195 quad_perm:[2,3,0,1] row_mask:0xf bank_mask:0xf bound_ctrl:1
	v_add_f32_dpp v132, v132, v132 quad_perm:[2,3,0,1] row_mask:0xf bank_mask:0xf bound_ctrl:1
	v_add_f32_dpp v133, v133, v133 quad_perm:[2,3,0,1] row_mask:0xf bank_mask:0xf bound_ctrl:1
	v_add_f32_dpp v194, v194, v194 row_half_mirror row_mask:0xf bank_mask:0xf bound_ctrl:1
	v_add_f32_dpp v195, v195, v195 row_half_mirror row_mask:0xf bank_mask:0xf bound_ctrl:1
	v_add_f32_dpp v132, v132, v132 row_half_mirror row_mask:0xf bank_mask:0xf bound_ctrl:1
	v_add_f32_dpp v133, v133, v133 row_half_mirror row_mask:0xf bank_mask:0xf bound_ctrl:1
	v_add_f32_dpp v194, v194, v194 row_mirror row_mask:0xf bank_mask:0xf bound_ctrl:1
	v_add_f32_dpp v195, v195, v195 row_mirror row_mask:0xf bank_mask:0xf bound_ctrl:1
	v_fmac_f32_e32 v186, v130, v56
	v_fmac_f32_e32 v187, v130, v57
	v_fmac_f32_e32 v188, v130, v58
	v_fmac_f32_e32 v189, v130, v59
	v_fmac_f32_e32 v190, v131, v56
	v_fmac_f32_e32 v191, v131, v57
	v_fmac_f32_e32 v192, v131, v58
	v_fmac_f32_e32 v193, v131, v59
	v_fmac_f32_e32 v186, v194, v52
	v_fmac_f32_e32 v187, v194, v53
	v_fmac_f32_e32 v188, v194, v54
	v_fmac_f32_e32 v189, v194, v55
	v_fmac_f32_e32 v190, v195, v52
	v_fmac_f32_e32 v191, v195, v53
	v_fmac_f32_e32 v192, v195, v54
	v_fmac_f32_e32 v193, v195, v55
	s_mov_b64 exec, s[8:9]
	ds_write_b64 v161, v[132:133] offset:10240
	s_mov_b64 exec, -1
	ds_read_b128 v[48:51], v152 offset:12544
	ds_read_b128 v[52:55], v152 offset:20736
	ds_read_b128 v[56:59], v152 offset:28928
	ds_read_b128 v[60:63], v152 offset:37120
	ds_read_b64 v[130:131], v69 offset:4352
	s_waitcnt lgkmcnt(12)
	v_mul_f32_e32 v194, v186, v8
	v_mul_f32_e32 v195, v190, v8
	v_mul_f32_e32 v132, v186, v20
	v_mul_f32_e32 v133, v190, v20
	v_fmac_f32_e32 v194, v187, v9
	v_fmac_f32_e32 v195, v191, v9
	v_fmac_f32_e32 v132, v187, v21
	v_fmac_f32_e32 v133, v191, v21
	v_fmac_f32_e32 v194, v188, v10
	v_fmac_f32_e32 v195, v192, v10
	v_fmac_f32_e32 v132, v188, v22
	v_fmac_f32_e32 v133, v192, v22
	v_fmac_f32_e32 v194, v189, v11
	v_fmac_f32_e32 v195, v193, v11
	v_fmac_f32_e32 v132, v189, v23
	v_fmac_f32_e32 v133, v193, v23
	v_add_f32_dpp v194, v194, v194 quad_perm:[1,0,3,2] row_mask:0xf bank_mask:0xf bound_ctrl:1
	v_add_f32_dpp v195, v195, v195 quad_perm:[1,0,3,2] row_mask:0xf bank_mask:0xf bound_ctrl:1
	v_add_f32_dpp v132, v132, v132 quad_perm:[1,0,3,2] row_mask:0xf bank_mask:0xf bound_ctrl:1
	v_add_f32_dpp v133, v133, v133 quad_perm:[1,0,3,2] row_mask:0xf bank_mask:0xf bound_ctrl:1
	v_add_f32_dpp v194, v194, v194 quad_perm:[2,3,0,1] row_mask:0xf bank_mask:0xf bound_ctrl:1
	v_add_f32_dpp v195, v195, v195 quad_perm:[2,3,0,1] row_mask:0xf bank_mask:0xf bound_ctrl:1
	v_add_f32_dpp v132, v132, v132 quad_perm:[2,3,0,1] row_mask:0xf bank_mask:0xf bound_ctrl:1
	v_add_f32_dpp v133, v133, v133 quad_perm:[2,3,0,1] row_mask:0xf bank_mask:0xf bound_ctrl:1
	v_add_f32_dpp v194, v194, v194 row_half_mirror row_mask:0xf bank_mask:0xf bound_ctrl:1
	v_add_f32_dpp v195, v195, v195 row_half_mirror row_mask:0xf bank_mask:0xf bound_ctrl:1
	v_add_f32_dpp v132, v132, v132 row_half_mirror row_mask:0xf bank_mask:0xf bound_ctrl:1
	v_add_f32_dpp v133, v133, v133 row_half_mirror row_mask:0xf bank_mask:0xf bound_ctrl:1
	v_add_f32_dpp v194, v194, v194 row_mirror row_mask:0xf bank_mask:0xf bound_ctrl:1
	v_add_f32_dpp v195, v195, v195 row_mirror row_mask:0xf bank_mask:0xf bound_ctrl:1
	v_fmac_f32_e32 v186, v64, v16
	v_fmac_f32_e32 v187, v64, v17
	v_fmac_f32_e32 v188, v64, v18
	v_fmac_f32_e32 v189, v64, v19
	v_fmac_f32_e32 v190, v65, v16
	v_fmac_f32_e32 v191, v65, v17
	v_fmac_f32_e32 v192, v65, v18
	v_fmac_f32_e32 v193, v65, v19
	v_fmac_f32_e32 v186, v194, v12
	v_fmac_f32_e32 v187, v194, v13
	v_fmac_f32_e32 v188, v194, v14
	v_fmac_f32_e32 v189, v194, v15
	v_fmac_f32_e32 v190, v195, v12
	v_fmac_f32_e32 v191, v195, v13
	v_fmac_f32_e32 v192, v195, v14
	v_fmac_f32_e32 v193, v195, v15
	s_mov_b64 exec, s[8:9]
	ds_write_b64 v161, v[132:133] offset:9728
	s_mov_b64 exec, -1
	ds_read_b128 v[8:11], v152 offset:12288
	ds_read_b128 v[12:15], v152 offset:20480
	ds_read_b128 v[16:19], v152 offset:28672
	ds_read_b128 v[20:23], v152 offset:36864
	ds_read_b64 v[64:65], v69 offset:4096
	s_waitcnt lgkmcnt(12)
	v_mul_f32_e32 v194, v186, v28
	v_mul_f32_e32 v195, v190, v28
	v_mul_f32_e32 v132, v186, v40
	v_mul_f32_e32 v133, v190, v40
	v_fmac_f32_e32 v194, v187, v29
	v_fmac_f32_e32 v195, v191, v29
	v_fmac_f32_e32 v132, v187, v41
	v_fmac_f32_e32 v133, v191, v41
	v_fmac_f32_e32 v194, v188, v30
	v_fmac_f32_e32 v195, v192, v30
	v_fmac_f32_e32 v132, v188, v42
	v_fmac_f32_e32 v133, v192, v42
	v_fmac_f32_e32 v194, v189, v31
	v_fmac_f32_e32 v195, v193, v31
	v_fmac_f32_e32 v132, v189, v43
	v_fmac_f32_e32 v133, v193, v43
	v_add_f32_dpp v194, v194, v194 quad_perm:[1,0,3,2] row_mask:0xf bank_mask:0xf bound_ctrl:1
	v_add_f32_dpp v195, v195, v195 quad_perm:[1,0,3,2] row_mask:0xf bank_mask:0xf bound_ctrl:1
	v_add_f32_dpp v132, v132, v132 quad_perm:[1,0,3,2] row_mask:0xf bank_mask:0xf bound_ctrl:1
	v_add_f32_dpp v133, v133, v133 quad_perm:[1,0,3,2] row_mask:0xf bank_mask:0xf bound_ctrl:1
	v_add_f32_dpp v194, v194, v194 quad_perm:[2,3,0,1] row_mask:0xf bank_mask:0xf bound_ctrl:1
	v_add_f32_dpp v195, v195, v195 quad_perm:[2,3,0,1] row_mask:0xf bank_mask:0xf bound_ctrl:1
	v_add_f32_dpp v132, v132, v132 quad_perm:[2,3,0,1] row_mask:0xf bank_mask:0xf bound_ctrl:1
	v_add_f32_dpp v133, v133, v133 quad_perm:[2,3,0,1] row_mask:0xf bank_mask:0xf bound_ctrl:1
	v_add_f32_dpp v194, v194, v194 row_half_mirror row_mask:0xf bank_mask:0xf bound_ctrl:1
	v_add_f32_dpp v195, v195, v195 row_half_mirror row_mask:0xf bank_mask:0xf bound_ctrl:1
	v_add_f32_dpp v132, v132, v132 row_half_mirror row_mask:0xf bank_mask:0xf bound_ctrl:1
	v_add_f32_dpp v133, v133, v133 row_half_mirror row_mask:0xf bank_mask:0xf bound_ctrl:1
	v_add_f32_dpp v194, v194, v194 row_mirror row_mask:0xf bank_mask:0xf bound_ctrl:1
	v_add_f32_dpp v195, v195, v195 row_mirror row_mask:0xf bank_mask:0xf bound_ctrl:1
	v_fmac_f32_e32 v186, v66, v36
	v_fmac_f32_e32 v187, v66, v37
	v_fmac_f32_e32 v188, v66, v38
	v_fmac_f32_e32 v189, v66, v39
	v_fmac_f32_e32 v190, v67, v36
	v_fmac_f32_e32 v191, v67, v37
	v_fmac_f32_e32 v192, v67, v38
	v_fmac_f32_e32 v193, v67, v39
	v_fmac_f32_e32 v186, v194, v32
	v_fmac_f32_e32 v187, v194, v33
	v_fmac_f32_e32 v188, v194, v34
	v_fmac_f32_e32 v189, v194, v35
	v_fmac_f32_e32 v190, v195, v32
	v_fmac_f32_e32 v191, v195, v33
	v_fmac_f32_e32 v192, v195, v34
	v_fmac_f32_e32 v193, v195, v35
	s_mov_b64 exec, s[8:9]
	ds_write_b64 v161, v[132:133] offset:9216
	s_mov_b64 exec, -1
	ds_read_b128 v[28:31], v152 offset:12032
	ds_read_b128 v[32:35], v152 offset:20224
	ds_read_b128 v[36:39], v152 offset:28416
	ds_read_b128 v[40:43], v152 offset:36608
	ds_read_b64 v[66:67], v69 offset:3840
	s_waitcnt lgkmcnt(12)
	v_mul_f32_e32 v194, v186, v48
	v_mul_f32_e32 v195, v190, v48
	v_mul_f32_e32 v132, v186, v60
	v_mul_f32_e32 v133, v190, v60
	v_fmac_f32_e32 v194, v187, v49
	v_fmac_f32_e32 v195, v191, v49
	v_fmac_f32_e32 v132, v187, v61
	v_fmac_f32_e32 v133, v191, v61
	v_fmac_f32_e32 v194, v188, v50
	v_fmac_f32_e32 v195, v192, v50
	v_fmac_f32_e32 v132, v188, v62
	v_fmac_f32_e32 v133, v192, v62
	v_fmac_f32_e32 v194, v189, v51
	v_fmac_f32_e32 v195, v193, v51
	v_fmac_f32_e32 v132, v189, v63
	v_fmac_f32_e32 v133, v193, v63
	v_add_f32_dpp v194, v194, v194 quad_perm:[1,0,3,2] row_mask:0xf bank_mask:0xf bound_ctrl:1
	v_add_f32_dpp v195, v195, v195 quad_perm:[1,0,3,2] row_mask:0xf bank_mask:0xf bound_ctrl:1
	v_add_f32_dpp v132, v132, v132 quad_perm:[1,0,3,2] row_mask:0xf bank_mask:0xf bound_ctrl:1
	v_add_f32_dpp v133, v133, v133 quad_perm:[1,0,3,2] row_mask:0xf bank_mask:0xf bound_ctrl:1
	v_add_f32_dpp v194, v194, v194 quad_perm:[2,3,0,1] row_mask:0xf bank_mask:0xf bound_ctrl:1
	v_add_f32_dpp v195, v195, v195 quad_perm:[2,3,0,1] row_mask:0xf bank_mask:0xf bound_ctrl:1
	v_add_f32_dpp v132, v132, v132 quad_perm:[2,3,0,1] row_mask:0xf bank_mask:0xf bound_ctrl:1
	v_add_f32_dpp v133, v133, v133 quad_perm:[2,3,0,1] row_mask:0xf bank_mask:0xf bound_ctrl:1
	v_add_f32_dpp v194, v194, v194 row_half_mirror row_mask:0xf bank_mask:0xf bound_ctrl:1
	v_add_f32_dpp v195, v195, v195 row_half_mirror row_mask:0xf bank_mask:0xf bound_ctrl:1
	v_add_f32_dpp v132, v132, v132 row_half_mirror row_mask:0xf bank_mask:0xf bound_ctrl:1
	v_add_f32_dpp v133, v133, v133 row_half_mirror row_mask:0xf bank_mask:0xf bound_ctrl:1
	v_add_f32_dpp v194, v194, v194 row_mirror row_mask:0xf bank_mask:0xf bound_ctrl:1
	v_add_f32_dpp v195, v195, v195 row_mirror row_mask:0xf bank_mask:0xf bound_ctrl:1
	v_fmac_f32_e32 v186, v130, v56
	v_fmac_f32_e32 v187, v130, v57
	v_fmac_f32_e32 v188, v130, v58
	v_fmac_f32_e32 v189, v130, v59
	v_fmac_f32_e32 v190, v131, v56
	v_fmac_f32_e32 v191, v131, v57
	v_fmac_f32_e32 v192, v131, v58
	v_fmac_f32_e32 v193, v131, v59
	v_fmac_f32_e32 v186, v194, v52
	v_fmac_f32_e32 v187, v194, v53
	v_fmac_f32_e32 v188, v194, v54
	v_fmac_f32_e32 v189, v194, v55
	v_fmac_f32_e32 v190, v195, v52
	v_fmac_f32_e32 v191, v195, v53
	v_fmac_f32_e32 v192, v195, v54
	v_fmac_f32_e32 v193, v195, v55
	s_mov_b64 exec, s[8:9]
	ds_write_b64 v161, v[132:133] offset:8704
	s_mov_b64 exec, -1
	ds_read_b128 v[48:51], v152 offset:11776
	ds_read_b128 v[52:55], v152 offset:19968
	ds_read_b128 v[56:59], v152 offset:28160
	ds_read_b128 v[60:63], v152 offset:36352
	ds_read_b64 v[130:131], v69 offset:3584
	s_waitcnt lgkmcnt(12)
	v_mul_f32_e32 v194, v186, v8
	v_mul_f32_e32 v195, v190, v8
	v_mul_f32_e32 v132, v186, v20
	v_mul_f32_e32 v133, v190, v20
	v_fmac_f32_e32 v194, v187, v9
	v_fmac_f32_e32 v195, v191, v9
	v_fmac_f32_e32 v132, v187, v21
	v_fmac_f32_e32 v133, v191, v21
	v_fmac_f32_e32 v194, v188, v10
	v_fmac_f32_e32 v195, v192, v10
	v_fmac_f32_e32 v132, v188, v22
	v_fmac_f32_e32 v133, v192, v22
	v_fmac_f32_e32 v194, v189, v11
	v_fmac_f32_e32 v195, v193, v11
	v_fmac_f32_e32 v132, v189, v23
	v_fmac_f32_e32 v133, v193, v23
	v_add_f32_dpp v194, v194, v194 quad_perm:[1,0,3,2] row_mask:0xf bank_mask:0xf bound_ctrl:1
	v_add_f32_dpp v195, v195, v195 quad_perm:[1,0,3,2] row_mask:0xf bank_mask:0xf bound_ctrl:1
	v_add_f32_dpp v132, v132, v132 quad_perm:[1,0,3,2] row_mask:0xf bank_mask:0xf bound_ctrl:1
	v_add_f32_dpp v133, v133, v133 quad_perm:[1,0,3,2] row_mask:0xf bank_mask:0xf bound_ctrl:1
	v_add_f32_dpp v194, v194, v194 quad_perm:[2,3,0,1] row_mask:0xf bank_mask:0xf bound_ctrl:1
	v_add_f32_dpp v195, v195, v195 quad_perm:[2,3,0,1] row_mask:0xf bank_mask:0xf bound_ctrl:1
	v_add_f32_dpp v132, v132, v132 quad_perm:[2,3,0,1] row_mask:0xf bank_mask:0xf bound_ctrl:1
	v_add_f32_dpp v133, v133, v133 quad_perm:[2,3,0,1] row_mask:0xf bank_mask:0xf bound_ctrl:1
	v_add_f32_dpp v194, v194, v194 row_half_mirror row_mask:0xf bank_mask:0xf bound_ctrl:1
	v_add_f32_dpp v195, v195, v195 row_half_mirror row_mask:0xf bank_mask:0xf bound_ctrl:1
	v_add_f32_dpp v132, v132, v132 row_half_mirror row_mask:0xf bank_mask:0xf bound_ctrl:1
	v_add_f32_dpp v133, v133, v133 row_half_mirror row_mask:0xf bank_mask:0xf bound_ctrl:1
	v_add_f32_dpp v194, v194, v194 row_mirror row_mask:0xf bank_mask:0xf bound_ctrl:1
	v_add_f32_dpp v195, v195, v195 row_mirror row_mask:0xf bank_mask:0xf bound_ctrl:1
	v_fmac_f32_e32 v186, v64, v16
	v_fmac_f32_e32 v187, v64, v17
	v_fmac_f32_e32 v188, v64, v18
	v_fmac_f32_e32 v189, v64, v19
	v_fmac_f32_e32 v190, v65, v16
	v_fmac_f32_e32 v191, v65, v17
	v_fmac_f32_e32 v192, v65, v18
	v_fmac_f32_e32 v193, v65, v19
	v_fmac_f32_e32 v186, v194, v12
	v_fmac_f32_e32 v187, v194, v13
	v_fmac_f32_e32 v188, v194, v14
	v_fmac_f32_e32 v189, v194, v15
	v_fmac_f32_e32 v190, v195, v12
	v_fmac_f32_e32 v191, v195, v13
	v_fmac_f32_e32 v192, v195, v14
	v_fmac_f32_e32 v193, v195, v15
	s_mov_b64 exec, s[8:9]
	ds_write_b64 v161, v[132:133] offset:8192
	s_mov_b64 exec, -1
	ds_read_b128 v[8:11], v152 offset:11520
	ds_read_b128 v[12:15], v152 offset:19712
	ds_read_b128 v[16:19], v152 offset:27904
	ds_read_b128 v[20:23], v152 offset:36096
	ds_read_b64 v[64:65], v69 offset:3328
	s_waitcnt lgkmcnt(12)
	v_mul_f32_e32 v194, v186, v28
	v_mul_f32_e32 v195, v190, v28
	v_mul_f32_e32 v132, v186, v40
	v_mul_f32_e32 v133, v190, v40
	v_fmac_f32_e32 v194, v187, v29
	v_fmac_f32_e32 v195, v191, v29
	v_fmac_f32_e32 v132, v187, v41
	v_fmac_f32_e32 v133, v191, v41
	v_fmac_f32_e32 v194, v188, v30
	v_fmac_f32_e32 v195, v192, v30
	v_fmac_f32_e32 v132, v188, v42
	v_fmac_f32_e32 v133, v192, v42
	v_fmac_f32_e32 v194, v189, v31
	v_fmac_f32_e32 v195, v193, v31
	v_fmac_f32_e32 v132, v189, v43
	v_fmac_f32_e32 v133, v193, v43
	v_add_f32_dpp v194, v194, v194 quad_perm:[1,0,3,2] row_mask:0xf bank_mask:0xf bound_ctrl:1
	v_add_f32_dpp v195, v195, v195 quad_perm:[1,0,3,2] row_mask:0xf bank_mask:0xf bound_ctrl:1
	v_add_f32_dpp v132, v132, v132 quad_perm:[1,0,3,2] row_mask:0xf bank_mask:0xf bound_ctrl:1
	v_add_f32_dpp v133, v133, v133 quad_perm:[1,0,3,2] row_mask:0xf bank_mask:0xf bound_ctrl:1
	v_add_f32_dpp v194, v194, v194 quad_perm:[2,3,0,1] row_mask:0xf bank_mask:0xf bound_ctrl:1
	v_add_f32_dpp v195, v195, v195 quad_perm:[2,3,0,1] row_mask:0xf bank_mask:0xf bound_ctrl:1
	v_add_f32_dpp v132, v132, v132 quad_perm:[2,3,0,1] row_mask:0xf bank_mask:0xf bound_ctrl:1
	v_add_f32_dpp v133, v133, v133 quad_perm:[2,3,0,1] row_mask:0xf bank_mask:0xf bound_ctrl:1
	v_add_f32_dpp v194, v194, v194 row_half_mirror row_mask:0xf bank_mask:0xf bound_ctrl:1
	v_add_f32_dpp v195, v195, v195 row_half_mirror row_mask:0xf bank_mask:0xf bound_ctrl:1
	v_add_f32_dpp v132, v132, v132 row_half_mirror row_mask:0xf bank_mask:0xf bound_ctrl:1
	v_add_f32_dpp v133, v133, v133 row_half_mirror row_mask:0xf bank_mask:0xf bound_ctrl:1
	v_add_f32_dpp v194, v194, v194 row_mirror row_mask:0xf bank_mask:0xf bound_ctrl:1
	v_add_f32_dpp v195, v195, v195 row_mirror row_mask:0xf bank_mask:0xf bound_ctrl:1
	v_fmac_f32_e32 v186, v66, v36
	v_fmac_f32_e32 v187, v66, v37
	v_fmac_f32_e32 v188, v66, v38
	v_fmac_f32_e32 v189, v66, v39
	v_fmac_f32_e32 v190, v67, v36
	v_fmac_f32_e32 v191, v67, v37
	v_fmac_f32_e32 v192, v67, v38
	v_fmac_f32_e32 v193, v67, v39
	v_fmac_f32_e32 v186, v194, v32
	v_fmac_f32_e32 v187, v194, v33
	v_fmac_f32_e32 v188, v194, v34
	v_fmac_f32_e32 v189, v194, v35
	v_fmac_f32_e32 v190, v195, v32
	v_fmac_f32_e32 v191, v195, v33
	v_fmac_f32_e32 v192, v195, v34
	v_fmac_f32_e32 v193, v195, v35
	s_mov_b64 exec, s[8:9]
	ds_write_b64 v161, v[132:133] offset:7680
	s_mov_b64 exec, -1
	ds_read_b128 v[28:31], v152 offset:11264
	ds_read_b128 v[32:35], v152 offset:19456
	ds_read_b128 v[36:39], v152 offset:27648
	ds_read_b128 v[40:43], v152 offset:35840
	ds_read_b64 v[66:67], v69 offset:3072
	s_waitcnt lgkmcnt(12)
	v_mul_f32_e32 v194, v186, v48
	v_mul_f32_e32 v195, v190, v48
	v_mul_f32_e32 v132, v186, v60
	v_mul_f32_e32 v133, v190, v60
	v_fmac_f32_e32 v194, v187, v49
	v_fmac_f32_e32 v195, v191, v49
	v_fmac_f32_e32 v132, v187, v61
	v_fmac_f32_e32 v133, v191, v61
	v_fmac_f32_e32 v194, v188, v50
	v_fmac_f32_e32 v195, v192, v50
	v_fmac_f32_e32 v132, v188, v62
	v_fmac_f32_e32 v133, v192, v62
	v_fmac_f32_e32 v194, v189, v51
	v_fmac_f32_e32 v195, v193, v51
	v_fmac_f32_e32 v132, v189, v63
	v_fmac_f32_e32 v133, v193, v63
	v_add_f32_dpp v194, v194, v194 quad_perm:[1,0,3,2] row_mask:0xf bank_mask:0xf bound_ctrl:1
	v_add_f32_dpp v195, v195, v195 quad_perm:[1,0,3,2] row_mask:0xf bank_mask:0xf bound_ctrl:1
	v_add_f32_dpp v132, v132, v132 quad_perm:[1,0,3,2] row_mask:0xf bank_mask:0xf bound_ctrl:1
	v_add_f32_dpp v133, v133, v133 quad_perm:[1,0,3,2] row_mask:0xf bank_mask:0xf bound_ctrl:1
	v_add_f32_dpp v194, v194, v194 quad_perm:[2,3,0,1] row_mask:0xf bank_mask:0xf bound_ctrl:1
	v_add_f32_dpp v195, v195, v195 quad_perm:[2,3,0,1] row_mask:0xf bank_mask:0xf bound_ctrl:1
	v_add_f32_dpp v132, v132, v132 quad_perm:[2,3,0,1] row_mask:0xf bank_mask:0xf bound_ctrl:1
	v_add_f32_dpp v133, v133, v133 quad_perm:[2,3,0,1] row_mask:0xf bank_mask:0xf bound_ctrl:1
	v_add_f32_dpp v194, v194, v194 row_half_mirror row_mask:0xf bank_mask:0xf bound_ctrl:1
	v_add_f32_dpp v195, v195, v195 row_half_mirror row_mask:0xf bank_mask:0xf bound_ctrl:1
	v_add_f32_dpp v132, v132, v132 row_half_mirror row_mask:0xf bank_mask:0xf bound_ctrl:1
	v_add_f32_dpp v133, v133, v133 row_half_mirror row_mask:0xf bank_mask:0xf bound_ctrl:1
	v_add_f32_dpp v194, v194, v194 row_mirror row_mask:0xf bank_mask:0xf bound_ctrl:1
	v_add_f32_dpp v195, v195, v195 row_mirror row_mask:0xf bank_mask:0xf bound_ctrl:1
	v_fmac_f32_e32 v186, v130, v56
	v_fmac_f32_e32 v187, v130, v57
	v_fmac_f32_e32 v188, v130, v58
	v_fmac_f32_e32 v189, v130, v59
	v_fmac_f32_e32 v190, v131, v56
	v_fmac_f32_e32 v191, v131, v57
	v_fmac_f32_e32 v192, v131, v58
	v_fmac_f32_e32 v193, v131, v59
	v_fmac_f32_e32 v186, v194, v52
	v_fmac_f32_e32 v187, v194, v53
	v_fmac_f32_e32 v188, v194, v54
	v_fmac_f32_e32 v189, v194, v55
	v_fmac_f32_e32 v190, v195, v52
	v_fmac_f32_e32 v191, v195, v53
	v_fmac_f32_e32 v192, v195, v54
	v_fmac_f32_e32 v193, v195, v55
	s_mov_b64 exec, s[8:9]
	ds_write_b64 v161, v[132:133] offset:7168
	s_mov_b64 exec, -1
	ds_read_b128 v[48:51], v152 offset:11008
	ds_read_b128 v[52:55], v152 offset:19200
	ds_read_b128 v[56:59], v152 offset:27392
	ds_read_b128 v[60:63], v152 offset:35584
	ds_read_b64 v[130:131], v69 offset:2816
	s_waitcnt lgkmcnt(12)
	v_mul_f32_e32 v194, v186, v8
	v_mul_f32_e32 v195, v190, v8
	v_mul_f32_e32 v132, v186, v20
	v_mul_f32_e32 v133, v190, v20
	v_fmac_f32_e32 v194, v187, v9
	v_fmac_f32_e32 v195, v191, v9
	v_fmac_f32_e32 v132, v187, v21
	v_fmac_f32_e32 v133, v191, v21
	v_fmac_f32_e32 v194, v188, v10
	v_fmac_f32_e32 v195, v192, v10
	v_fmac_f32_e32 v132, v188, v22
	v_fmac_f32_e32 v133, v192, v22
	v_fmac_f32_e32 v194, v189, v11
	v_fmac_f32_e32 v195, v193, v11
	v_fmac_f32_e32 v132, v189, v23
	v_fmac_f32_e32 v133, v193, v23
	v_add_f32_dpp v194, v194, v194 quad_perm:[1,0,3,2] row_mask:0xf bank_mask:0xf bound_ctrl:1
	v_add_f32_dpp v195, v195, v195 quad_perm:[1,0,3,2] row_mask:0xf bank_mask:0xf bound_ctrl:1
	v_add_f32_dpp v132, v132, v132 quad_perm:[1,0,3,2] row_mask:0xf bank_mask:0xf bound_ctrl:1
	v_add_f32_dpp v133, v133, v133 quad_perm:[1,0,3,2] row_mask:0xf bank_mask:0xf bound_ctrl:1
	v_add_f32_dpp v194, v194, v194 quad_perm:[2,3,0,1] row_mask:0xf bank_mask:0xf bound_ctrl:1
	v_add_f32_dpp v195, v195, v195 quad_perm:[2,3,0,1] row_mask:0xf bank_mask:0xf bound_ctrl:1
	v_add_f32_dpp v132, v132, v132 quad_perm:[2,3,0,1] row_mask:0xf bank_mask:0xf bound_ctrl:1
	v_add_f32_dpp v133, v133, v133 quad_perm:[2,3,0,1] row_mask:0xf bank_mask:0xf bound_ctrl:1
	v_add_f32_dpp v194, v194, v194 row_half_mirror row_mask:0xf bank_mask:0xf bound_ctrl:1
	v_add_f32_dpp v195, v195, v195 row_half_mirror row_mask:0xf bank_mask:0xf bound_ctrl:1
	v_add_f32_dpp v132, v132, v132 row_half_mirror row_mask:0xf bank_mask:0xf bound_ctrl:1
	v_add_f32_dpp v133, v133, v133 row_half_mirror row_mask:0xf bank_mask:0xf bound_ctrl:1
	v_add_f32_dpp v194, v194, v194 row_mirror row_mask:0xf bank_mask:0xf bound_ctrl:1
	v_add_f32_dpp v195, v195, v195 row_mirror row_mask:0xf bank_mask:0xf bound_ctrl:1
	v_fmac_f32_e32 v186, v64, v16
	v_fmac_f32_e32 v187, v64, v17
	v_fmac_f32_e32 v188, v64, v18
	v_fmac_f32_e32 v189, v64, v19
	v_fmac_f32_e32 v190, v65, v16
	v_fmac_f32_e32 v191, v65, v17
	v_fmac_f32_e32 v192, v65, v18
	v_fmac_f32_e32 v193, v65, v19
	v_fmac_f32_e32 v186, v194, v12
	v_fmac_f32_e32 v187, v194, v13
	v_fmac_f32_e32 v188, v194, v14
	v_fmac_f32_e32 v189, v194, v15
	v_fmac_f32_e32 v190, v195, v12
	v_fmac_f32_e32 v191, v195, v13
	v_fmac_f32_e32 v192, v195, v14
	v_fmac_f32_e32 v193, v195, v15
	s_mov_b64 exec, s[8:9]
	ds_write_b64 v161, v[132:133] offset:6656
	s_mov_b64 exec, -1
	ds_read_b128 v[8:11], v152 offset:10752
	ds_read_b128 v[12:15], v152 offset:18944
	ds_read_b128 v[16:19], v152 offset:27136
	ds_read_b128 v[20:23], v152 offset:35328
	ds_read_b64 v[64:65], v69 offset:2560
	s_waitcnt lgkmcnt(12)
	v_mul_f32_e32 v194, v186, v28
	v_mul_f32_e32 v195, v190, v28
	v_mul_f32_e32 v132, v186, v40
	v_mul_f32_e32 v133, v190, v40
	v_fmac_f32_e32 v194, v187, v29
	v_fmac_f32_e32 v195, v191, v29
	v_fmac_f32_e32 v132, v187, v41
	v_fmac_f32_e32 v133, v191, v41
	v_fmac_f32_e32 v194, v188, v30
	v_fmac_f32_e32 v195, v192, v30
	v_fmac_f32_e32 v132, v188, v42
	v_fmac_f32_e32 v133, v192, v42
	v_fmac_f32_e32 v194, v189, v31
	v_fmac_f32_e32 v195, v193, v31
	v_fmac_f32_e32 v132, v189, v43
	v_fmac_f32_e32 v133, v193, v43
	v_add_f32_dpp v194, v194, v194 quad_perm:[1,0,3,2] row_mask:0xf bank_mask:0xf bound_ctrl:1
	v_add_f32_dpp v195, v195, v195 quad_perm:[1,0,3,2] row_mask:0xf bank_mask:0xf bound_ctrl:1
	v_add_f32_dpp v132, v132, v132 quad_perm:[1,0,3,2] row_mask:0xf bank_mask:0xf bound_ctrl:1
	v_add_f32_dpp v133, v133, v133 quad_perm:[1,0,3,2] row_mask:0xf bank_mask:0xf bound_ctrl:1
	v_add_f32_dpp v194, v194, v194 quad_perm:[2,3,0,1] row_mask:0xf bank_mask:0xf bound_ctrl:1
	v_add_f32_dpp v195, v195, v195 quad_perm:[2,3,0,1] row_mask:0xf bank_mask:0xf bound_ctrl:1
	v_add_f32_dpp v132, v132, v132 quad_perm:[2,3,0,1] row_mask:0xf bank_mask:0xf bound_ctrl:1
	v_add_f32_dpp v133, v133, v133 quad_perm:[2,3,0,1] row_mask:0xf bank_mask:0xf bound_ctrl:1
	v_add_f32_dpp v194, v194, v194 row_half_mirror row_mask:0xf bank_mask:0xf bound_ctrl:1
	v_add_f32_dpp v195, v195, v195 row_half_mirror row_mask:0xf bank_mask:0xf bound_ctrl:1
	v_add_f32_dpp v132, v132, v132 row_half_mirror row_mask:0xf bank_mask:0xf bound_ctrl:1
	v_add_f32_dpp v133, v133, v133 row_half_mirror row_mask:0xf bank_mask:0xf bound_ctrl:1
	v_add_f32_dpp v194, v194, v194 row_mirror row_mask:0xf bank_mask:0xf bound_ctrl:1
	v_add_f32_dpp v195, v195, v195 row_mirror row_mask:0xf bank_mask:0xf bound_ctrl:1
	v_fmac_f32_e32 v186, v66, v36
	v_fmac_f32_e32 v187, v66, v37
	v_fmac_f32_e32 v188, v66, v38
	v_fmac_f32_e32 v189, v66, v39
	v_fmac_f32_e32 v190, v67, v36
	v_fmac_f32_e32 v191, v67, v37
	v_fmac_f32_e32 v192, v67, v38
	v_fmac_f32_e32 v193, v67, v39
	v_fmac_f32_e32 v186, v194, v32
	v_fmac_f32_e32 v187, v194, v33
	v_fmac_f32_e32 v188, v194, v34
	v_fmac_f32_e32 v189, v194, v35
	v_fmac_f32_e32 v190, v195, v32
	v_fmac_f32_e32 v191, v195, v33
	v_fmac_f32_e32 v192, v195, v34
	v_fmac_f32_e32 v193, v195, v35
	s_mov_b64 exec, s[8:9]
	ds_write_b64 v161, v[132:133] offset:6144
	s_mov_b64 exec, -1
	ds_read_b128 v[28:31], v152 offset:10496
	ds_read_b128 v[32:35], v152 offset:18688
	ds_read_b128 v[36:39], v152 offset:26880
	ds_read_b128 v[40:43], v152 offset:35072
	ds_read_b64 v[66:67], v69 offset:2304
	s_waitcnt lgkmcnt(12)
	v_mul_f32_e32 v194, v186, v48
	v_mul_f32_e32 v195, v190, v48
	v_mul_f32_e32 v132, v186, v60
	v_mul_f32_e32 v133, v190, v60
	v_fmac_f32_e32 v194, v187, v49
	v_fmac_f32_e32 v195, v191, v49
	v_fmac_f32_e32 v132, v187, v61
	v_fmac_f32_e32 v133, v191, v61
	v_fmac_f32_e32 v194, v188, v50
	v_fmac_f32_e32 v195, v192, v50
	v_fmac_f32_e32 v132, v188, v62
	v_fmac_f32_e32 v133, v192, v62
	v_fmac_f32_e32 v194, v189, v51
	v_fmac_f32_e32 v195, v193, v51
	v_fmac_f32_e32 v132, v189, v63
	v_fmac_f32_e32 v133, v193, v63
	v_add_f32_dpp v194, v194, v194 quad_perm:[1,0,3,2] row_mask:0xf bank_mask:0xf bound_ctrl:1
	v_add_f32_dpp v195, v195, v195 quad_perm:[1,0,3,2] row_mask:0xf bank_mask:0xf bound_ctrl:1
	v_add_f32_dpp v132, v132, v132 quad_perm:[1,0,3,2] row_mask:0xf bank_mask:0xf bound_ctrl:1
	v_add_f32_dpp v133, v133, v133 quad_perm:[1,0,3,2] row_mask:0xf bank_mask:0xf bound_ctrl:1
	v_add_f32_dpp v194, v194, v194 quad_perm:[2,3,0,1] row_mask:0xf bank_mask:0xf bound_ctrl:1
	v_add_f32_dpp v195, v195, v195 quad_perm:[2,3,0,1] row_mask:0xf bank_mask:0xf bound_ctrl:1
	v_add_f32_dpp v132, v132, v132 quad_perm:[2,3,0,1] row_mask:0xf bank_mask:0xf bound_ctrl:1
	v_add_f32_dpp v133, v133, v133 quad_perm:[2,3,0,1] row_mask:0xf bank_mask:0xf bound_ctrl:1
	v_add_f32_dpp v194, v194, v194 row_half_mirror row_mask:0xf bank_mask:0xf bound_ctrl:1
	v_add_f32_dpp v195, v195, v195 row_half_mirror row_mask:0xf bank_mask:0xf bound_ctrl:1
	v_add_f32_dpp v132, v132, v132 row_half_mirror row_mask:0xf bank_mask:0xf bound_ctrl:1
	v_add_f32_dpp v133, v133, v133 row_half_mirror row_mask:0xf bank_mask:0xf bound_ctrl:1
	v_add_f32_dpp v194, v194, v194 row_mirror row_mask:0xf bank_mask:0xf bound_ctrl:1
	v_add_f32_dpp v195, v195, v195 row_mirror row_mask:0xf bank_mask:0xf bound_ctrl:1
	v_fmac_f32_e32 v186, v130, v56
	v_fmac_f32_e32 v187, v130, v57
	v_fmac_f32_e32 v188, v130, v58
	v_fmac_f32_e32 v189, v130, v59
	v_fmac_f32_e32 v190, v131, v56
	v_fmac_f32_e32 v191, v131, v57
	v_fmac_f32_e32 v192, v131, v58
	v_fmac_f32_e32 v193, v131, v59
	v_fmac_f32_e32 v186, v194, v52
	v_fmac_f32_e32 v187, v194, v53
	v_fmac_f32_e32 v188, v194, v54
	v_fmac_f32_e32 v189, v194, v55
	v_fmac_f32_e32 v190, v195, v52
	v_fmac_f32_e32 v191, v195, v53
	v_fmac_f32_e32 v192, v195, v54
	v_fmac_f32_e32 v193, v195, v55
	s_mov_b64 exec, s[8:9]
	ds_write_b64 v161, v[132:133] offset:5632
	s_mov_b64 exec, -1
	ds_read_b128 v[48:51], v152 offset:10240
	ds_read_b128 v[52:55], v152 offset:18432
	ds_read_b128 v[56:59], v152 offset:26624
	ds_read_b128 v[60:63], v152 offset:34816
	ds_read_b64 v[130:131], v69 offset:2048
	s_waitcnt lgkmcnt(12)
	v_mul_f32_e32 v194, v186, v8
	v_mul_f32_e32 v195, v190, v8
	v_mul_f32_e32 v132, v186, v20
	v_mul_f32_e32 v133, v190, v20
	v_fmac_f32_e32 v194, v187, v9
	v_fmac_f32_e32 v195, v191, v9
	v_fmac_f32_e32 v132, v187, v21
	v_fmac_f32_e32 v133, v191, v21
	v_fmac_f32_e32 v194, v188, v10
	v_fmac_f32_e32 v195, v192, v10
	v_fmac_f32_e32 v132, v188, v22
	v_fmac_f32_e32 v133, v192, v22
	v_fmac_f32_e32 v194, v189, v11
	v_fmac_f32_e32 v195, v193, v11
	v_fmac_f32_e32 v132, v189, v23
	v_fmac_f32_e32 v133, v193, v23
	v_add_f32_dpp v194, v194, v194 quad_perm:[1,0,3,2] row_mask:0xf bank_mask:0xf bound_ctrl:1
	v_add_f32_dpp v195, v195, v195 quad_perm:[1,0,3,2] row_mask:0xf bank_mask:0xf bound_ctrl:1
	v_add_f32_dpp v132, v132, v132 quad_perm:[1,0,3,2] row_mask:0xf bank_mask:0xf bound_ctrl:1
	v_add_f32_dpp v133, v133, v133 quad_perm:[1,0,3,2] row_mask:0xf bank_mask:0xf bound_ctrl:1
	v_add_f32_dpp v194, v194, v194 quad_perm:[2,3,0,1] row_mask:0xf bank_mask:0xf bound_ctrl:1
	v_add_f32_dpp v195, v195, v195 quad_perm:[2,3,0,1] row_mask:0xf bank_mask:0xf bound_ctrl:1
	v_add_f32_dpp v132, v132, v132 quad_perm:[2,3,0,1] row_mask:0xf bank_mask:0xf bound_ctrl:1
	v_add_f32_dpp v133, v133, v133 quad_perm:[2,3,0,1] row_mask:0xf bank_mask:0xf bound_ctrl:1
	v_add_f32_dpp v194, v194, v194 row_half_mirror row_mask:0xf bank_mask:0xf bound_ctrl:1
	v_add_f32_dpp v195, v195, v195 row_half_mirror row_mask:0xf bank_mask:0xf bound_ctrl:1
	v_add_f32_dpp v132, v132, v132 row_half_mirror row_mask:0xf bank_mask:0xf bound_ctrl:1
	v_add_f32_dpp v133, v133, v133 row_half_mirror row_mask:0xf bank_mask:0xf bound_ctrl:1
	v_add_f32_dpp v194, v194, v194 row_mirror row_mask:0xf bank_mask:0xf bound_ctrl:1
	v_add_f32_dpp v195, v195, v195 row_mirror row_mask:0xf bank_mask:0xf bound_ctrl:1
	v_fmac_f32_e32 v186, v64, v16
	v_fmac_f32_e32 v187, v64, v17
	v_fmac_f32_e32 v188, v64, v18
	v_fmac_f32_e32 v189, v64, v19
	v_fmac_f32_e32 v190, v65, v16
	v_fmac_f32_e32 v191, v65, v17
	v_fmac_f32_e32 v192, v65, v18
	v_fmac_f32_e32 v193, v65, v19
	v_fmac_f32_e32 v186, v194, v12
	v_fmac_f32_e32 v187, v194, v13
	v_fmac_f32_e32 v188, v194, v14
	v_fmac_f32_e32 v189, v194, v15
	v_fmac_f32_e32 v190, v195, v12
	v_fmac_f32_e32 v191, v195, v13
	v_fmac_f32_e32 v192, v195, v14
	v_fmac_f32_e32 v193, v195, v15
	s_mov_b64 exec, s[8:9]
	ds_write_b64 v161, v[132:133] offset:5120
	s_mov_b64 exec, -1
	ds_read_b128 v[8:11], v152 offset:9984
	ds_read_b128 v[12:15], v152 offset:18176
	ds_read_b128 v[16:19], v152 offset:26368
	ds_read_b128 v[20:23], v152 offset:34560
	ds_read_b64 v[64:65], v69 offset:1792
	s_waitcnt lgkmcnt(12)
	v_mul_f32_e32 v194, v186, v28
	v_mul_f32_e32 v195, v190, v28
	v_mul_f32_e32 v132, v186, v40
	v_mul_f32_e32 v133, v190, v40
	v_fmac_f32_e32 v194, v187, v29
	v_fmac_f32_e32 v195, v191, v29
	v_fmac_f32_e32 v132, v187, v41
	v_fmac_f32_e32 v133, v191, v41
	v_fmac_f32_e32 v194, v188, v30
	v_fmac_f32_e32 v195, v192, v30
	v_fmac_f32_e32 v132, v188, v42
	v_fmac_f32_e32 v133, v192, v42
	v_fmac_f32_e32 v194, v189, v31
	v_fmac_f32_e32 v195, v193, v31
	v_fmac_f32_e32 v132, v189, v43
	v_fmac_f32_e32 v133, v193, v43
	v_add_f32_dpp v194, v194, v194 quad_perm:[1,0,3,2] row_mask:0xf bank_mask:0xf bound_ctrl:1
	v_add_f32_dpp v195, v195, v195 quad_perm:[1,0,3,2] row_mask:0xf bank_mask:0xf bound_ctrl:1
	v_add_f32_dpp v132, v132, v132 quad_perm:[1,0,3,2] row_mask:0xf bank_mask:0xf bound_ctrl:1
	v_add_f32_dpp v133, v133, v133 quad_perm:[1,0,3,2] row_mask:0xf bank_mask:0xf bound_ctrl:1
	v_add_f32_dpp v194, v194, v194 quad_perm:[2,3,0,1] row_mask:0xf bank_mask:0xf bound_ctrl:1
	v_add_f32_dpp v195, v195, v195 quad_perm:[2,3,0,1] row_mask:0xf bank_mask:0xf bound_ctrl:1
	v_add_f32_dpp v132, v132, v132 quad_perm:[2,3,0,1] row_mask:0xf bank_mask:0xf bound_ctrl:1
	v_add_f32_dpp v133, v133, v133 quad_perm:[2,3,0,1] row_mask:0xf bank_mask:0xf bound_ctrl:1
	v_add_f32_dpp v194, v194, v194 row_half_mirror row_mask:0xf bank_mask:0xf bound_ctrl:1
	v_add_f32_dpp v195, v195, v195 row_half_mirror row_mask:0xf bank_mask:0xf bound_ctrl:1
	v_add_f32_dpp v132, v132, v132 row_half_mirror row_mask:0xf bank_mask:0xf bound_ctrl:1
	v_add_f32_dpp v133, v133, v133 row_half_mirror row_mask:0xf bank_mask:0xf bound_ctrl:1
	v_add_f32_dpp v194, v194, v194 row_mirror row_mask:0xf bank_mask:0xf bound_ctrl:1
	v_add_f32_dpp v195, v195, v195 row_mirror row_mask:0xf bank_mask:0xf bound_ctrl:1
	v_fmac_f32_e32 v186, v66, v36
	v_fmac_f32_e32 v187, v66, v37
	v_fmac_f32_e32 v188, v66, v38
	v_fmac_f32_e32 v189, v66, v39
	v_fmac_f32_e32 v190, v67, v36
	v_fmac_f32_e32 v191, v67, v37
	v_fmac_f32_e32 v192, v67, v38
	v_fmac_f32_e32 v193, v67, v39
	v_fmac_f32_e32 v186, v194, v32
	v_fmac_f32_e32 v187, v194, v33
	v_fmac_f32_e32 v188, v194, v34
	v_fmac_f32_e32 v189, v194, v35
	v_fmac_f32_e32 v190, v195, v32
	v_fmac_f32_e32 v191, v195, v33
	v_fmac_f32_e32 v192, v195, v34
	v_fmac_f32_e32 v193, v195, v35
	s_mov_b64 exec, s[8:9]
	ds_write_b64 v161, v[132:133] offset:4608
	s_mov_b64 exec, -1
	ds_read_b128 v[28:31], v152 offset:9728
	ds_read_b128 v[32:35], v152 offset:17920
	ds_read_b128 v[36:39], v152 offset:26112
	ds_read_b128 v[40:43], v152 offset:34304
	ds_read_b64 v[66:67], v69 offset:1536
	s_waitcnt lgkmcnt(12)
	v_mul_f32_e32 v194, v186, v48
	v_mul_f32_e32 v195, v190, v48
	v_mul_f32_e32 v132, v186, v60
	v_mul_f32_e32 v133, v190, v60
	v_fmac_f32_e32 v194, v187, v49
	v_fmac_f32_e32 v195, v191, v49
	v_fmac_f32_e32 v132, v187, v61
	v_fmac_f32_e32 v133, v191, v61
	v_fmac_f32_e32 v194, v188, v50
	v_fmac_f32_e32 v195, v192, v50
	v_fmac_f32_e32 v132, v188, v62
	v_fmac_f32_e32 v133, v192, v62
	v_fmac_f32_e32 v194, v189, v51
	v_fmac_f32_e32 v195, v193, v51
	v_fmac_f32_e32 v132, v189, v63
	v_fmac_f32_e32 v133, v193, v63
	v_add_f32_dpp v194, v194, v194 quad_perm:[1,0,3,2] row_mask:0xf bank_mask:0xf bound_ctrl:1
	v_add_f32_dpp v195, v195, v195 quad_perm:[1,0,3,2] row_mask:0xf bank_mask:0xf bound_ctrl:1
	v_add_f32_dpp v132, v132, v132 quad_perm:[1,0,3,2] row_mask:0xf bank_mask:0xf bound_ctrl:1
	v_add_f32_dpp v133, v133, v133 quad_perm:[1,0,3,2] row_mask:0xf bank_mask:0xf bound_ctrl:1
	v_add_f32_dpp v194, v194, v194 quad_perm:[2,3,0,1] row_mask:0xf bank_mask:0xf bound_ctrl:1
	v_add_f32_dpp v195, v195, v195 quad_perm:[2,3,0,1] row_mask:0xf bank_mask:0xf bound_ctrl:1
	v_add_f32_dpp v132, v132, v132 quad_perm:[2,3,0,1] row_mask:0xf bank_mask:0xf bound_ctrl:1
	v_add_f32_dpp v133, v133, v133 quad_perm:[2,3,0,1] row_mask:0xf bank_mask:0xf bound_ctrl:1
	v_add_f32_dpp v194, v194, v194 row_half_mirror row_mask:0xf bank_mask:0xf bound_ctrl:1
	v_add_f32_dpp v195, v195, v195 row_half_mirror row_mask:0xf bank_mask:0xf bound_ctrl:1
	v_add_f32_dpp v132, v132, v132 row_half_mirror row_mask:0xf bank_mask:0xf bound_ctrl:1
	v_add_f32_dpp v133, v133, v133 row_half_mirror row_mask:0xf bank_mask:0xf bound_ctrl:1
	v_add_f32_dpp v194, v194, v194 row_mirror row_mask:0xf bank_mask:0xf bound_ctrl:1
	v_add_f32_dpp v195, v195, v195 row_mirror row_mask:0xf bank_mask:0xf bound_ctrl:1
	v_fmac_f32_e32 v186, v130, v56
	v_fmac_f32_e32 v187, v130, v57
	v_fmac_f32_e32 v188, v130, v58
	v_fmac_f32_e32 v189, v130, v59
	v_fmac_f32_e32 v190, v131, v56
	v_fmac_f32_e32 v191, v131, v57
	v_fmac_f32_e32 v192, v131, v58
	v_fmac_f32_e32 v193, v131, v59
	v_fmac_f32_e32 v186, v194, v52
	v_fmac_f32_e32 v187, v194, v53
	v_fmac_f32_e32 v188, v194, v54
	v_fmac_f32_e32 v189, v194, v55
	v_fmac_f32_e32 v190, v195, v52
	v_fmac_f32_e32 v191, v195, v53
	v_fmac_f32_e32 v192, v195, v54
	v_fmac_f32_e32 v193, v195, v55
	s_mov_b64 exec, s[8:9]
	ds_write_b64 v161, v[132:133] offset:4096
	s_mov_b64 exec, -1
	ds_read_b128 v[48:51], v152 offset:9472
	ds_read_b128 v[52:55], v152 offset:17664
	ds_read_b128 v[56:59], v152 offset:25856
	ds_read_b128 v[60:63], v152 offset:34048
	ds_read_b64 v[130:131], v69 offset:1280
	s_waitcnt lgkmcnt(12)
	v_mul_f32_e32 v194, v186, v8
	v_mul_f32_e32 v195, v190, v8
	v_mul_f32_e32 v132, v186, v20
	v_mul_f32_e32 v133, v190, v20
	v_fmac_f32_e32 v194, v187, v9
	v_fmac_f32_e32 v195, v191, v9
	v_fmac_f32_e32 v132, v187, v21
	v_fmac_f32_e32 v133, v191, v21
	v_fmac_f32_e32 v194, v188, v10
	v_fmac_f32_e32 v195, v192, v10
	v_fmac_f32_e32 v132, v188, v22
	v_fmac_f32_e32 v133, v192, v22
	v_fmac_f32_e32 v194, v189, v11
	v_fmac_f32_e32 v195, v193, v11
	v_fmac_f32_e32 v132, v189, v23
	v_fmac_f32_e32 v133, v193, v23
	v_add_f32_dpp v194, v194, v194 quad_perm:[1,0,3,2] row_mask:0xf bank_mask:0xf bound_ctrl:1
	v_add_f32_dpp v195, v195, v195 quad_perm:[1,0,3,2] row_mask:0xf bank_mask:0xf bound_ctrl:1
	v_add_f32_dpp v132, v132, v132 quad_perm:[1,0,3,2] row_mask:0xf bank_mask:0xf bound_ctrl:1
	v_add_f32_dpp v133, v133, v133 quad_perm:[1,0,3,2] row_mask:0xf bank_mask:0xf bound_ctrl:1
	v_add_f32_dpp v194, v194, v194 quad_perm:[2,3,0,1] row_mask:0xf bank_mask:0xf bound_ctrl:1
	v_add_f32_dpp v195, v195, v195 quad_perm:[2,3,0,1] row_mask:0xf bank_mask:0xf bound_ctrl:1
	v_add_f32_dpp v132, v132, v132 quad_perm:[2,3,0,1] row_mask:0xf bank_mask:0xf bound_ctrl:1
	v_add_f32_dpp v133, v133, v133 quad_perm:[2,3,0,1] row_mask:0xf bank_mask:0xf bound_ctrl:1
	v_add_f32_dpp v194, v194, v194 row_half_mirror row_mask:0xf bank_mask:0xf bound_ctrl:1
	v_add_f32_dpp v195, v195, v195 row_half_mirror row_mask:0xf bank_mask:0xf bound_ctrl:1
	v_add_f32_dpp v132, v132, v132 row_half_mirror row_mask:0xf bank_mask:0xf bound_ctrl:1
	v_add_f32_dpp v133, v133, v133 row_half_mirror row_mask:0xf bank_mask:0xf bound_ctrl:1
	v_add_f32_dpp v194, v194, v194 row_mirror row_mask:0xf bank_mask:0xf bound_ctrl:1
	v_add_f32_dpp v195, v195, v195 row_mirror row_mask:0xf bank_mask:0xf bound_ctrl:1
	v_fmac_f32_e32 v186, v64, v16
	v_fmac_f32_e32 v187, v64, v17
	v_fmac_f32_e32 v188, v64, v18
	v_fmac_f32_e32 v189, v64, v19
	v_fmac_f32_e32 v190, v65, v16
	v_fmac_f32_e32 v191, v65, v17
	v_fmac_f32_e32 v192, v65, v18
	v_fmac_f32_e32 v193, v65, v19
	v_fmac_f32_e32 v186, v194, v12
	v_fmac_f32_e32 v187, v194, v13
	v_fmac_f32_e32 v188, v194, v14
	v_fmac_f32_e32 v189, v194, v15
	v_fmac_f32_e32 v190, v195, v12
	v_fmac_f32_e32 v191, v195, v13
	v_fmac_f32_e32 v192, v195, v14
	v_fmac_f32_e32 v193, v195, v15
	s_mov_b64 exec, s[8:9]
	ds_write_b64 v161, v[132:133] offset:3584
	s_mov_b64 exec, -1
	ds_read_b128 v[8:11], v152 offset:9216
	ds_read_b128 v[12:15], v152 offset:17408
	ds_read_b128 v[16:19], v152 offset:25600
	ds_read_b128 v[20:23], v152 offset:33792
	ds_read_b64 v[64:65], v69 offset:1024
	s_waitcnt lgkmcnt(12)
	v_mul_f32_e32 v194, v186, v28
	v_mul_f32_e32 v195, v190, v28
	v_mul_f32_e32 v132, v186, v40
	v_mul_f32_e32 v133, v190, v40
	v_fmac_f32_e32 v194, v187, v29
	v_fmac_f32_e32 v195, v191, v29
	v_fmac_f32_e32 v132, v187, v41
	v_fmac_f32_e32 v133, v191, v41
	v_fmac_f32_e32 v194, v188, v30
	v_fmac_f32_e32 v195, v192, v30
	v_fmac_f32_e32 v132, v188, v42
	v_fmac_f32_e32 v133, v192, v42
	v_fmac_f32_e32 v194, v189, v31
	v_fmac_f32_e32 v195, v193, v31
	v_fmac_f32_e32 v132, v189, v43
	v_fmac_f32_e32 v133, v193, v43
	v_add_f32_dpp v194, v194, v194 quad_perm:[1,0,3,2] row_mask:0xf bank_mask:0xf bound_ctrl:1
	v_add_f32_dpp v195, v195, v195 quad_perm:[1,0,3,2] row_mask:0xf bank_mask:0xf bound_ctrl:1
	v_add_f32_dpp v132, v132, v132 quad_perm:[1,0,3,2] row_mask:0xf bank_mask:0xf bound_ctrl:1
	v_add_f32_dpp v133, v133, v133 quad_perm:[1,0,3,2] row_mask:0xf bank_mask:0xf bound_ctrl:1
	v_add_f32_dpp v194, v194, v194 quad_perm:[2,3,0,1] row_mask:0xf bank_mask:0xf bound_ctrl:1
	v_add_f32_dpp v195, v195, v195 quad_perm:[2,3,0,1] row_mask:0xf bank_mask:0xf bound_ctrl:1
	v_add_f32_dpp v132, v132, v132 quad_perm:[2,3,0,1] row_mask:0xf bank_mask:0xf bound_ctrl:1
	v_add_f32_dpp v133, v133, v133 quad_perm:[2,3,0,1] row_mask:0xf bank_mask:0xf bound_ctrl:1
	v_add_f32_dpp v194, v194, v194 row_half_mirror row_mask:0xf bank_mask:0xf bound_ctrl:1
	v_add_f32_dpp v195, v195, v195 row_half_mirror row_mask:0xf bank_mask:0xf bound_ctrl:1
	v_add_f32_dpp v132, v132, v132 row_half_mirror row_mask:0xf bank_mask:0xf bound_ctrl:1
	v_add_f32_dpp v133, v133, v133 row_half_mirror row_mask:0xf bank_mask:0xf bound_ctrl:1
	v_add_f32_dpp v194, v194, v194 row_mirror row_mask:0xf bank_mask:0xf bound_ctrl:1
	v_add_f32_dpp v195, v195, v195 row_mirror row_mask:0xf bank_mask:0xf bound_ctrl:1
	v_fmac_f32_e32 v186, v66, v36
	v_fmac_f32_e32 v187, v66, v37
	v_fmac_f32_e32 v188, v66, v38
	v_fmac_f32_e32 v189, v66, v39
	v_fmac_f32_e32 v190, v67, v36
	v_fmac_f32_e32 v191, v67, v37
	v_fmac_f32_e32 v192, v67, v38
	v_fmac_f32_e32 v193, v67, v39
	v_fmac_f32_e32 v186, v194, v32
	v_fmac_f32_e32 v187, v194, v33
	v_fmac_f32_e32 v188, v194, v34
	v_fmac_f32_e32 v189, v194, v35
	v_fmac_f32_e32 v190, v195, v32
	v_fmac_f32_e32 v191, v195, v33
	v_fmac_f32_e32 v192, v195, v34
	v_fmac_f32_e32 v193, v195, v35
	s_mov_b64 exec, s[8:9]
	ds_write_b64 v161, v[132:133] offset:3072
	s_mov_b64 exec, -1
	ds_read_b128 v[28:31], v152 offset:8960
	ds_read_b128 v[32:35], v152 offset:17152
	ds_read_b128 v[36:39], v152 offset:25344
	ds_read_b128 v[40:43], v152 offset:33536
	ds_read_b64 v[66:67], v69 offset:768
	s_waitcnt lgkmcnt(12)
	v_mul_f32_e32 v194, v186, v48
	v_mul_f32_e32 v195, v190, v48
	v_mul_f32_e32 v132, v186, v60
	v_mul_f32_e32 v133, v190, v60
	v_fmac_f32_e32 v194, v187, v49
	v_fmac_f32_e32 v195, v191, v49
	v_fmac_f32_e32 v132, v187, v61
	v_fmac_f32_e32 v133, v191, v61
	v_fmac_f32_e32 v194, v188, v50
	v_fmac_f32_e32 v195, v192, v50
	v_fmac_f32_e32 v132, v188, v62
	v_fmac_f32_e32 v133, v192, v62
	v_fmac_f32_e32 v194, v189, v51
	v_fmac_f32_e32 v195, v193, v51
	v_fmac_f32_e32 v132, v189, v63
	v_fmac_f32_e32 v133, v193, v63
	v_add_f32_dpp v194, v194, v194 quad_perm:[1,0,3,2] row_mask:0xf bank_mask:0xf bound_ctrl:1
	v_add_f32_dpp v195, v195, v195 quad_perm:[1,0,3,2] row_mask:0xf bank_mask:0xf bound_ctrl:1
	v_add_f32_dpp v132, v132, v132 quad_perm:[1,0,3,2] row_mask:0xf bank_mask:0xf bound_ctrl:1
	v_add_f32_dpp v133, v133, v133 quad_perm:[1,0,3,2] row_mask:0xf bank_mask:0xf bound_ctrl:1
	v_add_f32_dpp v194, v194, v194 quad_perm:[2,3,0,1] row_mask:0xf bank_mask:0xf bound_ctrl:1
	v_add_f32_dpp v195, v195, v195 quad_perm:[2,3,0,1] row_mask:0xf bank_mask:0xf bound_ctrl:1
	v_add_f32_dpp v132, v132, v132 quad_perm:[2,3,0,1] row_mask:0xf bank_mask:0xf bound_ctrl:1
	v_add_f32_dpp v133, v133, v133 quad_perm:[2,3,0,1] row_mask:0xf bank_mask:0xf bound_ctrl:1
	v_add_f32_dpp v194, v194, v194 row_half_mirror row_mask:0xf bank_mask:0xf bound_ctrl:1
	v_add_f32_dpp v195, v195, v195 row_half_mirror row_mask:0xf bank_mask:0xf bound_ctrl:1
	v_add_f32_dpp v132, v132, v132 row_half_mirror row_mask:0xf bank_mask:0xf bound_ctrl:1
	v_add_f32_dpp v133, v133, v133 row_half_mirror row_mask:0xf bank_mask:0xf bound_ctrl:1
	v_add_f32_dpp v194, v194, v194 row_mirror row_mask:0xf bank_mask:0xf bound_ctrl:1
	v_add_f32_dpp v195, v195, v195 row_mirror row_mask:0xf bank_mask:0xf bound_ctrl:1
	v_fmac_f32_e32 v186, v130, v56
	v_fmac_f32_e32 v187, v130, v57
	v_fmac_f32_e32 v188, v130, v58
	v_fmac_f32_e32 v189, v130, v59
	v_fmac_f32_e32 v190, v131, v56
	v_fmac_f32_e32 v191, v131, v57
	v_fmac_f32_e32 v192, v131, v58
	v_fmac_f32_e32 v193, v131, v59
	v_fmac_f32_e32 v186, v194, v52
	v_fmac_f32_e32 v187, v194, v53
	v_fmac_f32_e32 v188, v194, v54
	v_fmac_f32_e32 v189, v194, v55
	v_fmac_f32_e32 v190, v195, v52
	v_fmac_f32_e32 v191, v195, v53
	v_fmac_f32_e32 v192, v195, v54
	v_fmac_f32_e32 v193, v195, v55
	s_mov_b64 exec, s[8:9]
	ds_write_b64 v161, v[132:133] offset:2560
	s_mov_b64 exec, -1
	ds_read_b128 v[48:51], v152 offset:8704
	ds_read_b128 v[52:55], v152 offset:16896
	ds_read_b128 v[56:59], v152 offset:25088
	ds_read_b128 v[60:63], v152 offset:33280
	ds_read_b64 v[130:131], v69 offset:512
	s_waitcnt lgkmcnt(12)
	v_mul_f32_e32 v194, v186, v8
	v_mul_f32_e32 v195, v190, v8
	v_mul_f32_e32 v132, v186, v20
	v_mul_f32_e32 v133, v190, v20
	v_fmac_f32_e32 v194, v187, v9
	v_fmac_f32_e32 v195, v191, v9
	v_fmac_f32_e32 v132, v187, v21
	v_fmac_f32_e32 v133, v191, v21
	v_fmac_f32_e32 v194, v188, v10
	v_fmac_f32_e32 v195, v192, v10
	v_fmac_f32_e32 v132, v188, v22
	v_fmac_f32_e32 v133, v192, v22
	v_fmac_f32_e32 v194, v189, v11
	v_fmac_f32_e32 v195, v193, v11
	v_fmac_f32_e32 v132, v189, v23
	v_fmac_f32_e32 v133, v193, v23
	v_add_f32_dpp v194, v194, v194 quad_perm:[1,0,3,2] row_mask:0xf bank_mask:0xf bound_ctrl:1
	v_add_f32_dpp v195, v195, v195 quad_perm:[1,0,3,2] row_mask:0xf bank_mask:0xf bound_ctrl:1
	v_add_f32_dpp v132, v132, v132 quad_perm:[1,0,3,2] row_mask:0xf bank_mask:0xf bound_ctrl:1
	v_add_f32_dpp v133, v133, v133 quad_perm:[1,0,3,2] row_mask:0xf bank_mask:0xf bound_ctrl:1
	v_add_f32_dpp v194, v194, v194 quad_perm:[2,3,0,1] row_mask:0xf bank_mask:0xf bound_ctrl:1
	v_add_f32_dpp v195, v195, v195 quad_perm:[2,3,0,1] row_mask:0xf bank_mask:0xf bound_ctrl:1
	v_add_f32_dpp v132, v132, v132 quad_perm:[2,3,0,1] row_mask:0xf bank_mask:0xf bound_ctrl:1
	v_add_f32_dpp v133, v133, v133 quad_perm:[2,3,0,1] row_mask:0xf bank_mask:0xf bound_ctrl:1
	v_add_f32_dpp v194, v194, v194 row_half_mirror row_mask:0xf bank_mask:0xf bound_ctrl:1
	v_add_f32_dpp v195, v195, v195 row_half_mirror row_mask:0xf bank_mask:0xf bound_ctrl:1
	v_add_f32_dpp v132, v132, v132 row_half_mirror row_mask:0xf bank_mask:0xf bound_ctrl:1
	v_add_f32_dpp v133, v133, v133 row_half_mirror row_mask:0xf bank_mask:0xf bound_ctrl:1
	v_add_f32_dpp v194, v194, v194 row_mirror row_mask:0xf bank_mask:0xf bound_ctrl:1
	v_add_f32_dpp v195, v195, v195 row_mirror row_mask:0xf bank_mask:0xf bound_ctrl:1
	v_fmac_f32_e32 v186, v64, v16
	v_fmac_f32_e32 v187, v64, v17
	v_fmac_f32_e32 v188, v64, v18
	v_fmac_f32_e32 v189, v64, v19
	v_fmac_f32_e32 v190, v65, v16
	v_fmac_f32_e32 v191, v65, v17
	v_fmac_f32_e32 v192, v65, v18
	v_fmac_f32_e32 v193, v65, v19
	v_fmac_f32_e32 v186, v194, v12
	v_fmac_f32_e32 v187, v194, v13
	v_fmac_f32_e32 v188, v194, v14
	v_fmac_f32_e32 v189, v194, v15
	v_fmac_f32_e32 v190, v195, v12
	v_fmac_f32_e32 v191, v195, v13
	v_fmac_f32_e32 v192, v195, v14
	v_fmac_f32_e32 v193, v195, v15
	s_mov_b64 exec, s[8:9]
	ds_write_b64 v161, v[132:133] offset:2048
	s_mov_b64 exec, -1
	ds_read_b128 v[8:11], v152 offset:8448
	ds_read_b128 v[12:15], v152 offset:16640
	ds_read_b128 v[16:19], v152 offset:24832
	ds_read_b128 v[20:23], v152 offset:33024
	ds_read_b64 v[64:65], v69 offset:256
	s_waitcnt lgkmcnt(12)
	v_mul_f32_e32 v194, v186, v28
	v_mul_f32_e32 v195, v190, v28
	v_mul_f32_e32 v132, v186, v40
	v_mul_f32_e32 v133, v190, v40
	v_fmac_f32_e32 v194, v187, v29
	v_fmac_f32_e32 v195, v191, v29
	v_fmac_f32_e32 v132, v187, v41
	v_fmac_f32_e32 v133, v191, v41
	v_fmac_f32_e32 v194, v188, v30
	v_fmac_f32_e32 v195, v192, v30
	v_fmac_f32_e32 v132, v188, v42
	v_fmac_f32_e32 v133, v192, v42
	v_fmac_f32_e32 v194, v189, v31
	v_fmac_f32_e32 v195, v193, v31
	v_fmac_f32_e32 v132, v189, v43
	v_fmac_f32_e32 v133, v193, v43
	v_add_f32_dpp v194, v194, v194 quad_perm:[1,0,3,2] row_mask:0xf bank_mask:0xf bound_ctrl:1
	v_add_f32_dpp v195, v195, v195 quad_perm:[1,0,3,2] row_mask:0xf bank_mask:0xf bound_ctrl:1
	v_add_f32_dpp v132, v132, v132 quad_perm:[1,0,3,2] row_mask:0xf bank_mask:0xf bound_ctrl:1
	v_add_f32_dpp v133, v133, v133 quad_perm:[1,0,3,2] row_mask:0xf bank_mask:0xf bound_ctrl:1
	v_add_f32_dpp v194, v194, v194 quad_perm:[2,3,0,1] row_mask:0xf bank_mask:0xf bound_ctrl:1
	v_add_f32_dpp v195, v195, v195 quad_perm:[2,3,0,1] row_mask:0xf bank_mask:0xf bound_ctrl:1
	v_add_f32_dpp v132, v132, v132 quad_perm:[2,3,0,1] row_mask:0xf bank_mask:0xf bound_ctrl:1
	v_add_f32_dpp v133, v133, v133 quad_perm:[2,3,0,1] row_mask:0xf bank_mask:0xf bound_ctrl:1
	v_add_f32_dpp v194, v194, v194 row_half_mirror row_mask:0xf bank_mask:0xf bound_ctrl:1
	v_add_f32_dpp v195, v195, v195 row_half_mirror row_mask:0xf bank_mask:0xf bound_ctrl:1
	v_add_f32_dpp v132, v132, v132 row_half_mirror row_mask:0xf bank_mask:0xf bound_ctrl:1
	v_add_f32_dpp v133, v133, v133 row_half_mirror row_mask:0xf bank_mask:0xf bound_ctrl:1
	v_add_f32_dpp v194, v194, v194 row_mirror row_mask:0xf bank_mask:0xf bound_ctrl:1
	v_add_f32_dpp v195, v195, v195 row_mirror row_mask:0xf bank_mask:0xf bound_ctrl:1
	v_fmac_f32_e32 v186, v66, v36
	v_fmac_f32_e32 v187, v66, v37
	v_fmac_f32_e32 v188, v66, v38
	v_fmac_f32_e32 v189, v66, v39
	v_fmac_f32_e32 v190, v67, v36
	v_fmac_f32_e32 v191, v67, v37
	v_fmac_f32_e32 v192, v67, v38
	v_fmac_f32_e32 v193, v67, v39
	v_fmac_f32_e32 v186, v194, v32
	v_fmac_f32_e32 v187, v194, v33
	v_fmac_f32_e32 v188, v194, v34
	v_fmac_f32_e32 v189, v194, v35
	v_fmac_f32_e32 v190, v195, v32
	v_fmac_f32_e32 v191, v195, v33
	v_fmac_f32_e32 v192, v195, v34
	v_fmac_f32_e32 v193, v195, v35
	s_mov_b64 exec, s[8:9]
	ds_write_b64 v161, v[132:133] offset:1536
	s_mov_b64 exec, -1
	ds_read_b128 v[28:31], v152 offset:8192
	ds_read_b128 v[32:35], v152 offset:16384
	ds_read_b128 v[36:39], v152 offset:24576
	ds_read_b128 v[40:43], v152 offset:32768
	ds_read_b64 v[66:67], v69
	s_waitcnt lgkmcnt(12)
	v_mul_f32_e32 v194, v186, v48
	v_mul_f32_e32 v195, v190, v48
	v_mul_f32_e32 v132, v186, v60
	v_mul_f32_e32 v133, v190, v60
	v_fmac_f32_e32 v194, v187, v49
	v_fmac_f32_e32 v195, v191, v49
	v_fmac_f32_e32 v132, v187, v61
	v_fmac_f32_e32 v133, v191, v61
	v_fmac_f32_e32 v194, v188, v50
	v_fmac_f32_e32 v195, v192, v50
	v_fmac_f32_e32 v132, v188, v62
	v_fmac_f32_e32 v133, v192, v62
	v_fmac_f32_e32 v194, v189, v51
	v_fmac_f32_e32 v195, v193, v51
	v_fmac_f32_e32 v132, v189, v63
	v_fmac_f32_e32 v133, v193, v63
	v_add_f32_dpp v194, v194, v194 quad_perm:[1,0,3,2] row_mask:0xf bank_mask:0xf bound_ctrl:1
	v_add_f32_dpp v195, v195, v195 quad_perm:[1,0,3,2] row_mask:0xf bank_mask:0xf bound_ctrl:1
	v_add_f32_dpp v132, v132, v132 quad_perm:[1,0,3,2] row_mask:0xf bank_mask:0xf bound_ctrl:1
	v_add_f32_dpp v133, v133, v133 quad_perm:[1,0,3,2] row_mask:0xf bank_mask:0xf bound_ctrl:1
	v_add_f32_dpp v194, v194, v194 quad_perm:[2,3,0,1] row_mask:0xf bank_mask:0xf bound_ctrl:1
	v_add_f32_dpp v195, v195, v195 quad_perm:[2,3,0,1] row_mask:0xf bank_mask:0xf bound_ctrl:1
	v_add_f32_dpp v132, v132, v132 quad_perm:[2,3,0,1] row_mask:0xf bank_mask:0xf bound_ctrl:1
	v_add_f32_dpp v133, v133, v133 quad_perm:[2,3,0,1] row_mask:0xf bank_mask:0xf bound_ctrl:1
	v_add_f32_dpp v194, v194, v194 row_half_mirror row_mask:0xf bank_mask:0xf bound_ctrl:1
	v_add_f32_dpp v195, v195, v195 row_half_mirror row_mask:0xf bank_mask:0xf bound_ctrl:1
	v_add_f32_dpp v132, v132, v132 row_half_mirror row_mask:0xf bank_mask:0xf bound_ctrl:1
	v_add_f32_dpp v133, v133, v133 row_half_mirror row_mask:0xf bank_mask:0xf bound_ctrl:1
	v_add_f32_dpp v194, v194, v194 row_mirror row_mask:0xf bank_mask:0xf bound_ctrl:1
	v_add_f32_dpp v195, v195, v195 row_mirror row_mask:0xf bank_mask:0xf bound_ctrl:1
	v_fmac_f32_e32 v186, v130, v56
	v_fmac_f32_e32 v187, v130, v57
	v_fmac_f32_e32 v188, v130, v58
	v_fmac_f32_e32 v189, v130, v59
	v_fmac_f32_e32 v190, v131, v56
	v_fmac_f32_e32 v191, v131, v57
	v_fmac_f32_e32 v192, v131, v58
	v_fmac_f32_e32 v193, v131, v59
	v_fmac_f32_e32 v186, v194, v52
	v_fmac_f32_e32 v187, v194, v53
	v_fmac_f32_e32 v188, v194, v54
	v_fmac_f32_e32 v189, v194, v55
	v_fmac_f32_e32 v190, v195, v52
	v_fmac_f32_e32 v191, v195, v53
	v_fmac_f32_e32 v192, v195, v54
	v_fmac_f32_e32 v193, v195, v55
	s_mov_b64 exec, s[8:9]
	ds_write_b64 v161, v[132:133] offset:1024
	s_mov_b64 exec, -1
	s_waitcnt lgkmcnt(7)
	v_mul_f32_e32 v194, v186, v8
	v_mul_f32_e32 v195, v190, v8
	v_mul_f32_e32 v132, v186, v20
	v_mul_f32_e32 v133, v190, v20
	v_fmac_f32_e32 v194, v187, v9
	v_fmac_f32_e32 v195, v191, v9
	v_fmac_f32_e32 v132, v187, v21
	v_fmac_f32_e32 v133, v191, v21
	v_fmac_f32_e32 v194, v188, v10
	v_fmac_f32_e32 v195, v192, v10
	v_fmac_f32_e32 v132, v188, v22
	v_fmac_f32_e32 v133, v192, v22
	v_fmac_f32_e32 v194, v189, v11
	v_fmac_f32_e32 v195, v193, v11
	v_fmac_f32_e32 v132, v189, v23
	v_fmac_f32_e32 v133, v193, v23
	v_add_f32_dpp v194, v194, v194 quad_perm:[1,0,3,2] row_mask:0xf bank_mask:0xf bound_ctrl:1
	v_add_f32_dpp v195, v195, v195 quad_perm:[1,0,3,2] row_mask:0xf bank_mask:0xf bound_ctrl:1
	v_add_f32_dpp v132, v132, v132 quad_perm:[1,0,3,2] row_mask:0xf bank_mask:0xf bound_ctrl:1
	v_add_f32_dpp v133, v133, v133 quad_perm:[1,0,3,2] row_mask:0xf bank_mask:0xf bound_ctrl:1
	v_add_f32_dpp v194, v194, v194 quad_perm:[2,3,0,1] row_mask:0xf bank_mask:0xf bound_ctrl:1
	v_add_f32_dpp v195, v195, v195 quad_perm:[2,3,0,1] row_mask:0xf bank_mask:0xf bound_ctrl:1
	v_add_f32_dpp v132, v132, v132 quad_perm:[2,3,0,1] row_mask:0xf bank_mask:0xf bound_ctrl:1
	v_add_f32_dpp v133, v133, v133 quad_perm:[2,3,0,1] row_mask:0xf bank_mask:0xf bound_ctrl:1
	v_add_f32_dpp v194, v194, v194 row_half_mirror row_mask:0xf bank_mask:0xf bound_ctrl:1
	v_add_f32_dpp v195, v195, v195 row_half_mirror row_mask:0xf bank_mask:0xf bound_ctrl:1
	v_add_f32_dpp v132, v132, v132 row_half_mirror row_mask:0xf bank_mask:0xf bound_ctrl:1
	v_add_f32_dpp v133, v133, v133 row_half_mirror row_mask:0xf bank_mask:0xf bound_ctrl:1
	v_add_f32_dpp v194, v194, v194 row_mirror row_mask:0xf bank_mask:0xf bound_ctrl:1
	v_add_f32_dpp v195, v195, v195 row_mirror row_mask:0xf bank_mask:0xf bound_ctrl:1
	v_fmac_f32_e32 v186, v64, v16
	v_fmac_f32_e32 v187, v64, v17
	v_fmac_f32_e32 v188, v64, v18
	v_fmac_f32_e32 v189, v64, v19
	v_fmac_f32_e32 v190, v65, v16
	v_fmac_f32_e32 v191, v65, v17
	v_fmac_f32_e32 v192, v65, v18
	v_fmac_f32_e32 v193, v65, v19
	v_fmac_f32_e32 v186, v194, v12
	v_fmac_f32_e32 v187, v194, v13
	v_fmac_f32_e32 v188, v194, v14
	v_fmac_f32_e32 v189, v194, v15
	v_fmac_f32_e32 v190, v195, v12
	v_fmac_f32_e32 v191, v195, v13
	v_fmac_f32_e32 v192, v195, v14
	v_fmac_f32_e32 v193, v195, v15
	s_mov_b64 exec, s[8:9]
	ds_write_b64 v161, v[132:133] offset:512
	s_mov_b64 exec, -1
	s_waitcnt lgkmcnt(2)
	v_mul_f32_e32 v194, v186, v28
	v_mul_f32_e32 v195, v190, v28
	v_mul_f32_e32 v132, v186, v40
	v_mul_f32_e32 v133, v190, v40
	v_fmac_f32_e32 v194, v187, v29
	v_fmac_f32_e32 v195, v191, v29
	v_fmac_f32_e32 v132, v187, v41
	v_fmac_f32_e32 v133, v191, v41
	v_fmac_f32_e32 v194, v188, v30
	v_fmac_f32_e32 v195, v192, v30
	v_fmac_f32_e32 v132, v188, v42
	v_fmac_f32_e32 v133, v192, v42
	v_fmac_f32_e32 v194, v189, v31
	v_fmac_f32_e32 v195, v193, v31
	v_fmac_f32_e32 v132, v189, v43
	v_fmac_f32_e32 v133, v193, v43
	v_add_f32_dpp v194, v194, v194 quad_perm:[1,0,3,2] row_mask:0xf bank_mask:0xf bound_ctrl:1
	v_add_f32_dpp v195, v195, v195 quad_perm:[1,0,3,2] row_mask:0xf bank_mask:0xf bound_ctrl:1
	v_add_f32_dpp v132, v132, v132 quad_perm:[1,0,3,2] row_mask:0xf bank_mask:0xf bound_ctrl:1
	v_add_f32_dpp v133, v133, v133 quad_perm:[1,0,3,2] row_mask:0xf bank_mask:0xf bound_ctrl:1
	v_add_f32_dpp v194, v194, v194 quad_perm:[2,3,0,1] row_mask:0xf bank_mask:0xf bound_ctrl:1
	v_add_f32_dpp v195, v195, v195 quad_perm:[2,3,0,1] row_mask:0xf bank_mask:0xf bound_ctrl:1
	v_add_f32_dpp v132, v132, v132 quad_perm:[2,3,0,1] row_mask:0xf bank_mask:0xf bound_ctrl:1
	v_add_f32_dpp v133, v133, v133 quad_perm:[2,3,0,1] row_mask:0xf bank_mask:0xf bound_ctrl:1
	v_add_f32_dpp v194, v194, v194 row_half_mirror row_mask:0xf bank_mask:0xf bound_ctrl:1
	v_add_f32_dpp v195, v195, v195 row_half_mirror row_mask:0xf bank_mask:0xf bound_ctrl:1
	v_add_f32_dpp v132, v132, v132 row_half_mirror row_mask:0xf bank_mask:0xf bound_ctrl:1
	v_add_f32_dpp v133, v133, v133 row_half_mirror row_mask:0xf bank_mask:0xf bound_ctrl:1
	v_add_f32_dpp v194, v194, v194 row_mirror row_mask:0xf bank_mask:0xf bound_ctrl:1
	v_add_f32_dpp v195, v195, v195 row_mirror row_mask:0xf bank_mask:0xf bound_ctrl:1
	v_fmac_f32_e32 v186, v66, v36
	v_fmac_f32_e32 v187, v66, v37
	v_fmac_f32_e32 v188, v66, v38
	v_fmac_f32_e32 v189, v66, v39
	v_fmac_f32_e32 v190, v67, v36
	v_fmac_f32_e32 v191, v67, v37
	v_fmac_f32_e32 v192, v67, v38
	v_fmac_f32_e32 v193, v67, v39
	v_fmac_f32_e32 v186, v194, v32
	v_fmac_f32_e32 v187, v194, v33
	v_fmac_f32_e32 v188, v194, v34
	v_fmac_f32_e32 v189, v194, v35
	v_fmac_f32_e32 v190, v195, v32
	v_fmac_f32_e32 v191, v195, v33
	v_fmac_f32_e32 v192, v195, v34
	v_fmac_f32_e32 v193, v195, v35
	s_mov_b64 exec, s[8:9]
	ds_write_b64 v161, v[132:133]
	s_mov_b64 exec, -1
	ds_read_b128 v[4:7], v152 offset:57344
	s_waitcnt lgkmcnt(0)
	v_mul_f32_e32 v186, v186, v4
	v_mul_f32_e32 v187, v187, v5
	v_mul_f32_e32 v188, v188, v6
	v_mul_f32_e32 v189, v189, v7
	v_mul_f32_e32 v190, v190, v4
	v_mul_f32_e32 v191, v191, v5
	v_mul_f32_e32 v192, v192, v6
	v_mul_f32_e32 v193, v193, v7
	s_branch .LBB0_100

.LBB0_209:
	s_andn2_b64 vcc, exec, s[10:11]
	s_cbranch_vccnz .LBB0_211
	v_mul_f32_e32 v4, 0xbf60028a, v4
	v_mul_f32_e32 v5, 0xbf60028a, v5
	v_exp_f32_e32 v4, v4
	v_exp_f32_e32 v5, v5
	v_mul_f32_e32 v6, 0xbf60028a, v6
	v_mul_f32_e32 v7, 0xbf60028a, v7
	v_exp_f32_e32 v6, v6
	v_exp_f32_e32 v7, v7
	v_mul_f32_e32 v8, 0xbf60028a, v8
	v_mul_f32_e32 v9, 0xbf60028a, v9
	v_exp_f32_e32 v8, v8
	v_exp_f32_e32 v9, v9
	v_mul_f32_e32 v10, 0xbf60028a, v10
	v_mul_f32_e32 v11, 0xbf60028a, v11
	v_exp_f32_e32 v10, v10
	v_exp_f32_e32 v11, v11
	s_nop 1
	v_mul_f32_e32 v198, v4, v5
	v_mul_f32_e32 v201, v8, v9
	v_mul_f32_e32 v199, v198, v6
	v_mul_f32_e32 v202, v201, v10
	v_mul_f32_e32 v200, v199, v7
	v_mul_f32_e32 v203, v202, v11
	v_mbcnt_lo_u32_b32 v204, -1, 0
	v_mbcnt_hi_u32_b32 v204, -1, v204
	v_and_b32_e32 v205, 15, v204
	v_lshlrev_b32_e32 v205, 2, v205
	v_add_u32_e32 v206, 64, v205
	v_add_u32_e32 v207, 128, v205
	v_add_u32_e32 v208, 192, v205
	v_mov_b32_e32 v217, 1.0
	ds_bpermute_b32 v209, v205, v200
	ds_bpermute_b32 v210, v206, v200
	ds_bpermute_b32 v211, v207, v200
	ds_bpermute_b32 v212, v208, v200
	ds_bpermute_b32 v213, v205, v203
	ds_bpermute_b32 v214, v206, v203
	ds_bpermute_b32 v215, v207, v203
	ds_bpermute_b32 v216, v208, v203
	s_waitcnt lgkmcnt(0)
	v_cmp_lt_u32_e32 vcc, 15, v204
	v_cndmask_b32_e32 v218, v217, v209, vcc
	v_cndmask_b32_e32 v221, v217, v213, vcc
	v_cmp_lt_u32_e32 vcc, 31, v204
	v_cndmask_b32_e32 v219, v217, v210, vcc
	v_cndmask_b32_e32 v222, v217, v214, vcc
	v_cmp_lt_u32_e32 vcc, 47, v204
	v_cndmask_b32_e32 v220, v217, v211, vcc
	v_cndmask_b32_e32 v223, v217, v215, vcc
	v_mul_f32_e32 v224, v218, v219
	v_mul_f32_e32 v225, v221, v222
	v_mul_f32_e32 v226, v209, v210
	v_mul_f32_e32 v224, v224, v220
	v_mul_f32_e32 v225, v225, v223
	v_mul_f32_e32 v226, v226, v211
	v_mul_f32_e32 v226, v226, v212
	v_mul_f32_e32 v225, v225, v226
	v_mul_f32_e32 v230, v4, v224
	v_mul_f32_e32 v231, v198, v224
	v_mul_f32_e32 v232, v199, v224
	v_mul_f32_e32 v233, v200, v224
	v_mul_f32_e32 v234, v8, v225
	v_mul_f32_e32 v235, v201, v225
	v_mul_f32_e32 v236, v202, v225
	v_mul_f32_e32 v237, v203, v225
	ds_write2st64_b32 v145, v230, v231 offset0:224 offset1:225
	ds_write2st64_b32 v145, v232, v233 offset0:226 offset1:227
	ds_write2st64_b32 v145, v234, v235 offset0:240 offset1:241
	ds_write2st64_b32 v145, v236, v237 offset0:242 offset1:243
	s_waitcnt lgkmcnt(7)
	v_mul_f32_e32 v15, v29, v4
	ds_write2st64_b32 v145, v4, v5 offset1:1
	s_waitcnt lgkmcnt(7)
	v_mul_f32_e32 v4, v28, v5
	ds_write2st64_b32 v145, v15, v4 offset0:128 offset1:129
	s_waitcnt lgkmcnt(7)
	v_mul_f32_e32 v4, v26, v6
	s_waitcnt lgkmcnt(6)
	v_mul_f32_e32 v5, v25, v7
	ds_write2st64_b32 v145, v4, v5 offset0:130 offset1:131
	s_waitcnt lgkmcnt(6)
	v_mul_f32_e32 v4, v24, v8
	s_waitcnt lgkmcnt(5)
	v_mul_f32_e32 v5, v14, v9
	ds_write2st64_b32 v145, v4, v5 offset0:144 offset1:145
	s_waitcnt lgkmcnt(5)
	v_mul_f32_e32 v4, v13, v10
	s_waitcnt lgkmcnt(4)
	v_mul_f32_e32 v5, v12, v11
	ds_write2st64_b32 v145, v6, v7 offset0:2 offset1:3
	ds_write2st64_b32 v145, v8, v9 offset0:16 offset1:17
	ds_write2st64_b32 v145, v10, v11 offset0:18 offset1:19
	ds_write2st64_b32 v145, v4, v5 offset0:146 offset1:147

.LBB0_213:
	s_or_b64 exec, exec, s[10:11]
	v_add_u32_e32 v227, 0xffffff00, v152
	ds_read_b128 v[198:201], v152 offset:57344
	ds_read_b128 v[202:205], v227 offset:57344
	ds_read_b128 v[206:209], v152 offset:8192
	ds_read_b128 v[210:213], v152 offset:16384
	ds_read_b128 v[214:217], v152 offset:24576
	ds_read_b128 v[218:221], v152 offset:32768
	v_mov_b32_e32 v226, 1.0
	v_cmp_gt_u32_e32 vcc, 16, v134
	s_waitcnt lgkmcnt(4)
	v_rcp_f32_e32 v222, v198
	v_rcp_f32_e32 v223, v199
	v_rcp_f32_e32 v224, v200
	v_rcp_f32_e32 v225, v201
	v_cndmask_b32_e32 v202, v202, v226, vcc
	v_cndmask_b32_e32 v203, v203, v226, vcc
	v_cndmask_b32_e32 v204, v204, v226, vcc
	v_cndmask_b32_e32 v205, v205, v226, vcc
	s_waitcnt lgkmcnt(0)
	v_mul_f32_e32 v206, v206, v202
	v_mul_f32_e32 v207, v207, v203
	v_mul_f32_e32 v208, v208, v204
	v_mul_f32_e32 v209, v209, v205
	v_mul_f32_e32 v218, v218, v202
	v_mul_f32_e32 v219, v219, v203
	v_mul_f32_e32 v220, v220, v204
	v_mul_f32_e32 v221, v221, v205
	v_mul_f32_e32 v210, v210, v222
	v_mul_f32_e32 v211, v211, v223
	v_mul_f32_e32 v212, v212, v224
	v_mul_f32_e32 v213, v213, v225
	v_mul_f32_e32 v214, v214, v222
	v_mul_f32_e32 v215, v215, v223
	v_mul_f32_e32 v216, v216, v224
	v_mul_f32_e32 v217, v217, v225
	ds_write_b128 v152, v[206:209] offset:8192
	ds_write_b128 v152, v[218:221] offset:32768
	ds_write_b128 v152, v[210:213] offset:16384
	ds_write_b128 v152, v[214:217] offset:24576
	s_waitcnt lgkmcnt(0)
	s_barrier
	v_mbcnt_lo_u32_b32 v193, -1, 0
	v_mbcnt_hi_u32_b32 v193, -1, v193
	v_lshlrev_b32_e32 v193, 3, v193
	v_add_u32_e32 v193, 0xe000, v193
	v_cndmask_b32_e64 v192, v193, v146, s[8:9]
	ds_read_b128 v[8:11], v151 offset:8192
	ds_read_b128 v[12:15], v151 offset:16384
	ds_read_b128 v[16:19], v151 offset:24576
	ds_read_b128 v[20:23], v151 offset:32768
	ds_read_b64 v[64:65], v181
	ds_read_b128 v[28:31], v151 offset:8448
	ds_read_b128 v[32:35], v151 offset:16640
	ds_read_b128 v[36:39], v151 offset:24832
	ds_read_b128 v[40:43], v151 offset:33024
	ds_read_b64 v[66:67], v181 offset:256
	ds_read_b128 v[48:51], v151 offset:8704
	ds_read_b128 v[52:55], v151 offset:16896
	ds_read_b128 v[56:59], v151 offset:25088
	ds_read_b128 v[60:63], v151 offset:33280
	ds_read_b64 v[126:127], v181 offset:512
	s_waitcnt lgkmcnt(10)
	v_mul_f32_e32 v190, v182, v8
	v_mul_f32_e32 v191, v186, v8
	v_mul_f32_e32 v128, v182, v20
	v_mul_f32_e32 v129, v186, v20
	v_fmac_f32_e32 v190, v183, v9
	v_fmac_f32_e32 v191, v187, v9
	v_fmac_f32_e32 v128, v183, v21
	v_fmac_f32_e32 v129, v187, v21
	v_fmac_f32_e32 v190, v184, v10
	v_fmac_f32_e32 v191, v188, v10
	v_fmac_f32_e32 v128, v184, v22
	v_fmac_f32_e32 v129, v188, v22
	v_fmac_f32_e32 v190, v185, v11
	v_fmac_f32_e32 v191, v189, v11
	v_fmac_f32_e32 v128, v185, v23
	v_fmac_f32_e32 v129, v189, v23
	v_add_f32_dpp v190, v190, v190 quad_perm:[1,0,3,2] row_mask:0xf bank_mask:0xf bound_ctrl:1
	v_add_f32_dpp v191, v191, v191 quad_perm:[1,0,3,2] row_mask:0xf bank_mask:0xf bound_ctrl:1
	v_add_f32_dpp v128, v128, v128 quad_perm:[1,0,3,2] row_mask:0xf bank_mask:0xf bound_ctrl:1
	v_add_f32_dpp v129, v129, v129 quad_perm:[1,0,3,2] row_mask:0xf bank_mask:0xf bound_ctrl:1
	v_add_f32_dpp v190, v190, v190 quad_perm:[2,3,0,1] row_mask:0xf bank_mask:0xf bound_ctrl:1
	v_add_f32_dpp v191, v191, v191 quad_perm:[2,3,0,1] row_mask:0xf bank_mask:0xf bound_ctrl:1
	v_add_f32_dpp v128, v128, v128 quad_perm:[2,3,0,1] row_mask:0xf bank_mask:0xf bound_ctrl:1
	v_add_f32_dpp v129, v129, v129 quad_perm:[2,3,0,1] row_mask:0xf bank_mask:0xf bound_ctrl:1
	v_add_f32_dpp v190, v190, v190 row_half_mirror row_mask:0xf bank_mask:0xf bound_ctrl:1
	v_add_f32_dpp v191, v191, v191 row_half_mirror row_mask:0xf bank_mask:0xf bound_ctrl:1
	v_add_f32_dpp v128, v128, v128 row_half_mirror row_mask:0xf bank_mask:0xf bound_ctrl:1
	v_add_f32_dpp v129, v129, v129 row_half_mirror row_mask:0xf bank_mask:0xf bound_ctrl:1
	v_add_f32_dpp v190, v190, v190 row_mirror row_mask:0xf bank_mask:0xf bound_ctrl:1
	v_add_f32_dpp v191, v191, v191 row_mirror row_mask:0xf bank_mask:0xf bound_ctrl:1
	v_fmac_f32_e32 v182, v64, v16
	v_fmac_f32_e32 v183, v64, v17
	v_fmac_f32_e32 v184, v64, v18
	v_fmac_f32_e32 v185, v64, v19
	v_fmac_f32_e32 v186, v65, v16
	v_fmac_f32_e32 v187, v65, v17
	v_fmac_f32_e32 v188, v65, v18
	v_fmac_f32_e32 v189, v65, v19
	v_fmac_f32_e32 v182, v190, v12
	v_fmac_f32_e32 v183, v190, v13
	v_fmac_f32_e32 v184, v190, v14
	v_fmac_f32_e32 v185, v190, v15
	v_fmac_f32_e32 v186, v191, v12
	v_fmac_f32_e32 v187, v191, v13
	v_fmac_f32_e32 v188, v191, v14
	v_fmac_f32_e32 v189, v191, v15
	s_mov_b64 exec, s[8:9]
	ds_write_b64 v146, v[128:129]
	s_mov_b64 exec, -1
	ds_read_b128 v[8:11], v151 offset:8960
	ds_read_b128 v[12:15], v151 offset:17152
	ds_read_b128 v[16:19], v151 offset:25344
	ds_read_b128 v[20:23], v151 offset:33536
	ds_read_b64 v[64:65], v181 offset:768
	s_waitcnt lgkmcnt(11)
	v_mul_f32_e32 v190, v182, v28
	v_mul_f32_e32 v191, v186, v28
	v_mul_f32_e32 v128, v182, v40
	v_mul_f32_e32 v129, v186, v40
	v_fmac_f32_e32 v190, v183, v29
	v_fmac_f32_e32 v191, v187, v29
	v_fmac_f32_e32 v128, v183, v41
	v_fmac_f32_e32 v129, v187, v41
	v_fmac_f32_e32 v190, v184, v30
	v_fmac_f32_e32 v191, v188, v30
	v_fmac_f32_e32 v128, v184, v42
	v_fmac_f32_e32 v129, v188, v42
	v_fmac_f32_e32 v190, v185, v31
	v_fmac_f32_e32 v191, v189, v31
	v_fmac_f32_e32 v128, v185, v43
	v_fmac_f32_e32 v129, v189, v43
	v_add_f32_dpp v190, v190, v190 quad_perm:[1,0,3,2] row_mask:0xf bank_mask:0xf bound_ctrl:1
	v_add_f32_dpp v191, v191, v191 quad_perm:[1,0,3,2] row_mask:0xf bank_mask:0xf bound_ctrl:1
	v_add_f32_dpp v128, v128, v128 quad_perm:[1,0,3,2] row_mask:0xf bank_mask:0xf bound_ctrl:1
	v_add_f32_dpp v129, v129, v129 quad_perm:[1,0,3,2] row_mask:0xf bank_mask:0xf bound_ctrl:1
	v_add_f32_dpp v190, v190, v190 quad_perm:[2,3,0,1] row_mask:0xf bank_mask:0xf bound_ctrl:1
	v_add_f32_dpp v191, v191, v191 quad_perm:[2,3,0,1] row_mask:0xf bank_mask:0xf bound_ctrl:1
	v_add_f32_dpp v128, v128, v128 quad_perm:[2,3,0,1] row_mask:0xf bank_mask:0xf bound_ctrl:1
	v_add_f32_dpp v129, v129, v129 quad_perm:[2,3,0,1] row_mask:0xf bank_mask:0xf bound_ctrl:1
	v_add_f32_dpp v190, v190, v190 row_half_mirror row_mask:0xf bank_mask:0xf bound_ctrl:1
	v_add_f32_dpp v191, v191, v191 row_half_mirror row_mask:0xf bank_mask:0xf bound_ctrl:1
	v_add_f32_dpp v128, v128, v128 row_half_mirror row_mask:0xf bank_mask:0xf bound_ctrl:1
	v_add_f32_dpp v129, v129, v129 row_half_mirror row_mask:0xf bank_mask:0xf bound_ctrl:1
	v_add_f32_dpp v190, v190, v190 row_mirror row_mask:0xf bank_mask:0xf bound_ctrl:1
	v_add_f32_dpp v191, v191, v191 row_mirror row_mask:0xf bank_mask:0xf bound_ctrl:1
	v_fmac_f32_e32 v182, v66, v36
	v_fmac_f32_e32 v183, v66, v37
	v_fmac_f32_e32 v184, v66, v38
	v_fmac_f32_e32 v185, v66, v39
	v_fmac_f32_e32 v186, v67, v36
	v_fmac_f32_e32 v187, v67, v37
	v_fmac_f32_e32 v188, v67, v38
	v_fmac_f32_e32 v189, v67, v39
	v_fmac_f32_e32 v182, v190, v32
	v_fmac_f32_e32 v183, v190, v33
	v_fmac_f32_e32 v184, v190, v34
	v_fmac_f32_e32 v185, v190, v35
	v_fmac_f32_e32 v186, v191, v32
	v_fmac_f32_e32 v187, v191, v33
	v_fmac_f32_e32 v188, v191, v34
	v_fmac_f32_e32 v189, v191, v35
	s_mov_b64 exec, s[8:9]
	ds_write_b64 v146, v[128:129] offset:512
	s_mov_b64 exec, -1
	ds_read_b128 v[28:31], v151 offset:9216
	ds_read_b128 v[32:35], v151 offset:17408
	ds_read_b128 v[36:39], v151 offset:25600
	ds_read_b128 v[40:43], v151 offset:33792
	ds_read_b64 v[66:67], v181 offset:1024
	s_waitcnt lgkmcnt(12)
	v_mul_f32_e32 v190, v182, v48
	v_mul_f32_e32 v191, v186, v48
	v_mul_f32_e32 v128, v182, v60
	v_mul_f32_e32 v129, v186, v60
	v_fmac_f32_e32 v190, v183, v49
	v_fmac_f32_e32 v191, v187, v49
	v_fmac_f32_e32 v128, v183, v61
	v_fmac_f32_e32 v129, v187, v61
	v_fmac_f32_e32 v190, v184, v50
	v_fmac_f32_e32 v191, v188, v50
	v_fmac_f32_e32 v128, v184, v62
	v_fmac_f32_e32 v129, v188, v62
	v_fmac_f32_e32 v190, v185, v51
	v_fmac_f32_e32 v191, v189, v51
	v_fmac_f32_e32 v128, v185, v63
	v_fmac_f32_e32 v129, v189, v63
	v_add_f32_dpp v190, v190, v190 quad_perm:[1,0,3,2] row_mask:0xf bank_mask:0xf bound_ctrl:1
	v_add_f32_dpp v191, v191, v191 quad_perm:[1,0,3,2] row_mask:0xf bank_mask:0xf bound_ctrl:1
	v_add_f32_dpp v128, v128, v128 quad_perm:[1,0,3,2] row_mask:0xf bank_mask:0xf bound_ctrl:1
	v_add_f32_dpp v129, v129, v129 quad_perm:[1,0,3,2] row_mask:0xf bank_mask:0xf bound_ctrl:1
	v_add_f32_dpp v190, v190, v190 quad_perm:[2,3,0,1] row_mask:0xf bank_mask:0xf bound_ctrl:1
	v_add_f32_dpp v191, v191, v191 quad_perm:[2,3,0,1] row_mask:0xf bank_mask:0xf bound_ctrl:1
	v_add_f32_dpp v128, v128, v128 quad_perm:[2,3,0,1] row_mask:0xf bank_mask:0xf bound_ctrl:1
	v_add_f32_dpp v129, v129, v129 quad_perm:[2,3,0,1] row_mask:0xf bank_mask:0xf bound_ctrl:1
	v_add_f32_dpp v190, v190, v190 row_half_mirror row_mask:0xf bank_mask:0xf bound_ctrl:1
	v_add_f32_dpp v191, v191, v191 row_half_mirror row_mask:0xf bank_mask:0xf bound_ctrl:1
	v_add_f32_dpp v128, v128, v128 row_half_mirror row_mask:0xf bank_mask:0xf bound_ctrl:1
	v_add_f32_dpp v129, v129, v129 row_half_mirror row_mask:0xf bank_mask:0xf bound_ctrl:1
	v_add_f32_dpp v190, v190, v190 row_mirror row_mask:0xf bank_mask:0xf bound_ctrl:1
	v_add_f32_dpp v191, v191, v191 row_mirror row_mask:0xf bank_mask:0xf bound_ctrl:1
	v_fmac_f32_e32 v182, v126, v56
	v_fmac_f32_e32 v183, v126, v57
	v_fmac_f32_e32 v184, v126, v58
	v_fmac_f32_e32 v185, v126, v59
	v_fmac_f32_e32 v186, v127, v56
	v_fmac_f32_e32 v187, v127, v57
	v_fmac_f32_e32 v188, v127, v58
	v_fmac_f32_e32 v189, v127, v59
	v_fmac_f32_e32 v182, v190, v52
	v_fmac_f32_e32 v183, v190, v53
	v_fmac_f32_e32 v184, v190, v54
	v_fmac_f32_e32 v185, v190, v55
	v_fmac_f32_e32 v186, v191, v52
	v_fmac_f32_e32 v187, v191, v53
	v_fmac_f32_e32 v188, v191, v54
	v_fmac_f32_e32 v189, v191, v55
	s_mov_b64 exec, s[8:9]
	ds_write_b64 v146, v[128:129] offset:1024
	s_mov_b64 exec, -1
	ds_read_b128 v[48:51], v151 offset:9472
	ds_read_b128 v[52:55], v151 offset:17664
	ds_read_b128 v[56:59], v151 offset:25856
	ds_read_b128 v[60:63], v151 offset:34048
	ds_read_b64 v[126:127], v181 offset:1280
	s_waitcnt lgkmcnt(12)
	v_mul_f32_e32 v190, v182, v8
	v_mul_f32_e32 v191, v186, v8
	v_mul_f32_e32 v128, v182, v20
	v_mul_f32_e32 v129, v186, v20
	v_fmac_f32_e32 v190, v183, v9
	v_fmac_f32_e32 v191, v187, v9
	v_fmac_f32_e32 v128, v183, v21
	v_fmac_f32_e32 v129, v187, v21
	v_fmac_f32_e32 v190, v184, v10
	v_fmac_f32_e32 v191, v188, v10
	v_fmac_f32_e32 v128, v184, v22
	v_fmac_f32_e32 v129, v188, v22
	v_fmac_f32_e32 v190, v185, v11
	v_fmac_f32_e32 v191, v189, v11
	v_fmac_f32_e32 v128, v185, v23
	v_fmac_f32_e32 v129, v189, v23
	v_add_f32_dpp v190, v190, v190 quad_perm:[1,0,3,2] row_mask:0xf bank_mask:0xf bound_ctrl:1
	v_add_f32_dpp v191, v191, v191 quad_perm:[1,0,3,2] row_mask:0xf bank_mask:0xf bound_ctrl:1
	v_add_f32_dpp v128, v128, v128 quad_perm:[1,0,3,2] row_mask:0xf bank_mask:0xf bound_ctrl:1
	v_add_f32_dpp v129, v129, v129 quad_perm:[1,0,3,2] row_mask:0xf bank_mask:0xf bound_ctrl:1
	v_add_f32_dpp v190, v190, v190 quad_perm:[2,3,0,1] row_mask:0xf bank_mask:0xf bound_ctrl:1
	v_add_f32_dpp v191, v191, v191 quad_perm:[2,3,0,1] row_mask:0xf bank_mask:0xf bound_ctrl:1
	v_add_f32_dpp v128, v128, v128 quad_perm:[2,3,0,1] row_mask:0xf bank_mask:0xf bound_ctrl:1
	v_add_f32_dpp v129, v129, v129 quad_perm:[2,3,0,1] row_mask:0xf bank_mask:0xf bound_ctrl:1
	v_add_f32_dpp v190, v190, v190 row_half_mirror row_mask:0xf bank_mask:0xf bound_ctrl:1
	v_add_f32_dpp v191, v191, v191 row_half_mirror row_mask:0xf bank_mask:0xf bound_ctrl:1
	v_add_f32_dpp v128, v128, v128 row_half_mirror row_mask:0xf bank_mask:0xf bound_ctrl:1
	v_add_f32_dpp v129, v129, v129 row_half_mirror row_mask:0xf bank_mask:0xf bound_ctrl:1
	v_add_f32_dpp v190, v190, v190 row_mirror row_mask:0xf bank_mask:0xf bound_ctrl:1
	v_add_f32_dpp v191, v191, v191 row_mirror row_mask:0xf bank_mask:0xf bound_ctrl:1
	v_fmac_f32_e32 v182, v64, v16
	v_fmac_f32_e32 v183, v64, v17
	v_fmac_f32_e32 v184, v64, v18
	v_fmac_f32_e32 v185, v64, v19
	v_fmac_f32_e32 v186, v65, v16
	v_fmac_f32_e32 v187, v65, v17
	v_fmac_f32_e32 v188, v65, v18
	v_fmac_f32_e32 v189, v65, v19
	v_fmac_f32_e32 v182, v190, v12
	v_fmac_f32_e32 v183, v190, v13
	v_fmac_f32_e32 v184, v190, v14
	v_fmac_f32_e32 v185, v190, v15
	v_fmac_f32_e32 v186, v191, v12
	v_fmac_f32_e32 v187, v191, v13
	v_fmac_f32_e32 v188, v191, v14
	v_fmac_f32_e32 v189, v191, v15
	s_mov_b64 exec, s[8:9]
	ds_write_b64 v146, v[128:129] offset:1536
	s_mov_b64 exec, -1
	ds_read_b128 v[8:11], v151 offset:9728
	ds_read_b128 v[12:15], v151 offset:17920
	ds_read_b128 v[16:19], v151 offset:26112
	ds_read_b128 v[20:23], v151 offset:34304
	ds_read_b64 v[64:65], v181 offset:1536
	s_waitcnt lgkmcnt(12)
	v_mul_f32_e32 v190, v182, v28
	v_mul_f32_e32 v191, v186, v28
	v_mul_f32_e32 v128, v182, v40
	v_mul_f32_e32 v129, v186, v40
	v_fmac_f32_e32 v190, v183, v29
	v_fmac_f32_e32 v191, v187, v29
	v_fmac_f32_e32 v128, v183, v41
	v_fmac_f32_e32 v129, v187, v41
	v_fmac_f32_e32 v190, v184, v30
	v_fmac_f32_e32 v191, v188, v30
	v_fmac_f32_e32 v128, v184, v42
	v_fmac_f32_e32 v129, v188, v42
	v_fmac_f32_e32 v190, v185, v31
	v_fmac_f32_e32 v191, v189, v31
	v_fmac_f32_e32 v128, v185, v43
	v_fmac_f32_e32 v129, v189, v43
	v_add_f32_dpp v190, v190, v190 quad_perm:[1,0,3,2] row_mask:0xf bank_mask:0xf bound_ctrl:1
	v_add_f32_dpp v191, v191, v191 quad_perm:[1,0,3,2] row_mask:0xf bank_mask:0xf bound_ctrl:1
	v_add_f32_dpp v128, v128, v128 quad_perm:[1,0,3,2] row_mask:0xf bank_mask:0xf bound_ctrl:1
	v_add_f32_dpp v129, v129, v129 quad_perm:[1,0,3,2] row_mask:0xf bank_mask:0xf bound_ctrl:1
	v_add_f32_dpp v190, v190, v190 quad_perm:[2,3,0,1] row_mask:0xf bank_mask:0xf bound_ctrl:1
	v_add_f32_dpp v191, v191, v191 quad_perm:[2,3,0,1] row_mask:0xf bank_mask:0xf bound_ctrl:1
	v_add_f32_dpp v128, v128, v128 quad_perm:[2,3,0,1] row_mask:0xf bank_mask:0xf bound_ctrl:1
	v_add_f32_dpp v129, v129, v129 quad_perm:[2,3,0,1] row_mask:0xf bank_mask:0xf bound_ctrl:1
	v_add_f32_dpp v190, v190, v190 row_half_mirror row_mask:0xf bank_mask:0xf bound_ctrl:1
	v_add_f32_dpp v191, v191, v191 row_half_mirror row_mask:0xf bank_mask:0xf bound_ctrl:1
	v_add_f32_dpp v128, v128, v128 row_half_mirror row_mask:0xf bank_mask:0xf bound_ctrl:1
	v_add_f32_dpp v129, v129, v129 row_half_mirror row_mask:0xf bank_mask:0xf bound_ctrl:1
	v_add_f32_dpp v190, v190, v190 row_mirror row_mask:0xf bank_mask:0xf bound_ctrl:1
	v_add_f32_dpp v191, v191, v191 row_mirror row_mask:0xf bank_mask:0xf bound_ctrl:1
	v_fmac_f32_e32 v182, v66, v36
	v_fmac_f32_e32 v183, v66, v37
	v_fmac_f32_e32 v184, v66, v38
	v_fmac_f32_e32 v185, v66, v39
	v_fmac_f32_e32 v186, v67, v36
	v_fmac_f32_e32 v187, v67, v37
	v_fmac_f32_e32 v188, v67, v38
	v_fmac_f32_e32 v189, v67, v39
	v_fmac_f32_e32 v182, v190, v32
	v_fmac_f32_e32 v183, v190, v33
	v_fmac_f32_e32 v184, v190, v34
	v_fmac_f32_e32 v185, v190, v35
	v_fmac_f32_e32 v186, v191, v32
	v_fmac_f32_e32 v187, v191, v33
	v_fmac_f32_e32 v188, v191, v34
	v_fmac_f32_e32 v189, v191, v35
	s_mov_b64 exec, s[8:9]
	ds_write_b64 v146, v[128:129] offset:2048
	s_mov_b64 exec, -1
	ds_read_b128 v[28:31], v151 offset:9984
	ds_read_b128 v[32:35], v151 offset:18176
	ds_read_b128 v[36:39], v151 offset:26368
	ds_read_b128 v[40:43], v151 offset:34560
	ds_read_b64 v[66:67], v181 offset:1792
	s_waitcnt lgkmcnt(12)
	v_mul_f32_e32 v190, v182, v48
	v_mul_f32_e32 v191, v186, v48
	v_mul_f32_e32 v128, v182, v60
	v_mul_f32_e32 v129, v186, v60
	v_fmac_f32_e32 v190, v183, v49
	v_fmac_f32_e32 v191, v187, v49
	v_fmac_f32_e32 v128, v183, v61
	v_fmac_f32_e32 v129, v187, v61
	v_fmac_f32_e32 v190, v184, v50
	v_fmac_f32_e32 v191, v188, v50
	v_fmac_f32_e32 v128, v184, v62
	v_fmac_f32_e32 v129, v188, v62
	v_fmac_f32_e32 v190, v185, v51
	v_fmac_f32_e32 v191, v189, v51
	v_fmac_f32_e32 v128, v185, v63
	v_fmac_f32_e32 v129, v189, v63
	v_add_f32_dpp v190, v190, v190 quad_perm:[1,0,3,2] row_mask:0xf bank_mask:0xf bound_ctrl:1
	v_add_f32_dpp v191, v191, v191 quad_perm:[1,0,3,2] row_mask:0xf bank_mask:0xf bound_ctrl:1
	v_add_f32_dpp v128, v128, v128 quad_perm:[1,0,3,2] row_mask:0xf bank_mask:0xf bound_ctrl:1
	v_add_f32_dpp v129, v129, v129 quad_perm:[1,0,3,2] row_mask:0xf bank_mask:0xf bound_ctrl:1
	v_add_f32_dpp v190, v190, v190 quad_perm:[2,3,0,1] row_mask:0xf bank_mask:0xf bound_ctrl:1
	v_add_f32_dpp v191, v191, v191 quad_perm:[2,3,0,1] row_mask:0xf bank_mask:0xf bound_ctrl:1
	v_add_f32_dpp v128, v128, v128 quad_perm:[2,3,0,1] row_mask:0xf bank_mask:0xf bound_ctrl:1
	v_add_f32_dpp v129, v129, v129 quad_perm:[2,3,0,1] row_mask:0xf bank_mask:0xf bound_ctrl:1
	v_add_f32_dpp v190, v190, v190 row_half_mirror row_mask:0xf bank_mask:0xf bound_ctrl:1
	v_add_f32_dpp v191, v191, v191 row_half_mirror row_mask:0xf bank_mask:0xf bound_ctrl:1
	v_add_f32_dpp v128, v128, v128 row_half_mirror row_mask:0xf bank_mask:0xf bound_ctrl:1
	v_add_f32_dpp v129, v129, v129 row_half_mirror row_mask:0xf bank_mask:0xf bound_ctrl:1
	v_add_f32_dpp v190, v190, v190 row_mirror row_mask:0xf bank_mask:0xf bound_ctrl:1
	v_add_f32_dpp v191, v191, v191 row_mirror row_mask:0xf bank_mask:0xf bound_ctrl:1
	v_fmac_f32_e32 v182, v126, v56
	v_fmac_f32_e32 v183, v126, v57
	v_fmac_f32_e32 v184, v126, v58
	v_fmac_f32_e32 v185, v126, v59
	v_fmac_f32_e32 v186, v127, v56
	v_fmac_f32_e32 v187, v127, v57
	v_fmac_f32_e32 v188, v127, v58
	v_fmac_f32_e32 v189, v127, v59
	v_fmac_f32_e32 v182, v190, v52
	v_fmac_f32_e32 v183, v190, v53
	v_fmac_f32_e32 v184, v190, v54
	v_fmac_f32_e32 v185, v190, v55
	v_fmac_f32_e32 v186, v191, v52
	v_fmac_f32_e32 v187, v191, v53
	v_fmac_f32_e32 v188, v191, v54
	v_fmac_f32_e32 v189, v191, v55
	s_mov_b64 exec, s[8:9]
	ds_write_b64 v146, v[128:129] offset:2560
	s_mov_b64 exec, -1
	ds_read_b128 v[48:51], v151 offset:10240
	ds_read_b128 v[52:55], v151 offset:18432
	ds_read_b128 v[56:59], v151 offset:26624
	ds_read_b128 v[60:63], v151 offset:34816
	ds_read_b64 v[126:127], v181 offset:2048
	s_waitcnt lgkmcnt(12)
	v_mul_f32_e32 v190, v182, v8
	v_mul_f32_e32 v191, v186, v8
	v_mul_f32_e32 v128, v182, v20
	v_mul_f32_e32 v129, v186, v20
	v_fmac_f32_e32 v190, v183, v9
	v_fmac_f32_e32 v191, v187, v9
	v_fmac_f32_e32 v128, v183, v21
	v_fmac_f32_e32 v129, v187, v21
	v_fmac_f32_e32 v190, v184, v10
	v_fmac_f32_e32 v191, v188, v10
	v_fmac_f32_e32 v128, v184, v22
	v_fmac_f32_e32 v129, v188, v22
	v_fmac_f32_e32 v190, v185, v11
	v_fmac_f32_e32 v191, v189, v11
	v_fmac_f32_e32 v128, v185, v23
	v_fmac_f32_e32 v129, v189, v23
	v_add_f32_dpp v190, v190, v190 quad_perm:[1,0,3,2] row_mask:0xf bank_mask:0xf bound_ctrl:1
	v_add_f32_dpp v191, v191, v191 quad_perm:[1,0,3,2] row_mask:0xf bank_mask:0xf bound_ctrl:1
	v_add_f32_dpp v128, v128, v128 quad_perm:[1,0,3,2] row_mask:0xf bank_mask:0xf bound_ctrl:1
	v_add_f32_dpp v129, v129, v129 quad_perm:[1,0,3,2] row_mask:0xf bank_mask:0xf bound_ctrl:1
	v_add_f32_dpp v190, v190, v190 quad_perm:[2,3,0,1] row_mask:0xf bank_mask:0xf bound_ctrl:1
	v_add_f32_dpp v191, v191, v191 quad_perm:[2,3,0,1] row_mask:0xf bank_mask:0xf bound_ctrl:1
	v_add_f32_dpp v128, v128, v128 quad_perm:[2,3,0,1] row_mask:0xf bank_mask:0xf bound_ctrl:1
	v_add_f32_dpp v129, v129, v129 quad_perm:[2,3,0,1] row_mask:0xf bank_mask:0xf bound_ctrl:1
	v_add_f32_dpp v190, v190, v190 row_half_mirror row_mask:0xf bank_mask:0xf bound_ctrl:1
	v_add_f32_dpp v191, v191, v191 row_half_mirror row_mask:0xf bank_mask:0xf bound_ctrl:1
	v_add_f32_dpp v128, v128, v128 row_half_mirror row_mask:0xf bank_mask:0xf bound_ctrl:1
	v_add_f32_dpp v129, v129, v129 row_half_mirror row_mask:0xf bank_mask:0xf bound_ctrl:1
	v_add_f32_dpp v190, v190, v190 row_mirror row_mask:0xf bank_mask:0xf bound_ctrl:1
	v_add_f32_dpp v191, v191, v191 row_mirror row_mask:0xf bank_mask:0xf bound_ctrl:1
	v_fmac_f32_e32 v182, v64, v16
	v_fmac_f32_e32 v183, v64, v17
	v_fmac_f32_e32 v184, v64, v18
	v_fmac_f32_e32 v185, v64, v19
	v_fmac_f32_e32 v186, v65, v16
	v_fmac_f32_e32 v187, v65, v17
	v_fmac_f32_e32 v188, v65, v18
	v_fmac_f32_e32 v189, v65, v19
	v_fmac_f32_e32 v182, v190, v12
	v_fmac_f32_e32 v183, v190, v13
	v_fmac_f32_e32 v184, v190, v14
	v_fmac_f32_e32 v185, v190, v15
	v_fmac_f32_e32 v186, v191, v12
	v_fmac_f32_e32 v187, v191, v13
	v_fmac_f32_e32 v188, v191, v14
	v_fmac_f32_e32 v189, v191, v15
	s_mov_b64 exec, s[8:9]
	ds_write_b64 v146, v[128:129] offset:3072
	s_mov_b64 exec, -1
	ds_read_b128 v[8:11], v151 offset:10496
	ds_read_b128 v[12:15], v151 offset:18688
	ds_read_b128 v[16:19], v151 offset:26880
	ds_read_b128 v[20:23], v151 offset:35072
	ds_read_b64 v[64:65], v181 offset:2304
	s_waitcnt lgkmcnt(12)
	v_mul_f32_e32 v190, v182, v28
	v_mul_f32_e32 v191, v186, v28
	v_mul_f32_e32 v128, v182, v40
	v_mul_f32_e32 v129, v186, v40
	v_fmac_f32_e32 v190, v183, v29
	v_fmac_f32_e32 v191, v187, v29
	v_fmac_f32_e32 v128, v183, v41
	v_fmac_f32_e32 v129, v187, v41
	v_fmac_f32_e32 v190, v184, v30
	v_fmac_f32_e32 v191, v188, v30
	v_fmac_f32_e32 v128, v184, v42
	v_fmac_f32_e32 v129, v188, v42
	v_fmac_f32_e32 v190, v185, v31
	v_fmac_f32_e32 v191, v189, v31
	v_fmac_f32_e32 v128, v185, v43
	v_fmac_f32_e32 v129, v189, v43
	v_add_f32_dpp v190, v190, v190 quad_perm:[1,0,3,2] row_mask:0xf bank_mask:0xf bound_ctrl:1
	v_add_f32_dpp v191, v191, v191 quad_perm:[1,0,3,2] row_mask:0xf bank_mask:0xf bound_ctrl:1
	v_add_f32_dpp v128, v128, v128 quad_perm:[1,0,3,2] row_mask:0xf bank_mask:0xf bound_ctrl:1
	v_add_f32_dpp v129, v129, v129 quad_perm:[1,0,3,2] row_mask:0xf bank_mask:0xf bound_ctrl:1
	v_add_f32_dpp v190, v190, v190 quad_perm:[2,3,0,1] row_mask:0xf bank_mask:0xf bound_ctrl:1
	v_add_f32_dpp v191, v191, v191 quad_perm:[2,3,0,1] row_mask:0xf bank_mask:0xf bound_ctrl:1
	v_add_f32_dpp v128, v128, v128 quad_perm:[2,3,0,1] row_mask:0xf bank_mask:0xf bound_ctrl:1
	v_add_f32_dpp v129, v129, v129 quad_perm:[2,3,0,1] row_mask:0xf bank_mask:0xf bound_ctrl:1
	v_add_f32_dpp v190, v190, v190 row_half_mirror row_mask:0xf bank_mask:0xf bound_ctrl:1
	v_add_f32_dpp v191, v191, v191 row_half_mirror row_mask:0xf bank_mask:0xf bound_ctrl:1
	v_add_f32_dpp v128, v128, v128 row_half_mirror row_mask:0xf bank_mask:0xf bound_ctrl:1
	v_add_f32_dpp v129, v129, v129 row_half_mirror row_mask:0xf bank_mask:0xf bound_ctrl:1
	v_add_f32_dpp v190, v190, v190 row_mirror row_mask:0xf bank_mask:0xf bound_ctrl:1
	v_add_f32_dpp v191, v191, v191 row_mirror row_mask:0xf bank_mask:0xf bound_ctrl:1
	v_fmac_f32_e32 v182, v66, v36
	v_fmac_f32_e32 v183, v66, v37
	v_fmac_f32_e32 v184, v66, v38
	v_fmac_f32_e32 v185, v66, v39
	v_fmac_f32_e32 v186, v67, v36
	v_fmac_f32_e32 v187, v67, v37
	v_fmac_f32_e32 v188, v67, v38
	v_fmac_f32_e32 v189, v67, v39
	v_fmac_f32_e32 v182, v190, v32
	v_fmac_f32_e32 v183, v190, v33
	v_fmac_f32_e32 v184, v190, v34
	v_fmac_f32_e32 v185, v190, v35
	v_fmac_f32_e32 v186, v191, v32
	v_fmac_f32_e32 v187, v191, v33
	v_fmac_f32_e32 v188, v191, v34
	v_fmac_f32_e32 v189, v191, v35
	s_mov_b64 exec, s[8:9]
	ds_write_b64 v146, v[128:129] offset:3584
	s_mov_b64 exec, -1
	ds_read_b128 v[28:31], v151 offset:10752
	ds_read_b128 v[32:35], v151 offset:18944
	ds_read_b128 v[36:39], v151 offset:27136
	ds_read_b128 v[40:43], v151 offset:35328
	ds_read_b64 v[66:67], v181 offset:2560
	s_waitcnt lgkmcnt(12)
	v_mul_f32_e32 v190, v182, v48
	v_mul_f32_e32 v191, v186, v48
	v_mul_f32_e32 v128, v182, v60
	v_mul_f32_e32 v129, v186, v60
	v_fmac_f32_e32 v190, v183, v49
	v_fmac_f32_e32 v191, v187, v49
	v_fmac_f32_e32 v128, v183, v61
	v_fmac_f32_e32 v129, v187, v61
	v_fmac_f32_e32 v190, v184, v50
	v_fmac_f32_e32 v191, v188, v50
	v_fmac_f32_e32 v128, v184, v62
	v_fmac_f32_e32 v129, v188, v62
	v_fmac_f32_e32 v190, v185, v51
	v_fmac_f32_e32 v191, v189, v51
	v_fmac_f32_e32 v128, v185, v63
	v_fmac_f32_e32 v129, v189, v63
	v_add_f32_dpp v190, v190, v190 quad_perm:[1,0,3,2] row_mask:0xf bank_mask:0xf bound_ctrl:1
	v_add_f32_dpp v191, v191, v191 quad_perm:[1,0,3,2] row_mask:0xf bank_mask:0xf bound_ctrl:1
	v_add_f32_dpp v128, v128, v128 quad_perm:[1,0,3,2] row_mask:0xf bank_mask:0xf bound_ctrl:1
	v_add_f32_dpp v129, v129, v129 quad_perm:[1,0,3,2] row_mask:0xf bank_mask:0xf bound_ctrl:1
	v_add_f32_dpp v190, v190, v190 quad_perm:[2,3,0,1] row_mask:0xf bank_mask:0xf bound_ctrl:1
	v_add_f32_dpp v191, v191, v191 quad_perm:[2,3,0,1] row_mask:0xf bank_mask:0xf bound_ctrl:1
	v_add_f32_dpp v128, v128, v128 quad_perm:[2,3,0,1] row_mask:0xf bank_mask:0xf bound_ctrl:1
	v_add_f32_dpp v129, v129, v129 quad_perm:[2,3,0,1] row_mask:0xf bank_mask:0xf bound_ctrl:1
	v_add_f32_dpp v190, v190, v190 row_half_mirror row_mask:0xf bank_mask:0xf bound_ctrl:1
	v_add_f32_dpp v191, v191, v191 row_half_mirror row_mask:0xf bank_mask:0xf bound_ctrl:1
	v_add_f32_dpp v128, v128, v128 row_half_mirror row_mask:0xf bank_mask:0xf bound_ctrl:1
	v_add_f32_dpp v129, v129, v129 row_half_mirror row_mask:0xf bank_mask:0xf bound_ctrl:1
	v_add_f32_dpp v190, v190, v190 row_mirror row_mask:0xf bank_mask:0xf bound_ctrl:1
	v_add_f32_dpp v191, v191, v191 row_mirror row_mask:0xf bank_mask:0xf bound_ctrl:1
	v_fmac_f32_e32 v182, v126, v56
	v_fmac_f32_e32 v183, v126, v57
	v_fmac_f32_e32 v184, v126, v58
	v_fmac_f32_e32 v185, v126, v59
	v_fmac_f32_e32 v186, v127, v56
	v_fmac_f32_e32 v187, v127, v57
	v_fmac_f32_e32 v188, v127, v58
	v_fmac_f32_e32 v189, v127, v59
	v_fmac_f32_e32 v182, v190, v52
	v_fmac_f32_e32 v183, v190, v53
	v_fmac_f32_e32 v184, v190, v54
	v_fmac_f32_e32 v185, v190, v55
	v_fmac_f32_e32 v186, v191, v52
	v_fmac_f32_e32 v187, v191, v53
	v_fmac_f32_e32 v188, v191, v54
	v_fmac_f32_e32 v189, v191, v55
	s_mov_b64 exec, s[8:9]
	ds_write_b64 v146, v[128:129] offset:4096
	s_mov_b64 exec, -1
	ds_read_b128 v[48:51], v151 offset:11008
	ds_read_b128 v[52:55], v151 offset:19200
	ds_read_b128 v[56:59], v151 offset:27392
	ds_read_b128 v[60:63], v151 offset:35584
	ds_read_b64 v[126:127], v181 offset:2816
	s_waitcnt lgkmcnt(12)
	v_mul_f32_e32 v190, v182, v8
	v_mul_f32_e32 v191, v186, v8
	v_mul_f32_e32 v128, v182, v20
	v_mul_f32_e32 v129, v186, v20
	v_fmac_f32_e32 v190, v183, v9
	v_fmac_f32_e32 v191, v187, v9
	v_fmac_f32_e32 v128, v183, v21
	v_fmac_f32_e32 v129, v187, v21
	v_fmac_f32_e32 v190, v184, v10
	v_fmac_f32_e32 v191, v188, v10
	v_fmac_f32_e32 v128, v184, v22
	v_fmac_f32_e32 v129, v188, v22
	v_fmac_f32_e32 v190, v185, v11
	v_fmac_f32_e32 v191, v189, v11
	v_fmac_f32_e32 v128, v185, v23
	v_fmac_f32_e32 v129, v189, v23
	v_add_f32_dpp v190, v190, v190 quad_perm:[1,0,3,2] row_mask:0xf bank_mask:0xf bound_ctrl:1
	v_add_f32_dpp v191, v191, v191 quad_perm:[1,0,3,2] row_mask:0xf bank_mask:0xf bound_ctrl:1
	v_add_f32_dpp v128, v128, v128 quad_perm:[1,0,3,2] row_mask:0xf bank_mask:0xf bound_ctrl:1
	v_add_f32_dpp v129, v129, v129 quad_perm:[1,0,3,2] row_mask:0xf bank_mask:0xf bound_ctrl:1
	v_add_f32_dpp v190, v190, v190 quad_perm:[2,3,0,1] row_mask:0xf bank_mask:0xf bound_ctrl:1
	v_add_f32_dpp v191, v191, v191 quad_perm:[2,3,0,1] row_mask:0xf bank_mask:0xf bound_ctrl:1
	v_add_f32_dpp v128, v128, v128 quad_perm:[2,3,0,1] row_mask:0xf bank_mask:0xf bound_ctrl:1
	v_add_f32_dpp v129, v129, v129 quad_perm:[2,3,0,1] row_mask:0xf bank_mask:0xf bound_ctrl:1
	v_add_f32_dpp v190, v190, v190 row_half_mirror row_mask:0xf bank_mask:0xf bound_ctrl:1
	v_add_f32_dpp v191, v191, v191 row_half_mirror row_mask:0xf bank_mask:0xf bound_ctrl:1
	v_add_f32_dpp v128, v128, v128 row_half_mirror row_mask:0xf bank_mask:0xf bound_ctrl:1
	v_add_f32_dpp v129, v129, v129 row_half_mirror row_mask:0xf bank_mask:0xf bound_ctrl:1
	v_add_f32_dpp v190, v190, v190 row_mirror row_mask:0xf bank_mask:0xf bound_ctrl:1
	v_add_f32_dpp v191, v191, v191 row_mirror row_mask:0xf bank_mask:0xf bound_ctrl:1
	v_fmac_f32_e32 v182, v64, v16
	v_fmac_f32_e32 v183, v64, v17
	v_fmac_f32_e32 v184, v64, v18
	v_fmac_f32_e32 v185, v64, v19
	v_fmac_f32_e32 v186, v65, v16
	v_fmac_f32_e32 v187, v65, v17
	v_fmac_f32_e32 v188, v65, v18
	v_fmac_f32_e32 v189, v65, v19
	v_fmac_f32_e32 v182, v190, v12
	v_fmac_f32_e32 v183, v190, v13
	v_fmac_f32_e32 v184, v190, v14
	v_fmac_f32_e32 v185, v190, v15
	v_fmac_f32_e32 v186, v191, v12
	v_fmac_f32_e32 v187, v191, v13
	v_fmac_f32_e32 v188, v191, v14
	v_fmac_f32_e32 v189, v191, v15
	s_mov_b64 exec, s[8:9]
	ds_write_b64 v146, v[128:129] offset:4608
	s_mov_b64 exec, -1
	ds_read_b128 v[8:11], v151 offset:11264
	ds_read_b128 v[12:15], v151 offset:19456
	ds_read_b128 v[16:19], v151 offset:27648
	ds_read_b128 v[20:23], v151 offset:35840
	ds_read_b64 v[64:65], v181 offset:3072
	s_waitcnt lgkmcnt(12)
	v_mul_f32_e32 v190, v182, v28
	v_mul_f32_e32 v191, v186, v28
	v_mul_f32_e32 v128, v182, v40
	v_mul_f32_e32 v129, v186, v40
	v_fmac_f32_e32 v190, v183, v29
	v_fmac_f32_e32 v191, v187, v29
	v_fmac_f32_e32 v128, v183, v41
	v_fmac_f32_e32 v129, v187, v41
	v_fmac_f32_e32 v190, v184, v30
	v_fmac_f32_e32 v191, v188, v30
	v_fmac_f32_e32 v128, v184, v42
	v_fmac_f32_e32 v129, v188, v42
	v_fmac_f32_e32 v190, v185, v31
	v_fmac_f32_e32 v191, v189, v31
	v_fmac_f32_e32 v128, v185, v43
	v_fmac_f32_e32 v129, v189, v43
	v_add_f32_dpp v190, v190, v190 quad_perm:[1,0,3,2] row_mask:0xf bank_mask:0xf bound_ctrl:1
	v_add_f32_dpp v191, v191, v191 quad_perm:[1,0,3,2] row_mask:0xf bank_mask:0xf bound_ctrl:1
	v_add_f32_dpp v128, v128, v128 quad_perm:[1,0,3,2] row_mask:0xf bank_mask:0xf bound_ctrl:1
	v_add_f32_dpp v129, v129, v129 quad_perm:[1,0,3,2] row_mask:0xf bank_mask:0xf bound_ctrl:1
	v_add_f32_dpp v190, v190, v190 quad_perm:[2,3,0,1] row_mask:0xf bank_mask:0xf bound_ctrl:1
	v_add_f32_dpp v191, v191, v191 quad_perm:[2,3,0,1] row_mask:0xf bank_mask:0xf bound_ctrl:1
	v_add_f32_dpp v128, v128, v128 quad_perm:[2,3,0,1] row_mask:0xf bank_mask:0xf bound_ctrl:1
	v_add_f32_dpp v129, v129, v129 quad_perm:[2,3,0,1] row_mask:0xf bank_mask:0xf bound_ctrl:1
	v_add_f32_dpp v190, v190, v190 row_half_mirror row_mask:0xf bank_mask:0xf bound_ctrl:1
	v_add_f32_dpp v191, v191, v191 row_half_mirror row_mask:0xf bank_mask:0xf bound_ctrl:1
	v_add_f32_dpp v128, v128, v128 row_half_mirror row_mask:0xf bank_mask:0xf bound_ctrl:1
	v_add_f32_dpp v129, v129, v129 row_half_mirror row_mask:0xf bank_mask:0xf bound_ctrl:1
	v_add_f32_dpp v190, v190, v190 row_mirror row_mask:0xf bank_mask:0xf bound_ctrl:1
	v_add_f32_dpp v191, v191, v191 row_mirror row_mask:0xf bank_mask:0xf bound_ctrl:1
	v_fmac_f32_e32 v182, v66, v36
	v_fmac_f32_e32 v183, v66, v37
	v_fmac_f32_e32 v184, v66, v38
	v_fmac_f32_e32 v185, v66, v39
	v_fmac_f32_e32 v186, v67, v36
	v_fmac_f32_e32 v187, v67, v37
	v_fmac_f32_e32 v188, v67, v38
	v_fmac_f32_e32 v189, v67, v39
	v_fmac_f32_e32 v182, v190, v32
	v_fmac_f32_e32 v183, v190, v33
	v_fmac_f32_e32 v184, v190, v34
	v_fmac_f32_e32 v185, v190, v35
	v_fmac_f32_e32 v186, v191, v32
	v_fmac_f32_e32 v187, v191, v33
	v_fmac_f32_e32 v188, v191, v34
	v_fmac_f32_e32 v189, v191, v35
	s_mov_b64 exec, s[8:9]
	ds_write_b64 v146, v[128:129] offset:5120
	s_mov_b64 exec, -1
	ds_read_b128 v[28:31], v151 offset:11520
	ds_read_b128 v[32:35], v151 offset:19712
	ds_read_b128 v[36:39], v151 offset:27904
	ds_read_b128 v[40:43], v151 offset:36096
	ds_read_b64 v[66:67], v181 offset:3328
	s_waitcnt lgkmcnt(12)
	v_mul_f32_e32 v190, v182, v48
	v_mul_f32_e32 v191, v186, v48
	v_mul_f32_e32 v128, v182, v60
	v_mul_f32_e32 v129, v186, v60
	v_fmac_f32_e32 v190, v183, v49
	v_fmac_f32_e32 v191, v187, v49
	v_fmac_f32_e32 v128, v183, v61
	v_fmac_f32_e32 v129, v187, v61
	v_fmac_f32_e32 v190, v184, v50
	v_fmac_f32_e32 v191, v188, v50
	v_fmac_f32_e32 v128, v184, v62
	v_fmac_f32_e32 v129, v188, v62
	v_fmac_f32_e32 v190, v185, v51
	v_fmac_f32_e32 v191, v189, v51
	v_fmac_f32_e32 v128, v185, v63
	v_fmac_f32_e32 v129, v189, v63
	v_add_f32_dpp v190, v190, v190 quad_perm:[1,0,3,2] row_mask:0xf bank_mask:0xf bound_ctrl:1
	v_add_f32_dpp v191, v191, v191 quad_perm:[1,0,3,2] row_mask:0xf bank_mask:0xf bound_ctrl:1
	v_add_f32_dpp v128, v128, v128 quad_perm:[1,0,3,2] row_mask:0xf bank_mask:0xf bound_ctrl:1
	v_add_f32_dpp v129, v129, v129 quad_perm:[1,0,3,2] row_mask:0xf bank_mask:0xf bound_ctrl:1
	v_add_f32_dpp v190, v190, v190 quad_perm:[2,3,0,1] row_mask:0xf bank_mask:0xf bound_ctrl:1
	v_add_f32_dpp v191, v191, v191 quad_perm:[2,3,0,1] row_mask:0xf bank_mask:0xf bound_ctrl:1
	v_add_f32_dpp v128, v128, v128 quad_perm:[2,3,0,1] row_mask:0xf bank_mask:0xf bound_ctrl:1
	v_add_f32_dpp v129, v129, v129 quad_perm:[2,3,0,1] row_mask:0xf bank_mask:0xf bound_ctrl:1
	v_add_f32_dpp v190, v190, v190 row_half_mirror row_mask:0xf bank_mask:0xf bound_ctrl:1
	v_add_f32_dpp v191, v191, v191 row_half_mirror row_mask:0xf bank_mask:0xf bound_ctrl:1
	v_add_f32_dpp v128, v128, v128 row_half_mirror row_mask:0xf bank_mask:0xf bound_ctrl:1
	v_add_f32_dpp v129, v129, v129 row_half_mirror row_mask:0xf bank_mask:0xf bound_ctrl:1
	v_add_f32_dpp v190, v190, v190 row_mirror row_mask:0xf bank_mask:0xf bound_ctrl:1
	v_add_f32_dpp v191, v191, v191 row_mirror row_mask:0xf bank_mask:0xf bound_ctrl:1
	v_fmac_f32_e32 v182, v126, v56
	v_fmac_f32_e32 v183, v126, v57
	v_fmac_f32_e32 v184, v126, v58
	v_fmac_f32_e32 v185, v126, v59
	v_fmac_f32_e32 v186, v127, v56
	v_fmac_f32_e32 v187, v127, v57
	v_fmac_f32_e32 v188, v127, v58
	v_fmac_f32_e32 v189, v127, v59
	v_fmac_f32_e32 v182, v190, v52
	v_fmac_f32_e32 v183, v190, v53
	v_fmac_f32_e32 v184, v190, v54
	v_fmac_f32_e32 v185, v190, v55
	v_fmac_f32_e32 v186, v191, v52
	v_fmac_f32_e32 v187, v191, v53
	v_fmac_f32_e32 v188, v191, v54
	v_fmac_f32_e32 v189, v191, v55
	s_mov_b64 exec, s[8:9]
	ds_write_b64 v146, v[128:129] offset:5632
	s_mov_b64 exec, -1
	ds_read_b128 v[48:51], v151 offset:11776
	ds_read_b128 v[52:55], v151 offset:19968
	ds_read_b128 v[56:59], v151 offset:28160
	ds_read_b128 v[60:63], v151 offset:36352
	ds_read_b64 v[126:127], v181 offset:3584
	s_waitcnt lgkmcnt(12)
	v_mul_f32_e32 v190, v182, v8
	v_mul_f32_e32 v191, v186, v8
	v_mul_f32_e32 v128, v182, v20
	v_mul_f32_e32 v129, v186, v20
	v_fmac_f32_e32 v190, v183, v9
	v_fmac_f32_e32 v191, v187, v9
	v_fmac_f32_e32 v128, v183, v21
	v_fmac_f32_e32 v129, v187, v21
	v_fmac_f32_e32 v190, v184, v10
	v_fmac_f32_e32 v191, v188, v10
	v_fmac_f32_e32 v128, v184, v22
	v_fmac_f32_e32 v129, v188, v22
	v_fmac_f32_e32 v190, v185, v11
	v_fmac_f32_e32 v191, v189, v11
	v_fmac_f32_e32 v128, v185, v23
	v_fmac_f32_e32 v129, v189, v23
	v_add_f32_dpp v190, v190, v190 quad_perm:[1,0,3,2] row_mask:0xf bank_mask:0xf bound_ctrl:1
	v_add_f32_dpp v191, v191, v191 quad_perm:[1,0,3,2] row_mask:0xf bank_mask:0xf bound_ctrl:1
	v_add_f32_dpp v128, v128, v128 quad_perm:[1,0,3,2] row_mask:0xf bank_mask:0xf bound_ctrl:1
	v_add_f32_dpp v129, v129, v129 quad_perm:[1,0,3,2] row_mask:0xf bank_mask:0xf bound_ctrl:1
	v_add_f32_dpp v190, v190, v190 quad_perm:[2,3,0,1] row_mask:0xf bank_mask:0xf bound_ctrl:1
	v_add_f32_dpp v191, v191, v191 quad_perm:[2,3,0,1] row_mask:0xf bank_mask:0xf bound_ctrl:1
	v_add_f32_dpp v128, v128, v128 quad_perm:[2,3,0,1] row_mask:0xf bank_mask:0xf bound_ctrl:1
	v_add_f32_dpp v129, v129, v129 quad_perm:[2,3,0,1] row_mask:0xf bank_mask:0xf bound_ctrl:1
	v_add_f32_dpp v190, v190, v190 row_half_mirror row_mask:0xf bank_mask:0xf bound_ctrl:1
	v_add_f32_dpp v191, v191, v191 row_half_mirror row_mask:0xf bank_mask:0xf bound_ctrl:1
	v_add_f32_dpp v128, v128, v128 row_half_mirror row_mask:0xf bank_mask:0xf bound_ctrl:1
	v_add_f32_dpp v129, v129, v129 row_half_mirror row_mask:0xf bank_mask:0xf bound_ctrl:1
	v_add_f32_dpp v190, v190, v190 row_mirror row_mask:0xf bank_mask:0xf bound_ctrl:1
	v_add_f32_dpp v191, v191, v191 row_mirror row_mask:0xf bank_mask:0xf bound_ctrl:1
	v_fmac_f32_e32 v182, v64, v16
	v_fmac_f32_e32 v183, v64, v17
	v_fmac_f32_e32 v184, v64, v18
	v_fmac_f32_e32 v185, v64, v19
	v_fmac_f32_e32 v186, v65, v16
	v_fmac_f32_e32 v187, v65, v17
	v_fmac_f32_e32 v188, v65, v18
	v_fmac_f32_e32 v189, v65, v19
	v_fmac_f32_e32 v182, v190, v12
	v_fmac_f32_e32 v183, v190, v13
	v_fmac_f32_e32 v184, v190, v14
	v_fmac_f32_e32 v185, v190, v15
	v_fmac_f32_e32 v186, v191, v12
	v_fmac_f32_e32 v187, v191, v13
	v_fmac_f32_e32 v188, v191, v14
	v_fmac_f32_e32 v189, v191, v15
	s_mov_b64 exec, s[8:9]
	ds_write_b64 v146, v[128:129] offset:6144
	s_mov_b64 exec, -1
	ds_read_b128 v[8:11], v151 offset:12032
	ds_read_b128 v[12:15], v151 offset:20224
	ds_read_b128 v[16:19], v151 offset:28416
	ds_read_b128 v[20:23], v151 offset:36608
	ds_read_b64 v[64:65], v181 offset:3840
	s_waitcnt lgkmcnt(12)
	v_mul_f32_e32 v190, v182, v28
	v_mul_f32_e32 v191, v186, v28
	v_mul_f32_e32 v128, v182, v40
	v_mul_f32_e32 v129, v186, v40
	v_fmac_f32_e32 v190, v183, v29
	v_fmac_f32_e32 v191, v187, v29
	v_fmac_f32_e32 v128, v183, v41
	v_fmac_f32_e32 v129, v187, v41
	v_fmac_f32_e32 v190, v184, v30
	v_fmac_f32_e32 v191, v188, v30
	v_fmac_f32_e32 v128, v184, v42
	v_fmac_f32_e32 v129, v188, v42
	v_fmac_f32_e32 v190, v185, v31
	v_fmac_f32_e32 v191, v189, v31
	v_fmac_f32_e32 v128, v185, v43
	v_fmac_f32_e32 v129, v189, v43
	v_add_f32_dpp v190, v190, v190 quad_perm:[1,0,3,2] row_mask:0xf bank_mask:0xf bound_ctrl:1
	v_add_f32_dpp v191, v191, v191 quad_perm:[1,0,3,2] row_mask:0xf bank_mask:0xf bound_ctrl:1
	v_add_f32_dpp v128, v128, v128 quad_perm:[1,0,3,2] row_mask:0xf bank_mask:0xf bound_ctrl:1
	v_add_f32_dpp v129, v129, v129 quad_perm:[1,0,3,2] row_mask:0xf bank_mask:0xf bound_ctrl:1
	v_add_f32_dpp v190, v190, v190 quad_perm:[2,3,0,1] row_mask:0xf bank_mask:0xf bound_ctrl:1
	v_add_f32_dpp v191, v191, v191 quad_perm:[2,3,0,1] row_mask:0xf bank_mask:0xf bound_ctrl:1
	v_add_f32_dpp v128, v128, v128 quad_perm:[2,3,0,1] row_mask:0xf bank_mask:0xf bound_ctrl:1
	v_add_f32_dpp v129, v129, v129 quad_perm:[2,3,0,1] row_mask:0xf bank_mask:0xf bound_ctrl:1
	v_add_f32_dpp v190, v190, v190 row_half_mirror row_mask:0xf bank_mask:0xf bound_ctrl:1
	v_add_f32_dpp v191, v191, v191 row_half_mirror row_mask:0xf bank_mask:0xf bound_ctrl:1
	v_add_f32_dpp v128, v128, v128 row_half_mirror row_mask:0xf bank_mask:0xf bound_ctrl:1
	v_add_f32_dpp v129, v129, v129 row_half_mirror row_mask:0xf bank_mask:0xf bound_ctrl:1
	v_add_f32_dpp v190, v190, v190 row_mirror row_mask:0xf bank_mask:0xf bound_ctrl:1
	v_add_f32_dpp v191, v191, v191 row_mirror row_mask:0xf bank_mask:0xf bound_ctrl:1
	v_fmac_f32_e32 v182, v66, v36
	v_fmac_f32_e32 v183, v66, v37
	v_fmac_f32_e32 v184, v66, v38
	v_fmac_f32_e32 v185, v66, v39
	v_fmac_f32_e32 v186, v67, v36
	v_fmac_f32_e32 v187, v67, v37
	v_fmac_f32_e32 v188, v67, v38
	v_fmac_f32_e32 v189, v67, v39
	v_fmac_f32_e32 v182, v190, v32
	v_fmac_f32_e32 v183, v190, v33
	v_fmac_f32_e32 v184, v190, v34
	v_fmac_f32_e32 v185, v190, v35
	v_fmac_f32_e32 v186, v191, v32
	v_fmac_f32_e32 v187, v191, v33
	v_fmac_f32_e32 v188, v191, v34
	v_fmac_f32_e32 v189, v191, v35
	s_mov_b64 exec, s[8:9]
	ds_write_b64 v146, v[128:129] offset:6656
	s_mov_b64 exec, -1
	ds_read_b128 v[28:31], v151 offset:12288
	ds_read_b128 v[32:35], v151 offset:20480
	ds_read_b128 v[36:39], v151 offset:28672
	ds_read_b128 v[40:43], v151 offset:36864
	ds_read_b64 v[66:67], v181 offset:4096
	s_waitcnt lgkmcnt(12)
	v_mul_f32_e32 v190, v182, v48
	v_mul_f32_e32 v191, v186, v48
	v_mul_f32_e32 v128, v182, v60
	v_mul_f32_e32 v129, v186, v60
	v_fmac_f32_e32 v190, v183, v49
	v_fmac_f32_e32 v191, v187, v49
	v_fmac_f32_e32 v128, v183, v61
	v_fmac_f32_e32 v129, v187, v61
	v_fmac_f32_e32 v190, v184, v50
	v_fmac_f32_e32 v191, v188, v50
	v_fmac_f32_e32 v128, v184, v62
	v_fmac_f32_e32 v129, v188, v62
	v_fmac_f32_e32 v190, v185, v51
	v_fmac_f32_e32 v191, v189, v51
	v_fmac_f32_e32 v128, v185, v63
	v_fmac_f32_e32 v129, v189, v63
	v_add_f32_dpp v190, v190, v190 quad_perm:[1,0,3,2] row_mask:0xf bank_mask:0xf bound_ctrl:1
	v_add_f32_dpp v191, v191, v191 quad_perm:[1,0,3,2] row_mask:0xf bank_mask:0xf bound_ctrl:1
	v_add_f32_dpp v128, v128, v128 quad_perm:[1,0,3,2] row_mask:0xf bank_mask:0xf bound_ctrl:1
	v_add_f32_dpp v129, v129, v129 quad_perm:[1,0,3,2] row_mask:0xf bank_mask:0xf bound_ctrl:1
	v_add_f32_dpp v190, v190, v190 quad_perm:[2,3,0,1] row_mask:0xf bank_mask:0xf bound_ctrl:1
	v_add_f32_dpp v191, v191, v191 quad_perm:[2,3,0,1] row_mask:0xf bank_mask:0xf bound_ctrl:1
	v_add_f32_dpp v128, v128, v128 quad_perm:[2,3,0,1] row_mask:0xf bank_mask:0xf bound_ctrl:1
	v_add_f32_dpp v129, v129, v129 quad_perm:[2,3,0,1] row_mask:0xf bank_mask:0xf bound_ctrl:1
	v_add_f32_dpp v190, v190, v190 row_half_mirror row_mask:0xf bank_mask:0xf bound_ctrl:1
	v_add_f32_dpp v191, v191, v191 row_half_mirror row_mask:0xf bank_mask:0xf bound_ctrl:1
	v_add_f32_dpp v128, v128, v128 row_half_mirror row_mask:0xf bank_mask:0xf bound_ctrl:1
	v_add_f32_dpp v129, v129, v129 row_half_mirror row_mask:0xf bank_mask:0xf bound_ctrl:1
	v_add_f32_dpp v190, v190, v190 row_mirror row_mask:0xf bank_mask:0xf bound_ctrl:1
	v_add_f32_dpp v191, v191, v191 row_mirror row_mask:0xf bank_mask:0xf bound_ctrl:1
	v_fmac_f32_e32 v182, v126, v56
	v_fmac_f32_e32 v183, v126, v57
	v_fmac_f32_e32 v184, v126, v58
	v_fmac_f32_e32 v185, v126, v59
	v_fmac_f32_e32 v186, v127, v56
	v_fmac_f32_e32 v187, v127, v57
	v_fmac_f32_e32 v188, v127, v58
	v_fmac_f32_e32 v189, v127, v59
	v_fmac_f32_e32 v182, v190, v52
	v_fmac_f32_e32 v183, v190, v53
	v_fmac_f32_e32 v184, v190, v54
	v_fmac_f32_e32 v185, v190, v55
	v_fmac_f32_e32 v186, v191, v52
	v_fmac_f32_e32 v187, v191, v53
	v_fmac_f32_e32 v188, v191, v54
	v_fmac_f32_e32 v189, v191, v55
	s_mov_b64 exec, s[8:9]
	ds_write_b64 v146, v[128:129] offset:7168
	s_mov_b64 exec, -1
	ds_read_b128 v[48:51], v151 offset:12544
	ds_read_b128 v[52:55], v151 offset:20736
	ds_read_b128 v[56:59], v151 offset:28928
	ds_read_b128 v[60:63], v151 offset:37120
	ds_read_b64 v[126:127], v181 offset:4352
	s_waitcnt lgkmcnt(12)
	v_mul_f32_e32 v190, v182, v8
	v_mul_f32_e32 v191, v186, v8
	v_mul_f32_e32 v128, v182, v20
	v_mul_f32_e32 v129, v186, v20
	v_fmac_f32_e32 v190, v183, v9
	v_fmac_f32_e32 v191, v187, v9
	v_fmac_f32_e32 v128, v183, v21
	v_fmac_f32_e32 v129, v187, v21
	v_fmac_f32_e32 v190, v184, v10
	v_fmac_f32_e32 v191, v188, v10
	v_fmac_f32_e32 v128, v184, v22
	v_fmac_f32_e32 v129, v188, v22
	v_fmac_f32_e32 v190, v185, v11
	v_fmac_f32_e32 v191, v189, v11
	v_fmac_f32_e32 v128, v185, v23
	v_fmac_f32_e32 v129, v189, v23
	v_add_f32_dpp v190, v190, v190 quad_perm:[1,0,3,2] row_mask:0xf bank_mask:0xf bound_ctrl:1
	v_add_f32_dpp v191, v191, v191 quad_perm:[1,0,3,2] row_mask:0xf bank_mask:0xf bound_ctrl:1
	v_add_f32_dpp v128, v128, v128 quad_perm:[1,0,3,2] row_mask:0xf bank_mask:0xf bound_ctrl:1
	v_add_f32_dpp v129, v129, v129 quad_perm:[1,0,3,2] row_mask:0xf bank_mask:0xf bound_ctrl:1
	v_add_f32_dpp v190, v190, v190 quad_perm:[2,3,0,1] row_mask:0xf bank_mask:0xf bound_ctrl:1
	v_add_f32_dpp v191, v191, v191 quad_perm:[2,3,0,1] row_mask:0xf bank_mask:0xf bound_ctrl:1
	v_add_f32_dpp v128, v128, v128 quad_perm:[2,3,0,1] row_mask:0xf bank_mask:0xf bound_ctrl:1
	v_add_f32_dpp v129, v129, v129 quad_perm:[2,3,0,1] row_mask:0xf bank_mask:0xf bound_ctrl:1
	v_add_f32_dpp v190, v190, v190 row_half_mirror row_mask:0xf bank_mask:0xf bound_ctrl:1
	v_add_f32_dpp v191, v191, v191 row_half_mirror row_mask:0xf bank_mask:0xf bound_ctrl:1
	v_add_f32_dpp v128, v128, v128 row_half_mirror row_mask:0xf bank_mask:0xf bound_ctrl:1
	v_add_f32_dpp v129, v129, v129 row_half_mirror row_mask:0xf bank_mask:0xf bound_ctrl:1
	v_add_f32_dpp v190, v190, v190 row_mirror row_mask:0xf bank_mask:0xf bound_ctrl:1
	v_add_f32_dpp v191, v191, v191 row_mirror row_mask:0xf bank_mask:0xf bound_ctrl:1
	v_fmac_f32_e32 v182, v64, v16
	v_fmac_f32_e32 v183, v64, v17
	v_fmac_f32_e32 v184, v64, v18
	v_fmac_f32_e32 v185, v64, v19
	v_fmac_f32_e32 v186, v65, v16
	v_fmac_f32_e32 v187, v65, v17
	v_fmac_f32_e32 v188, v65, v18
	v_fmac_f32_e32 v189, v65, v19
	v_fmac_f32_e32 v182, v190, v12
	v_fmac_f32_e32 v183, v190, v13
	v_fmac_f32_e32 v184, v190, v14
	v_fmac_f32_e32 v185, v190, v15
	v_fmac_f32_e32 v186, v191, v12
	v_fmac_f32_e32 v187, v191, v13
	v_fmac_f32_e32 v188, v191, v14
	v_fmac_f32_e32 v189, v191, v15
	s_mov_b64 exec, s[8:9]
	ds_write_b64 v146, v[128:129] offset:7680
	s_mov_b64 exec, -1
	ds_read_b128 v[8:11], v151 offset:12800
	ds_read_b128 v[12:15], v151 offset:20992
	ds_read_b128 v[16:19], v151 offset:29184
	ds_read_b128 v[20:23], v151 offset:37376
	ds_read_b64 v[64:65], v181 offset:4608
	s_waitcnt lgkmcnt(12)
	v_mul_f32_e32 v190, v182, v28
	v_mul_f32_e32 v191, v186, v28
	v_mul_f32_e32 v128, v182, v40
	v_mul_f32_e32 v129, v186, v40
	v_fmac_f32_e32 v190, v183, v29
	v_fmac_f32_e32 v191, v187, v29
	v_fmac_f32_e32 v128, v183, v41
	v_fmac_f32_e32 v129, v187, v41
	v_fmac_f32_e32 v190, v184, v30
	v_fmac_f32_e32 v191, v188, v30
	v_fmac_f32_e32 v128, v184, v42
	v_fmac_f32_e32 v129, v188, v42
	v_fmac_f32_e32 v190, v185, v31
	v_fmac_f32_e32 v191, v189, v31
	v_fmac_f32_e32 v128, v185, v43
	v_fmac_f32_e32 v129, v189, v43
	v_add_f32_dpp v190, v190, v190 quad_perm:[1,0,3,2] row_mask:0xf bank_mask:0xf bound_ctrl:1
	v_add_f32_dpp v191, v191, v191 quad_perm:[1,0,3,2] row_mask:0xf bank_mask:0xf bound_ctrl:1
	v_add_f32_dpp v128, v128, v128 quad_perm:[1,0,3,2] row_mask:0xf bank_mask:0xf bound_ctrl:1
	v_add_f32_dpp v129, v129, v129 quad_perm:[1,0,3,2] row_mask:0xf bank_mask:0xf bound_ctrl:1
	v_add_f32_dpp v190, v190, v190 quad_perm:[2,3,0,1] row_mask:0xf bank_mask:0xf bound_ctrl:1
	v_add_f32_dpp v191, v191, v191 quad_perm:[2,3,0,1] row_mask:0xf bank_mask:0xf bound_ctrl:1
	v_add_f32_dpp v128, v128, v128 quad_perm:[2,3,0,1] row_mask:0xf bank_mask:0xf bound_ctrl:1
	v_add_f32_dpp v129, v129, v129 quad_perm:[2,3,0,1] row_mask:0xf bank_mask:0xf bound_ctrl:1
	v_add_f32_dpp v190, v190, v190 row_half_mirror row_mask:0xf bank_mask:0xf bound_ctrl:1
	v_add_f32_dpp v191, v191, v191 row_half_mirror row_mask:0xf bank_mask:0xf bound_ctrl:1
	v_add_f32_dpp v128, v128, v128 row_half_mirror row_mask:0xf bank_mask:0xf bound_ctrl:1
	v_add_f32_dpp v129, v129, v129 row_half_mirror row_mask:0xf bank_mask:0xf bound_ctrl:1
	v_add_f32_dpp v190, v190, v190 row_mirror row_mask:0xf bank_mask:0xf bound_ctrl:1
	v_add_f32_dpp v191, v191, v191 row_mirror row_mask:0xf bank_mask:0xf bound_ctrl:1
	v_fmac_f32_e32 v182, v66, v36
	v_fmac_f32_e32 v183, v66, v37
	v_fmac_f32_e32 v184, v66, v38
	v_fmac_f32_e32 v185, v66, v39
	v_fmac_f32_e32 v186, v67, v36
	v_fmac_f32_e32 v187, v67, v37
	v_fmac_f32_e32 v188, v67, v38
	v_fmac_f32_e32 v189, v67, v39
	v_fmac_f32_e32 v182, v190, v32
	v_fmac_f32_e32 v183, v190, v33
	v_fmac_f32_e32 v184, v190, v34
	v_fmac_f32_e32 v185, v190, v35
	v_fmac_f32_e32 v186, v191, v32
	v_fmac_f32_e32 v187, v191, v33
	v_fmac_f32_e32 v188, v191, v34
	v_fmac_f32_e32 v189, v191, v35
	s_mov_b64 exec, s[8:9]
	ds_write_b64 v146, v[128:129] offset:8192
	s_mov_b64 exec, -1
	ds_read_b128 v[28:31], v151 offset:13056
	ds_read_b128 v[32:35], v151 offset:21248
	ds_read_b128 v[36:39], v151 offset:29440
	ds_read_b128 v[40:43], v151 offset:37632
	ds_read_b64 v[66:67], v181 offset:4864
	s_waitcnt lgkmcnt(12)
	v_mul_f32_e32 v190, v182, v48
	v_mul_f32_e32 v191, v186, v48
	v_mul_f32_e32 v128, v182, v60
	v_mul_f32_e32 v129, v186, v60
	v_fmac_f32_e32 v190, v183, v49
	v_fmac_f32_e32 v191, v187, v49
	v_fmac_f32_e32 v128, v183, v61
	v_fmac_f32_e32 v129, v187, v61
	v_fmac_f32_e32 v190, v184, v50
	v_fmac_f32_e32 v191, v188, v50
	v_fmac_f32_e32 v128, v184, v62
	v_fmac_f32_e32 v129, v188, v62
	v_fmac_f32_e32 v190, v185, v51
	v_fmac_f32_e32 v191, v189, v51
	v_fmac_f32_e32 v128, v185, v63
	v_fmac_f32_e32 v129, v189, v63
	v_add_f32_dpp v190, v190, v190 quad_perm:[1,0,3,2] row_mask:0xf bank_mask:0xf bound_ctrl:1
	v_add_f32_dpp v191, v191, v191 quad_perm:[1,0,3,2] row_mask:0xf bank_mask:0xf bound_ctrl:1
	v_add_f32_dpp v128, v128, v128 quad_perm:[1,0,3,2] row_mask:0xf bank_mask:0xf bound_ctrl:1
	v_add_f32_dpp v129, v129, v129 quad_perm:[1,0,3,2] row_mask:0xf bank_mask:0xf bound_ctrl:1
	v_add_f32_dpp v190, v190, v190 quad_perm:[2,3,0,1] row_mask:0xf bank_mask:0xf bound_ctrl:1
	v_add_f32_dpp v191, v191, v191 quad_perm:[2,3,0,1] row_mask:0xf bank_mask:0xf bound_ctrl:1
	v_add_f32_dpp v128, v128, v128 quad_perm:[2,3,0,1] row_mask:0xf bank_mask:0xf bound_ctrl:1
	v_add_f32_dpp v129, v129, v129 quad_perm:[2,3,0,1] row_mask:0xf bank_mask:0xf bound_ctrl:1
	v_add_f32_dpp v190, v190, v190 row_half_mirror row_mask:0xf bank_mask:0xf bound_ctrl:1
	v_add_f32_dpp v191, v191, v191 row_half_mirror row_mask:0xf bank_mask:0xf bound_ctrl:1
	v_add_f32_dpp v128, v128, v128 row_half_mirror row_mask:0xf bank_mask:0xf bound_ctrl:1
	v_add_f32_dpp v129, v129, v129 row_half_mirror row_mask:0xf bank_mask:0xf bound_ctrl:1
	v_add_f32_dpp v190, v190, v190 row_mirror row_mask:0xf bank_mask:0xf bound_ctrl:1
	v_add_f32_dpp v191, v191, v191 row_mirror row_mask:0xf bank_mask:0xf bound_ctrl:1
	v_fmac_f32_e32 v182, v126, v56
	v_fmac_f32_e32 v183, v126, v57
	v_fmac_f32_e32 v184, v126, v58
	v_fmac_f32_e32 v185, v126, v59
	v_fmac_f32_e32 v186, v127, v56
	v_fmac_f32_e32 v187, v127, v57
	v_fmac_f32_e32 v188, v127, v58
	v_fmac_f32_e32 v189, v127, v59
	v_fmac_f32_e32 v182, v190, v52
	v_fmac_f32_e32 v183, v190, v53
	v_fmac_f32_e32 v184, v190, v54
	v_fmac_f32_e32 v185, v190, v55
	v_fmac_f32_e32 v186, v191, v52
	v_fmac_f32_e32 v187, v191, v53
	v_fmac_f32_e32 v188, v191, v54
	v_fmac_f32_e32 v189, v191, v55
	s_mov_b64 exec, s[8:9]
	ds_write_b64 v146, v[128:129] offset:8704
	s_mov_b64 exec, -1
	ds_read_b128 v[48:51], v151 offset:13312
	ds_read_b128 v[52:55], v151 offset:21504
	ds_read_b128 v[56:59], v151 offset:29696
	ds_read_b128 v[60:63], v151 offset:37888
	ds_read_b64 v[126:127], v181 offset:5120
	s_waitcnt lgkmcnt(12)
	v_mul_f32_e32 v190, v182, v8
	v_mul_f32_e32 v191, v186, v8
	v_mul_f32_e32 v128, v182, v20
	v_mul_f32_e32 v129, v186, v20
	v_fmac_f32_e32 v190, v183, v9
	v_fmac_f32_e32 v191, v187, v9
	v_fmac_f32_e32 v128, v183, v21
	v_fmac_f32_e32 v129, v187, v21
	v_fmac_f32_e32 v190, v184, v10
	v_fmac_f32_e32 v191, v188, v10
	v_fmac_f32_e32 v128, v184, v22
	v_fmac_f32_e32 v129, v188, v22
	v_fmac_f32_e32 v190, v185, v11
	v_fmac_f32_e32 v191, v189, v11
	v_fmac_f32_e32 v128, v185, v23
	v_fmac_f32_e32 v129, v189, v23
	v_add_f32_dpp v190, v190, v190 quad_perm:[1,0,3,2] row_mask:0xf bank_mask:0xf bound_ctrl:1
	v_add_f32_dpp v191, v191, v191 quad_perm:[1,0,3,2] row_mask:0xf bank_mask:0xf bound_ctrl:1
	v_add_f32_dpp v128, v128, v128 quad_perm:[1,0,3,2] row_mask:0xf bank_mask:0xf bound_ctrl:1
	v_add_f32_dpp v129, v129, v129 quad_perm:[1,0,3,2] row_mask:0xf bank_mask:0xf bound_ctrl:1
	v_add_f32_dpp v190, v190, v190 quad_perm:[2,3,0,1] row_mask:0xf bank_mask:0xf bound_ctrl:1
	v_add_f32_dpp v191, v191, v191 quad_perm:[2,3,0,1] row_mask:0xf bank_mask:0xf bound_ctrl:1
	v_add_f32_dpp v128, v128, v128 quad_perm:[2,3,0,1] row_mask:0xf bank_mask:0xf bound_ctrl:1
	v_add_f32_dpp v129, v129, v129 quad_perm:[2,3,0,1] row_mask:0xf bank_mask:0xf bound_ctrl:1
	v_add_f32_dpp v190, v190, v190 row_half_mirror row_mask:0xf bank_mask:0xf bound_ctrl:1
	v_add_f32_dpp v191, v191, v191 row_half_mirror row_mask:0xf bank_mask:0xf bound_ctrl:1
	v_add_f32_dpp v128, v128, v128 row_half_mirror row_mask:0xf bank_mask:0xf bound_ctrl:1
	v_add_f32_dpp v129, v129, v129 row_half_mirror row_mask:0xf bank_mask:0xf bound_ctrl:1
	v_add_f32_dpp v190, v190, v190 row_mirror row_mask:0xf bank_mask:0xf bound_ctrl:1
	v_add_f32_dpp v191, v191, v191 row_mirror row_mask:0xf bank_mask:0xf bound_ctrl:1
	v_fmac_f32_e32 v182, v64, v16
	v_fmac_f32_e32 v183, v64, v17
	v_fmac_f32_e32 v184, v64, v18
	v_fmac_f32_e32 v185, v64, v19
	v_fmac_f32_e32 v186, v65, v16
	v_fmac_f32_e32 v187, v65, v17
	v_fmac_f32_e32 v188, v65, v18
	v_fmac_f32_e32 v189, v65, v19
	v_fmac_f32_e32 v182, v190, v12
	v_fmac_f32_e32 v183, v190, v13
	v_fmac_f32_e32 v184, v190, v14
	v_fmac_f32_e32 v185, v190, v15
	v_fmac_f32_e32 v186, v191, v12
	v_fmac_f32_e32 v187, v191, v13
	v_fmac_f32_e32 v188, v191, v14
	v_fmac_f32_e32 v189, v191, v15
	s_mov_b64 exec, s[8:9]
	ds_write_b64 v146, v[128:129] offset:9216
	s_mov_b64 exec, -1
	ds_read_b128 v[8:11], v151 offset:13568
	ds_read_b128 v[12:15], v151 offset:21760
	ds_read_b128 v[16:19], v151 offset:29952
	ds_read_b128 v[20:23], v151 offset:38144
	ds_read_b64 v[64:65], v181 offset:5376
	s_waitcnt lgkmcnt(12)
	v_mul_f32_e32 v190, v182, v28
	v_mul_f32_e32 v191, v186, v28
	v_mul_f32_e32 v128, v182, v40
	v_mul_f32_e32 v129, v186, v40
	v_fmac_f32_e32 v190, v183, v29
	v_fmac_f32_e32 v191, v187, v29
	v_fmac_f32_e32 v128, v183, v41
	v_fmac_f32_e32 v129, v187, v41
	v_fmac_f32_e32 v190, v184, v30
	v_fmac_f32_e32 v191, v188, v30
	v_fmac_f32_e32 v128, v184, v42
	v_fmac_f32_e32 v129, v188, v42
	v_fmac_f32_e32 v190, v185, v31
	v_fmac_f32_e32 v191, v189, v31
	v_fmac_f32_e32 v128, v185, v43
	v_fmac_f32_e32 v129, v189, v43
	v_add_f32_dpp v190, v190, v190 quad_perm:[1,0,3,2] row_mask:0xf bank_mask:0xf bound_ctrl:1
	v_add_f32_dpp v191, v191, v191 quad_perm:[1,0,3,2] row_mask:0xf bank_mask:0xf bound_ctrl:1
	v_add_f32_dpp v128, v128, v128 quad_perm:[1,0,3,2] row_mask:0xf bank_mask:0xf bound_ctrl:1
	v_add_f32_dpp v129, v129, v129 quad_perm:[1,0,3,2] row_mask:0xf bank_mask:0xf bound_ctrl:1
	v_add_f32_dpp v190, v190, v190 quad_perm:[2,3,0,1] row_mask:0xf bank_mask:0xf bound_ctrl:1
	v_add_f32_dpp v191, v191, v191 quad_perm:[2,3,0,1] row_mask:0xf bank_mask:0xf bound_ctrl:1
	v_add_f32_dpp v128, v128, v128 quad_perm:[2,3,0,1] row_mask:0xf bank_mask:0xf bound_ctrl:1
	v_add_f32_dpp v129, v129, v129 quad_perm:[2,3,0,1] row_mask:0xf bank_mask:0xf bound_ctrl:1
	v_add_f32_dpp v190, v190, v190 row_half_mirror row_mask:0xf bank_mask:0xf bound_ctrl:1
	v_add_f32_dpp v191, v191, v191 row_half_mirror row_mask:0xf bank_mask:0xf bound_ctrl:1
	v_add_f32_dpp v128, v128, v128 row_half_mirror row_mask:0xf bank_mask:0xf bound_ctrl:1
	v_add_f32_dpp v129, v129, v129 row_half_mirror row_mask:0xf bank_mask:0xf bound_ctrl:1
	v_add_f32_dpp v190, v190, v190 row_mirror row_mask:0xf bank_mask:0xf bound_ctrl:1
	v_add_f32_dpp v191, v191, v191 row_mirror row_mask:0xf bank_mask:0xf bound_ctrl:1
	v_fmac_f32_e32 v182, v66, v36
	v_fmac_f32_e32 v183, v66, v37
	v_fmac_f32_e32 v184, v66, v38
	v_fmac_f32_e32 v185, v66, v39
	v_fmac_f32_e32 v186, v67, v36
	v_fmac_f32_e32 v187, v67, v37
	v_fmac_f32_e32 v188, v67, v38
	v_fmac_f32_e32 v189, v67, v39
	v_fmac_f32_e32 v182, v190, v32
	v_fmac_f32_e32 v183, v190, v33
	v_fmac_f32_e32 v184, v190, v34
	v_fmac_f32_e32 v185, v190, v35
	v_fmac_f32_e32 v186, v191, v32
	v_fmac_f32_e32 v187, v191, v33
	v_fmac_f32_e32 v188, v191, v34
	v_fmac_f32_e32 v189, v191, v35
	s_mov_b64 exec, s[8:9]
	ds_write_b64 v146, v[128:129] offset:9728
	s_mov_b64 exec, -1
	ds_read_b128 v[28:31], v151 offset:13824
	ds_read_b128 v[32:35], v151 offset:22016
	ds_read_b128 v[36:39], v151 offset:30208
	ds_read_b128 v[40:43], v151 offset:38400
	ds_read_b64 v[66:67], v181 offset:5632
	s_waitcnt lgkmcnt(12)
	v_mul_f32_e32 v190, v182, v48
	v_mul_f32_e32 v191, v186, v48
	v_mul_f32_e32 v128, v182, v60
	v_mul_f32_e32 v129, v186, v60
	v_fmac_f32_e32 v190, v183, v49
	v_fmac_f32_e32 v191, v187, v49
	v_fmac_f32_e32 v128, v183, v61
	v_fmac_f32_e32 v129, v187, v61
	v_fmac_f32_e32 v190, v184, v50
	v_fmac_f32_e32 v191, v188, v50
	v_fmac_f32_e32 v128, v184, v62
	v_fmac_f32_e32 v129, v188, v62
	v_fmac_f32_e32 v190, v185, v51
	v_fmac_f32_e32 v191, v189, v51
	v_fmac_f32_e32 v128, v185, v63
	v_fmac_f32_e32 v129, v189, v63
	v_add_f32_dpp v190, v190, v190 quad_perm:[1,0,3,2] row_mask:0xf bank_mask:0xf bound_ctrl:1
	v_add_f32_dpp v191, v191, v191 quad_perm:[1,0,3,2] row_mask:0xf bank_mask:0xf bound_ctrl:1
	v_add_f32_dpp v128, v128, v128 quad_perm:[1,0,3,2] row_mask:0xf bank_mask:0xf bound_ctrl:1
	v_add_f32_dpp v129, v129, v129 quad_perm:[1,0,3,2] row_mask:0xf bank_mask:0xf bound_ctrl:1
	v_add_f32_dpp v190, v190, v190 quad_perm:[2,3,0,1] row_mask:0xf bank_mask:0xf bound_ctrl:1
	v_add_f32_dpp v191, v191, v191 quad_perm:[2,3,0,1] row_mask:0xf bank_mask:0xf bound_ctrl:1
	v_add_f32_dpp v128, v128, v128 quad_perm:[2,3,0,1] row_mask:0xf bank_mask:0xf bound_ctrl:1
	v_add_f32_dpp v129, v129, v129 quad_perm:[2,3,0,1] row_mask:0xf bank_mask:0xf bound_ctrl:1
	v_add_f32_dpp v190, v190, v190 row_half_mirror row_mask:0xf bank_mask:0xf bound_ctrl:1
	v_add_f32_dpp v191, v191, v191 row_half_mirror row_mask:0xf bank_mask:0xf bound_ctrl:1
	v_add_f32_dpp v128, v128, v128 row_half_mirror row_mask:0xf bank_mask:0xf bound_ctrl:1
	v_add_f32_dpp v129, v129, v129 row_half_mirror row_mask:0xf bank_mask:0xf bound_ctrl:1
	v_add_f32_dpp v190, v190, v190 row_mirror row_mask:0xf bank_mask:0xf bound_ctrl:1
	v_add_f32_dpp v191, v191, v191 row_mirror row_mask:0xf bank_mask:0xf bound_ctrl:1
	v_fmac_f32_e32 v182, v126, v56
	v_fmac_f32_e32 v183, v126, v57
	v_fmac_f32_e32 v184, v126, v58
	v_fmac_f32_e32 v185, v126, v59
	v_fmac_f32_e32 v186, v127, v56
	v_fmac_f32_e32 v187, v127, v57
	v_fmac_f32_e32 v188, v127, v58
	v_fmac_f32_e32 v189, v127, v59
	v_fmac_f32_e32 v182, v190, v52
	v_fmac_f32_e32 v183, v190, v53
	v_fmac_f32_e32 v184, v190, v54
	v_fmac_f32_e32 v185, v190, v55
	v_fmac_f32_e32 v186, v191, v52
	v_fmac_f32_e32 v187, v191, v53
	v_fmac_f32_e32 v188, v191, v54
	v_fmac_f32_e32 v189, v191, v55
	s_mov_b64 exec, s[8:9]
	ds_write_b64 v146, v[128:129] offset:10240
	s_mov_b64 exec, -1
	ds_read_b128 v[48:51], v151 offset:14080
	ds_read_b128 v[52:55], v151 offset:22272
	ds_read_b128 v[56:59], v151 offset:30464
	ds_read_b128 v[60:63], v151 offset:38656
	ds_read_b64 v[126:127], v181 offset:5888
	s_waitcnt lgkmcnt(12)
	v_mul_f32_e32 v190, v182, v8
	v_mul_f32_e32 v191, v186, v8
	v_mul_f32_e32 v128, v182, v20
	v_mul_f32_e32 v129, v186, v20
	v_fmac_f32_e32 v190, v183, v9
	v_fmac_f32_e32 v191, v187, v9
	v_fmac_f32_e32 v128, v183, v21
	v_fmac_f32_e32 v129, v187, v21
	v_fmac_f32_e32 v190, v184, v10
	v_fmac_f32_e32 v191, v188, v10
	v_fmac_f32_e32 v128, v184, v22
	v_fmac_f32_e32 v129, v188, v22
	v_fmac_f32_e32 v190, v185, v11
	v_fmac_f32_e32 v191, v189, v11
	v_fmac_f32_e32 v128, v185, v23
	v_fmac_f32_e32 v129, v189, v23
	v_add_f32_dpp v190, v190, v190 quad_perm:[1,0,3,2] row_mask:0xf bank_mask:0xf bound_ctrl:1
	v_add_f32_dpp v191, v191, v191 quad_perm:[1,0,3,2] row_mask:0xf bank_mask:0xf bound_ctrl:1
	v_add_f32_dpp v128, v128, v128 quad_perm:[1,0,3,2] row_mask:0xf bank_mask:0xf bound_ctrl:1
	v_add_f32_dpp v129, v129, v129 quad_perm:[1,0,3,2] row_mask:0xf bank_mask:0xf bound_ctrl:1
	v_add_f32_dpp v190, v190, v190 quad_perm:[2,3,0,1] row_mask:0xf bank_mask:0xf bound_ctrl:1
	v_add_f32_dpp v191, v191, v191 quad_perm:[2,3,0,1] row_mask:0xf bank_mask:0xf bound_ctrl:1
	v_add_f32_dpp v128, v128, v128 quad_perm:[2,3,0,1] row_mask:0xf bank_mask:0xf bound_ctrl:1
	v_add_f32_dpp v129, v129, v129 quad_perm:[2,3,0,1] row_mask:0xf bank_mask:0xf bound_ctrl:1
	v_add_f32_dpp v190, v190, v190 row_half_mirror row_mask:0xf bank_mask:0xf bound_ctrl:1
	v_add_f32_dpp v191, v191, v191 row_half_mirror row_mask:0xf bank_mask:0xf bound_ctrl:1
	v_add_f32_dpp v128, v128, v128 row_half_mirror row_mask:0xf bank_mask:0xf bound_ctrl:1
	v_add_f32_dpp v129, v129, v129 row_half_mirror row_mask:0xf bank_mask:0xf bound_ctrl:1
	v_add_f32_dpp v190, v190, v190 row_mirror row_mask:0xf bank_mask:0xf bound_ctrl:1
	v_add_f32_dpp v191, v191, v191 row_mirror row_mask:0xf bank_mask:0xf bound_ctrl:1
	v_fmac_f32_e32 v182, v64, v16
	v_fmac_f32_e32 v183, v64, v17
	v_fmac_f32_e32 v184, v64, v18
	v_fmac_f32_e32 v185, v64, v19
	v_fmac_f32_e32 v186, v65, v16
	v_fmac_f32_e32 v187, v65, v17
	v_fmac_f32_e32 v188, v65, v18
	v_fmac_f32_e32 v189, v65, v19
	v_fmac_f32_e32 v182, v190, v12
	v_fmac_f32_e32 v183, v190, v13
	v_fmac_f32_e32 v184, v190, v14
	v_fmac_f32_e32 v185, v190, v15
	v_fmac_f32_e32 v186, v191, v12
	v_fmac_f32_e32 v187, v191, v13
	v_fmac_f32_e32 v188, v191, v14
	v_fmac_f32_e32 v189, v191, v15
	s_mov_b64 exec, s[8:9]
	ds_write_b64 v146, v[128:129] offset:10752
	s_mov_b64 exec, -1
	ds_read_b128 v[8:11], v151 offset:14336
	ds_read_b128 v[12:15], v151 offset:22528
	ds_read_b128 v[16:19], v151 offset:30720
	ds_read_b128 v[20:23], v151 offset:38912
	ds_read_b64 v[64:65], v181 offset:6144
	s_waitcnt lgkmcnt(12)
	v_mul_f32_e32 v190, v182, v28
	v_mul_f32_e32 v191, v186, v28
	v_mul_f32_e32 v128, v182, v40
	v_mul_f32_e32 v129, v186, v40
	v_fmac_f32_e32 v190, v183, v29
	v_fmac_f32_e32 v191, v187, v29
	v_fmac_f32_e32 v128, v183, v41
	v_fmac_f32_e32 v129, v187, v41
	v_fmac_f32_e32 v190, v184, v30
	v_fmac_f32_e32 v191, v188, v30
	v_fmac_f32_e32 v128, v184, v42
	v_fmac_f32_e32 v129, v188, v42
	v_fmac_f32_e32 v190, v185, v31
	v_fmac_f32_e32 v191, v189, v31
	v_fmac_f32_e32 v128, v185, v43
	v_fmac_f32_e32 v129, v189, v43
	v_add_f32_dpp v190, v190, v190 quad_perm:[1,0,3,2] row_mask:0xf bank_mask:0xf bound_ctrl:1
	v_add_f32_dpp v191, v191, v191 quad_perm:[1,0,3,2] row_mask:0xf bank_mask:0xf bound_ctrl:1
	v_add_f32_dpp v128, v128, v128 quad_perm:[1,0,3,2] row_mask:0xf bank_mask:0xf bound_ctrl:1
	v_add_f32_dpp v129, v129, v129 quad_perm:[1,0,3,2] row_mask:0xf bank_mask:0xf bound_ctrl:1
	v_add_f32_dpp v190, v190, v190 quad_perm:[2,3,0,1] row_mask:0xf bank_mask:0xf bound_ctrl:1
	v_add_f32_dpp v191, v191, v191 quad_perm:[2,3,0,1] row_mask:0xf bank_mask:0xf bound_ctrl:1
	v_add_f32_dpp v128, v128, v128 quad_perm:[2,3,0,1] row_mask:0xf bank_mask:0xf bound_ctrl:1
	v_add_f32_dpp v129, v129, v129 quad_perm:[2,3,0,1] row_mask:0xf bank_mask:0xf bound_ctrl:1
	v_add_f32_dpp v190, v190, v190 row_half_mirror row_mask:0xf bank_mask:0xf bound_ctrl:1
	v_add_f32_dpp v191, v191, v191 row_half_mirror row_mask:0xf bank_mask:0xf bound_ctrl:1
	v_add_f32_dpp v128, v128, v128 row_half_mirror row_mask:0xf bank_mask:0xf bound_ctrl:1
	v_add_f32_dpp v129, v129, v129 row_half_mirror row_mask:0xf bank_mask:0xf bound_ctrl:1
	v_add_f32_dpp v190, v190, v190 row_mirror row_mask:0xf bank_mask:0xf bound_ctrl:1
	v_add_f32_dpp v191, v191, v191 row_mirror row_mask:0xf bank_mask:0xf bound_ctrl:1
	v_fmac_f32_e32 v182, v66, v36
	v_fmac_f32_e32 v183, v66, v37
	v_fmac_f32_e32 v184, v66, v38
	v_fmac_f32_e32 v185, v66, v39
	v_fmac_f32_e32 v186, v67, v36
	v_fmac_f32_e32 v187, v67, v37
	v_fmac_f32_e32 v188, v67, v38
	v_fmac_f32_e32 v189, v67, v39
	v_fmac_f32_e32 v182, v190, v32
	v_fmac_f32_e32 v183, v190, v33
	v_fmac_f32_e32 v184, v190, v34
	v_fmac_f32_e32 v185, v190, v35
	v_fmac_f32_e32 v186, v191, v32
	v_fmac_f32_e32 v187, v191, v33
	v_fmac_f32_e32 v188, v191, v34
	v_fmac_f32_e32 v189, v191, v35
	s_mov_b64 exec, s[8:9]
	ds_write_b64 v146, v[128:129] offset:11264
	s_mov_b64 exec, -1
	ds_read_b128 v[28:31], v151 offset:14592
	ds_read_b128 v[32:35], v151 offset:22784
	ds_read_b128 v[36:39], v151 offset:30976
	ds_read_b128 v[40:43], v151 offset:39168
	ds_read_b64 v[66:67], v181 offset:6400
	s_waitcnt lgkmcnt(12)
	v_mul_f32_e32 v190, v182, v48
	v_mul_f32_e32 v191, v186, v48
	v_mul_f32_e32 v128, v182, v60
	v_mul_f32_e32 v129, v186, v60
	v_fmac_f32_e32 v190, v183, v49
	v_fmac_f32_e32 v191, v187, v49
	v_fmac_f32_e32 v128, v183, v61
	v_fmac_f32_e32 v129, v187, v61
	v_fmac_f32_e32 v190, v184, v50
	v_fmac_f32_e32 v191, v188, v50
	v_fmac_f32_e32 v128, v184, v62
	v_fmac_f32_e32 v129, v188, v62
	v_fmac_f32_e32 v190, v185, v51
	v_fmac_f32_e32 v191, v189, v51
	v_fmac_f32_e32 v128, v185, v63
	v_fmac_f32_e32 v129, v189, v63
	v_add_f32_dpp v190, v190, v190 quad_perm:[1,0,3,2] row_mask:0xf bank_mask:0xf bound_ctrl:1
	v_add_f32_dpp v191, v191, v191 quad_perm:[1,0,3,2] row_mask:0xf bank_mask:0xf bound_ctrl:1
	v_add_f32_dpp v128, v128, v128 quad_perm:[1,0,3,2] row_mask:0xf bank_mask:0xf bound_ctrl:1
	v_add_f32_dpp v129, v129, v129 quad_perm:[1,0,3,2] row_mask:0xf bank_mask:0xf bound_ctrl:1
	v_add_f32_dpp v190, v190, v190 quad_perm:[2,3,0,1] row_mask:0xf bank_mask:0xf bound_ctrl:1
	v_add_f32_dpp v191, v191, v191 quad_perm:[2,3,0,1] row_mask:0xf bank_mask:0xf bound_ctrl:1
	v_add_f32_dpp v128, v128, v128 quad_perm:[2,3,0,1] row_mask:0xf bank_mask:0xf bound_ctrl:1
	v_add_f32_dpp v129, v129, v129 quad_perm:[2,3,0,1] row_mask:0xf bank_mask:0xf bound_ctrl:1
	v_add_f32_dpp v190, v190, v190 row_half_mirror row_mask:0xf bank_mask:0xf bound_ctrl:1
	v_add_f32_dpp v191, v191, v191 row_half_mirror row_mask:0xf bank_mask:0xf bound_ctrl:1
	v_add_f32_dpp v128, v128, v128 row_half_mirror row_mask:0xf bank_mask:0xf bound_ctrl:1
	v_add_f32_dpp v129, v129, v129 row_half_mirror row_mask:0xf bank_mask:0xf bound_ctrl:1
	v_add_f32_dpp v190, v190, v190 row_mirror row_mask:0xf bank_mask:0xf bound_ctrl:1
	v_add_f32_dpp v191, v191, v191 row_mirror row_mask:0xf bank_mask:0xf bound_ctrl:1
	v_fmac_f32_e32 v182, v126, v56
	v_fmac_f32_e32 v183, v126, v57
	v_fmac_f32_e32 v184, v126, v58
	v_fmac_f32_e32 v185, v126, v59
	v_fmac_f32_e32 v186, v127, v56
	v_fmac_f32_e32 v187, v127, v57
	v_fmac_f32_e32 v188, v127, v58
	v_fmac_f32_e32 v189, v127, v59
	v_fmac_f32_e32 v182, v190, v52
	v_fmac_f32_e32 v183, v190, v53
	v_fmac_f32_e32 v184, v190, v54
	v_fmac_f32_e32 v185, v190, v55
	v_fmac_f32_e32 v186, v191, v52
	v_fmac_f32_e32 v187, v191, v53
	v_fmac_f32_e32 v188, v191, v54
	v_fmac_f32_e32 v189, v191, v55
	s_mov_b64 exec, s[8:9]
	ds_write_b64 v146, v[128:129] offset:11776
	s_mov_b64 exec, -1
	ds_read_b128 v[48:51], v151 offset:14848
	ds_read_b128 v[52:55], v151 offset:23040
	ds_read_b128 v[56:59], v151 offset:31232
	ds_read_b128 v[60:63], v151 offset:39424
	ds_read_b64 v[126:127], v181 offset:6656
	s_waitcnt lgkmcnt(12)
	v_mul_f32_e32 v190, v182, v8
	v_mul_f32_e32 v191, v186, v8
	v_mul_f32_e32 v128, v182, v20
	v_mul_f32_e32 v129, v186, v20
	v_fmac_f32_e32 v190, v183, v9
	v_fmac_f32_e32 v191, v187, v9
	v_fmac_f32_e32 v128, v183, v21
	v_fmac_f32_e32 v129, v187, v21
	v_fmac_f32_e32 v190, v184, v10
	v_fmac_f32_e32 v191, v188, v10
	v_fmac_f32_e32 v128, v184, v22
	v_fmac_f32_e32 v129, v188, v22
	v_fmac_f32_e32 v190, v185, v11
	v_fmac_f32_e32 v191, v189, v11
	v_fmac_f32_e32 v128, v185, v23
	v_fmac_f32_e32 v129, v189, v23
	v_add_f32_dpp v190, v190, v190 quad_perm:[1,0,3,2] row_mask:0xf bank_mask:0xf bound_ctrl:1
	v_add_f32_dpp v191, v191, v191 quad_perm:[1,0,3,2] row_mask:0xf bank_mask:0xf bound_ctrl:1
	v_add_f32_dpp v128, v128, v128 quad_perm:[1,0,3,2] row_mask:0xf bank_mask:0xf bound_ctrl:1
	v_add_f32_dpp v129, v129, v129 quad_perm:[1,0,3,2] row_mask:0xf bank_mask:0xf bound_ctrl:1
	v_add_f32_dpp v190, v190, v190 quad_perm:[2,3,0,1] row_mask:0xf bank_mask:0xf bound_ctrl:1
	v_add_f32_dpp v191, v191, v191 quad_perm:[2,3,0,1] row_mask:0xf bank_mask:0xf bound_ctrl:1
	v_add_f32_dpp v128, v128, v128 quad_perm:[2,3,0,1] row_mask:0xf bank_mask:0xf bound_ctrl:1
	v_add_f32_dpp v129, v129, v129 quad_perm:[2,3,0,1] row_mask:0xf bank_mask:0xf bound_ctrl:1
	v_add_f32_dpp v190, v190, v190 row_half_mirror row_mask:0xf bank_mask:0xf bound_ctrl:1
	v_add_f32_dpp v191, v191, v191 row_half_mirror row_mask:0xf bank_mask:0xf bound_ctrl:1
	v_add_f32_dpp v128, v128, v128 row_half_mirror row_mask:0xf bank_mask:0xf bound_ctrl:1
	v_add_f32_dpp v129, v129, v129 row_half_mirror row_mask:0xf bank_mask:0xf bound_ctrl:1
	v_add_f32_dpp v190, v190, v190 row_mirror row_mask:0xf bank_mask:0xf bound_ctrl:1
	v_add_f32_dpp v191, v191, v191 row_mirror row_mask:0xf bank_mask:0xf bound_ctrl:1
	v_fmac_f32_e32 v182, v64, v16
	v_fmac_f32_e32 v183, v64, v17
	v_fmac_f32_e32 v184, v64, v18
	v_fmac_f32_e32 v185, v64, v19
	v_fmac_f32_e32 v186, v65, v16
	v_fmac_f32_e32 v187, v65, v17
	v_fmac_f32_e32 v188, v65, v18
	v_fmac_f32_e32 v189, v65, v19
	v_fmac_f32_e32 v182, v190, v12
	v_fmac_f32_e32 v183, v190, v13
	v_fmac_f32_e32 v184, v190, v14
	v_fmac_f32_e32 v185, v190, v15
	v_fmac_f32_e32 v186, v191, v12
	v_fmac_f32_e32 v187, v191, v13
	v_fmac_f32_e32 v188, v191, v14
	v_fmac_f32_e32 v189, v191, v15
	s_mov_b64 exec, s[8:9]
	ds_write_b64 v146, v[128:129] offset:12288
	s_mov_b64 exec, -1
	ds_read_b128 v[8:11], v151 offset:15104
	ds_read_b128 v[12:15], v151 offset:23296
	ds_read_b128 v[16:19], v151 offset:31488
	ds_read_b128 v[20:23], v151 offset:39680
	ds_read_b64 v[64:65], v181 offset:6912
	s_waitcnt lgkmcnt(12)
	v_mul_f32_e32 v190, v182, v28
	v_mul_f32_e32 v191, v186, v28
	v_mul_f32_e32 v128, v182, v40
	v_mul_f32_e32 v129, v186, v40
	v_fmac_f32_e32 v190, v183, v29
	v_fmac_f32_e32 v191, v187, v29
	v_fmac_f32_e32 v128, v183, v41
	v_fmac_f32_e32 v129, v187, v41
	v_fmac_f32_e32 v190, v184, v30
	v_fmac_f32_e32 v191, v188, v30
	v_fmac_f32_e32 v128, v184, v42
	v_fmac_f32_e32 v129, v188, v42
	v_fmac_f32_e32 v190, v185, v31
	v_fmac_f32_e32 v191, v189, v31
	v_fmac_f32_e32 v128, v185, v43
	v_fmac_f32_e32 v129, v189, v43
	v_add_f32_dpp v190, v190, v190 quad_perm:[1,0,3,2] row_mask:0xf bank_mask:0xf bound_ctrl:1
	v_add_f32_dpp v191, v191, v191 quad_perm:[1,0,3,2] row_mask:0xf bank_mask:0xf bound_ctrl:1
	v_add_f32_dpp v128, v128, v128 quad_perm:[1,0,3,2] row_mask:0xf bank_mask:0xf bound_ctrl:1
	v_add_f32_dpp v129, v129, v129 quad_perm:[1,0,3,2] row_mask:0xf bank_mask:0xf bound_ctrl:1
	v_add_f32_dpp v190, v190, v190 quad_perm:[2,3,0,1] row_mask:0xf bank_mask:0xf bound_ctrl:1
	v_add_f32_dpp v191, v191, v191 quad_perm:[2,3,0,1] row_mask:0xf bank_mask:0xf bound_ctrl:1
	v_add_f32_dpp v128, v128, v128 quad_perm:[2,3,0,1] row_mask:0xf bank_mask:0xf bound_ctrl:1
	v_add_f32_dpp v129, v129, v129 quad_perm:[2,3,0,1] row_mask:0xf bank_mask:0xf bound_ctrl:1
	v_add_f32_dpp v190, v190, v190 row_half_mirror row_mask:0xf bank_mask:0xf bound_ctrl:1
	v_add_f32_dpp v191, v191, v191 row_half_mirror row_mask:0xf bank_mask:0xf bound_ctrl:1
	v_add_f32_dpp v128, v128, v128 row_half_mirror row_mask:0xf bank_mask:0xf bound_ctrl:1
	v_add_f32_dpp v129, v129, v129 row_half_mirror row_mask:0xf bank_mask:0xf bound_ctrl:1
	v_add_f32_dpp v190, v190, v190 row_mirror row_mask:0xf bank_mask:0xf bound_ctrl:1
	v_add_f32_dpp v191, v191, v191 row_mirror row_mask:0xf bank_mask:0xf bound_ctrl:1
	v_fmac_f32_e32 v182, v66, v36
	v_fmac_f32_e32 v183, v66, v37
	v_fmac_f32_e32 v184, v66, v38
	v_fmac_f32_e32 v185, v66, v39
	v_fmac_f32_e32 v186, v67, v36
	v_fmac_f32_e32 v187, v67, v37
	v_fmac_f32_e32 v188, v67, v38
	v_fmac_f32_e32 v189, v67, v39
	v_fmac_f32_e32 v182, v190, v32
	v_fmac_f32_e32 v183, v190, v33
	v_fmac_f32_e32 v184, v190, v34
	v_fmac_f32_e32 v185, v190, v35
	v_fmac_f32_e32 v186, v191, v32
	v_fmac_f32_e32 v187, v191, v33
	v_fmac_f32_e32 v188, v191, v34
	v_fmac_f32_e32 v189, v191, v35
	s_mov_b64 exec, s[8:9]
	ds_write_b64 v146, v[128:129] offset:12800
	s_mov_b64 exec, -1
	ds_read_b128 v[28:31], v151 offset:15360
	ds_read_b128 v[32:35], v151 offset:23552
	ds_read_b128 v[36:39], v151 offset:31744
	ds_read_b128 v[40:43], v151 offset:39936
	ds_read_b64 v[66:67], v181 offset:7168
	s_waitcnt lgkmcnt(12)
	v_mul_f32_e32 v190, v182, v48
	v_mul_f32_e32 v191, v186, v48
	v_mul_f32_e32 v128, v182, v60
	v_mul_f32_e32 v129, v186, v60
	v_fmac_f32_e32 v190, v183, v49
	v_fmac_f32_e32 v191, v187, v49
	v_fmac_f32_e32 v128, v183, v61
	v_fmac_f32_e32 v129, v187, v61
	v_fmac_f32_e32 v190, v184, v50
	v_fmac_f32_e32 v191, v188, v50
	v_fmac_f32_e32 v128, v184, v62
	v_fmac_f32_e32 v129, v188, v62
	v_fmac_f32_e32 v190, v185, v51
	v_fmac_f32_e32 v191, v189, v51
	v_fmac_f32_e32 v128, v185, v63
	v_fmac_f32_e32 v129, v189, v63
	v_add_f32_dpp v190, v190, v190 quad_perm:[1,0,3,2] row_mask:0xf bank_mask:0xf bound_ctrl:1
	v_add_f32_dpp v191, v191, v191 quad_perm:[1,0,3,2] row_mask:0xf bank_mask:0xf bound_ctrl:1
	v_add_f32_dpp v128, v128, v128 quad_perm:[1,0,3,2] row_mask:0xf bank_mask:0xf bound_ctrl:1
	v_add_f32_dpp v129, v129, v129 quad_perm:[1,0,3,2] row_mask:0xf bank_mask:0xf bound_ctrl:1
	v_add_f32_dpp v190, v190, v190 quad_perm:[2,3,0,1] row_mask:0xf bank_mask:0xf bound_ctrl:1
	v_add_f32_dpp v191, v191, v191 quad_perm:[2,3,0,1] row_mask:0xf bank_mask:0xf bound_ctrl:1
	v_add_f32_dpp v128, v128, v128 quad_perm:[2,3,0,1] row_mask:0xf bank_mask:0xf bound_ctrl:1
	v_add_f32_dpp v129, v129, v129 quad_perm:[2,3,0,1] row_mask:0xf bank_mask:0xf bound_ctrl:1
	v_add_f32_dpp v190, v190, v190 row_half_mirror row_mask:0xf bank_mask:0xf bound_ctrl:1
	v_add_f32_dpp v191, v191, v191 row_half_mirror row_mask:0xf bank_mask:0xf bound_ctrl:1
	v_add_f32_dpp v128, v128, v128 row_half_mirror row_mask:0xf bank_mask:0xf bound_ctrl:1
	v_add_f32_dpp v129, v129, v129 row_half_mirror row_mask:0xf bank_mask:0xf bound_ctrl:1
	v_add_f32_dpp v190, v190, v190 row_mirror row_mask:0xf bank_mask:0xf bound_ctrl:1
	v_add_f32_dpp v191, v191, v191 row_mirror row_mask:0xf bank_mask:0xf bound_ctrl:1
	v_fmac_f32_e32 v182, v126, v56
	v_fmac_f32_e32 v183, v126, v57
	v_fmac_f32_e32 v184, v126, v58
	v_fmac_f32_e32 v185, v126, v59
	v_fmac_f32_e32 v186, v127, v56
	v_fmac_f32_e32 v187, v127, v57
	v_fmac_f32_e32 v188, v127, v58
	v_fmac_f32_e32 v189, v127, v59
	v_fmac_f32_e32 v182, v190, v52
	v_fmac_f32_e32 v183, v190, v53
	v_fmac_f32_e32 v184, v190, v54
	v_fmac_f32_e32 v185, v190, v55
	v_fmac_f32_e32 v186, v191, v52
	v_fmac_f32_e32 v187, v191, v53
	v_fmac_f32_e32 v188, v191, v54
	v_fmac_f32_e32 v189, v191, v55
	s_mov_b64 exec, s[8:9]
	ds_write_b64 v146, v[128:129] offset:13312
	s_mov_b64 exec, -1
	ds_read_b128 v[48:51], v151 offset:15616
	ds_read_b128 v[52:55], v151 offset:23808
	ds_read_b128 v[56:59], v151 offset:32000
	ds_read_b128 v[60:63], v151 offset:40192
	ds_read_b64 v[126:127], v181 offset:7424
	s_waitcnt lgkmcnt(12)
	v_mul_f32_e32 v190, v182, v8
	v_mul_f32_e32 v191, v186, v8
	v_mul_f32_e32 v128, v182, v20
	v_mul_f32_e32 v129, v186, v20
	v_fmac_f32_e32 v190, v183, v9
	v_fmac_f32_e32 v191, v187, v9
	v_fmac_f32_e32 v128, v183, v21
	v_fmac_f32_e32 v129, v187, v21
	v_fmac_f32_e32 v190, v184, v10
	v_fmac_f32_e32 v191, v188, v10
	v_fmac_f32_e32 v128, v184, v22
	v_fmac_f32_e32 v129, v188, v22
	v_fmac_f32_e32 v190, v185, v11
	v_fmac_f32_e32 v191, v189, v11
	v_fmac_f32_e32 v128, v185, v23
	v_fmac_f32_e32 v129, v189, v23
	v_add_f32_dpp v190, v190, v190 quad_perm:[1,0,3,2] row_mask:0xf bank_mask:0xf bound_ctrl:1
	v_add_f32_dpp v191, v191, v191 quad_perm:[1,0,3,2] row_mask:0xf bank_mask:0xf bound_ctrl:1
	v_add_f32_dpp v128, v128, v128 quad_perm:[1,0,3,2] row_mask:0xf bank_mask:0xf bound_ctrl:1
	v_add_f32_dpp v129, v129, v129 quad_perm:[1,0,3,2] row_mask:0xf bank_mask:0xf bound_ctrl:1
	v_add_f32_dpp v190, v190, v190 quad_perm:[2,3,0,1] row_mask:0xf bank_mask:0xf bound_ctrl:1
	v_add_f32_dpp v191, v191, v191 quad_perm:[2,3,0,1] row_mask:0xf bank_mask:0xf bound_ctrl:1
	v_add_f32_dpp v128, v128, v128 quad_perm:[2,3,0,1] row_mask:0xf bank_mask:0xf bound_ctrl:1
	v_add_f32_dpp v129, v129, v129 quad_perm:[2,3,0,1] row_mask:0xf bank_mask:0xf bound_ctrl:1
	v_add_f32_dpp v190, v190, v190 row_half_mirror row_mask:0xf bank_mask:0xf bound_ctrl:1
	v_add_f32_dpp v191, v191, v191 row_half_mirror row_mask:0xf bank_mask:0xf bound_ctrl:1
	v_add_f32_dpp v128, v128, v128 row_half_mirror row_mask:0xf bank_mask:0xf bound_ctrl:1
	v_add_f32_dpp v129, v129, v129 row_half_mirror row_mask:0xf bank_mask:0xf bound_ctrl:1
	v_add_f32_dpp v190, v190, v190 row_mirror row_mask:0xf bank_mask:0xf bound_ctrl:1
	v_add_f32_dpp v191, v191, v191 row_mirror row_mask:0xf bank_mask:0xf bound_ctrl:1
	v_fmac_f32_e32 v182, v64, v16
	v_fmac_f32_e32 v183, v64, v17
	v_fmac_f32_e32 v184, v64, v18
	v_fmac_f32_e32 v185, v64, v19
	v_fmac_f32_e32 v186, v65, v16
	v_fmac_f32_e32 v187, v65, v17
	v_fmac_f32_e32 v188, v65, v18
	v_fmac_f32_e32 v189, v65, v19
	v_fmac_f32_e32 v182, v190, v12
	v_fmac_f32_e32 v183, v190, v13
	v_fmac_f32_e32 v184, v190, v14
	v_fmac_f32_e32 v185, v190, v15
	v_fmac_f32_e32 v186, v191, v12
	v_fmac_f32_e32 v187, v191, v13
	v_fmac_f32_e32 v188, v191, v14
	v_fmac_f32_e32 v189, v191, v15
	s_mov_b64 exec, s[8:9]
	ds_write_b64 v146, v[128:129] offset:13824
	s_mov_b64 exec, -1
	ds_read_b128 v[8:11], v151 offset:15872
	ds_read_b128 v[12:15], v151 offset:24064
	ds_read_b128 v[16:19], v151 offset:32256
	ds_read_b128 v[20:23], v151 offset:40448
	ds_read_b64 v[64:65], v181 offset:7680
	s_waitcnt lgkmcnt(12)
	v_mul_f32_e32 v190, v182, v28
	v_mul_f32_e32 v191, v186, v28
	v_mul_f32_e32 v128, v182, v40
	v_mul_f32_e32 v129, v186, v40
	v_fmac_f32_e32 v190, v183, v29
	v_fmac_f32_e32 v191, v187, v29
	v_fmac_f32_e32 v128, v183, v41
	v_fmac_f32_e32 v129, v187, v41
	v_fmac_f32_e32 v190, v184, v30
	v_fmac_f32_e32 v191, v188, v30
	v_fmac_f32_e32 v128, v184, v42
	v_fmac_f32_e32 v129, v188, v42
	v_fmac_f32_e32 v190, v185, v31
	v_fmac_f32_e32 v191, v189, v31
	v_fmac_f32_e32 v128, v185, v43
	v_fmac_f32_e32 v129, v189, v43
	v_add_f32_dpp v190, v190, v190 quad_perm:[1,0,3,2] row_mask:0xf bank_mask:0xf bound_ctrl:1
	v_add_f32_dpp v191, v191, v191 quad_perm:[1,0,3,2] row_mask:0xf bank_mask:0xf bound_ctrl:1
	v_add_f32_dpp v128, v128, v128 quad_perm:[1,0,3,2] row_mask:0xf bank_mask:0xf bound_ctrl:1
	v_add_f32_dpp v129, v129, v129 quad_perm:[1,0,3,2] row_mask:0xf bank_mask:0xf bound_ctrl:1
	v_add_f32_dpp v190, v190, v190 quad_perm:[2,3,0,1] row_mask:0xf bank_mask:0xf bound_ctrl:1
	v_add_f32_dpp v191, v191, v191 quad_perm:[2,3,0,1] row_mask:0xf bank_mask:0xf bound_ctrl:1
	v_add_f32_dpp v128, v128, v128 quad_perm:[2,3,0,1] row_mask:0xf bank_mask:0xf bound_ctrl:1
	v_add_f32_dpp v129, v129, v129 quad_perm:[2,3,0,1] row_mask:0xf bank_mask:0xf bound_ctrl:1
	v_add_f32_dpp v190, v190, v190 row_half_mirror row_mask:0xf bank_mask:0xf bound_ctrl:1
	v_add_f32_dpp v191, v191, v191 row_half_mirror row_mask:0xf bank_mask:0xf bound_ctrl:1
	v_add_f32_dpp v128, v128, v128 row_half_mirror row_mask:0xf bank_mask:0xf bound_ctrl:1
	v_add_f32_dpp v129, v129, v129 row_half_mirror row_mask:0xf bank_mask:0xf bound_ctrl:1
	v_add_f32_dpp v190, v190, v190 row_mirror row_mask:0xf bank_mask:0xf bound_ctrl:1
	v_add_f32_dpp v191, v191, v191 row_mirror row_mask:0xf bank_mask:0xf bound_ctrl:1
	v_fmac_f32_e32 v182, v66, v36
	v_fmac_f32_e32 v183, v66, v37
	v_fmac_f32_e32 v184, v66, v38
	v_fmac_f32_e32 v185, v66, v39
	v_fmac_f32_e32 v186, v67, v36
	v_fmac_f32_e32 v187, v67, v37
	v_fmac_f32_e32 v188, v67, v38
	v_fmac_f32_e32 v189, v67, v39
	v_fmac_f32_e32 v182, v190, v32
	v_fmac_f32_e32 v183, v190, v33
	v_fmac_f32_e32 v184, v190, v34
	v_fmac_f32_e32 v185, v190, v35
	v_fmac_f32_e32 v186, v191, v32
	v_fmac_f32_e32 v187, v191, v33
	v_fmac_f32_e32 v188, v191, v34
	v_fmac_f32_e32 v189, v191, v35
	s_mov_b64 exec, s[8:9]
	ds_write_b64 v146, v[128:129] offset:14336
	s_mov_b64 exec, -1
	ds_read_b128 v[28:31], v151 offset:16128
	ds_read_b128 v[32:35], v151 offset:24320
	ds_read_b128 v[36:39], v151 offset:32512
	ds_read_b128 v[40:43], v151 offset:40704
	ds_read_b64 v[66:67], v181 offset:7936
	s_waitcnt lgkmcnt(12)
	v_mul_f32_e32 v190, v182, v48
	v_mul_f32_e32 v191, v186, v48
	v_mul_f32_e32 v128, v182, v60
	v_mul_f32_e32 v129, v186, v60
	v_fmac_f32_e32 v190, v183, v49
	v_fmac_f32_e32 v191, v187, v49
	v_fmac_f32_e32 v128, v183, v61
	v_fmac_f32_e32 v129, v187, v61
	v_fmac_f32_e32 v190, v184, v50
	v_fmac_f32_e32 v191, v188, v50
	v_fmac_f32_e32 v128, v184, v62
	v_fmac_f32_e32 v129, v188, v62
	v_fmac_f32_e32 v190, v185, v51
	v_fmac_f32_e32 v191, v189, v51
	v_fmac_f32_e32 v128, v185, v63
	v_fmac_f32_e32 v129, v189, v63
	v_add_f32_dpp v190, v190, v190 quad_perm:[1,0,3,2] row_mask:0xf bank_mask:0xf bound_ctrl:1
	v_add_f32_dpp v191, v191, v191 quad_perm:[1,0,3,2] row_mask:0xf bank_mask:0xf bound_ctrl:1
	v_add_f32_dpp v128, v128, v128 quad_perm:[1,0,3,2] row_mask:0xf bank_mask:0xf bound_ctrl:1
	v_add_f32_dpp v129, v129, v129 quad_perm:[1,0,3,2] row_mask:0xf bank_mask:0xf bound_ctrl:1
	v_add_f32_dpp v190, v190, v190 quad_perm:[2,3,0,1] row_mask:0xf bank_mask:0xf bound_ctrl:1
	v_add_f32_dpp v191, v191, v191 quad_perm:[2,3,0,1] row_mask:0xf bank_mask:0xf bound_ctrl:1
	v_add_f32_dpp v128, v128, v128 quad_perm:[2,3,0,1] row_mask:0xf bank_mask:0xf bound_ctrl:1
	v_add_f32_dpp v129, v129, v129 quad_perm:[2,3,0,1] row_mask:0xf bank_mask:0xf bound_ctrl:1
	v_add_f32_dpp v190, v190, v190 row_half_mirror row_mask:0xf bank_mask:0xf bound_ctrl:1
	v_add_f32_dpp v191, v191, v191 row_half_mirror row_mask:0xf bank_mask:0xf bound_ctrl:1
	v_add_f32_dpp v128, v128, v128 row_half_mirror row_mask:0xf bank_mask:0xf bound_ctrl:1
	v_add_f32_dpp v129, v129, v129 row_half_mirror row_mask:0xf bank_mask:0xf bound_ctrl:1
	v_add_f32_dpp v190, v190, v190 row_mirror row_mask:0xf bank_mask:0xf bound_ctrl:1
	v_add_f32_dpp v191, v191, v191 row_mirror row_mask:0xf bank_mask:0xf bound_ctrl:1
	v_fmac_f32_e32 v182, v126, v56
	v_fmac_f32_e32 v183, v126, v57
	v_fmac_f32_e32 v184, v126, v58
	v_fmac_f32_e32 v185, v126, v59
	v_fmac_f32_e32 v186, v127, v56
	v_fmac_f32_e32 v187, v127, v57
	v_fmac_f32_e32 v188, v127, v58
	v_fmac_f32_e32 v189, v127, v59
	v_fmac_f32_e32 v182, v190, v52
	v_fmac_f32_e32 v183, v190, v53
	v_fmac_f32_e32 v184, v190, v54
	v_fmac_f32_e32 v185, v190, v55
	v_fmac_f32_e32 v186, v191, v52
	v_fmac_f32_e32 v187, v191, v53
	v_fmac_f32_e32 v188, v191, v54
	v_fmac_f32_e32 v189, v191, v55
	s_mov_b64 exec, s[8:9]
	ds_write_b64 v146, v[128:129] offset:14848
	s_mov_b64 exec, -1
	s_waitcnt lgkmcnt(7)
	v_mul_f32_e32 v190, v182, v8
	v_mul_f32_e32 v191, v186, v8
	v_mul_f32_e32 v128, v182, v20
	v_mul_f32_e32 v129, v186, v20
	v_fmac_f32_e32 v190, v183, v9
	v_fmac_f32_e32 v191, v187, v9
	v_fmac_f32_e32 v128, v183, v21
	v_fmac_f32_e32 v129, v187, v21
	v_fmac_f32_e32 v190, v184, v10
	v_fmac_f32_e32 v191, v188, v10
	v_fmac_f32_e32 v128, v184, v22
	v_fmac_f32_e32 v129, v188, v22
	v_fmac_f32_e32 v190, v185, v11
	v_fmac_f32_e32 v191, v189, v11
	v_fmac_f32_e32 v128, v185, v23
	v_fmac_f32_e32 v129, v189, v23
	v_add_f32_dpp v190, v190, v190 quad_perm:[1,0,3,2] row_mask:0xf bank_mask:0xf bound_ctrl:1
	v_add_f32_dpp v191, v191, v191 quad_perm:[1,0,3,2] row_mask:0xf bank_mask:0xf bound_ctrl:1
	v_add_f32_dpp v128, v128, v128 quad_perm:[1,0,3,2] row_mask:0xf bank_mask:0xf bound_ctrl:1
	v_add_f32_dpp v129, v129, v129 quad_perm:[1,0,3,2] row_mask:0xf bank_mask:0xf bound_ctrl:1
	v_add_f32_dpp v190, v190, v190 quad_perm:[2,3,0,1] row_mask:0xf bank_mask:0xf bound_ctrl:1
	v_add_f32_dpp v191, v191, v191 quad_perm:[2,3,0,1] row_mask:0xf bank_mask:0xf bound_ctrl:1
	v_add_f32_dpp v128, v128, v128 quad_perm:[2,3,0,1] row_mask:0xf bank_mask:0xf bound_ctrl:1
	v_add_f32_dpp v129, v129, v129 quad_perm:[2,3,0,1] row_mask:0xf bank_mask:0xf bound_ctrl:1
	v_add_f32_dpp v190, v190, v190 row_half_mirror row_mask:0xf bank_mask:0xf bound_ctrl:1
	v_add_f32_dpp v191, v191, v191 row_half_mirror row_mask:0xf bank_mask:0xf bound_ctrl:1
	v_add_f32_dpp v128, v128, v128 row_half_mirror row_mask:0xf bank_mask:0xf bound_ctrl:1
	v_add_f32_dpp v129, v129, v129 row_half_mirror row_mask:0xf bank_mask:0xf bound_ctrl:1
	v_add_f32_dpp v190, v190, v190 row_mirror row_mask:0xf bank_mask:0xf bound_ctrl:1
	v_add_f32_dpp v191, v191, v191 row_mirror row_mask:0xf bank_mask:0xf bound_ctrl:1
	v_fmac_f32_e32 v182, v64, v16
	v_fmac_f32_e32 v183, v64, v17
	v_fmac_f32_e32 v184, v64, v18
	v_fmac_f32_e32 v185, v64, v19
	v_fmac_f32_e32 v186, v65, v16
	v_fmac_f32_e32 v187, v65, v17
	v_fmac_f32_e32 v188, v65, v18
	v_fmac_f32_e32 v189, v65, v19
	v_fmac_f32_e32 v182, v190, v12
	v_fmac_f32_e32 v183, v190, v13
	v_fmac_f32_e32 v184, v190, v14
	v_fmac_f32_e32 v185, v190, v15
	v_fmac_f32_e32 v186, v191, v12
	v_fmac_f32_e32 v187, v191, v13
	v_fmac_f32_e32 v188, v191, v14
	v_fmac_f32_e32 v189, v191, v15
	s_mov_b64 exec, s[8:9]
	ds_write_b64 v146, v[128:129] offset:15360
	s_mov_b64 exec, -1
	s_waitcnt lgkmcnt(2)
	v_mul_f32_e32 v190, v182, v28
	v_mul_f32_e32 v191, v186, v28
	v_mul_f32_e32 v128, v182, v40
	v_mul_f32_e32 v129, v186, v40
	v_fmac_f32_e32 v190, v183, v29
	v_fmac_f32_e32 v191, v187, v29
	v_fmac_f32_e32 v128, v183, v41
	v_fmac_f32_e32 v129, v187, v41
	v_fmac_f32_e32 v190, v184, v30
	v_fmac_f32_e32 v191, v188, v30
	v_fmac_f32_e32 v128, v184, v42
	v_fmac_f32_e32 v129, v188, v42
	v_fmac_f32_e32 v190, v185, v31
	v_fmac_f32_e32 v191, v189, v31
	v_fmac_f32_e32 v128, v185, v43
	v_fmac_f32_e32 v129, v189, v43
	v_add_f32_dpp v190, v190, v190 quad_perm:[1,0,3,2] row_mask:0xf bank_mask:0xf bound_ctrl:1
	v_add_f32_dpp v191, v191, v191 quad_perm:[1,0,3,2] row_mask:0xf bank_mask:0xf bound_ctrl:1
	v_add_f32_dpp v128, v128, v128 quad_perm:[1,0,3,2] row_mask:0xf bank_mask:0xf bound_ctrl:1
	v_add_f32_dpp v129, v129, v129 quad_perm:[1,0,3,2] row_mask:0xf bank_mask:0xf bound_ctrl:1
	v_add_f32_dpp v190, v190, v190 quad_perm:[2,3,0,1] row_mask:0xf bank_mask:0xf bound_ctrl:1
	v_add_f32_dpp v191, v191, v191 quad_perm:[2,3,0,1] row_mask:0xf bank_mask:0xf bound_ctrl:1
	v_add_f32_dpp v128, v128, v128 quad_perm:[2,3,0,1] row_mask:0xf bank_mask:0xf bound_ctrl:1
	v_add_f32_dpp v129, v129, v129 quad_perm:[2,3,0,1] row_mask:0xf bank_mask:0xf bound_ctrl:1
	v_add_f32_dpp v190, v190, v190 row_half_mirror row_mask:0xf bank_mask:0xf bound_ctrl:1
	v_add_f32_dpp v191, v191, v191 row_half_mirror row_mask:0xf bank_mask:0xf bound_ctrl:1
	v_add_f32_dpp v128, v128, v128 row_half_mirror row_mask:0xf bank_mask:0xf bound_ctrl:1
	v_add_f32_dpp v129, v129, v129 row_half_mirror row_mask:0xf bank_mask:0xf bound_ctrl:1
	v_add_f32_dpp v190, v190, v190 row_mirror row_mask:0xf bank_mask:0xf bound_ctrl:1
	v_add_f32_dpp v191, v191, v191 row_mirror row_mask:0xf bank_mask:0xf bound_ctrl:1
	v_fmac_f32_e32 v182, v66, v36
	v_fmac_f32_e32 v183, v66, v37
	v_fmac_f32_e32 v184, v66, v38
	v_fmac_f32_e32 v185, v66, v39
	v_fmac_f32_e32 v186, v67, v36
	v_fmac_f32_e32 v187, v67, v37
	v_fmac_f32_e32 v188, v67, v38
	v_fmac_f32_e32 v189, v67, v39
	v_fmac_f32_e32 v182, v190, v32
	v_fmac_f32_e32 v183, v190, v33
	v_fmac_f32_e32 v184, v190, v34
	v_fmac_f32_e32 v185, v190, v35
	v_fmac_f32_e32 v186, v191, v32
	v_fmac_f32_e32 v187, v191, v33
	v_fmac_f32_e32 v188, v191, v34
	v_fmac_f32_e32 v189, v191, v35
	s_mov_b64 exec, s[8:9]
	ds_write_b64 v146, v[128:129] offset:15872
	s_mov_b64 exec, -1
	ds_read_b128 v[4:7], v151 offset:65280
	s_waitcnt lgkmcnt(0)
	v_mul_f32_e32 v182, v182, v4
	v_mul_f32_e32 v183, v183, v5
	v_mul_f32_e32 v184, v184, v6
	v_mul_f32_e32 v185, v185, v7
	v_mul_f32_e32 v186, v186, v4
	v_mul_f32_e32 v187, v187, v5
	v_mul_f32_e32 v188, v188, v6
	v_mul_f32_e32 v189, v189, v7
	s_branch .LBB0_182

.LBB0_292:
	s_andn2_b64 vcc, exec, s[12:13]
	s_cbranch_vccnz .LBB0_294
	v_mul_f32_e32 v4, 0xbf60028a, v4
	v_mul_f32_e32 v5, 0xbf60028a, v5
	v_exp_f32_e32 v4, v4
	v_exp_f32_e32 v5, v5
	v_mul_f32_e32 v6, 0xbf60028a, v6
	v_mul_f32_e32 v7, 0xbf60028a, v7
	v_exp_f32_e32 v6, v6
	v_exp_f32_e32 v7, v7
	v_mul_f32_e32 v8, 0xbf60028a, v8
	v_mul_f32_e32 v9, 0xbf60028a, v9
	v_exp_f32_e32 v8, v8
	v_exp_f32_e32 v9, v9
	v_mul_f32_e32 v10, 0xbf60028a, v10
	v_mul_f32_e32 v11, 0xbf60028a, v11
	v_exp_f32_e32 v10, v10
	v_exp_f32_e32 v11, v11
	s_nop 1
	v_mul_f32_e32 v198, v7, v6
	v_mul_f32_e32 v201, v11, v10
	v_mul_f32_e32 v199, v198, v5
	v_mul_f32_e32 v202, v201, v9
	v_mul_f32_e32 v200, v199, v4
	v_mul_f32_e32 v203, v202, v8
	v_mbcnt_lo_u32_b32 v204, -1, 0
	v_mbcnt_hi_u32_b32 v204, -1, v204
	v_and_b32_e32 v205, 15, v204
	v_lshlrev_b32_e32 v205, 2, v205
	v_add_u32_e32 v206, 64, v205
	v_add_u32_e32 v207, 128, v205
	v_add_u32_e32 v208, 192, v205
	v_mov_b32_e32 v217, 1.0
	ds_bpermute_b32 v209, v205, v200
	ds_bpermute_b32 v210, v206, v200
	ds_bpermute_b32 v211, v207, v200
	ds_bpermute_b32 v212, v208, v200
	ds_bpermute_b32 v213, v205, v203
	ds_bpermute_b32 v214, v206, v203
	ds_bpermute_b32 v215, v207, v203
	ds_bpermute_b32 v216, v208, v203
	s_waitcnt lgkmcnt(0)
	v_cmp_gt_u32_e32 vcc, 16, v204
	v_cndmask_b32_e32 v218, v217, v210, vcc
	v_cndmask_b32_e32 v221, v217, v214, vcc
	v_cmp_gt_u32_e32 vcc, 32, v204
	v_cndmask_b32_e32 v219, v217, v211, vcc
	v_cndmask_b32_e32 v222, v217, v215, vcc
	v_cmp_gt_u32_e32 vcc, 48, v204
	v_cndmask_b32_e32 v220, v217, v212, vcc
	v_cndmask_b32_e32 v223, v217, v216, vcc
	v_mul_f32_e32 v225, v221, v222
	v_mul_f32_e32 v224, v218, v219
	v_mul_f32_e32 v226, v213, v214
	v_mul_f32_e32 v225, v225, v223
	v_mul_f32_e32 v224, v224, v220
	v_mul_f32_e32 v226, v226, v215
	v_mul_f32_e32 v226, v226, v216
	v_mul_f32_e32 v224, v224, v226
	v_mul_f32_e32 v230, v200, v224
	v_mul_f32_e32 v231, v199, v224
	v_mul_f32_e32 v232, v198, v224
	v_mul_f32_e32 v233, v7, v224
	v_mul_f32_e32 v234, v203, v225
	v_mul_f32_e32 v235, v202, v225
	v_mul_f32_e32 v236, v201, v225
	v_mul_f32_e32 v237, v11, v225
	ds_write2st64_b32 v156, v230, v231 offset0:224 offset1:225
	ds_write2st64_b32 v156, v232, v233 offset0:226 offset1:227
	ds_write2st64_b32 v156, v234, v235 offset0:240 offset1:241
	ds_write2st64_b32 v156, v236, v237 offset0:242 offset1:243
	s_waitcnt lgkmcnt(7)
	v_mul_f32_e32 v15, v29, v4
	ds_write2st64_b32 v156, v4, v5 offset1:1
	s_waitcnt lgkmcnt(7)
	v_mul_f32_e32 v4, v28, v5
	ds_write2st64_b32 v156, v15, v4 offset0:128 offset1:129
	s_waitcnt lgkmcnt(7)
	v_mul_f32_e32 v4, v26, v6
	s_waitcnt lgkmcnt(6)
	v_mul_f32_e32 v5, v25, v7
	ds_write2st64_b32 v156, v4, v5 offset0:130 offset1:131
	s_waitcnt lgkmcnt(6)
	v_mul_f32_e32 v4, v24, v8
	s_waitcnt lgkmcnt(5)
	v_mul_f32_e32 v5, v14, v9
	ds_write2st64_b32 v156, v4, v5 offset0:144 offset1:145
	s_waitcnt lgkmcnt(5)
	v_mul_f32_e32 v4, v13, v10
	s_waitcnt lgkmcnt(4)
	v_mul_f32_e32 v5, v12, v11
	ds_write2st64_b32 v156, v6, v7 offset0:2 offset1:3
	ds_write2st64_b32 v156, v8, v9 offset0:16 offset1:17
	ds_write2st64_b32 v156, v10, v11 offset0:18 offset1:19
	ds_write2st64_b32 v156, v4, v5 offset0:146 offset1:147

.LBB0_296:
	s_or_b64 exec, exec, s[12:13]
	v_add_u32_e32 v227, 0x100, v146
	ds_read_b128 v[198:201], v146 offset:57344
	ds_read_b128 v[202:205], v227 offset:57344
	ds_read_b128 v[206:209], v146 offset:8192
	ds_read_b128 v[210:213], v146 offset:16384
	ds_read_b128 v[214:217], v146 offset:24576
	ds_read_b128 v[218:221], v146 offset:32768
	v_mov_b32_e32 v226, 1.0
	v_cmp_lt_u32_e32 vcc, 495, v134
	s_waitcnt lgkmcnt(4)
	v_rcp_f32_e32 v222, v198
	v_rcp_f32_e32 v223, v199
	v_rcp_f32_e32 v224, v200
	v_rcp_f32_e32 v225, v201
	v_cndmask_b32_e32 v202, v202, v226, vcc
	v_cndmask_b32_e32 v203, v203, v226, vcc
	v_cndmask_b32_e32 v204, v204, v226, vcc
	v_cndmask_b32_e32 v205, v205, v226, vcc
	s_waitcnt lgkmcnt(0)
	v_mul_f32_e32 v206, v206, v202
	v_mul_f32_e32 v207, v207, v203
	v_mul_f32_e32 v208, v208, v204
	v_mul_f32_e32 v209, v209, v205
	v_mul_f32_e32 v218, v218, v202
	v_mul_f32_e32 v219, v219, v203
	v_mul_f32_e32 v220, v220, v204
	v_mul_f32_e32 v221, v221, v205
	v_mul_f32_e32 v210, v210, v222
	v_mul_f32_e32 v211, v211, v223
	v_mul_f32_e32 v212, v212, v224
	v_mul_f32_e32 v213, v213, v225
	v_mul_f32_e32 v214, v214, v222
	v_mul_f32_e32 v215, v215, v223
	v_mul_f32_e32 v216, v216, v224
	v_mul_f32_e32 v217, v217, v225
	ds_write_b128 v146, v[206:209] offset:8192
	ds_write_b128 v146, v[218:221] offset:32768
	ds_write_b128 v146, v[210:213] offset:16384
	ds_write_b128 v146, v[214:217] offset:24576
	s_waitcnt lgkmcnt(0)
	s_barrier
	v_mbcnt_lo_u32_b32 v186, -1, 0
	v_mbcnt_hi_u32_b32 v186, -1, v186
	v_lshlrev_b32_e32 v186, 2, v186
	v_add_u32_e32 v186, 0xe000, v186
	v_cndmask_b32_e64 v185, v186, v152, s[8:9]
	ds_read_b128 v[8:11], v145 offset:16128
	ds_read_b128 v[12:15], v145 offset:24320
	ds_read_b128 v[16:19], v145 offset:32512
	ds_read_b128 v[20:23], v145 offset:40704
	ds_read_b32 v126, v151 offset:57088
	ds_read_b128 v[28:31], v145 offset:15872
	ds_read_b128 v[32:35], v145 offset:24064
	ds_read_b128 v[36:39], v145 offset:32256
	ds_read_b128 v[40:43], v145 offset:40448
	ds_read_b32 v127, v151 offset:56832
	ds_read_b128 v[48:51], v145 offset:15616
	ds_read_b128 v[52:55], v145 offset:23808
	ds_read_b128 v[56:59], v145 offset:32000
	ds_read_b128 v[60:63], v145 offset:40192
	ds_read_b32 v69, v151 offset:56576
	s_waitcnt lgkmcnt(10)
	v_mul_f32_e32 v183, v179, v8
	v_mul_f32_e32 v184, v179, v20
	v_fmac_f32_e32 v183, v180, v9
	v_fmac_f32_e32 v184, v180, v21
	v_fmac_f32_e32 v183, v181, v10
	v_fmac_f32_e32 v184, v181, v22
	v_fmac_f32_e32 v183, v182, v11
	v_fmac_f32_e32 v184, v182, v23
	v_fmac_f32_e32 v179, v126, v16
	v_add_f32_dpp v183, v183, v183 quad_perm:[1,0,3,2] row_mask:0xf bank_mask:0xf bound_ctrl:1
	v_add_f32_dpp v184, v184, v184 quad_perm:[1,0,3,2] row_mask:0xf bank_mask:0xf bound_ctrl:1
	v_fmac_f32_e32 v180, v126, v17
	v_add_f32_dpp v183, v183, v183 quad_perm:[2,3,0,1] row_mask:0xf bank_mask:0xf bound_ctrl:1
	v_add_f32_dpp v184, v184, v184 quad_perm:[2,3,0,1] row_mask:0xf bank_mask:0xf bound_ctrl:1
	v_fmac_f32_e32 v181, v126, v18
	v_add_f32_dpp v183, v183, v183 row_half_mirror row_mask:0xf bank_mask:0xf bound_ctrl:1
	v_add_f32_dpp v184, v184, v184 row_half_mirror row_mask:0xf bank_mask:0xf bound_ctrl:1
	v_fmac_f32_e32 v182, v126, v19
	v_add_f32_dpp v183, v183, v183 row_mirror row_mask:0xf bank_mask:0xf bound_ctrl:1
	v_fmac_f32_e32 v179, v183, v12
	v_fmac_f32_e32 v180, v183, v13
	v_fmac_f32_e32 v181, v183, v14
	v_fmac_f32_e32 v182, v183, v15
	s_mov_b64 exec, s[8:9]
	ds_write_b32 v152, v184 offset:15872
	s_mov_b64 exec, -1
	ds_read_b128 v[8:11], v145 offset:15360
	ds_read_b128 v[12:15], v145 offset:23552
	ds_read_b128 v[16:19], v145 offset:31744
	ds_read_b128 v[20:23], v145 offset:39936
	ds_read_b32 v126, v151 offset:56320
	s_waitcnt lgkmcnt(11)
	v_mul_f32_e32 v183, v179, v28
	v_mul_f32_e32 v184, v179, v40
	v_fmac_f32_e32 v183, v180, v29
	v_fmac_f32_e32 v184, v180, v41
	v_fmac_f32_e32 v183, v181, v30
	v_fmac_f32_e32 v184, v181, v42
	v_fmac_f32_e32 v183, v182, v31
	v_fmac_f32_e32 v184, v182, v43
	v_fmac_f32_e32 v179, v127, v36
	v_add_f32_dpp v183, v183, v183 quad_perm:[1,0,3,2] row_mask:0xf bank_mask:0xf bound_ctrl:1
	v_add_f32_dpp v184, v184, v184 quad_perm:[1,0,3,2] row_mask:0xf bank_mask:0xf bound_ctrl:1
	v_fmac_f32_e32 v180, v127, v37
	v_add_f32_dpp v183, v183, v183 quad_perm:[2,3,0,1] row_mask:0xf bank_mask:0xf bound_ctrl:1
	v_add_f32_dpp v184, v184, v184 quad_perm:[2,3,0,1] row_mask:0xf bank_mask:0xf bound_ctrl:1
	v_fmac_f32_e32 v181, v127, v38
	v_add_f32_dpp v183, v183, v183 row_half_mirror row_mask:0xf bank_mask:0xf bound_ctrl:1
	v_add_f32_dpp v184, v184, v184 row_half_mirror row_mask:0xf bank_mask:0xf bound_ctrl:1
	v_fmac_f32_e32 v182, v127, v39
	v_add_f32_dpp v183, v183, v183 row_mirror row_mask:0xf bank_mask:0xf bound_ctrl:1
	v_fmac_f32_e32 v179, v183, v32
	v_fmac_f32_e32 v180, v183, v33
	v_fmac_f32_e32 v181, v183, v34
	v_fmac_f32_e32 v182, v183, v35
	s_mov_b64 exec, s[8:9]
	ds_write_b32 v152, v184 offset:15360
	s_mov_b64 exec, -1
	ds_read_b128 v[28:31], v145 offset:15104
	ds_read_b128 v[32:35], v145 offset:23296
	ds_read_b128 v[36:39], v145 offset:31488
	ds_read_b128 v[40:43], v145 offset:39680
	ds_read_b32 v127, v151 offset:56064
	s_waitcnt lgkmcnt(12)
	v_mul_f32_e32 v183, v179, v48
	v_mul_f32_e32 v184, v179, v60
	v_fmac_f32_e32 v183, v180, v49
	v_fmac_f32_e32 v184, v180, v61
	v_fmac_f32_e32 v183, v181, v50
	v_fmac_f32_e32 v184, v181, v62
	v_fmac_f32_e32 v183, v182, v51
	v_fmac_f32_e32 v184, v182, v63
	v_fmac_f32_e32 v179, v69, v56
	v_add_f32_dpp v183, v183, v183 quad_perm:[1,0,3,2] row_mask:0xf bank_mask:0xf bound_ctrl:1
	v_add_f32_dpp v184, v184, v184 quad_perm:[1,0,3,2] row_mask:0xf bank_mask:0xf bound_ctrl:1
	v_fmac_f32_e32 v180, v69, v57
	v_add_f32_dpp v183, v183, v183 quad_perm:[2,3,0,1] row_mask:0xf bank_mask:0xf bound_ctrl:1
	v_add_f32_dpp v184, v184, v184 quad_perm:[2,3,0,1] row_mask:0xf bank_mask:0xf bound_ctrl:1
	v_fmac_f32_e32 v181, v69, v58
	v_add_f32_dpp v183, v183, v183 row_half_mirror row_mask:0xf bank_mask:0xf bound_ctrl:1
	v_add_f32_dpp v184, v184, v184 row_half_mirror row_mask:0xf bank_mask:0xf bound_ctrl:1
	v_fmac_f32_e32 v182, v69, v59
	v_add_f32_dpp v183, v183, v183 row_mirror row_mask:0xf bank_mask:0xf bound_ctrl:1
	v_fmac_f32_e32 v179, v183, v52
	v_fmac_f32_e32 v180, v183, v53
	v_fmac_f32_e32 v181, v183, v54
	v_fmac_f32_e32 v182, v183, v55
	s_mov_b64 exec, s[8:9]
	ds_write_b32 v152, v184 offset:14848
	s_mov_b64 exec, -1
	ds_read_b128 v[48:51], v145 offset:14848
	ds_read_b128 v[52:55], v145 offset:23040
	ds_read_b128 v[56:59], v145 offset:31232
	ds_read_b128 v[60:63], v145 offset:39424
	ds_read_b32 v69, v151 offset:55808
	s_waitcnt lgkmcnt(12)
	v_mul_f32_e32 v183, v179, v8
	v_mul_f32_e32 v184, v179, v20
	v_fmac_f32_e32 v183, v180, v9
	v_fmac_f32_e32 v184, v180, v21
	v_fmac_f32_e32 v183, v181, v10
	v_fmac_f32_e32 v184, v181, v22
	v_fmac_f32_e32 v183, v182, v11
	v_fmac_f32_e32 v184, v182, v23
	v_fmac_f32_e32 v179, v126, v16
	v_add_f32_dpp v183, v183, v183 quad_perm:[1,0,3,2] row_mask:0xf bank_mask:0xf bound_ctrl:1
	v_add_f32_dpp v184, v184, v184 quad_perm:[1,0,3,2] row_mask:0xf bank_mask:0xf bound_ctrl:1
	v_fmac_f32_e32 v180, v126, v17
	v_add_f32_dpp v183, v183, v183 quad_perm:[2,3,0,1] row_mask:0xf bank_mask:0xf bound_ctrl:1
	v_add_f32_dpp v184, v184, v184 quad_perm:[2,3,0,1] row_mask:0xf bank_mask:0xf bound_ctrl:1
	v_fmac_f32_e32 v181, v126, v18
	v_add_f32_dpp v183, v183, v183 row_half_mirror row_mask:0xf bank_mask:0xf bound_ctrl:1
	v_add_f32_dpp v184, v184, v184 row_half_mirror row_mask:0xf bank_mask:0xf bound_ctrl:1
	v_fmac_f32_e32 v182, v126, v19
	v_add_f32_dpp v183, v183, v183 row_mirror row_mask:0xf bank_mask:0xf bound_ctrl:1
	v_fmac_f32_e32 v179, v183, v12
	v_fmac_f32_e32 v180, v183, v13
	v_fmac_f32_e32 v181, v183, v14
	v_fmac_f32_e32 v182, v183, v15
	s_mov_b64 exec, s[8:9]
	ds_write_b32 v152, v184 offset:14336
	s_mov_b64 exec, -1
	ds_read_b128 v[8:11], v145 offset:14592
	ds_read_b128 v[12:15], v145 offset:22784
	ds_read_b128 v[16:19], v145 offset:30976
	ds_read_b128 v[20:23], v145 offset:39168
	ds_read_b32 v126, v151 offset:55552
	s_waitcnt lgkmcnt(12)
	v_mul_f32_e32 v183, v179, v28
	v_mul_f32_e32 v184, v179, v40
	v_fmac_f32_e32 v183, v180, v29
	v_fmac_f32_e32 v184, v180, v41
	v_fmac_f32_e32 v183, v181, v30
	v_fmac_f32_e32 v184, v181, v42
	v_fmac_f32_e32 v183, v182, v31
	v_fmac_f32_e32 v184, v182, v43
	v_fmac_f32_e32 v179, v127, v36
	v_add_f32_dpp v183, v183, v183 quad_perm:[1,0,3,2] row_mask:0xf bank_mask:0xf bound_ctrl:1
	v_add_f32_dpp v184, v184, v184 quad_perm:[1,0,3,2] row_mask:0xf bank_mask:0xf bound_ctrl:1
	v_fmac_f32_e32 v180, v127, v37
	v_add_f32_dpp v183, v183, v183 quad_perm:[2,3,0,1] row_mask:0xf bank_mask:0xf bound_ctrl:1
	v_add_f32_dpp v184, v184, v184 quad_perm:[2,3,0,1] row_mask:0xf bank_mask:0xf bound_ctrl:1
	v_fmac_f32_e32 v181, v127, v38
	v_add_f32_dpp v183, v183, v183 row_half_mirror row_mask:0xf bank_mask:0xf bound_ctrl:1
	v_add_f32_dpp v184, v184, v184 row_half_mirror row_mask:0xf bank_mask:0xf bound_ctrl:1
	v_fmac_f32_e32 v182, v127, v39
	v_add_f32_dpp v183, v183, v183 row_mirror row_mask:0xf bank_mask:0xf bound_ctrl:1
	v_fmac_f32_e32 v179, v183, v32
	v_fmac_f32_e32 v180, v183, v33
	v_fmac_f32_e32 v181, v183, v34
	v_fmac_f32_e32 v182, v183, v35
	s_mov_b64 exec, s[8:9]
	ds_write_b32 v152, v184 offset:13824
	s_mov_b64 exec, -1
	ds_read_b128 v[28:31], v145 offset:14336
	ds_read_b128 v[32:35], v145 offset:22528
	ds_read_b128 v[36:39], v145 offset:30720
	ds_read_b128 v[40:43], v145 offset:38912
	ds_read_b32 v127, v151 offset:55296
	s_waitcnt lgkmcnt(12)
	v_mul_f32_e32 v183, v179, v48
	v_mul_f32_e32 v184, v179, v60
	v_fmac_f32_e32 v183, v180, v49
	v_fmac_f32_e32 v184, v180, v61
	v_fmac_f32_e32 v183, v181, v50
	v_fmac_f32_e32 v184, v181, v62
	v_fmac_f32_e32 v183, v182, v51
	v_fmac_f32_e32 v184, v182, v63
	v_fmac_f32_e32 v179, v69, v56
	v_add_f32_dpp v183, v183, v183 quad_perm:[1,0,3,2] row_mask:0xf bank_mask:0xf bound_ctrl:1
	v_add_f32_dpp v184, v184, v184 quad_perm:[1,0,3,2] row_mask:0xf bank_mask:0xf bound_ctrl:1
	v_fmac_f32_e32 v180, v69, v57
	v_add_f32_dpp v183, v183, v183 quad_perm:[2,3,0,1] row_mask:0xf bank_mask:0xf bound_ctrl:1
	v_add_f32_dpp v184, v184, v184 quad_perm:[2,3,0,1] row_mask:0xf bank_mask:0xf bound_ctrl:1
	v_fmac_f32_e32 v181, v69, v58
	v_add_f32_dpp v183, v183, v183 row_half_mirror row_mask:0xf bank_mask:0xf bound_ctrl:1
	v_add_f32_dpp v184, v184, v184 row_half_mirror row_mask:0xf bank_mask:0xf bound_ctrl:1
	v_fmac_f32_e32 v182, v69, v59
	v_add_f32_dpp v183, v183, v183 row_mirror row_mask:0xf bank_mask:0xf bound_ctrl:1
	v_fmac_f32_e32 v179, v183, v52
	v_fmac_f32_e32 v180, v183, v53
	v_fmac_f32_e32 v181, v183, v54
	v_fmac_f32_e32 v182, v183, v55
	s_mov_b64 exec, s[8:9]
	ds_write_b32 v152, v184 offset:13312
	s_mov_b64 exec, -1
	ds_read_b128 v[48:51], v145 offset:14080
	ds_read_b128 v[52:55], v145 offset:22272
	ds_read_b128 v[56:59], v145 offset:30464
	ds_read_b128 v[60:63], v145 offset:38656
	ds_read_b32 v69, v151 offset:55040
	s_waitcnt lgkmcnt(12)
	v_mul_f32_e32 v183, v179, v8
	v_mul_f32_e32 v184, v179, v20
	v_fmac_f32_e32 v183, v180, v9
	v_fmac_f32_e32 v184, v180, v21
	v_fmac_f32_e32 v183, v181, v10
	v_fmac_f32_e32 v184, v181, v22
	v_fmac_f32_e32 v183, v182, v11
	v_fmac_f32_e32 v184, v182, v23
	v_fmac_f32_e32 v179, v126, v16
	v_add_f32_dpp v183, v183, v183 quad_perm:[1,0,3,2] row_mask:0xf bank_mask:0xf bound_ctrl:1
	v_add_f32_dpp v184, v184, v184 quad_perm:[1,0,3,2] row_mask:0xf bank_mask:0xf bound_ctrl:1
	v_fmac_f32_e32 v180, v126, v17
	v_add_f32_dpp v183, v183, v183 quad_perm:[2,3,0,1] row_mask:0xf bank_mask:0xf bound_ctrl:1
	v_add_f32_dpp v184, v184, v184 quad_perm:[2,3,0,1] row_mask:0xf bank_mask:0xf bound_ctrl:1
	v_fmac_f32_e32 v181, v126, v18
	v_add_f32_dpp v183, v183, v183 row_half_mirror row_mask:0xf bank_mask:0xf bound_ctrl:1
	v_add_f32_dpp v184, v184, v184 row_half_mirror row_mask:0xf bank_mask:0xf bound_ctrl:1
	v_fmac_f32_e32 v182, v126, v19
	v_add_f32_dpp v183, v183, v183 row_mirror row_mask:0xf bank_mask:0xf bound_ctrl:1
	v_fmac_f32_e32 v179, v183, v12
	v_fmac_f32_e32 v180, v183, v13
	v_fmac_f32_e32 v181, v183, v14
	v_fmac_f32_e32 v182, v183, v15
	s_mov_b64 exec, s[8:9]
	ds_write_b32 v152, v184 offset:12800
	s_mov_b64 exec, -1
	ds_read_b128 v[8:11], v145 offset:13824
	ds_read_b128 v[12:15], v145 offset:22016
	ds_read_b128 v[16:19], v145 offset:30208
	ds_read_b128 v[20:23], v145 offset:38400
	ds_read_b32 v126, v151 offset:54784
	s_waitcnt lgkmcnt(12)
	v_mul_f32_e32 v183, v179, v28
	v_mul_f32_e32 v184, v179, v40
	v_fmac_f32_e32 v183, v180, v29
	v_fmac_f32_e32 v184, v180, v41
	v_fmac_f32_e32 v183, v181, v30
	v_fmac_f32_e32 v184, v181, v42
	v_fmac_f32_e32 v183, v182, v31
	v_fmac_f32_e32 v184, v182, v43
	v_fmac_f32_e32 v179, v127, v36
	v_add_f32_dpp v183, v183, v183 quad_perm:[1,0,3,2] row_mask:0xf bank_mask:0xf bound_ctrl:1
	v_add_f32_dpp v184, v184, v184 quad_perm:[1,0,3,2] row_mask:0xf bank_mask:0xf bound_ctrl:1
	v_fmac_f32_e32 v180, v127, v37
	v_add_f32_dpp v183, v183, v183 quad_perm:[2,3,0,1] row_mask:0xf bank_mask:0xf bound_ctrl:1
	v_add_f32_dpp v184, v184, v184 quad_perm:[2,3,0,1] row_mask:0xf bank_mask:0xf bound_ctrl:1
	v_fmac_f32_e32 v181, v127, v38
	v_add_f32_dpp v183, v183, v183 row_half_mirror row_mask:0xf bank_mask:0xf bound_ctrl:1
	v_add_f32_dpp v184, v184, v184 row_half_mirror row_mask:0xf bank_mask:0xf bound_ctrl:1
	v_fmac_f32_e32 v182, v127, v39
	v_add_f32_dpp v183, v183, v183 row_mirror row_mask:0xf bank_mask:0xf bound_ctrl:1
	v_fmac_f32_e32 v179, v183, v32
	v_fmac_f32_e32 v180, v183, v33
	v_fmac_f32_e32 v181, v183, v34
	v_fmac_f32_e32 v182, v183, v35
	s_mov_b64 exec, s[8:9]
	ds_write_b32 v152, v184 offset:12288
	s_mov_b64 exec, -1
	ds_read_b128 v[28:31], v145 offset:13568
	ds_read_b128 v[32:35], v145 offset:21760
	ds_read_b128 v[36:39], v145 offset:29952
	ds_read_b128 v[40:43], v145 offset:38144
	ds_read_b32 v127, v151 offset:54528
	s_waitcnt lgkmcnt(12)
	v_mul_f32_e32 v183, v179, v48
	v_mul_f32_e32 v184, v179, v60
	v_fmac_f32_e32 v183, v180, v49
	v_fmac_f32_e32 v184, v180, v61
	v_fmac_f32_e32 v183, v181, v50
	v_fmac_f32_e32 v184, v181, v62
	v_fmac_f32_e32 v183, v182, v51
	v_fmac_f32_e32 v184, v182, v63
	v_fmac_f32_e32 v179, v69, v56
	v_add_f32_dpp v183, v183, v183 quad_perm:[1,0,3,2] row_mask:0xf bank_mask:0xf bound_ctrl:1
	v_add_f32_dpp v184, v184, v184 quad_perm:[1,0,3,2] row_mask:0xf bank_mask:0xf bound_ctrl:1
	v_fmac_f32_e32 v180, v69, v57
	v_add_f32_dpp v183, v183, v183 quad_perm:[2,3,0,1] row_mask:0xf bank_mask:0xf bound_ctrl:1
	v_add_f32_dpp v184, v184, v184 quad_perm:[2,3,0,1] row_mask:0xf bank_mask:0xf bound_ctrl:1
	v_fmac_f32_e32 v181, v69, v58
	v_add_f32_dpp v183, v183, v183 row_half_mirror row_mask:0xf bank_mask:0xf bound_ctrl:1
	v_add_f32_dpp v184, v184, v184 row_half_mirror row_mask:0xf bank_mask:0xf bound_ctrl:1
	v_fmac_f32_e32 v182, v69, v59
	v_add_f32_dpp v183, v183, v183 row_mirror row_mask:0xf bank_mask:0xf bound_ctrl:1
	v_fmac_f32_e32 v179, v183, v52
	v_fmac_f32_e32 v180, v183, v53
	v_fmac_f32_e32 v181, v183, v54
	v_fmac_f32_e32 v182, v183, v55
	s_mov_b64 exec, s[8:9]
	ds_write_b32 v152, v184 offset:11776
	s_mov_b64 exec, -1
	ds_read_b128 v[48:51], v145 offset:13312
	ds_read_b128 v[52:55], v145 offset:21504
	ds_read_b128 v[56:59], v145 offset:29696
	ds_read_b128 v[60:63], v145 offset:37888
	ds_read_b32 v69, v151 offset:54272
	s_waitcnt lgkmcnt(12)
	v_mul_f32_e32 v183, v179, v8
	v_mul_f32_e32 v184, v179, v20
	v_fmac_f32_e32 v183, v180, v9
	v_fmac_f32_e32 v184, v180, v21
	v_fmac_f32_e32 v183, v181, v10
	v_fmac_f32_e32 v184, v181, v22
	v_fmac_f32_e32 v183, v182, v11
	v_fmac_f32_e32 v184, v182, v23
	v_fmac_f32_e32 v179, v126, v16
	v_add_f32_dpp v183, v183, v183 quad_perm:[1,0,3,2] row_mask:0xf bank_mask:0xf bound_ctrl:1
	v_add_f32_dpp v184, v184, v184 quad_perm:[1,0,3,2] row_mask:0xf bank_mask:0xf bound_ctrl:1
	v_fmac_f32_e32 v180, v126, v17
	v_add_f32_dpp v183, v183, v183 quad_perm:[2,3,0,1] row_mask:0xf bank_mask:0xf bound_ctrl:1
	v_add_f32_dpp v184, v184, v184 quad_perm:[2,3,0,1] row_mask:0xf bank_mask:0xf bound_ctrl:1
	v_fmac_f32_e32 v181, v126, v18
	v_add_f32_dpp v183, v183, v183 row_half_mirror row_mask:0xf bank_mask:0xf bound_ctrl:1
	v_add_f32_dpp v184, v184, v184 row_half_mirror row_mask:0xf bank_mask:0xf bound_ctrl:1
	v_fmac_f32_e32 v182, v126, v19
	v_add_f32_dpp v183, v183, v183 row_mirror row_mask:0xf bank_mask:0xf bound_ctrl:1
	v_fmac_f32_e32 v179, v183, v12
	v_fmac_f32_e32 v180, v183, v13
	v_fmac_f32_e32 v181, v183, v14
	v_fmac_f32_e32 v182, v183, v15
	s_mov_b64 exec, s[8:9]
	ds_write_b32 v152, v184 offset:11264
	s_mov_b64 exec, -1
	ds_read_b128 v[8:11], v145 offset:13056
	ds_read_b128 v[12:15], v145 offset:21248
	ds_read_b128 v[16:19], v145 offset:29440
	ds_read_b128 v[20:23], v145 offset:37632
	ds_read_b32 v126, v151 offset:54016
	s_waitcnt lgkmcnt(12)
	v_mul_f32_e32 v183, v179, v28
	v_mul_f32_e32 v184, v179, v40
	v_fmac_f32_e32 v183, v180, v29
	v_fmac_f32_e32 v184, v180, v41
	v_fmac_f32_e32 v183, v181, v30
	v_fmac_f32_e32 v184, v181, v42
	v_fmac_f32_e32 v183, v182, v31
	v_fmac_f32_e32 v184, v182, v43
	v_fmac_f32_e32 v179, v127, v36
	v_add_f32_dpp v183, v183, v183 quad_perm:[1,0,3,2] row_mask:0xf bank_mask:0xf bound_ctrl:1
	v_add_f32_dpp v184, v184, v184 quad_perm:[1,0,3,2] row_mask:0xf bank_mask:0xf bound_ctrl:1
	v_fmac_f32_e32 v180, v127, v37
	v_add_f32_dpp v183, v183, v183 quad_perm:[2,3,0,1] row_mask:0xf bank_mask:0xf bound_ctrl:1
	v_add_f32_dpp v184, v184, v184 quad_perm:[2,3,0,1] row_mask:0xf bank_mask:0xf bound_ctrl:1
	v_fmac_f32_e32 v181, v127, v38
	v_add_f32_dpp v183, v183, v183 row_half_mirror row_mask:0xf bank_mask:0xf bound_ctrl:1
	v_add_f32_dpp v184, v184, v184 row_half_mirror row_mask:0xf bank_mask:0xf bound_ctrl:1
	v_fmac_f32_e32 v182, v127, v39
	v_add_f32_dpp v183, v183, v183 row_mirror row_mask:0xf bank_mask:0xf bound_ctrl:1
	v_fmac_f32_e32 v179, v183, v32
	v_fmac_f32_e32 v180, v183, v33
	v_fmac_f32_e32 v181, v183, v34
	v_fmac_f32_e32 v182, v183, v35
	s_mov_b64 exec, s[8:9]
	ds_write_b32 v152, v184 offset:10752
	s_mov_b64 exec, -1
	ds_read_b128 v[28:31], v145 offset:12800
	ds_read_b128 v[32:35], v145 offset:20992
	ds_read_b128 v[36:39], v145 offset:29184
	ds_read_b128 v[40:43], v145 offset:37376
	ds_read_b32 v127, v151 offset:53760
	s_waitcnt lgkmcnt(12)
	v_mul_f32_e32 v183, v179, v48
	v_mul_f32_e32 v184, v179, v60
	v_fmac_f32_e32 v183, v180, v49
	v_fmac_f32_e32 v184, v180, v61
	v_fmac_f32_e32 v183, v181, v50
	v_fmac_f32_e32 v184, v181, v62
	v_fmac_f32_e32 v183, v182, v51
	v_fmac_f32_e32 v184, v182, v63
	v_fmac_f32_e32 v179, v69, v56
	v_add_f32_dpp v183, v183, v183 quad_perm:[1,0,3,2] row_mask:0xf bank_mask:0xf bound_ctrl:1
	v_add_f32_dpp v184, v184, v184 quad_perm:[1,0,3,2] row_mask:0xf bank_mask:0xf bound_ctrl:1
	v_fmac_f32_e32 v180, v69, v57
	v_add_f32_dpp v183, v183, v183 quad_perm:[2,3,0,1] row_mask:0xf bank_mask:0xf bound_ctrl:1
	v_add_f32_dpp v184, v184, v184 quad_perm:[2,3,0,1] row_mask:0xf bank_mask:0xf bound_ctrl:1
	v_fmac_f32_e32 v181, v69, v58
	v_add_f32_dpp v183, v183, v183 row_half_mirror row_mask:0xf bank_mask:0xf bound_ctrl:1
	v_add_f32_dpp v184, v184, v184 row_half_mirror row_mask:0xf bank_mask:0xf bound_ctrl:1
	v_fmac_f32_e32 v182, v69, v59
	v_add_f32_dpp v183, v183, v183 row_mirror row_mask:0xf bank_mask:0xf bound_ctrl:1
	v_fmac_f32_e32 v179, v183, v52
	v_fmac_f32_e32 v180, v183, v53
	v_fmac_f32_e32 v181, v183, v54
	v_fmac_f32_e32 v182, v183, v55
	s_mov_b64 exec, s[8:9]
	ds_write_b32 v152, v184 offset:10240
	s_mov_b64 exec, -1
	ds_read_b128 v[48:51], v145 offset:12544
	ds_read_b128 v[52:55], v145 offset:20736
	ds_read_b128 v[56:59], v145 offset:28928
	ds_read_b128 v[60:63], v145 offset:37120
	ds_read_b32 v69, v151 offset:53504
	s_waitcnt lgkmcnt(12)
	v_mul_f32_e32 v183, v179, v8
	v_mul_f32_e32 v184, v179, v20
	v_fmac_f32_e32 v183, v180, v9
	v_fmac_f32_e32 v184, v180, v21
	v_fmac_f32_e32 v183, v181, v10
	v_fmac_f32_e32 v184, v181, v22
	v_fmac_f32_e32 v183, v182, v11
	v_fmac_f32_e32 v184, v182, v23
	v_fmac_f32_e32 v179, v126, v16
	v_add_f32_dpp v183, v183, v183 quad_perm:[1,0,3,2] row_mask:0xf bank_mask:0xf bound_ctrl:1
	v_add_f32_dpp v184, v184, v184 quad_perm:[1,0,3,2] row_mask:0xf bank_mask:0xf bound_ctrl:1
	v_fmac_f32_e32 v180, v126, v17
	v_add_f32_dpp v183, v183, v183 quad_perm:[2,3,0,1] row_mask:0xf bank_mask:0xf bound_ctrl:1
	v_add_f32_dpp v184, v184, v184 quad_perm:[2,3,0,1] row_mask:0xf bank_mask:0xf bound_ctrl:1
	v_fmac_f32_e32 v181, v126, v18
	v_add_f32_dpp v183, v183, v183 row_half_mirror row_mask:0xf bank_mask:0xf bound_ctrl:1
	v_add_f32_dpp v184, v184, v184 row_half_mirror row_mask:0xf bank_mask:0xf bound_ctrl:1
	v_fmac_f32_e32 v182, v126, v19
	v_add_f32_dpp v183, v183, v183 row_mirror row_mask:0xf bank_mask:0xf bound_ctrl:1
	v_fmac_f32_e32 v179, v183, v12
	v_fmac_f32_e32 v180, v183, v13
	v_fmac_f32_e32 v181, v183, v14
	v_fmac_f32_e32 v182, v183, v15
	s_mov_b64 exec, s[8:9]
	ds_write_b32 v152, v184 offset:9728
	s_mov_b64 exec, -1
	ds_read_b128 v[8:11], v145 offset:12288
	ds_read_b128 v[12:15], v145 offset:20480
	ds_read_b128 v[16:19], v145 offset:28672
	ds_read_b128 v[20:23], v145 offset:36864
	ds_read_b32 v126, v151 offset:53248
	s_waitcnt lgkmcnt(12)
	v_mul_f32_e32 v183, v179, v28
	v_mul_f32_e32 v184, v179, v40
	v_fmac_f32_e32 v183, v180, v29
	v_fmac_f32_e32 v184, v180, v41
	v_fmac_f32_e32 v183, v181, v30
	v_fmac_f32_e32 v184, v181, v42
	v_fmac_f32_e32 v183, v182, v31
	v_fmac_f32_e32 v184, v182, v43
	v_fmac_f32_e32 v179, v127, v36
	v_add_f32_dpp v183, v183, v183 quad_perm:[1,0,3,2] row_mask:0xf bank_mask:0xf bound_ctrl:1
	v_add_f32_dpp v184, v184, v184 quad_perm:[1,0,3,2] row_mask:0xf bank_mask:0xf bound_ctrl:1
	v_fmac_f32_e32 v180, v127, v37
	v_add_f32_dpp v183, v183, v183 quad_perm:[2,3,0,1] row_mask:0xf bank_mask:0xf bound_ctrl:1
	v_add_f32_dpp v184, v184, v184 quad_perm:[2,3,0,1] row_mask:0xf bank_mask:0xf bound_ctrl:1
	v_fmac_f32_e32 v181, v127, v38
	v_add_f32_dpp v183, v183, v183 row_half_mirror row_mask:0xf bank_mask:0xf bound_ctrl:1
	v_add_f32_dpp v184, v184, v184 row_half_mirror row_mask:0xf bank_mask:0xf bound_ctrl:1
	v_fmac_f32_e32 v182, v127, v39
	v_add_f32_dpp v183, v183, v183 row_mirror row_mask:0xf bank_mask:0xf bound_ctrl:1
	v_fmac_f32_e32 v179, v183, v32
	v_fmac_f32_e32 v180, v183, v33
	v_fmac_f32_e32 v181, v183, v34
	v_fmac_f32_e32 v182, v183, v35
	s_mov_b64 exec, s[8:9]
	ds_write_b32 v152, v184 offset:9216
	s_mov_b64 exec, -1
	ds_read_b128 v[28:31], v145 offset:12032
	ds_read_b128 v[32:35], v145 offset:20224
	ds_read_b128 v[36:39], v145 offset:28416
	ds_read_b128 v[40:43], v145 offset:36608
	ds_read_b32 v127, v151 offset:52992
	s_waitcnt lgkmcnt(12)
	v_mul_f32_e32 v183, v179, v48
	v_mul_f32_e32 v184, v179, v60
	v_fmac_f32_e32 v183, v180, v49
	v_fmac_f32_e32 v184, v180, v61
	v_fmac_f32_e32 v183, v181, v50
	v_fmac_f32_e32 v184, v181, v62
	v_fmac_f32_e32 v183, v182, v51
	v_fmac_f32_e32 v184, v182, v63
	v_fmac_f32_e32 v179, v69, v56
	v_add_f32_dpp v183, v183, v183 quad_perm:[1,0,3,2] row_mask:0xf bank_mask:0xf bound_ctrl:1
	v_add_f32_dpp v184, v184, v184 quad_perm:[1,0,3,2] row_mask:0xf bank_mask:0xf bound_ctrl:1
	v_fmac_f32_e32 v180, v69, v57
	v_add_f32_dpp v183, v183, v183 quad_perm:[2,3,0,1] row_mask:0xf bank_mask:0xf bound_ctrl:1
	v_add_f32_dpp v184, v184, v184 quad_perm:[2,3,0,1] row_mask:0xf bank_mask:0xf bound_ctrl:1
	v_fmac_f32_e32 v181, v69, v58
	v_add_f32_dpp v183, v183, v183 row_half_mirror row_mask:0xf bank_mask:0xf bound_ctrl:1
	v_add_f32_dpp v184, v184, v184 row_half_mirror row_mask:0xf bank_mask:0xf bound_ctrl:1
	v_fmac_f32_e32 v182, v69, v59
	v_add_f32_dpp v183, v183, v183 row_mirror row_mask:0xf bank_mask:0xf bound_ctrl:1
	v_fmac_f32_e32 v179, v183, v52
	v_fmac_f32_e32 v180, v183, v53
	v_fmac_f32_e32 v181, v183, v54
	v_fmac_f32_e32 v182, v183, v55
	s_mov_b64 exec, s[8:9]
	ds_write_b32 v152, v184 offset:8704
	s_mov_b64 exec, -1
	ds_read_b128 v[48:51], v145 offset:11776
	ds_read_b128 v[52:55], v145 offset:19968
	ds_read_b128 v[56:59], v145 offset:28160
	ds_read_b128 v[60:63], v145 offset:36352
	ds_read_b32 v69, v151 offset:52736
	s_waitcnt lgkmcnt(12)
	v_mul_f32_e32 v183, v179, v8
	v_mul_f32_e32 v184, v179, v20
	v_fmac_f32_e32 v183, v180, v9
	v_fmac_f32_e32 v184, v180, v21
	v_fmac_f32_e32 v183, v181, v10
	v_fmac_f32_e32 v184, v181, v22
	v_fmac_f32_e32 v183, v182, v11
	v_fmac_f32_e32 v184, v182, v23
	v_fmac_f32_e32 v179, v126, v16
	v_add_f32_dpp v183, v183, v183 quad_perm:[1,0,3,2] row_mask:0xf bank_mask:0xf bound_ctrl:1
	v_add_f32_dpp v184, v184, v184 quad_perm:[1,0,3,2] row_mask:0xf bank_mask:0xf bound_ctrl:1
	v_fmac_f32_e32 v180, v126, v17
	v_add_f32_dpp v183, v183, v183 quad_perm:[2,3,0,1] row_mask:0xf bank_mask:0xf bound_ctrl:1
	v_add_f32_dpp v184, v184, v184 quad_perm:[2,3,0,1] row_mask:0xf bank_mask:0xf bound_ctrl:1
	v_fmac_f32_e32 v181, v126, v18
	v_add_f32_dpp v183, v183, v183 row_half_mirror row_mask:0xf bank_mask:0xf bound_ctrl:1
	v_add_f32_dpp v184, v184, v184 row_half_mirror row_mask:0xf bank_mask:0xf bound_ctrl:1
	v_fmac_f32_e32 v182, v126, v19
	v_add_f32_dpp v183, v183, v183 row_mirror row_mask:0xf bank_mask:0xf bound_ctrl:1
	v_fmac_f32_e32 v179, v183, v12
	v_fmac_f32_e32 v180, v183, v13
	v_fmac_f32_e32 v181, v183, v14
	v_fmac_f32_e32 v182, v183, v15
	s_mov_b64 exec, s[8:9]
	ds_write_b32 v152, v184 offset:8192
	s_mov_b64 exec, -1
	ds_read_b128 v[8:11], v145 offset:11520
	ds_read_b128 v[12:15], v145 offset:19712
	ds_read_b128 v[16:19], v145 offset:27904
	ds_read_b128 v[20:23], v145 offset:36096
	ds_read_b32 v126, v151 offset:52480
	s_waitcnt lgkmcnt(12)
	v_mul_f32_e32 v183, v179, v28
	v_mul_f32_e32 v184, v179, v40
	v_fmac_f32_e32 v183, v180, v29
	v_fmac_f32_e32 v184, v180, v41
	v_fmac_f32_e32 v183, v181, v30
	v_fmac_f32_e32 v184, v181, v42
	v_fmac_f32_e32 v183, v182, v31
	v_fmac_f32_e32 v184, v182, v43
	v_fmac_f32_e32 v179, v127, v36
	v_add_f32_dpp v183, v183, v183 quad_perm:[1,0,3,2] row_mask:0xf bank_mask:0xf bound_ctrl:1
	v_add_f32_dpp v184, v184, v184 quad_perm:[1,0,3,2] row_mask:0xf bank_mask:0xf bound_ctrl:1
	v_fmac_f32_e32 v180, v127, v37
	v_add_f32_dpp v183, v183, v183 quad_perm:[2,3,0,1] row_mask:0xf bank_mask:0xf bound_ctrl:1
	v_add_f32_dpp v184, v184, v184 quad_perm:[2,3,0,1] row_mask:0xf bank_mask:0xf bound_ctrl:1
	v_fmac_f32_e32 v181, v127, v38
	v_add_f32_dpp v183, v183, v183 row_half_mirror row_mask:0xf bank_mask:0xf bound_ctrl:1
	v_add_f32_dpp v184, v184, v184 row_half_mirror row_mask:0xf bank_mask:0xf bound_ctrl:1
	v_fmac_f32_e32 v182, v127, v39
	v_add_f32_dpp v183, v183, v183 row_mirror row_mask:0xf bank_mask:0xf bound_ctrl:1
	v_fmac_f32_e32 v179, v183, v32
	v_fmac_f32_e32 v180, v183, v33
	v_fmac_f32_e32 v181, v183, v34
	v_fmac_f32_e32 v182, v183, v35
	s_mov_b64 exec, s[8:9]
	ds_write_b32 v152, v184 offset:7680
	s_mov_b64 exec, -1
	ds_read_b128 v[28:31], v145 offset:11264
	ds_read_b128 v[32:35], v145 offset:19456
	ds_read_b128 v[36:39], v145 offset:27648
	ds_read_b128 v[40:43], v145 offset:35840
	ds_read_b32 v127, v151 offset:52224
	s_waitcnt lgkmcnt(12)
	v_mul_f32_e32 v183, v179, v48
	v_mul_f32_e32 v184, v179, v60
	v_fmac_f32_e32 v183, v180, v49
	v_fmac_f32_e32 v184, v180, v61
	v_fmac_f32_e32 v183, v181, v50
	v_fmac_f32_e32 v184, v181, v62
	v_fmac_f32_e32 v183, v182, v51
	v_fmac_f32_e32 v184, v182, v63
	v_fmac_f32_e32 v179, v69, v56
	v_add_f32_dpp v183, v183, v183 quad_perm:[1,0,3,2] row_mask:0xf bank_mask:0xf bound_ctrl:1
	v_add_f32_dpp v184, v184, v184 quad_perm:[1,0,3,2] row_mask:0xf bank_mask:0xf bound_ctrl:1
	v_fmac_f32_e32 v180, v69, v57
	v_add_f32_dpp v183, v183, v183 quad_perm:[2,3,0,1] row_mask:0xf bank_mask:0xf bound_ctrl:1
	v_add_f32_dpp v184, v184, v184 quad_perm:[2,3,0,1] row_mask:0xf bank_mask:0xf bound_ctrl:1
	v_fmac_f32_e32 v181, v69, v58
	v_add_f32_dpp v183, v183, v183 row_half_mirror row_mask:0xf bank_mask:0xf bound_ctrl:1
	v_add_f32_dpp v184, v184, v184 row_half_mirror row_mask:0xf bank_mask:0xf bound_ctrl:1
	v_fmac_f32_e32 v182, v69, v59
	v_add_f32_dpp v183, v183, v183 row_mirror row_mask:0xf bank_mask:0xf bound_ctrl:1
	v_fmac_f32_e32 v179, v183, v52
	v_fmac_f32_e32 v180, v183, v53
	v_fmac_f32_e32 v181, v183, v54
	v_fmac_f32_e32 v182, v183, v55
	s_mov_b64 exec, s[8:9]
	ds_write_b32 v152, v184 offset:7168
	s_mov_b64 exec, -1
	ds_read_b128 v[48:51], v145 offset:11008
	ds_read_b128 v[52:55], v145 offset:19200
	ds_read_b128 v[56:59], v145 offset:27392
	ds_read_b128 v[60:63], v145 offset:35584
	ds_read_b32 v69, v151 offset:51968
	s_waitcnt lgkmcnt(12)
	v_mul_f32_e32 v183, v179, v8
	v_mul_f32_e32 v184, v179, v20
	v_fmac_f32_e32 v183, v180, v9
	v_fmac_f32_e32 v184, v180, v21
	v_fmac_f32_e32 v183, v181, v10
	v_fmac_f32_e32 v184, v181, v22
	v_fmac_f32_e32 v183, v182, v11
	v_fmac_f32_e32 v184, v182, v23
	v_fmac_f32_e32 v179, v126, v16
	v_add_f32_dpp v183, v183, v183 quad_perm:[1,0,3,2] row_mask:0xf bank_mask:0xf bound_ctrl:1
	v_add_f32_dpp v184, v184, v184 quad_perm:[1,0,3,2] row_mask:0xf bank_mask:0xf bound_ctrl:1
	v_fmac_f32_e32 v180, v126, v17
	v_add_f32_dpp v183, v183, v183 quad_perm:[2,3,0,1] row_mask:0xf bank_mask:0xf bound_ctrl:1
	v_add_f32_dpp v184, v184, v184 quad_perm:[2,3,0,1] row_mask:0xf bank_mask:0xf bound_ctrl:1
	v_fmac_f32_e32 v181, v126, v18
	v_add_f32_dpp v183, v183, v183 row_half_mirror row_mask:0xf bank_mask:0xf bound_ctrl:1
	v_add_f32_dpp v184, v184, v184 row_half_mirror row_mask:0xf bank_mask:0xf bound_ctrl:1
	v_fmac_f32_e32 v182, v126, v19
	v_add_f32_dpp v183, v183, v183 row_mirror row_mask:0xf bank_mask:0xf bound_ctrl:1
	v_fmac_f32_e32 v179, v183, v12
	v_fmac_f32_e32 v180, v183, v13
	v_fmac_f32_e32 v181, v183, v14
	v_fmac_f32_e32 v182, v183, v15
	s_mov_b64 exec, s[8:9]
	ds_write_b32 v152, v184 offset:6656
	s_mov_b64 exec, -1
	ds_read_b128 v[8:11], v145 offset:10752
	ds_read_b128 v[12:15], v145 offset:18944
	ds_read_b128 v[16:19], v145 offset:27136
	ds_read_b128 v[20:23], v145 offset:35328
	ds_read_b32 v126, v151 offset:51712
	s_waitcnt lgkmcnt(12)
	v_mul_f32_e32 v183, v179, v28
	v_mul_f32_e32 v184, v179, v40
	v_fmac_f32_e32 v183, v180, v29
	v_fmac_f32_e32 v184, v180, v41
	v_fmac_f32_e32 v183, v181, v30
	v_fmac_f32_e32 v184, v181, v42
	v_fmac_f32_e32 v183, v182, v31
	v_fmac_f32_e32 v184, v182, v43
	v_fmac_f32_e32 v179, v127, v36
	v_add_f32_dpp v183, v183, v183 quad_perm:[1,0,3,2] row_mask:0xf bank_mask:0xf bound_ctrl:1
	v_add_f32_dpp v184, v184, v184 quad_perm:[1,0,3,2] row_mask:0xf bank_mask:0xf bound_ctrl:1
	v_fmac_f32_e32 v180, v127, v37
	v_add_f32_dpp v183, v183, v183 quad_perm:[2,3,0,1] row_mask:0xf bank_mask:0xf bound_ctrl:1
	v_add_f32_dpp v184, v184, v184 quad_perm:[2,3,0,1] row_mask:0xf bank_mask:0xf bound_ctrl:1
	v_fmac_f32_e32 v181, v127, v38
	v_add_f32_dpp v183, v183, v183 row_half_mirror row_mask:0xf bank_mask:0xf bound_ctrl:1
	v_add_f32_dpp v184, v184, v184 row_half_mirror row_mask:0xf bank_mask:0xf bound_ctrl:1
	v_fmac_f32_e32 v182, v127, v39
	v_add_f32_dpp v183, v183, v183 row_mirror row_mask:0xf bank_mask:0xf bound_ctrl:1
	v_fmac_f32_e32 v179, v183, v32
	v_fmac_f32_e32 v180, v183, v33
	v_fmac_f32_e32 v181, v183, v34
	v_fmac_f32_e32 v182, v183, v35
	s_mov_b64 exec, s[8:9]
	ds_write_b32 v152, v184 offset:6144
	s_mov_b64 exec, -1
	ds_read_b128 v[28:31], v145 offset:10496
	ds_read_b128 v[32:35], v145 offset:18688
	ds_read_b128 v[36:39], v145 offset:26880
	ds_read_b128 v[40:43], v145 offset:35072
	ds_read_b32 v127, v151 offset:51456
	s_waitcnt lgkmcnt(12)
	v_mul_f32_e32 v183, v179, v48
	v_mul_f32_e32 v184, v179, v60
	v_fmac_f32_e32 v183, v180, v49
	v_fmac_f32_e32 v184, v180, v61
	v_fmac_f32_e32 v183, v181, v50
	v_fmac_f32_e32 v184, v181, v62
	v_fmac_f32_e32 v183, v182, v51
	v_fmac_f32_e32 v184, v182, v63
	v_fmac_f32_e32 v179, v69, v56
	v_add_f32_dpp v183, v183, v183 quad_perm:[1,0,3,2] row_mask:0xf bank_mask:0xf bound_ctrl:1
	v_add_f32_dpp v184, v184, v184 quad_perm:[1,0,3,2] row_mask:0xf bank_mask:0xf bound_ctrl:1
	v_fmac_f32_e32 v180, v69, v57
	v_add_f32_dpp v183, v183, v183 quad_perm:[2,3,0,1] row_mask:0xf bank_mask:0xf bound_ctrl:1
	v_add_f32_dpp v184, v184, v184 quad_perm:[2,3,0,1] row_mask:0xf bank_mask:0xf bound_ctrl:1
	v_fmac_f32_e32 v181, v69, v58
	v_add_f32_dpp v183, v183, v183 row_half_mirror row_mask:0xf bank_mask:0xf bound_ctrl:1
	v_add_f32_dpp v184, v184, v184 row_half_mirror row_mask:0xf bank_mask:0xf bound_ctrl:1
	v_fmac_f32_e32 v182, v69, v59
	v_add_f32_dpp v183, v183, v183 row_mirror row_mask:0xf bank_mask:0xf bound_ctrl:1
	v_fmac_f32_e32 v179, v183, v52
	v_fmac_f32_e32 v180, v183, v53
	v_fmac_f32_e32 v181, v183, v54
	v_fmac_f32_e32 v182, v183, v55
	s_mov_b64 exec, s[8:9]
	ds_write_b32 v152, v184 offset:5632
	s_mov_b64 exec, -1
	ds_read_b128 v[48:51], v145 offset:10240
	ds_read_b128 v[52:55], v145 offset:18432
	ds_read_b128 v[56:59], v145 offset:26624
	ds_read_b128 v[60:63], v145 offset:34816
	ds_read_b32 v69, v151 offset:51200
	s_waitcnt lgkmcnt(12)
	v_mul_f32_e32 v183, v179, v8
	v_mul_f32_e32 v184, v179, v20
	v_fmac_f32_e32 v183, v180, v9
	v_fmac_f32_e32 v184, v180, v21
	v_fmac_f32_e32 v183, v181, v10
	v_fmac_f32_e32 v184, v181, v22
	v_fmac_f32_e32 v183, v182, v11
	v_fmac_f32_e32 v184, v182, v23
	v_fmac_f32_e32 v179, v126, v16
	v_add_f32_dpp v183, v183, v183 quad_perm:[1,0,3,2] row_mask:0xf bank_mask:0xf bound_ctrl:1
	v_add_f32_dpp v184, v184, v184 quad_perm:[1,0,3,2] row_mask:0xf bank_mask:0xf bound_ctrl:1
	v_fmac_f32_e32 v180, v126, v17
	v_add_f32_dpp v183, v183, v183 quad_perm:[2,3,0,1] row_mask:0xf bank_mask:0xf bound_ctrl:1
	v_add_f32_dpp v184, v184, v184 quad_perm:[2,3,0,1] row_mask:0xf bank_mask:0xf bound_ctrl:1
	v_fmac_f32_e32 v181, v126, v18
	v_add_f32_dpp v183, v183, v183 row_half_mirror row_mask:0xf bank_mask:0xf bound_ctrl:1
	v_add_f32_dpp v184, v184, v184 row_half_mirror row_mask:0xf bank_mask:0xf bound_ctrl:1
	v_fmac_f32_e32 v182, v126, v19
	v_add_f32_dpp v183, v183, v183 row_mirror row_mask:0xf bank_mask:0xf bound_ctrl:1
	v_fmac_f32_e32 v179, v183, v12
	v_fmac_f32_e32 v180, v183, v13
	v_fmac_f32_e32 v181, v183, v14
	v_fmac_f32_e32 v182, v183, v15
	s_mov_b64 exec, s[8:9]
	ds_write_b32 v152, v184 offset:5120
	s_mov_b64 exec, -1
	ds_read_b128 v[8:11], v145 offset:9984
	ds_read_b128 v[12:15], v145 offset:18176
	ds_read_b128 v[16:19], v145 offset:26368
	ds_read_b128 v[20:23], v145 offset:34560
	ds_read_b32 v126, v151 offset:50944
	s_waitcnt lgkmcnt(12)
	v_mul_f32_e32 v183, v179, v28
	v_mul_f32_e32 v184, v179, v40
	v_fmac_f32_e32 v183, v180, v29
	v_fmac_f32_e32 v184, v180, v41
	v_fmac_f32_e32 v183, v181, v30
	v_fmac_f32_e32 v184, v181, v42
	v_fmac_f32_e32 v183, v182, v31
	v_fmac_f32_e32 v184, v182, v43
	v_fmac_f32_e32 v179, v127, v36
	v_add_f32_dpp v183, v183, v183 quad_perm:[1,0,3,2] row_mask:0xf bank_mask:0xf bound_ctrl:1
	v_add_f32_dpp v184, v184, v184 quad_perm:[1,0,3,2] row_mask:0xf bank_mask:0xf bound_ctrl:1
	v_fmac_f32_e32 v180, v127, v37
	v_add_f32_dpp v183, v183, v183 quad_perm:[2,3,0,1] row_mask:0xf bank_mask:0xf bound_ctrl:1
	v_add_f32_dpp v184, v184, v184 quad_perm:[2,3,0,1] row_mask:0xf bank_mask:0xf bound_ctrl:1
	v_fmac_f32_e32 v181, v127, v38
	v_add_f32_dpp v183, v183, v183 row_half_mirror row_mask:0xf bank_mask:0xf bound_ctrl:1
	v_add_f32_dpp v184, v184, v184 row_half_mirror row_mask:0xf bank_mask:0xf bound_ctrl:1
	v_fmac_f32_e32 v182, v127, v39
	v_add_f32_dpp v183, v183, v183 row_mirror row_mask:0xf bank_mask:0xf bound_ctrl:1
	v_fmac_f32_e32 v179, v183, v32
	v_fmac_f32_e32 v180, v183, v33
	v_fmac_f32_e32 v181, v183, v34
	v_fmac_f32_e32 v182, v183, v35
	s_mov_b64 exec, s[8:9]
	ds_write_b32 v152, v184 offset:4608
	s_mov_b64 exec, -1
	ds_read_b128 v[28:31], v145 offset:9728
	ds_read_b128 v[32:35], v145 offset:17920
	ds_read_b128 v[36:39], v145 offset:26112
	ds_read_b128 v[40:43], v145 offset:34304
	ds_read_b32 v127, v151 offset:50688
	s_waitcnt lgkmcnt(12)
	v_mul_f32_e32 v183, v179, v48
	v_mul_f32_e32 v184, v179, v60
	v_fmac_f32_e32 v183, v180, v49
	v_fmac_f32_e32 v184, v180, v61
	v_fmac_f32_e32 v183, v181, v50
	v_fmac_f32_e32 v184, v181, v62
	v_fmac_f32_e32 v183, v182, v51
	v_fmac_f32_e32 v184, v182, v63
	v_fmac_f32_e32 v179, v69, v56
	v_add_f32_dpp v183, v183, v183 quad_perm:[1,0,3,2] row_mask:0xf bank_mask:0xf bound_ctrl:1
	v_add_f32_dpp v184, v184, v184 quad_perm:[1,0,3,2] row_mask:0xf bank_mask:0xf bound_ctrl:1
	v_fmac_f32_e32 v180, v69, v57
	v_add_f32_dpp v183, v183, v183 quad_perm:[2,3,0,1] row_mask:0xf bank_mask:0xf bound_ctrl:1
	v_add_f32_dpp v184, v184, v184 quad_perm:[2,3,0,1] row_mask:0xf bank_mask:0xf bound_ctrl:1
	v_fmac_f32_e32 v181, v69, v58
	v_add_f32_dpp v183, v183, v183 row_half_mirror row_mask:0xf bank_mask:0xf bound_ctrl:1
	v_add_f32_dpp v184, v184, v184 row_half_mirror row_mask:0xf bank_mask:0xf bound_ctrl:1
	v_fmac_f32_e32 v182, v69, v59
	v_add_f32_dpp v183, v183, v183 row_mirror row_mask:0xf bank_mask:0xf bound_ctrl:1
	v_fmac_f32_e32 v179, v183, v52
	v_fmac_f32_e32 v180, v183, v53
	v_fmac_f32_e32 v181, v183, v54
	v_fmac_f32_e32 v182, v183, v55
	s_mov_b64 exec, s[8:9]
	ds_write_b32 v152, v184 offset:4096
	s_mov_b64 exec, -1
	ds_read_b128 v[48:51], v145 offset:9472
	ds_read_b128 v[52:55], v145 offset:17664
	ds_read_b128 v[56:59], v145 offset:25856
	ds_read_b128 v[60:63], v145 offset:34048
	ds_read_b32 v69, v151 offset:50432
	s_waitcnt lgkmcnt(12)
	v_mul_f32_e32 v183, v179, v8
	v_mul_f32_e32 v184, v179, v20
	v_fmac_f32_e32 v183, v180, v9
	v_fmac_f32_e32 v184, v180, v21
	v_fmac_f32_e32 v183, v181, v10
	v_fmac_f32_e32 v184, v181, v22
	v_fmac_f32_e32 v183, v182, v11
	v_fmac_f32_e32 v184, v182, v23
	v_fmac_f32_e32 v179, v126, v16
	v_add_f32_dpp v183, v183, v183 quad_perm:[1,0,3,2] row_mask:0xf bank_mask:0xf bound_ctrl:1
	v_add_f32_dpp v184, v184, v184 quad_perm:[1,0,3,2] row_mask:0xf bank_mask:0xf bound_ctrl:1
	v_fmac_f32_e32 v180, v126, v17
	v_add_f32_dpp v183, v183, v183 quad_perm:[2,3,0,1] row_mask:0xf bank_mask:0xf bound_ctrl:1
	v_add_f32_dpp v184, v184, v184 quad_perm:[2,3,0,1] row_mask:0xf bank_mask:0xf bound_ctrl:1
	v_fmac_f32_e32 v181, v126, v18
	v_add_f32_dpp v183, v183, v183 row_half_mirror row_mask:0xf bank_mask:0xf bound_ctrl:1
	v_add_f32_dpp v184, v184, v184 row_half_mirror row_mask:0xf bank_mask:0xf bound_ctrl:1
	v_fmac_f32_e32 v182, v126, v19
	v_add_f32_dpp v183, v183, v183 row_mirror row_mask:0xf bank_mask:0xf bound_ctrl:1
	v_fmac_f32_e32 v179, v183, v12
	v_fmac_f32_e32 v180, v183, v13
	v_fmac_f32_e32 v181, v183, v14
	v_fmac_f32_e32 v182, v183, v15
	s_mov_b64 exec, s[8:9]
	ds_write_b32 v152, v184 offset:3584
	s_mov_b64 exec, -1
	ds_read_b128 v[8:11], v145 offset:9216
	ds_read_b128 v[12:15], v145 offset:17408
	ds_read_b128 v[16:19], v145 offset:25600
	ds_read_b128 v[20:23], v145 offset:33792
	ds_read_b32 v126, v151 offset:50176
	s_waitcnt lgkmcnt(12)
	v_mul_f32_e32 v183, v179, v28
	v_mul_f32_e32 v184, v179, v40
	v_fmac_f32_e32 v183, v180, v29
	v_fmac_f32_e32 v184, v180, v41
	v_fmac_f32_e32 v183, v181, v30
	v_fmac_f32_e32 v184, v181, v42
	v_fmac_f32_e32 v183, v182, v31
	v_fmac_f32_e32 v184, v182, v43
	v_fmac_f32_e32 v179, v127, v36
	v_add_f32_dpp v183, v183, v183 quad_perm:[1,0,3,2] row_mask:0xf bank_mask:0xf bound_ctrl:1
	v_add_f32_dpp v184, v184, v184 quad_perm:[1,0,3,2] row_mask:0xf bank_mask:0xf bound_ctrl:1
	v_fmac_f32_e32 v180, v127, v37
	v_add_f32_dpp v183, v183, v183 quad_perm:[2,3,0,1] row_mask:0xf bank_mask:0xf bound_ctrl:1
	v_add_f32_dpp v184, v184, v184 quad_perm:[2,3,0,1] row_mask:0xf bank_mask:0xf bound_ctrl:1
	v_fmac_f32_e32 v181, v127, v38
	v_add_f32_dpp v183, v183, v183 row_half_mirror row_mask:0xf bank_mask:0xf bound_ctrl:1
	v_add_f32_dpp v184, v184, v184 row_half_mirror row_mask:0xf bank_mask:0xf bound_ctrl:1
	v_fmac_f32_e32 v182, v127, v39
	v_add_f32_dpp v183, v183, v183 row_mirror row_mask:0xf bank_mask:0xf bound_ctrl:1
	v_fmac_f32_e32 v179, v183, v32
	v_fmac_f32_e32 v180, v183, v33
	v_fmac_f32_e32 v181, v183, v34
	v_fmac_f32_e32 v182, v183, v35
	s_mov_b64 exec, s[8:9]
	ds_write_b32 v152, v184 offset:3072
	s_mov_b64 exec, -1
	ds_read_b128 v[28:31], v145 offset:8960
	ds_read_b128 v[32:35], v145 offset:17152
	ds_read_b128 v[36:39], v145 offset:25344
	ds_read_b128 v[40:43], v145 offset:33536
	ds_read_b32 v127, v151 offset:49920
	s_waitcnt lgkmcnt(12)
	v_mul_f32_e32 v183, v179, v48
	v_mul_f32_e32 v184, v179, v60
	v_fmac_f32_e32 v183, v180, v49
	v_fmac_f32_e32 v184, v180, v61
	v_fmac_f32_e32 v183, v181, v50
	v_fmac_f32_e32 v184, v181, v62
	v_fmac_f32_e32 v183, v182, v51
	v_fmac_f32_e32 v184, v182, v63
	v_fmac_f32_e32 v179, v69, v56
	v_add_f32_dpp v183, v183, v183 quad_perm:[1,0,3,2] row_mask:0xf bank_mask:0xf bound_ctrl:1
	v_add_f32_dpp v184, v184, v184 quad_perm:[1,0,3,2] row_mask:0xf bank_mask:0xf bound_ctrl:1
	v_fmac_f32_e32 v180, v69, v57
	v_add_f32_dpp v183, v183, v183 quad_perm:[2,3,0,1] row_mask:0xf bank_mask:0xf bound_ctrl:1
	v_add_f32_dpp v184, v184, v184 quad_perm:[2,3,0,1] row_mask:0xf bank_mask:0xf bound_ctrl:1
	v_fmac_f32_e32 v181, v69, v58
	v_add_f32_dpp v183, v183, v183 row_half_mirror row_mask:0xf bank_mask:0xf bound_ctrl:1
	v_add_f32_dpp v184, v184, v184 row_half_mirror row_mask:0xf bank_mask:0xf bound_ctrl:1
	v_fmac_f32_e32 v182, v69, v59
	v_add_f32_dpp v183, v183, v183 row_mirror row_mask:0xf bank_mask:0xf bound_ctrl:1
	v_fmac_f32_e32 v179, v183, v52
	v_fmac_f32_e32 v180, v183, v53
	v_fmac_f32_e32 v181, v183, v54
	v_fmac_f32_e32 v182, v183, v55
	s_mov_b64 exec, s[8:9]
	ds_write_b32 v152, v184 offset:2560
	s_mov_b64 exec, -1
	ds_read_b128 v[48:51], v145 offset:8704
	ds_read_b128 v[52:55], v145 offset:16896
	ds_read_b128 v[56:59], v145 offset:25088
	ds_read_b128 v[60:63], v145 offset:33280
	ds_read_b32 v69, v151 offset:49664
	s_waitcnt lgkmcnt(12)
	v_mul_f32_e32 v183, v179, v8
	v_mul_f32_e32 v184, v179, v20
	v_fmac_f32_e32 v183, v180, v9
	v_fmac_f32_e32 v184, v180, v21
	v_fmac_f32_e32 v183, v181, v10
	v_fmac_f32_e32 v184, v181, v22
	v_fmac_f32_e32 v183, v182, v11
	v_fmac_f32_e32 v184, v182, v23
	v_fmac_f32_e32 v179, v126, v16
	v_add_f32_dpp v183, v183, v183 quad_perm:[1,0,3,2] row_mask:0xf bank_mask:0xf bound_ctrl:1
	v_add_f32_dpp v184, v184, v184 quad_perm:[1,0,3,2] row_mask:0xf bank_mask:0xf bound_ctrl:1
	v_fmac_f32_e32 v180, v126, v17
	v_add_f32_dpp v183, v183, v183 quad_perm:[2,3,0,1] row_mask:0xf bank_mask:0xf bound_ctrl:1
	v_add_f32_dpp v184, v184, v184 quad_perm:[2,3,0,1] row_mask:0xf bank_mask:0xf bound_ctrl:1
	v_fmac_f32_e32 v181, v126, v18
	v_add_f32_dpp v183, v183, v183 row_half_mirror row_mask:0xf bank_mask:0xf bound_ctrl:1
	v_add_f32_dpp v184, v184, v184 row_half_mirror row_mask:0xf bank_mask:0xf bound_ctrl:1
	v_fmac_f32_e32 v182, v126, v19
	v_add_f32_dpp v183, v183, v183 row_mirror row_mask:0xf bank_mask:0xf bound_ctrl:1
	v_fmac_f32_e32 v179, v183, v12
	v_fmac_f32_e32 v180, v183, v13
	v_fmac_f32_e32 v181, v183, v14
	v_fmac_f32_e32 v182, v183, v15
	s_mov_b64 exec, s[8:9]
	ds_write_b32 v152, v184 offset:2048
	s_mov_b64 exec, -1
	ds_read_b128 v[8:11], v145 offset:8448
	ds_read_b128 v[12:15], v145 offset:16640
	ds_read_b128 v[16:19], v145 offset:24832
	ds_read_b128 v[20:23], v145 offset:33024
	ds_read_b32 v126, v151 offset:49408
	s_waitcnt lgkmcnt(12)
	v_mul_f32_e32 v183, v179, v28
	v_mul_f32_e32 v184, v179, v40
	v_fmac_f32_e32 v183, v180, v29
	v_fmac_f32_e32 v184, v180, v41
	v_fmac_f32_e32 v183, v181, v30
	v_fmac_f32_e32 v184, v181, v42
	v_fmac_f32_e32 v183, v182, v31
	v_fmac_f32_e32 v184, v182, v43
	v_fmac_f32_e32 v179, v127, v36
	v_add_f32_dpp v183, v183, v183 quad_perm:[1,0,3,2] row_mask:0xf bank_mask:0xf bound_ctrl:1
	v_add_f32_dpp v184, v184, v184 quad_perm:[1,0,3,2] row_mask:0xf bank_mask:0xf bound_ctrl:1
	v_fmac_f32_e32 v180, v127, v37
	v_add_f32_dpp v183, v183, v183 quad_perm:[2,3,0,1] row_mask:0xf bank_mask:0xf bound_ctrl:1
	v_add_f32_dpp v184, v184, v184 quad_perm:[2,3,0,1] row_mask:0xf bank_mask:0xf bound_ctrl:1
	v_fmac_f32_e32 v181, v127, v38
	v_add_f32_dpp v183, v183, v183 row_half_mirror row_mask:0xf bank_mask:0xf bound_ctrl:1
	v_add_f32_dpp v184, v184, v184 row_half_mirror row_mask:0xf bank_mask:0xf bound_ctrl:1
	v_fmac_f32_e32 v182, v127, v39
	v_add_f32_dpp v183, v183, v183 row_mirror row_mask:0xf bank_mask:0xf bound_ctrl:1
	v_fmac_f32_e32 v179, v183, v32
	v_fmac_f32_e32 v180, v183, v33
	v_fmac_f32_e32 v181, v183, v34
	v_fmac_f32_e32 v182, v183, v35
	s_mov_b64 exec, s[8:9]
	ds_write_b32 v152, v184 offset:1536
	s_mov_b64 exec, -1
	ds_read_b128 v[28:31], v145 offset:8192
	ds_read_b128 v[32:35], v145 offset:16384
	ds_read_b128 v[36:39], v145 offset:24576
	ds_read_b128 v[40:43], v145 offset:32768
	ds_read_b32 v127, v151 offset:49152
	s_waitcnt lgkmcnt(12)
	v_mul_f32_e32 v183, v179, v48
	v_mul_f32_e32 v184, v179, v60
	v_fmac_f32_e32 v183, v180, v49
	v_fmac_f32_e32 v184, v180, v61
	v_fmac_f32_e32 v183, v181, v50
	v_fmac_f32_e32 v184, v181, v62
	v_fmac_f32_e32 v183, v182, v51
	v_fmac_f32_e32 v184, v182, v63
	v_fmac_f32_e32 v179, v69, v56
	v_add_f32_dpp v183, v183, v183 quad_perm:[1,0,3,2] row_mask:0xf bank_mask:0xf bound_ctrl:1
	v_add_f32_dpp v184, v184, v184 quad_perm:[1,0,3,2] row_mask:0xf bank_mask:0xf bound_ctrl:1
	v_fmac_f32_e32 v180, v69, v57
	v_add_f32_dpp v183, v183, v183 quad_perm:[2,3,0,1] row_mask:0xf bank_mask:0xf bound_ctrl:1
	v_add_f32_dpp v184, v184, v184 quad_perm:[2,3,0,1] row_mask:0xf bank_mask:0xf bound_ctrl:1
	v_fmac_f32_e32 v181, v69, v58
	v_add_f32_dpp v183, v183, v183 row_half_mirror row_mask:0xf bank_mask:0xf bound_ctrl:1
	v_add_f32_dpp v184, v184, v184 row_half_mirror row_mask:0xf bank_mask:0xf bound_ctrl:1
	v_fmac_f32_e32 v182, v69, v59
	v_add_f32_dpp v183, v183, v183 row_mirror row_mask:0xf bank_mask:0xf bound_ctrl:1
	v_fmac_f32_e32 v179, v183, v52
	v_fmac_f32_e32 v180, v183, v53
	v_fmac_f32_e32 v181, v183, v54
	v_fmac_f32_e32 v182, v183, v55
	s_mov_b64 exec, s[8:9]
	ds_write_b32 v152, v184 offset:1024
	s_mov_b64 exec, -1
	s_waitcnt lgkmcnt(7)
	v_mul_f32_e32 v183, v179, v8
	v_mul_f32_e32 v184, v179, v20
	v_fmac_f32_e32 v183, v180, v9
	v_fmac_f32_e32 v184, v180, v21
	v_fmac_f32_e32 v183, v181, v10
	v_fmac_f32_e32 v184, v181, v22
	v_fmac_f32_e32 v183, v182, v11
	v_fmac_f32_e32 v184, v182, v23
	v_fmac_f32_e32 v179, v126, v16
	v_add_f32_dpp v183, v183, v183 quad_perm:[1,0,3,2] row_mask:0xf bank_mask:0xf bound_ctrl:1
	v_add_f32_dpp v184, v184, v184 quad_perm:[1,0,3,2] row_mask:0xf bank_mask:0xf bound_ctrl:1
	v_fmac_f32_e32 v180, v126, v17
	v_add_f32_dpp v183, v183, v183 quad_perm:[2,3,0,1] row_mask:0xf bank_mask:0xf bound_ctrl:1
	v_add_f32_dpp v184, v184, v184 quad_perm:[2,3,0,1] row_mask:0xf bank_mask:0xf bound_ctrl:1
	v_fmac_f32_e32 v181, v126, v18
	v_add_f32_dpp v183, v183, v183 row_half_mirror row_mask:0xf bank_mask:0xf bound_ctrl:1
	v_add_f32_dpp v184, v184, v184 row_half_mirror row_mask:0xf bank_mask:0xf bound_ctrl:1
	v_fmac_f32_e32 v182, v126, v19
	v_add_f32_dpp v183, v183, v183 row_mirror row_mask:0xf bank_mask:0xf bound_ctrl:1
	v_fmac_f32_e32 v179, v183, v12
	v_fmac_f32_e32 v180, v183, v13
	v_fmac_f32_e32 v181, v183, v14
	v_fmac_f32_e32 v182, v183, v15
	s_mov_b64 exec, s[8:9]
	ds_write_b32 v152, v184 offset:512
	s_mov_b64 exec, -1
	s_waitcnt lgkmcnt(2)
	v_mul_f32_e32 v183, v179, v28
	v_mul_f32_e32 v184, v179, v40
	v_fmac_f32_e32 v183, v180, v29
	v_fmac_f32_e32 v184, v180, v41
	v_fmac_f32_e32 v183, v181, v30
	v_fmac_f32_e32 v184, v181, v42
	v_fmac_f32_e32 v183, v182, v31
	v_fmac_f32_e32 v184, v182, v43
	v_fmac_f32_e32 v179, v127, v36
	v_add_f32_dpp v183, v183, v183 quad_perm:[1,0,3,2] row_mask:0xf bank_mask:0xf bound_ctrl:1
	v_add_f32_dpp v184, v184, v184 quad_perm:[1,0,3,2] row_mask:0xf bank_mask:0xf bound_ctrl:1
	v_fmac_f32_e32 v180, v127, v37
	v_add_f32_dpp v183, v183, v183 quad_perm:[2,3,0,1] row_mask:0xf bank_mask:0xf bound_ctrl:1
	v_add_f32_dpp v184, v184, v184 quad_perm:[2,3,0,1] row_mask:0xf bank_mask:0xf bound_ctrl:1
	v_fmac_f32_e32 v181, v127, v38
	v_add_f32_dpp v183, v183, v183 row_half_mirror row_mask:0xf bank_mask:0xf bound_ctrl:1
	v_add_f32_dpp v184, v184, v184 row_half_mirror row_mask:0xf bank_mask:0xf bound_ctrl:1
	v_fmac_f32_e32 v182, v127, v39
	v_add_f32_dpp v183, v183, v183 row_mirror row_mask:0xf bank_mask:0xf bound_ctrl:1
	v_fmac_f32_e32 v179, v183, v32
	v_fmac_f32_e32 v180, v183, v33
	v_fmac_f32_e32 v181, v183, v34
	v_fmac_f32_e32 v182, v183, v35
	s_mov_b64 exec, s[8:9]
	ds_write_b32 v152, v184
	s_mov_b64 exec, -1
	ds_read_b128 v[4:7], v145 offset:57344
	s_waitcnt lgkmcnt(0)
	v_mul_f32_e32 v179, v179, v4
	v_mul_f32_e32 v180, v180, v5
	v_mul_f32_e32 v181, v181, v6
	v_mul_f32_e32 v182, v182, v7
	s_waitcnt lgkmcnt(0)
	s_barrier
	s_and_saveexec_b64 s[12:13], s[10:11]
	s_cbranch_execz .LBB0_265
	ds_read_b128 v[4:7], v153
	ds_read_b128 v[8:11], v153 offset:256
	s_waitcnt lgkmcnt(0)
	v_pk_add_f32 v[10:11], v[6:7], v[10:11]
	v_pk_add_f32 v[8:9], v[4:5], v[8:9]
	ds_read_b128 v[4:7], v150
	s_waitcnt lgkmcnt(0)
	v_pk_add_f32 v[6:7], v[10:11], v[6:7]
	v_pk_add_f32 v[4:5], v[8:9], v[4:5]
	s_nop 0
	v_cvt_pk_bf16_f32 v4, v4, v5
	v_cvt_pk_bf16_f32 v5, v6, v7
	v_lshlrev_b64 v[6:7], 11, v[124:125]
	v_lshl_add_u64 v[6:7], v[106:107], 0, v[6:7]
	global_store_dwordx2 v[6:7], v[4:5], off
	s_branch .LBB0_265

.LBB0_376:
	s_andn2_b64 vcc, exec, s[10:11]
	s_cbranch_vccnz .LBB0_378
	v_mul_f32_e32 v4, 0xbf60028a, v4
	v_mul_f32_e32 v5, 0xbf60028a, v5
	v_exp_f32_e32 v4, v4
	v_exp_f32_e32 v5, v5
	v_mul_f32_e32 v6, 0xbf60028a, v6
	v_mul_f32_e32 v7, 0xbf60028a, v7
	v_exp_f32_e32 v6, v6
	v_exp_f32_e32 v7, v7
	v_mul_f32_e32 v8, 0xbf60028a, v8
	v_mul_f32_e32 v9, 0xbf60028a, v9
	v_exp_f32_e32 v8, v8
	v_exp_f32_e32 v9, v9
	v_mul_f32_e32 v10, 0xbf60028a, v10
	v_mul_f32_e32 v11, 0xbf60028a, v11
	v_exp_f32_e32 v10, v10
	v_exp_f32_e32 v11, v11
	s_nop 1
	v_mul_f32_e32 v198, v4, v5
	v_mul_f32_e32 v201, v8, v9
	v_mul_f32_e32 v199, v198, v6
	v_mul_f32_e32 v202, v201, v10
	v_mul_f32_e32 v200, v199, v7
	v_mul_f32_e32 v203, v202, v11
	v_mbcnt_lo_u32_b32 v204, -1, 0
	v_mbcnt_hi_u32_b32 v204, -1, v204
	v_and_b32_e32 v205, 15, v204
	v_lshlrev_b32_e32 v205, 2, v205
	v_add_u32_e32 v206, 64, v205
	v_add_u32_e32 v207, 128, v205
	v_add_u32_e32 v208, 192, v205
	v_mov_b32_e32 v217, 1.0
	ds_bpermute_b32 v209, v205, v200
	ds_bpermute_b32 v210, v206, v200
	ds_bpermute_b32 v211, v207, v200
	ds_bpermute_b32 v212, v208, v200
	ds_bpermute_b32 v213, v205, v203
	ds_bpermute_b32 v214, v206, v203
	ds_bpermute_b32 v215, v207, v203
	ds_bpermute_b32 v216, v208, v203
	s_waitcnt lgkmcnt(0)
	v_cmp_lt_u32_e32 vcc, 15, v204
	v_cndmask_b32_e32 v218, v217, v209, vcc
	v_cndmask_b32_e32 v221, v217, v213, vcc
	v_cmp_lt_u32_e32 vcc, 31, v204
	v_cndmask_b32_e32 v219, v217, v210, vcc
	v_cndmask_b32_e32 v222, v217, v214, vcc
	v_cmp_lt_u32_e32 vcc, 47, v204
	v_cndmask_b32_e32 v220, v217, v211, vcc
	v_cndmask_b32_e32 v223, v217, v215, vcc
	v_mul_f32_e32 v224, v218, v219
	v_mul_f32_e32 v225, v221, v222
	v_mul_f32_e32 v226, v209, v210
	v_mul_f32_e32 v224, v224, v220
	v_mul_f32_e32 v225, v225, v223
	v_mul_f32_e32 v226, v226, v211
	v_mul_f32_e32 v226, v226, v212
	v_mul_f32_e32 v225, v225, v226
	v_mul_f32_e32 v230, v4, v224
	v_mul_f32_e32 v231, v198, v224
	v_mul_f32_e32 v232, v199, v224
	v_mul_f32_e32 v233, v200, v224
	v_mul_f32_e32 v234, v8, v225
	v_mul_f32_e32 v235, v201, v225
	v_mul_f32_e32 v236, v202, v225
	v_mul_f32_e32 v237, v203, v225
	ds_write2st64_b32 v129, v230, v231 offset0:224 offset1:225
	ds_write2st64_b32 v129, v232, v233 offset0:226 offset1:227
	ds_write2st64_b32 v129, v234, v235 offset0:240 offset1:241
	ds_write2st64_b32 v129, v236, v237 offset0:242 offset1:243
	s_waitcnt lgkmcnt(7)
	v_mul_f32_e32 v15, v29, v4
	ds_write2st64_b32 v129, v4, v5 offset1:1
	s_waitcnt lgkmcnt(7)
	v_mul_f32_e32 v4, v28, v5
	ds_write2st64_b32 v129, v15, v4 offset0:128 offset1:129
	s_waitcnt lgkmcnt(7)
	v_mul_f32_e32 v4, v26, v6
	s_waitcnt lgkmcnt(6)
	v_mul_f32_e32 v5, v25, v7
	ds_write2st64_b32 v129, v4, v5 offset0:130 offset1:131
	s_waitcnt lgkmcnt(6)
	v_mul_f32_e32 v4, v24, v8
	s_waitcnt lgkmcnt(5)
	v_mul_f32_e32 v5, v14, v9
	ds_write2st64_b32 v129, v4, v5 offset0:144 offset1:145
	s_waitcnt lgkmcnt(5)
	v_mul_f32_e32 v4, v13, v10
	s_waitcnt lgkmcnt(4)
	v_mul_f32_e32 v5, v12, v11
	ds_write2st64_b32 v129, v6, v7 offset0:2 offset1:3
	ds_write2st64_b32 v129, v8, v9 offset0:16 offset1:17
	ds_write2st64_b32 v129, v10, v11 offset0:18 offset1:19
	ds_write2st64_b32 v129, v4, v5 offset0:146 offset1:147

.LBB0_380:
	s_or_b64 exec, exec, s[10:11]
	v_add_u32_e32 v227, 0xffffff00, v143
	ds_read_b128 v[198:201], v143 offset:57344
	ds_read_b128 v[202:205], v227 offset:57344
	ds_read_b128 v[206:209], v143 offset:8192
	ds_read_b128 v[210:213], v143 offset:16384
	ds_read_b128 v[214:217], v143 offset:24576
	ds_read_b128 v[218:221], v143 offset:32768
	v_mov_b32_e32 v226, 1.0
	v_cmp_gt_u32_e32 vcc, 16, v134
	s_waitcnt lgkmcnt(4)
	v_rcp_f32_e32 v222, v198
	v_rcp_f32_e32 v223, v199
	v_rcp_f32_e32 v224, v200
	v_rcp_f32_e32 v225, v201
	v_cndmask_b32_e32 v202, v202, v226, vcc
	v_cndmask_b32_e32 v203, v203, v226, vcc
	v_cndmask_b32_e32 v204, v204, v226, vcc
	v_cndmask_b32_e32 v205, v205, v226, vcc
	s_waitcnt lgkmcnt(0)
	v_mul_f32_e32 v206, v206, v202
	v_mul_f32_e32 v207, v207, v203
	v_mul_f32_e32 v208, v208, v204
	v_mul_f32_e32 v209, v209, v205
	v_mul_f32_e32 v218, v218, v202
	v_mul_f32_e32 v219, v219, v203
	v_mul_f32_e32 v220, v220, v204
	v_mul_f32_e32 v221, v221, v205
	v_mul_f32_e32 v210, v210, v222
	v_mul_f32_e32 v211, v211, v223
	v_mul_f32_e32 v212, v212, v224
	v_mul_f32_e32 v213, v213, v225
	v_mul_f32_e32 v214, v214, v222
	v_mul_f32_e32 v215, v215, v223
	v_mul_f32_e32 v216, v216, v224
	v_mul_f32_e32 v217, v217, v225
	ds_write_b128 v143, v[206:209] offset:8192
	ds_write_b128 v143, v[218:221] offset:32768
	ds_write_b128 v143, v[210:213] offset:16384
	ds_write_b128 v143, v[214:217] offset:24576
	s_waitcnt lgkmcnt(0)
	s_barrier
	v_mbcnt_lo_u32_b32 v177, -1, 0
	v_mbcnt_hi_u32_b32 v177, -1, v177
	v_lshlrev_b32_e32 v177, 2, v177
	v_add_u32_e32 v177, 0xe000, v177
	v_cndmask_b32_e64 v176, v177, v149, s[6:7]
	ds_read_b128 v[8:11], v142 offset:8192
	ds_read_b128 v[12:15], v142 offset:16384
	ds_read_b128 v[16:19], v142 offset:24576
	ds_read_b128 v[20:23], v142 offset:32768
	ds_read_b32 v122, v148 offset:49152
	ds_read_b128 v[28:31], v142 offset:8448
	ds_read_b128 v[32:35], v142 offset:16640
	ds_read_b128 v[36:39], v142 offset:24832
	ds_read_b128 v[40:43], v142 offset:33024
	ds_read_b32 v123, v148 offset:49408
	ds_read_b128 v[48:51], v142 offset:8704
	ds_read_b128 v[52:55], v142 offset:16896
	ds_read_b128 v[56:59], v142 offset:25088
	ds_read_b128 v[60:63], v142 offset:33280
	ds_read_b32 v65, v148 offset:49664
	s_waitcnt lgkmcnt(10)
	v_mul_f32_e32 v174, v170, v8
	v_mul_f32_e32 v175, v170, v20
	v_fmac_f32_e32 v174, v171, v9
	v_fmac_f32_e32 v175, v171, v21
	v_fmac_f32_e32 v174, v172, v10
	v_fmac_f32_e32 v175, v172, v22
	v_fmac_f32_e32 v174, v173, v11
	v_fmac_f32_e32 v175, v173, v23
	v_fmac_f32_e32 v170, v122, v16
	v_add_f32_dpp v174, v174, v174 quad_perm:[1,0,3,2] row_mask:0xf bank_mask:0xf bound_ctrl:1
	v_add_f32_dpp v175, v175, v175 quad_perm:[1,0,3,2] row_mask:0xf bank_mask:0xf bound_ctrl:1
	v_fmac_f32_e32 v171, v122, v17
	v_add_f32_dpp v174, v174, v174 quad_perm:[2,3,0,1] row_mask:0xf bank_mask:0xf bound_ctrl:1
	v_add_f32_dpp v175, v175, v175 quad_perm:[2,3,0,1] row_mask:0xf bank_mask:0xf bound_ctrl:1
	v_fmac_f32_e32 v172, v122, v18
	v_add_f32_dpp v174, v174, v174 row_half_mirror row_mask:0xf bank_mask:0xf bound_ctrl:1
	v_add_f32_dpp v175, v175, v175 row_half_mirror row_mask:0xf bank_mask:0xf bound_ctrl:1
	v_fmac_f32_e32 v173, v122, v19
	v_add_f32_dpp v174, v174, v174 row_mirror row_mask:0xf bank_mask:0xf bound_ctrl:1
	v_fmac_f32_e32 v170, v174, v12
	v_fmac_f32_e32 v171, v174, v13
	v_fmac_f32_e32 v172, v174, v14
	v_fmac_f32_e32 v173, v174, v15
	s_mov_b64 exec, s[6:7]
	ds_write_b32 v149, v175
	s_mov_b64 exec, -1
	ds_read_b128 v[8:11], v142 offset:8960
	ds_read_b128 v[12:15], v142 offset:17152
	ds_read_b128 v[16:19], v142 offset:25344
	ds_read_b128 v[20:23], v142 offset:33536
	ds_read_b32 v122, v148 offset:49920
	s_waitcnt lgkmcnt(11)
	v_mul_f32_e32 v174, v170, v28
	v_mul_f32_e32 v175, v170, v40
	v_fmac_f32_e32 v174, v171, v29
	v_fmac_f32_e32 v175, v171, v41
	v_fmac_f32_e32 v174, v172, v30
	v_fmac_f32_e32 v175, v172, v42
	v_fmac_f32_e32 v174, v173, v31
	v_fmac_f32_e32 v175, v173, v43
	v_fmac_f32_e32 v170, v123, v36
	v_add_f32_dpp v174, v174, v174 quad_perm:[1,0,3,2] row_mask:0xf bank_mask:0xf bound_ctrl:1
	v_add_f32_dpp v175, v175, v175 quad_perm:[1,0,3,2] row_mask:0xf bank_mask:0xf bound_ctrl:1
	v_fmac_f32_e32 v171, v123, v37
	v_add_f32_dpp v174, v174, v174 quad_perm:[2,3,0,1] row_mask:0xf bank_mask:0xf bound_ctrl:1
	v_add_f32_dpp v175, v175, v175 quad_perm:[2,3,0,1] row_mask:0xf bank_mask:0xf bound_ctrl:1
	v_fmac_f32_e32 v172, v123, v38
	v_add_f32_dpp v174, v174, v174 row_half_mirror row_mask:0xf bank_mask:0xf bound_ctrl:1
	v_add_f32_dpp v175, v175, v175 row_half_mirror row_mask:0xf bank_mask:0xf bound_ctrl:1
	v_fmac_f32_e32 v173, v123, v39
	v_add_f32_dpp v174, v174, v174 row_mirror row_mask:0xf bank_mask:0xf bound_ctrl:1
	v_fmac_f32_e32 v170, v174, v32
	v_fmac_f32_e32 v171, v174, v33
	v_fmac_f32_e32 v172, v174, v34
	v_fmac_f32_e32 v173, v174, v35
	s_mov_b64 exec, s[6:7]
	ds_write_b32 v149, v175 offset:512
	s_mov_b64 exec, -1
	ds_read_b128 v[28:31], v142 offset:9216
	ds_read_b128 v[32:35], v142 offset:17408
	ds_read_b128 v[36:39], v142 offset:25600
	ds_read_b128 v[40:43], v142 offset:33792
	ds_read_b32 v123, v148 offset:50176
	s_waitcnt lgkmcnt(12)
	v_mul_f32_e32 v174, v170, v48
	v_mul_f32_e32 v175, v170, v60
	v_fmac_f32_e32 v174, v171, v49
	v_fmac_f32_e32 v175, v171, v61
	v_fmac_f32_e32 v174, v172, v50
	v_fmac_f32_e32 v175, v172, v62
	v_fmac_f32_e32 v174, v173, v51
	v_fmac_f32_e32 v175, v173, v63
	v_fmac_f32_e32 v170, v65, v56
	v_add_f32_dpp v174, v174, v174 quad_perm:[1,0,3,2] row_mask:0xf bank_mask:0xf bound_ctrl:1
	v_add_f32_dpp v175, v175, v175 quad_perm:[1,0,3,2] row_mask:0xf bank_mask:0xf bound_ctrl:1
	v_fmac_f32_e32 v171, v65, v57
	v_add_f32_dpp v174, v174, v174 quad_perm:[2,3,0,1] row_mask:0xf bank_mask:0xf bound_ctrl:1
	v_add_f32_dpp v175, v175, v175 quad_perm:[2,3,0,1] row_mask:0xf bank_mask:0xf bound_ctrl:1
	v_fmac_f32_e32 v172, v65, v58
	v_add_f32_dpp v174, v174, v174 row_half_mirror row_mask:0xf bank_mask:0xf bound_ctrl:1
	v_add_f32_dpp v175, v175, v175 row_half_mirror row_mask:0xf bank_mask:0xf bound_ctrl:1
	v_fmac_f32_e32 v173, v65, v59
	v_add_f32_dpp v174, v174, v174 row_mirror row_mask:0xf bank_mask:0xf bound_ctrl:1
	v_fmac_f32_e32 v170, v174, v52
	v_fmac_f32_e32 v171, v174, v53
	v_fmac_f32_e32 v172, v174, v54
	v_fmac_f32_e32 v173, v174, v55
	s_mov_b64 exec, s[6:7]
	ds_write_b32 v149, v175 offset:1024
	s_mov_b64 exec, -1
	ds_read_b128 v[48:51], v142 offset:9472
	ds_read_b128 v[52:55], v142 offset:17664
	ds_read_b128 v[56:59], v142 offset:25856
	ds_read_b128 v[60:63], v142 offset:34048
	ds_read_b32 v65, v148 offset:50432
	s_waitcnt lgkmcnt(12)
	v_mul_f32_e32 v174, v170, v8
	v_mul_f32_e32 v175, v170, v20
	v_fmac_f32_e32 v174, v171, v9
	v_fmac_f32_e32 v175, v171, v21
	v_fmac_f32_e32 v174, v172, v10
	v_fmac_f32_e32 v175, v172, v22
	v_fmac_f32_e32 v174, v173, v11
	v_fmac_f32_e32 v175, v173, v23
	v_fmac_f32_e32 v170, v122, v16
	v_add_f32_dpp v174, v174, v174 quad_perm:[1,0,3,2] row_mask:0xf bank_mask:0xf bound_ctrl:1
	v_add_f32_dpp v175, v175, v175 quad_perm:[1,0,3,2] row_mask:0xf bank_mask:0xf bound_ctrl:1
	v_fmac_f32_e32 v171, v122, v17
	v_add_f32_dpp v174, v174, v174 quad_perm:[2,3,0,1] row_mask:0xf bank_mask:0xf bound_ctrl:1
	v_add_f32_dpp v175, v175, v175 quad_perm:[2,3,0,1] row_mask:0xf bank_mask:0xf bound_ctrl:1
	v_fmac_f32_e32 v172, v122, v18
	v_add_f32_dpp v174, v174, v174 row_half_mirror row_mask:0xf bank_mask:0xf bound_ctrl:1
	v_add_f32_dpp v175, v175, v175 row_half_mirror row_mask:0xf bank_mask:0xf bound_ctrl:1
	v_fmac_f32_e32 v173, v122, v19
	v_add_f32_dpp v174, v174, v174 row_mirror row_mask:0xf bank_mask:0xf bound_ctrl:1
	v_fmac_f32_e32 v170, v174, v12
	v_fmac_f32_e32 v171, v174, v13
	v_fmac_f32_e32 v172, v174, v14
	v_fmac_f32_e32 v173, v174, v15
	s_mov_b64 exec, s[6:7]
	ds_write_b32 v149, v175 offset:1536
	s_mov_b64 exec, -1
	ds_read_b128 v[8:11], v142 offset:9728
	ds_read_b128 v[12:15], v142 offset:17920
	ds_read_b128 v[16:19], v142 offset:26112
	ds_read_b128 v[20:23], v142 offset:34304
	ds_read_b32 v122, v148 offset:50688
	s_waitcnt lgkmcnt(12)
	v_mul_f32_e32 v174, v170, v28
	v_mul_f32_e32 v175, v170, v40
	v_fmac_f32_e32 v174, v171, v29
	v_fmac_f32_e32 v175, v171, v41
	v_fmac_f32_e32 v174, v172, v30
	v_fmac_f32_e32 v175, v172, v42
	v_fmac_f32_e32 v174, v173, v31
	v_fmac_f32_e32 v175, v173, v43
	v_fmac_f32_e32 v170, v123, v36
	v_add_f32_dpp v174, v174, v174 quad_perm:[1,0,3,2] row_mask:0xf bank_mask:0xf bound_ctrl:1
	v_add_f32_dpp v175, v175, v175 quad_perm:[1,0,3,2] row_mask:0xf bank_mask:0xf bound_ctrl:1
	v_fmac_f32_e32 v171, v123, v37
	v_add_f32_dpp v174, v174, v174 quad_perm:[2,3,0,1] row_mask:0xf bank_mask:0xf bound_ctrl:1
	v_add_f32_dpp v175, v175, v175 quad_perm:[2,3,0,1] row_mask:0xf bank_mask:0xf bound_ctrl:1
	v_fmac_f32_e32 v172, v123, v38
	v_add_f32_dpp v174, v174, v174 row_half_mirror row_mask:0xf bank_mask:0xf bound_ctrl:1
	v_add_f32_dpp v175, v175, v175 row_half_mirror row_mask:0xf bank_mask:0xf bound_ctrl:1
	v_fmac_f32_e32 v173, v123, v39
	v_add_f32_dpp v174, v174, v174 row_mirror row_mask:0xf bank_mask:0xf bound_ctrl:1
	v_fmac_f32_e32 v170, v174, v32
	v_fmac_f32_e32 v171, v174, v33
	v_fmac_f32_e32 v172, v174, v34
	v_fmac_f32_e32 v173, v174, v35
	s_mov_b64 exec, s[6:7]
	ds_write_b32 v149, v175 offset:2048
	s_mov_b64 exec, -1
	ds_read_b128 v[28:31], v142 offset:9984
	ds_read_b128 v[32:35], v142 offset:18176
	ds_read_b128 v[36:39], v142 offset:26368
	ds_read_b128 v[40:43], v142 offset:34560
	ds_read_b32 v123, v148 offset:50944
	s_waitcnt lgkmcnt(12)
	v_mul_f32_e32 v174, v170, v48
	v_mul_f32_e32 v175, v170, v60
	v_fmac_f32_e32 v174, v171, v49
	v_fmac_f32_e32 v175, v171, v61
	v_fmac_f32_e32 v174, v172, v50
	v_fmac_f32_e32 v175, v172, v62
	v_fmac_f32_e32 v174, v173, v51
	v_fmac_f32_e32 v175, v173, v63
	v_fmac_f32_e32 v170, v65, v56
	v_add_f32_dpp v174, v174, v174 quad_perm:[1,0,3,2] row_mask:0xf bank_mask:0xf bound_ctrl:1
	v_add_f32_dpp v175, v175, v175 quad_perm:[1,0,3,2] row_mask:0xf bank_mask:0xf bound_ctrl:1
	v_fmac_f32_e32 v171, v65, v57
	v_add_f32_dpp v174, v174, v174 quad_perm:[2,3,0,1] row_mask:0xf bank_mask:0xf bound_ctrl:1
	v_add_f32_dpp v175, v175, v175 quad_perm:[2,3,0,1] row_mask:0xf bank_mask:0xf bound_ctrl:1
	v_fmac_f32_e32 v172, v65, v58
	v_add_f32_dpp v174, v174, v174 row_half_mirror row_mask:0xf bank_mask:0xf bound_ctrl:1
	v_add_f32_dpp v175, v175, v175 row_half_mirror row_mask:0xf bank_mask:0xf bound_ctrl:1
	v_fmac_f32_e32 v173, v65, v59
	v_add_f32_dpp v174, v174, v174 row_mirror row_mask:0xf bank_mask:0xf bound_ctrl:1
	v_fmac_f32_e32 v170, v174, v52
	v_fmac_f32_e32 v171, v174, v53
	v_fmac_f32_e32 v172, v174, v54
	v_fmac_f32_e32 v173, v174, v55
	s_mov_b64 exec, s[6:7]
	ds_write_b32 v149, v175 offset:2560
	s_mov_b64 exec, -1
	ds_read_b128 v[48:51], v142 offset:10240
	ds_read_b128 v[52:55], v142 offset:18432
	ds_read_b128 v[56:59], v142 offset:26624
	ds_read_b128 v[60:63], v142 offset:34816
	ds_read_b32 v65, v148 offset:51200
	s_waitcnt lgkmcnt(12)
	v_mul_f32_e32 v174, v170, v8
	v_mul_f32_e32 v175, v170, v20
	v_fmac_f32_e32 v174, v171, v9
	v_fmac_f32_e32 v175, v171, v21
	v_fmac_f32_e32 v174, v172, v10
	v_fmac_f32_e32 v175, v172, v22
	v_fmac_f32_e32 v174, v173, v11
	v_fmac_f32_e32 v175, v173, v23
	v_fmac_f32_e32 v170, v122, v16
	v_add_f32_dpp v174, v174, v174 quad_perm:[1,0,3,2] row_mask:0xf bank_mask:0xf bound_ctrl:1
	v_add_f32_dpp v175, v175, v175 quad_perm:[1,0,3,2] row_mask:0xf bank_mask:0xf bound_ctrl:1
	v_fmac_f32_e32 v171, v122, v17
	v_add_f32_dpp v174, v174, v174 quad_perm:[2,3,0,1] row_mask:0xf bank_mask:0xf bound_ctrl:1
	v_add_f32_dpp v175, v175, v175 quad_perm:[2,3,0,1] row_mask:0xf bank_mask:0xf bound_ctrl:1
	v_fmac_f32_e32 v172, v122, v18
	v_add_f32_dpp v174, v174, v174 row_half_mirror row_mask:0xf bank_mask:0xf bound_ctrl:1
	v_add_f32_dpp v175, v175, v175 row_half_mirror row_mask:0xf bank_mask:0xf bound_ctrl:1
	v_fmac_f32_e32 v173, v122, v19
	v_add_f32_dpp v174, v174, v174 row_mirror row_mask:0xf bank_mask:0xf bound_ctrl:1
	v_fmac_f32_e32 v170, v174, v12
	v_fmac_f32_e32 v171, v174, v13
	v_fmac_f32_e32 v172, v174, v14
	v_fmac_f32_e32 v173, v174, v15
	s_mov_b64 exec, s[6:7]
	ds_write_b32 v149, v175 offset:3072
	s_mov_b64 exec, -1
	ds_read_b128 v[8:11], v142 offset:10496
	ds_read_b128 v[12:15], v142 offset:18688
	ds_read_b128 v[16:19], v142 offset:26880
	ds_read_b128 v[20:23], v142 offset:35072
	ds_read_b32 v122, v148 offset:51456
	s_waitcnt lgkmcnt(12)
	v_mul_f32_e32 v174, v170, v28
	v_mul_f32_e32 v175, v170, v40
	v_fmac_f32_e32 v174, v171, v29
	v_fmac_f32_e32 v175, v171, v41
	v_fmac_f32_e32 v174, v172, v30
	v_fmac_f32_e32 v175, v172, v42
	v_fmac_f32_e32 v174, v173, v31
	v_fmac_f32_e32 v175, v173, v43
	v_fmac_f32_e32 v170, v123, v36
	v_add_f32_dpp v174, v174, v174 quad_perm:[1,0,3,2] row_mask:0xf bank_mask:0xf bound_ctrl:1
	v_add_f32_dpp v175, v175, v175 quad_perm:[1,0,3,2] row_mask:0xf bank_mask:0xf bound_ctrl:1
	v_fmac_f32_e32 v171, v123, v37
	v_add_f32_dpp v174, v174, v174 quad_perm:[2,3,0,1] row_mask:0xf bank_mask:0xf bound_ctrl:1
	v_add_f32_dpp v175, v175, v175 quad_perm:[2,3,0,1] row_mask:0xf bank_mask:0xf bound_ctrl:1
	v_fmac_f32_e32 v172, v123, v38
	v_add_f32_dpp v174, v174, v174 row_half_mirror row_mask:0xf bank_mask:0xf bound_ctrl:1
	v_add_f32_dpp v175, v175, v175 row_half_mirror row_mask:0xf bank_mask:0xf bound_ctrl:1
	v_fmac_f32_e32 v173, v123, v39
	v_add_f32_dpp v174, v174, v174 row_mirror row_mask:0xf bank_mask:0xf bound_ctrl:1
	v_fmac_f32_e32 v170, v174, v32
	v_fmac_f32_e32 v171, v174, v33
	v_fmac_f32_e32 v172, v174, v34
	v_fmac_f32_e32 v173, v174, v35
	s_mov_b64 exec, s[6:7]
	ds_write_b32 v149, v175 offset:3584
	s_mov_b64 exec, -1
	ds_read_b128 v[28:31], v142 offset:10752
	ds_read_b128 v[32:35], v142 offset:18944
	ds_read_b128 v[36:39], v142 offset:27136
	ds_read_b128 v[40:43], v142 offset:35328
	ds_read_b32 v123, v148 offset:51712
	s_waitcnt lgkmcnt(12)
	v_mul_f32_e32 v174, v170, v48
	v_mul_f32_e32 v175, v170, v60
	v_fmac_f32_e32 v174, v171, v49
	v_fmac_f32_e32 v175, v171, v61
	v_fmac_f32_e32 v174, v172, v50
	v_fmac_f32_e32 v175, v172, v62
	v_fmac_f32_e32 v174, v173, v51
	v_fmac_f32_e32 v175, v173, v63
	v_fmac_f32_e32 v170, v65, v56
	v_add_f32_dpp v174, v174, v174 quad_perm:[1,0,3,2] row_mask:0xf bank_mask:0xf bound_ctrl:1
	v_add_f32_dpp v175, v175, v175 quad_perm:[1,0,3,2] row_mask:0xf bank_mask:0xf bound_ctrl:1
	v_fmac_f32_e32 v171, v65, v57
	v_add_f32_dpp v174, v174, v174 quad_perm:[2,3,0,1] row_mask:0xf bank_mask:0xf bound_ctrl:1
	v_add_f32_dpp v175, v175, v175 quad_perm:[2,3,0,1] row_mask:0xf bank_mask:0xf bound_ctrl:1
	v_fmac_f32_e32 v172, v65, v58
	v_add_f32_dpp v174, v174, v174 row_half_mirror row_mask:0xf bank_mask:0xf bound_ctrl:1
	v_add_f32_dpp v175, v175, v175 row_half_mirror row_mask:0xf bank_mask:0xf bound_ctrl:1
	v_fmac_f32_e32 v173, v65, v59
	v_add_f32_dpp v174, v174, v174 row_mirror row_mask:0xf bank_mask:0xf bound_ctrl:1
	v_fmac_f32_e32 v170, v174, v52
	v_fmac_f32_e32 v171, v174, v53
	v_fmac_f32_e32 v172, v174, v54
	v_fmac_f32_e32 v173, v174, v55
	s_mov_b64 exec, s[6:7]
	ds_write_b32 v149, v175 offset:4096
	s_mov_b64 exec, -1
	ds_read_b128 v[48:51], v142 offset:11008
	ds_read_b128 v[52:55], v142 offset:19200
	ds_read_b128 v[56:59], v142 offset:27392
	ds_read_b128 v[60:63], v142 offset:35584
	ds_read_b32 v65, v148 offset:51968
	s_waitcnt lgkmcnt(12)
	v_mul_f32_e32 v174, v170, v8
	v_mul_f32_e32 v175, v170, v20
	v_fmac_f32_e32 v174, v171, v9
	v_fmac_f32_e32 v175, v171, v21
	v_fmac_f32_e32 v174, v172, v10
	v_fmac_f32_e32 v175, v172, v22
	v_fmac_f32_e32 v174, v173, v11
	v_fmac_f32_e32 v175, v173, v23
	v_fmac_f32_e32 v170, v122, v16
	v_add_f32_dpp v174, v174, v174 quad_perm:[1,0,3,2] row_mask:0xf bank_mask:0xf bound_ctrl:1
	v_add_f32_dpp v175, v175, v175 quad_perm:[1,0,3,2] row_mask:0xf bank_mask:0xf bound_ctrl:1
	v_fmac_f32_e32 v171, v122, v17
	v_add_f32_dpp v174, v174, v174 quad_perm:[2,3,0,1] row_mask:0xf bank_mask:0xf bound_ctrl:1
	v_add_f32_dpp v175, v175, v175 quad_perm:[2,3,0,1] row_mask:0xf bank_mask:0xf bound_ctrl:1
	v_fmac_f32_e32 v172, v122, v18
	v_add_f32_dpp v174, v174, v174 row_half_mirror row_mask:0xf bank_mask:0xf bound_ctrl:1
	v_add_f32_dpp v175, v175, v175 row_half_mirror row_mask:0xf bank_mask:0xf bound_ctrl:1
	v_fmac_f32_e32 v173, v122, v19
	v_add_f32_dpp v174, v174, v174 row_mirror row_mask:0xf bank_mask:0xf bound_ctrl:1
	v_fmac_f32_e32 v170, v174, v12
	v_fmac_f32_e32 v171, v174, v13
	v_fmac_f32_e32 v172, v174, v14
	v_fmac_f32_e32 v173, v174, v15
	s_mov_b64 exec, s[6:7]
	ds_write_b32 v149, v175 offset:4608
	s_mov_b64 exec, -1
	ds_read_b128 v[8:11], v142 offset:11264
	ds_read_b128 v[12:15], v142 offset:19456
	ds_read_b128 v[16:19], v142 offset:27648
	ds_read_b128 v[20:23], v142 offset:35840
	ds_read_b32 v122, v148 offset:52224
	s_waitcnt lgkmcnt(12)
	v_mul_f32_e32 v174, v170, v28
	v_mul_f32_e32 v175, v170, v40
	v_fmac_f32_e32 v174, v171, v29
	v_fmac_f32_e32 v175, v171, v41
	v_fmac_f32_e32 v174, v172, v30
	v_fmac_f32_e32 v175, v172, v42
	v_fmac_f32_e32 v174, v173, v31
	v_fmac_f32_e32 v175, v173, v43
	v_fmac_f32_e32 v170, v123, v36
	v_add_f32_dpp v174, v174, v174 quad_perm:[1,0,3,2] row_mask:0xf bank_mask:0xf bound_ctrl:1
	v_add_f32_dpp v175, v175, v175 quad_perm:[1,0,3,2] row_mask:0xf bank_mask:0xf bound_ctrl:1
	v_fmac_f32_e32 v171, v123, v37
	v_add_f32_dpp v174, v174, v174 quad_perm:[2,3,0,1] row_mask:0xf bank_mask:0xf bound_ctrl:1
	v_add_f32_dpp v175, v175, v175 quad_perm:[2,3,0,1] row_mask:0xf bank_mask:0xf bound_ctrl:1
	v_fmac_f32_e32 v172, v123, v38
	v_add_f32_dpp v174, v174, v174 row_half_mirror row_mask:0xf bank_mask:0xf bound_ctrl:1
	v_add_f32_dpp v175, v175, v175 row_half_mirror row_mask:0xf bank_mask:0xf bound_ctrl:1
	v_fmac_f32_e32 v173, v123, v39
	v_add_f32_dpp v174, v174, v174 row_mirror row_mask:0xf bank_mask:0xf bound_ctrl:1
	v_fmac_f32_e32 v170, v174, v32
	v_fmac_f32_e32 v171, v174, v33
	v_fmac_f32_e32 v172, v174, v34
	v_fmac_f32_e32 v173, v174, v35
	s_mov_b64 exec, s[6:7]
	ds_write_b32 v149, v175 offset:5120
	s_mov_b64 exec, -1
	ds_read_b128 v[28:31], v142 offset:11520
	ds_read_b128 v[32:35], v142 offset:19712
	ds_read_b128 v[36:39], v142 offset:27904
	ds_read_b128 v[40:43], v142 offset:36096
	ds_read_b32 v123, v148 offset:52480
	s_waitcnt lgkmcnt(12)
	v_mul_f32_e32 v174, v170, v48
	v_mul_f32_e32 v175, v170, v60
	v_fmac_f32_e32 v174, v171, v49
	v_fmac_f32_e32 v175, v171, v61
	v_fmac_f32_e32 v174, v172, v50
	v_fmac_f32_e32 v175, v172, v62
	v_fmac_f32_e32 v174, v173, v51
	v_fmac_f32_e32 v175, v173, v63
	v_fmac_f32_e32 v170, v65, v56
	v_add_f32_dpp v174, v174, v174 quad_perm:[1,0,3,2] row_mask:0xf bank_mask:0xf bound_ctrl:1
	v_add_f32_dpp v175, v175, v175 quad_perm:[1,0,3,2] row_mask:0xf bank_mask:0xf bound_ctrl:1
	v_fmac_f32_e32 v171, v65, v57
	v_add_f32_dpp v174, v174, v174 quad_perm:[2,3,0,1] row_mask:0xf bank_mask:0xf bound_ctrl:1
	v_add_f32_dpp v175, v175, v175 quad_perm:[2,3,0,1] row_mask:0xf bank_mask:0xf bound_ctrl:1
	v_fmac_f32_e32 v172, v65, v58
	v_add_f32_dpp v174, v174, v174 row_half_mirror row_mask:0xf bank_mask:0xf bound_ctrl:1
	v_add_f32_dpp v175, v175, v175 row_half_mirror row_mask:0xf bank_mask:0xf bound_ctrl:1
	v_fmac_f32_e32 v173, v65, v59
	v_add_f32_dpp v174, v174, v174 row_mirror row_mask:0xf bank_mask:0xf bound_ctrl:1
	v_fmac_f32_e32 v170, v174, v52
	v_fmac_f32_e32 v171, v174, v53
	v_fmac_f32_e32 v172, v174, v54
	v_fmac_f32_e32 v173, v174, v55
	s_mov_b64 exec, s[6:7]
	ds_write_b32 v149, v175 offset:5632
	s_mov_b64 exec, -1
	ds_read_b128 v[48:51], v142 offset:11776
	ds_read_b128 v[52:55], v142 offset:19968
	ds_read_b128 v[56:59], v142 offset:28160
	ds_read_b128 v[60:63], v142 offset:36352
	ds_read_b32 v65, v148 offset:52736
	s_waitcnt lgkmcnt(12)
	v_mul_f32_e32 v174, v170, v8
	v_mul_f32_e32 v175, v170, v20
	v_fmac_f32_e32 v174, v171, v9
	v_fmac_f32_e32 v175, v171, v21
	v_fmac_f32_e32 v174, v172, v10
	v_fmac_f32_e32 v175, v172, v22
	v_fmac_f32_e32 v174, v173, v11
	v_fmac_f32_e32 v175, v173, v23
	v_fmac_f32_e32 v170, v122, v16
	v_add_f32_dpp v174, v174, v174 quad_perm:[1,0,3,2] row_mask:0xf bank_mask:0xf bound_ctrl:1
	v_add_f32_dpp v175, v175, v175 quad_perm:[1,0,3,2] row_mask:0xf bank_mask:0xf bound_ctrl:1
	v_fmac_f32_e32 v171, v122, v17
	v_add_f32_dpp v174, v174, v174 quad_perm:[2,3,0,1] row_mask:0xf bank_mask:0xf bound_ctrl:1
	v_add_f32_dpp v175, v175, v175 quad_perm:[2,3,0,1] row_mask:0xf bank_mask:0xf bound_ctrl:1
	v_fmac_f32_e32 v172, v122, v18
	v_add_f32_dpp v174, v174, v174 row_half_mirror row_mask:0xf bank_mask:0xf bound_ctrl:1
	v_add_f32_dpp v175, v175, v175 row_half_mirror row_mask:0xf bank_mask:0xf bound_ctrl:1
	v_fmac_f32_e32 v173, v122, v19
	v_add_f32_dpp v174, v174, v174 row_mirror row_mask:0xf bank_mask:0xf bound_ctrl:1
	v_fmac_f32_e32 v170, v174, v12
	v_fmac_f32_e32 v171, v174, v13
	v_fmac_f32_e32 v172, v174, v14
	v_fmac_f32_e32 v173, v174, v15
	s_mov_b64 exec, s[6:7]
	ds_write_b32 v149, v175 offset:6144
	s_mov_b64 exec, -1
	ds_read_b128 v[8:11], v142 offset:12032
	ds_read_b128 v[12:15], v142 offset:20224
	ds_read_b128 v[16:19], v142 offset:28416
	ds_read_b128 v[20:23], v142 offset:36608
	ds_read_b32 v122, v148 offset:52992
	s_waitcnt lgkmcnt(12)
	v_mul_f32_e32 v174, v170, v28
	v_mul_f32_e32 v175, v170, v40
	v_fmac_f32_e32 v174, v171, v29
	v_fmac_f32_e32 v175, v171, v41
	v_fmac_f32_e32 v174, v172, v30
	v_fmac_f32_e32 v175, v172, v42
	v_fmac_f32_e32 v174, v173, v31
	v_fmac_f32_e32 v175, v173, v43
	v_fmac_f32_e32 v170, v123, v36
	v_add_f32_dpp v174, v174, v174 quad_perm:[1,0,3,2] row_mask:0xf bank_mask:0xf bound_ctrl:1
	v_add_f32_dpp v175, v175, v175 quad_perm:[1,0,3,2] row_mask:0xf bank_mask:0xf bound_ctrl:1
	v_fmac_f32_e32 v171, v123, v37
	v_add_f32_dpp v174, v174, v174 quad_perm:[2,3,0,1] row_mask:0xf bank_mask:0xf bound_ctrl:1
	v_add_f32_dpp v175, v175, v175 quad_perm:[2,3,0,1] row_mask:0xf bank_mask:0xf bound_ctrl:1
	v_fmac_f32_e32 v172, v123, v38
	v_add_f32_dpp v174, v174, v174 row_half_mirror row_mask:0xf bank_mask:0xf bound_ctrl:1
	v_add_f32_dpp v175, v175, v175 row_half_mirror row_mask:0xf bank_mask:0xf bound_ctrl:1
	v_fmac_f32_e32 v173, v123, v39
	v_add_f32_dpp v174, v174, v174 row_mirror row_mask:0xf bank_mask:0xf bound_ctrl:1
	v_fmac_f32_e32 v170, v174, v32
	v_fmac_f32_e32 v171, v174, v33
	v_fmac_f32_e32 v172, v174, v34
	v_fmac_f32_e32 v173, v174, v35
	s_mov_b64 exec, s[6:7]
	ds_write_b32 v149, v175 offset:6656
	s_mov_b64 exec, -1
	ds_read_b128 v[28:31], v142 offset:12288
	ds_read_b128 v[32:35], v142 offset:20480
	ds_read_b128 v[36:39], v142 offset:28672
	ds_read_b128 v[40:43], v142 offset:36864
	ds_read_b32 v123, v148 offset:53248
	s_waitcnt lgkmcnt(12)
	v_mul_f32_e32 v174, v170, v48
	v_mul_f32_e32 v175, v170, v60
	v_fmac_f32_e32 v174, v171, v49
	v_fmac_f32_e32 v175, v171, v61
	v_fmac_f32_e32 v174, v172, v50
	v_fmac_f32_e32 v175, v172, v62
	v_fmac_f32_e32 v174, v173, v51
	v_fmac_f32_e32 v175, v173, v63
	v_fmac_f32_e32 v170, v65, v56
	v_add_f32_dpp v174, v174, v174 quad_perm:[1,0,3,2] row_mask:0xf bank_mask:0xf bound_ctrl:1
	v_add_f32_dpp v175, v175, v175 quad_perm:[1,0,3,2] row_mask:0xf bank_mask:0xf bound_ctrl:1
	v_fmac_f32_e32 v171, v65, v57
	v_add_f32_dpp v174, v174, v174 quad_perm:[2,3,0,1] row_mask:0xf bank_mask:0xf bound_ctrl:1
	v_add_f32_dpp v175, v175, v175 quad_perm:[2,3,0,1] row_mask:0xf bank_mask:0xf bound_ctrl:1
	v_fmac_f32_e32 v172, v65, v58
	v_add_f32_dpp v174, v174, v174 row_half_mirror row_mask:0xf bank_mask:0xf bound_ctrl:1
	v_add_f32_dpp v175, v175, v175 row_half_mirror row_mask:0xf bank_mask:0xf bound_ctrl:1
	v_fmac_f32_e32 v173, v65, v59
	v_add_f32_dpp v174, v174, v174 row_mirror row_mask:0xf bank_mask:0xf bound_ctrl:1
	v_fmac_f32_e32 v170, v174, v52
	v_fmac_f32_e32 v171, v174, v53
	v_fmac_f32_e32 v172, v174, v54
	v_fmac_f32_e32 v173, v174, v55
	s_mov_b64 exec, s[6:7]
	ds_write_b32 v149, v175 offset:7168
	s_mov_b64 exec, -1
	ds_read_b128 v[48:51], v142 offset:12544
	ds_read_b128 v[52:55], v142 offset:20736
	ds_read_b128 v[56:59], v142 offset:28928
	ds_read_b128 v[60:63], v142 offset:37120
	ds_read_b32 v65, v148 offset:53504
	s_waitcnt lgkmcnt(12)
	v_mul_f32_e32 v174, v170, v8
	v_mul_f32_e32 v175, v170, v20
	v_fmac_f32_e32 v174, v171, v9
	v_fmac_f32_e32 v175, v171, v21
	v_fmac_f32_e32 v174, v172, v10
	v_fmac_f32_e32 v175, v172, v22
	v_fmac_f32_e32 v174, v173, v11
	v_fmac_f32_e32 v175, v173, v23
	v_fmac_f32_e32 v170, v122, v16
	v_add_f32_dpp v174, v174, v174 quad_perm:[1,0,3,2] row_mask:0xf bank_mask:0xf bound_ctrl:1
	v_add_f32_dpp v175, v175, v175 quad_perm:[1,0,3,2] row_mask:0xf bank_mask:0xf bound_ctrl:1
	v_fmac_f32_e32 v171, v122, v17
	v_add_f32_dpp v174, v174, v174 quad_perm:[2,3,0,1] row_mask:0xf bank_mask:0xf bound_ctrl:1
	v_add_f32_dpp v175, v175, v175 quad_perm:[2,3,0,1] row_mask:0xf bank_mask:0xf bound_ctrl:1
	v_fmac_f32_e32 v172, v122, v18
	v_add_f32_dpp v174, v174, v174 row_half_mirror row_mask:0xf bank_mask:0xf bound_ctrl:1
	v_add_f32_dpp v175, v175, v175 row_half_mirror row_mask:0xf bank_mask:0xf bound_ctrl:1
	v_fmac_f32_e32 v173, v122, v19
	v_add_f32_dpp v174, v174, v174 row_mirror row_mask:0xf bank_mask:0xf bound_ctrl:1
	v_fmac_f32_e32 v170, v174, v12
	v_fmac_f32_e32 v171, v174, v13
	v_fmac_f32_e32 v172, v174, v14
	v_fmac_f32_e32 v173, v174, v15
	s_mov_b64 exec, s[6:7]
	ds_write_b32 v149, v175 offset:7680
	s_mov_b64 exec, -1
	ds_read_b128 v[8:11], v142 offset:12800
	ds_read_b128 v[12:15], v142 offset:20992
	ds_read_b128 v[16:19], v142 offset:29184
	ds_read_b128 v[20:23], v142 offset:37376
	ds_read_b32 v122, v148 offset:53760
	s_waitcnt lgkmcnt(12)
	v_mul_f32_e32 v174, v170, v28
	v_mul_f32_e32 v175, v170, v40
	v_fmac_f32_e32 v174, v171, v29
	v_fmac_f32_e32 v175, v171, v41
	v_fmac_f32_e32 v174, v172, v30
	v_fmac_f32_e32 v175, v172, v42
	v_fmac_f32_e32 v174, v173, v31
	v_fmac_f32_e32 v175, v173, v43
	v_fmac_f32_e32 v170, v123, v36
	v_add_f32_dpp v174, v174, v174 quad_perm:[1,0,3,2] row_mask:0xf bank_mask:0xf bound_ctrl:1
	v_add_f32_dpp v175, v175, v175 quad_perm:[1,0,3,2] row_mask:0xf bank_mask:0xf bound_ctrl:1
	v_fmac_f32_e32 v171, v123, v37
	v_add_f32_dpp v174, v174, v174 quad_perm:[2,3,0,1] row_mask:0xf bank_mask:0xf bound_ctrl:1
	v_add_f32_dpp v175, v175, v175 quad_perm:[2,3,0,1] row_mask:0xf bank_mask:0xf bound_ctrl:1
	v_fmac_f32_e32 v172, v123, v38
	v_add_f32_dpp v174, v174, v174 row_half_mirror row_mask:0xf bank_mask:0xf bound_ctrl:1
	v_add_f32_dpp v175, v175, v175 row_half_mirror row_mask:0xf bank_mask:0xf bound_ctrl:1
	v_fmac_f32_e32 v173, v123, v39
	v_add_f32_dpp v174, v174, v174 row_mirror row_mask:0xf bank_mask:0xf bound_ctrl:1
	v_fmac_f32_e32 v170, v174, v32
	v_fmac_f32_e32 v171, v174, v33
	v_fmac_f32_e32 v172, v174, v34
	v_fmac_f32_e32 v173, v174, v35
	s_mov_b64 exec, s[6:7]
	ds_write_b32 v149, v175 offset:8192
	s_mov_b64 exec, -1
	ds_read_b128 v[28:31], v142 offset:13056
	ds_read_b128 v[32:35], v142 offset:21248
	ds_read_b128 v[36:39], v142 offset:29440
	ds_read_b128 v[40:43], v142 offset:37632
	ds_read_b32 v123, v148 offset:54016
	s_waitcnt lgkmcnt(12)
	v_mul_f32_e32 v174, v170, v48
	v_mul_f32_e32 v175, v170, v60
	v_fmac_f32_e32 v174, v171, v49
	v_fmac_f32_e32 v175, v171, v61
	v_fmac_f32_e32 v174, v172, v50
	v_fmac_f32_e32 v175, v172, v62
	v_fmac_f32_e32 v174, v173, v51
	v_fmac_f32_e32 v175, v173, v63
	v_fmac_f32_e32 v170, v65, v56
	v_add_f32_dpp v174, v174, v174 quad_perm:[1,0,3,2] row_mask:0xf bank_mask:0xf bound_ctrl:1
	v_add_f32_dpp v175, v175, v175 quad_perm:[1,0,3,2] row_mask:0xf bank_mask:0xf bound_ctrl:1
	v_fmac_f32_e32 v171, v65, v57
	v_add_f32_dpp v174, v174, v174 quad_perm:[2,3,0,1] row_mask:0xf bank_mask:0xf bound_ctrl:1
	v_add_f32_dpp v175, v175, v175 quad_perm:[2,3,0,1] row_mask:0xf bank_mask:0xf bound_ctrl:1
	v_fmac_f32_e32 v172, v65, v58
	v_add_f32_dpp v174, v174, v174 row_half_mirror row_mask:0xf bank_mask:0xf bound_ctrl:1
	v_add_f32_dpp v175, v175, v175 row_half_mirror row_mask:0xf bank_mask:0xf bound_ctrl:1
	v_fmac_f32_e32 v173, v65, v59
	v_add_f32_dpp v174, v174, v174 row_mirror row_mask:0xf bank_mask:0xf bound_ctrl:1
	v_fmac_f32_e32 v170, v174, v52
	v_fmac_f32_e32 v171, v174, v53
	v_fmac_f32_e32 v172, v174, v54
	v_fmac_f32_e32 v173, v174, v55
	s_mov_b64 exec, s[6:7]
	ds_write_b32 v149, v175 offset:8704
	s_mov_b64 exec, -1
	ds_read_b128 v[48:51], v142 offset:13312
	ds_read_b128 v[52:55], v142 offset:21504
	ds_read_b128 v[56:59], v142 offset:29696
	ds_read_b128 v[60:63], v142 offset:37888
	ds_read_b32 v65, v148 offset:54272
	s_waitcnt lgkmcnt(12)
	v_mul_f32_e32 v174, v170, v8
	v_mul_f32_e32 v175, v170, v20
	v_fmac_f32_e32 v174, v171, v9
	v_fmac_f32_e32 v175, v171, v21
	v_fmac_f32_e32 v174, v172, v10
	v_fmac_f32_e32 v175, v172, v22
	v_fmac_f32_e32 v174, v173, v11
	v_fmac_f32_e32 v175, v173, v23
	v_fmac_f32_e32 v170, v122, v16
	v_add_f32_dpp v174, v174, v174 quad_perm:[1,0,3,2] row_mask:0xf bank_mask:0xf bound_ctrl:1
	v_add_f32_dpp v175, v175, v175 quad_perm:[1,0,3,2] row_mask:0xf bank_mask:0xf bound_ctrl:1
	v_fmac_f32_e32 v171, v122, v17
	v_add_f32_dpp v174, v174, v174 quad_perm:[2,3,0,1] row_mask:0xf bank_mask:0xf bound_ctrl:1
	v_add_f32_dpp v175, v175, v175 quad_perm:[2,3,0,1] row_mask:0xf bank_mask:0xf bound_ctrl:1
	v_fmac_f32_e32 v172, v122, v18
	v_add_f32_dpp v174, v174, v174 row_half_mirror row_mask:0xf bank_mask:0xf bound_ctrl:1
	v_add_f32_dpp v175, v175, v175 row_half_mirror row_mask:0xf bank_mask:0xf bound_ctrl:1
	v_fmac_f32_e32 v173, v122, v19
	v_add_f32_dpp v174, v174, v174 row_mirror row_mask:0xf bank_mask:0xf bound_ctrl:1
	v_fmac_f32_e32 v170, v174, v12
	v_fmac_f32_e32 v171, v174, v13
	v_fmac_f32_e32 v172, v174, v14
	v_fmac_f32_e32 v173, v174, v15
	s_mov_b64 exec, s[6:7]
	ds_write_b32 v149, v175 offset:9216
	s_mov_b64 exec, -1
	ds_read_b128 v[8:11], v142 offset:13568
	ds_read_b128 v[12:15], v142 offset:21760
	ds_read_b128 v[16:19], v142 offset:29952
	ds_read_b128 v[20:23], v142 offset:38144
	ds_read_b32 v122, v148 offset:54528
	s_waitcnt lgkmcnt(12)
	v_mul_f32_e32 v174, v170, v28
	v_mul_f32_e32 v175, v170, v40
	v_fmac_f32_e32 v174, v171, v29
	v_fmac_f32_e32 v175, v171, v41
	v_fmac_f32_e32 v174, v172, v30
	v_fmac_f32_e32 v175, v172, v42
	v_fmac_f32_e32 v174, v173, v31
	v_fmac_f32_e32 v175, v173, v43
	v_fmac_f32_e32 v170, v123, v36
	v_add_f32_dpp v174, v174, v174 quad_perm:[1,0,3,2] row_mask:0xf bank_mask:0xf bound_ctrl:1
	v_add_f32_dpp v175, v175, v175 quad_perm:[1,0,3,2] row_mask:0xf bank_mask:0xf bound_ctrl:1
	v_fmac_f32_e32 v171, v123, v37
	v_add_f32_dpp v174, v174, v174 quad_perm:[2,3,0,1] row_mask:0xf bank_mask:0xf bound_ctrl:1
	v_add_f32_dpp v175, v175, v175 quad_perm:[2,3,0,1] row_mask:0xf bank_mask:0xf bound_ctrl:1
	v_fmac_f32_e32 v172, v123, v38
	v_add_f32_dpp v174, v174, v174 row_half_mirror row_mask:0xf bank_mask:0xf bound_ctrl:1
	v_add_f32_dpp v175, v175, v175 row_half_mirror row_mask:0xf bank_mask:0xf bound_ctrl:1
	v_fmac_f32_e32 v173, v123, v39
	v_add_f32_dpp v174, v174, v174 row_mirror row_mask:0xf bank_mask:0xf bound_ctrl:1
	v_fmac_f32_e32 v170, v174, v32
	v_fmac_f32_e32 v171, v174, v33
	v_fmac_f32_e32 v172, v174, v34
	v_fmac_f32_e32 v173, v174, v35
	s_mov_b64 exec, s[6:7]
	ds_write_b32 v149, v175 offset:9728
	s_mov_b64 exec, -1
	ds_read_b128 v[28:31], v142 offset:13824
	ds_read_b128 v[32:35], v142 offset:22016
	ds_read_b128 v[36:39], v142 offset:30208
	ds_read_b128 v[40:43], v142 offset:38400
	ds_read_b32 v123, v148 offset:54784
	s_waitcnt lgkmcnt(12)
	v_mul_f32_e32 v174, v170, v48
	v_mul_f32_e32 v175, v170, v60
	v_fmac_f32_e32 v174, v171, v49
	v_fmac_f32_e32 v175, v171, v61
	v_fmac_f32_e32 v174, v172, v50
	v_fmac_f32_e32 v175, v172, v62
	v_fmac_f32_e32 v174, v173, v51
	v_fmac_f32_e32 v175, v173, v63
	v_fmac_f32_e32 v170, v65, v56
	v_add_f32_dpp v174, v174, v174 quad_perm:[1,0,3,2] row_mask:0xf bank_mask:0xf bound_ctrl:1
	v_add_f32_dpp v175, v175, v175 quad_perm:[1,0,3,2] row_mask:0xf bank_mask:0xf bound_ctrl:1
	v_fmac_f32_e32 v171, v65, v57
	v_add_f32_dpp v174, v174, v174 quad_perm:[2,3,0,1] row_mask:0xf bank_mask:0xf bound_ctrl:1
	v_add_f32_dpp v175, v175, v175 quad_perm:[2,3,0,1] row_mask:0xf bank_mask:0xf bound_ctrl:1
	v_fmac_f32_e32 v172, v65, v58
	v_add_f32_dpp v174, v174, v174 row_half_mirror row_mask:0xf bank_mask:0xf bound_ctrl:1
	v_add_f32_dpp v175, v175, v175 row_half_mirror row_mask:0xf bank_mask:0xf bound_ctrl:1
	v_fmac_f32_e32 v173, v65, v59
	v_add_f32_dpp v174, v174, v174 row_mirror row_mask:0xf bank_mask:0xf bound_ctrl:1
	v_fmac_f32_e32 v170, v174, v52
	v_fmac_f32_e32 v171, v174, v53
	v_fmac_f32_e32 v172, v174, v54
	v_fmac_f32_e32 v173, v174, v55
	s_mov_b64 exec, s[6:7]
	ds_write_b32 v149, v175 offset:10240
	s_mov_b64 exec, -1
	ds_read_b128 v[48:51], v142 offset:14080
	ds_read_b128 v[52:55], v142 offset:22272
	ds_read_b128 v[56:59], v142 offset:30464
	ds_read_b128 v[60:63], v142 offset:38656
	ds_read_b32 v65, v148 offset:55040
	s_waitcnt lgkmcnt(12)
	v_mul_f32_e32 v174, v170, v8
	v_mul_f32_e32 v175, v170, v20
	v_fmac_f32_e32 v174, v171, v9
	v_fmac_f32_e32 v175, v171, v21
	v_fmac_f32_e32 v174, v172, v10
	v_fmac_f32_e32 v175, v172, v22
	v_fmac_f32_e32 v174, v173, v11
	v_fmac_f32_e32 v175, v173, v23
	v_fmac_f32_e32 v170, v122, v16
	v_add_f32_dpp v174, v174, v174 quad_perm:[1,0,3,2] row_mask:0xf bank_mask:0xf bound_ctrl:1
	v_add_f32_dpp v175, v175, v175 quad_perm:[1,0,3,2] row_mask:0xf bank_mask:0xf bound_ctrl:1
	v_fmac_f32_e32 v171, v122, v17
	v_add_f32_dpp v174, v174, v174 quad_perm:[2,3,0,1] row_mask:0xf bank_mask:0xf bound_ctrl:1
	v_add_f32_dpp v175, v175, v175 quad_perm:[2,3,0,1] row_mask:0xf bank_mask:0xf bound_ctrl:1
	v_fmac_f32_e32 v172, v122, v18
	v_add_f32_dpp v174, v174, v174 row_half_mirror row_mask:0xf bank_mask:0xf bound_ctrl:1
	v_add_f32_dpp v175, v175, v175 row_half_mirror row_mask:0xf bank_mask:0xf bound_ctrl:1
	v_fmac_f32_e32 v173, v122, v19
	v_add_f32_dpp v174, v174, v174 row_mirror row_mask:0xf bank_mask:0xf bound_ctrl:1
	v_fmac_f32_e32 v170, v174, v12
	v_fmac_f32_e32 v171, v174, v13
	v_fmac_f32_e32 v172, v174, v14
	v_fmac_f32_e32 v173, v174, v15
	s_mov_b64 exec, s[6:7]
	ds_write_b32 v149, v175 offset:10752
	s_mov_b64 exec, -1
	ds_read_b128 v[8:11], v142 offset:14336
	ds_read_b128 v[12:15], v142 offset:22528
	ds_read_b128 v[16:19], v142 offset:30720
	ds_read_b128 v[20:23], v142 offset:38912
	ds_read_b32 v122, v148 offset:55296
	s_waitcnt lgkmcnt(12)
	v_mul_f32_e32 v174, v170, v28
	v_mul_f32_e32 v175, v170, v40
	v_fmac_f32_e32 v174, v171, v29
	v_fmac_f32_e32 v175, v171, v41
	v_fmac_f32_e32 v174, v172, v30
	v_fmac_f32_e32 v175, v172, v42
	v_fmac_f32_e32 v174, v173, v31
	v_fmac_f32_e32 v175, v173, v43
	v_fmac_f32_e32 v170, v123, v36
	v_add_f32_dpp v174, v174, v174 quad_perm:[1,0,3,2] row_mask:0xf bank_mask:0xf bound_ctrl:1
	v_add_f32_dpp v175, v175, v175 quad_perm:[1,0,3,2] row_mask:0xf bank_mask:0xf bound_ctrl:1
	v_fmac_f32_e32 v171, v123, v37
	v_add_f32_dpp v174, v174, v174 quad_perm:[2,3,0,1] row_mask:0xf bank_mask:0xf bound_ctrl:1
	v_add_f32_dpp v175, v175, v175 quad_perm:[2,3,0,1] row_mask:0xf bank_mask:0xf bound_ctrl:1
	v_fmac_f32_e32 v172, v123, v38
	v_add_f32_dpp v174, v174, v174 row_half_mirror row_mask:0xf bank_mask:0xf bound_ctrl:1
	v_add_f32_dpp v175, v175, v175 row_half_mirror row_mask:0xf bank_mask:0xf bound_ctrl:1
	v_fmac_f32_e32 v173, v123, v39
	v_add_f32_dpp v174, v174, v174 row_mirror row_mask:0xf bank_mask:0xf bound_ctrl:1
	v_fmac_f32_e32 v170, v174, v32
	v_fmac_f32_e32 v171, v174, v33
	v_fmac_f32_e32 v172, v174, v34
	v_fmac_f32_e32 v173, v174, v35
	s_mov_b64 exec, s[6:7]
	ds_write_b32 v149, v175 offset:11264
	s_mov_b64 exec, -1
	ds_read_b128 v[28:31], v142 offset:14592
	ds_read_b128 v[32:35], v142 offset:22784
	ds_read_b128 v[36:39], v142 offset:30976
	ds_read_b128 v[40:43], v142 offset:39168
	ds_read_b32 v123, v148 offset:55552
	s_waitcnt lgkmcnt(12)
	v_mul_f32_e32 v174, v170, v48
	v_mul_f32_e32 v175, v170, v60
	v_fmac_f32_e32 v174, v171, v49
	v_fmac_f32_e32 v175, v171, v61
	v_fmac_f32_e32 v174, v172, v50
	v_fmac_f32_e32 v175, v172, v62
	v_fmac_f32_e32 v174, v173, v51
	v_fmac_f32_e32 v175, v173, v63
	v_fmac_f32_e32 v170, v65, v56
	v_add_f32_dpp v174, v174, v174 quad_perm:[1,0,3,2] row_mask:0xf bank_mask:0xf bound_ctrl:1
	v_add_f32_dpp v175, v175, v175 quad_perm:[1,0,3,2] row_mask:0xf bank_mask:0xf bound_ctrl:1
	v_fmac_f32_e32 v171, v65, v57
	v_add_f32_dpp v174, v174, v174 quad_perm:[2,3,0,1] row_mask:0xf bank_mask:0xf bound_ctrl:1
	v_add_f32_dpp v175, v175, v175 quad_perm:[2,3,0,1] row_mask:0xf bank_mask:0xf bound_ctrl:1
	v_fmac_f32_e32 v172, v65, v58
	v_add_f32_dpp v174, v174, v174 row_half_mirror row_mask:0xf bank_mask:0xf bound_ctrl:1
	v_add_f32_dpp v175, v175, v175 row_half_mirror row_mask:0xf bank_mask:0xf bound_ctrl:1
	v_fmac_f32_e32 v173, v65, v59
	v_add_f32_dpp v174, v174, v174 row_mirror row_mask:0xf bank_mask:0xf bound_ctrl:1
	v_fmac_f32_e32 v170, v174, v52
	v_fmac_f32_e32 v171, v174, v53
	v_fmac_f32_e32 v172, v174, v54
	v_fmac_f32_e32 v173, v174, v55
	s_mov_b64 exec, s[6:7]
	ds_write_b32 v149, v175 offset:11776
	s_mov_b64 exec, -1
	ds_read_b128 v[48:51], v142 offset:14848
	ds_read_b128 v[52:55], v142 offset:23040
	ds_read_b128 v[56:59], v142 offset:31232
	ds_read_b128 v[60:63], v142 offset:39424
	ds_read_b32 v65, v148 offset:55808
	s_waitcnt lgkmcnt(12)
	v_mul_f32_e32 v174, v170, v8
	v_mul_f32_e32 v175, v170, v20
	v_fmac_f32_e32 v174, v171, v9
	v_fmac_f32_e32 v175, v171, v21
	v_fmac_f32_e32 v174, v172, v10
	v_fmac_f32_e32 v175, v172, v22
	v_fmac_f32_e32 v174, v173, v11
	v_fmac_f32_e32 v175, v173, v23
	v_fmac_f32_e32 v170, v122, v16
	v_add_f32_dpp v174, v174, v174 quad_perm:[1,0,3,2] row_mask:0xf bank_mask:0xf bound_ctrl:1
	v_add_f32_dpp v175, v175, v175 quad_perm:[1,0,3,2] row_mask:0xf bank_mask:0xf bound_ctrl:1
	v_fmac_f32_e32 v171, v122, v17
	v_add_f32_dpp v174, v174, v174 quad_perm:[2,3,0,1] row_mask:0xf bank_mask:0xf bound_ctrl:1
	v_add_f32_dpp v175, v175, v175 quad_perm:[2,3,0,1] row_mask:0xf bank_mask:0xf bound_ctrl:1
	v_fmac_f32_e32 v172, v122, v18
	v_add_f32_dpp v174, v174, v174 row_half_mirror row_mask:0xf bank_mask:0xf bound_ctrl:1
	v_add_f32_dpp v175, v175, v175 row_half_mirror row_mask:0xf bank_mask:0xf bound_ctrl:1
	v_fmac_f32_e32 v173, v122, v19
	v_add_f32_dpp v174, v174, v174 row_mirror row_mask:0xf bank_mask:0xf bound_ctrl:1
	v_fmac_f32_e32 v170, v174, v12
	v_fmac_f32_e32 v171, v174, v13
	v_fmac_f32_e32 v172, v174, v14
	v_fmac_f32_e32 v173, v174, v15
	s_mov_b64 exec, s[6:7]
	ds_write_b32 v149, v175 offset:12288
	s_mov_b64 exec, -1
	ds_read_b128 v[8:11], v142 offset:15104
	ds_read_b128 v[12:15], v142 offset:23296
	ds_read_b128 v[16:19], v142 offset:31488
	ds_read_b128 v[20:23], v142 offset:39680
	ds_read_b32 v122, v148 offset:56064
	s_waitcnt lgkmcnt(12)
	v_mul_f32_e32 v174, v170, v28
	v_mul_f32_e32 v175, v170, v40
	v_fmac_f32_e32 v174, v171, v29
	v_fmac_f32_e32 v175, v171, v41
	v_fmac_f32_e32 v174, v172, v30
	v_fmac_f32_e32 v175, v172, v42
	v_fmac_f32_e32 v174, v173, v31
	v_fmac_f32_e32 v175, v173, v43
	v_fmac_f32_e32 v170, v123, v36
	v_add_f32_dpp v174, v174, v174 quad_perm:[1,0,3,2] row_mask:0xf bank_mask:0xf bound_ctrl:1
	v_add_f32_dpp v175, v175, v175 quad_perm:[1,0,3,2] row_mask:0xf bank_mask:0xf bound_ctrl:1
	v_fmac_f32_e32 v171, v123, v37
	v_add_f32_dpp v174, v174, v174 quad_perm:[2,3,0,1] row_mask:0xf bank_mask:0xf bound_ctrl:1
	v_add_f32_dpp v175, v175, v175 quad_perm:[2,3,0,1] row_mask:0xf bank_mask:0xf bound_ctrl:1
	v_fmac_f32_e32 v172, v123, v38
	v_add_f32_dpp v174, v174, v174 row_half_mirror row_mask:0xf bank_mask:0xf bound_ctrl:1
	v_add_f32_dpp v175, v175, v175 row_half_mirror row_mask:0xf bank_mask:0xf bound_ctrl:1
	v_fmac_f32_e32 v173, v123, v39
	v_add_f32_dpp v174, v174, v174 row_mirror row_mask:0xf bank_mask:0xf bound_ctrl:1
	v_fmac_f32_e32 v170, v174, v32
	v_fmac_f32_e32 v171, v174, v33
	v_fmac_f32_e32 v172, v174, v34
	v_fmac_f32_e32 v173, v174, v35
	s_mov_b64 exec, s[6:7]
	ds_write_b32 v149, v175 offset:12800
	s_mov_b64 exec, -1
	ds_read_b128 v[28:31], v142 offset:15360
	ds_read_b128 v[32:35], v142 offset:23552
	ds_read_b128 v[36:39], v142 offset:31744
	ds_read_b128 v[40:43], v142 offset:39936
	ds_read_b32 v123, v148 offset:56320
	s_waitcnt lgkmcnt(12)
	v_mul_f32_e32 v174, v170, v48
	v_mul_f32_e32 v175, v170, v60
	v_fmac_f32_e32 v174, v171, v49
	v_fmac_f32_e32 v175, v171, v61
	v_fmac_f32_e32 v174, v172, v50
	v_fmac_f32_e32 v175, v172, v62
	v_fmac_f32_e32 v174, v173, v51
	v_fmac_f32_e32 v175, v173, v63
	v_fmac_f32_e32 v170, v65, v56
	v_add_f32_dpp v174, v174, v174 quad_perm:[1,0,3,2] row_mask:0xf bank_mask:0xf bound_ctrl:1
	v_add_f32_dpp v175, v175, v175 quad_perm:[1,0,3,2] row_mask:0xf bank_mask:0xf bound_ctrl:1
	v_fmac_f32_e32 v171, v65, v57
	v_add_f32_dpp v174, v174, v174 quad_perm:[2,3,0,1] row_mask:0xf bank_mask:0xf bound_ctrl:1
	v_add_f32_dpp v175, v175, v175 quad_perm:[2,3,0,1] row_mask:0xf bank_mask:0xf bound_ctrl:1
	v_fmac_f32_e32 v172, v65, v58
	v_add_f32_dpp v174, v174, v174 row_half_mirror row_mask:0xf bank_mask:0xf bound_ctrl:1
	v_add_f32_dpp v175, v175, v175 row_half_mirror row_mask:0xf bank_mask:0xf bound_ctrl:1
	v_fmac_f32_e32 v173, v65, v59
	v_add_f32_dpp v174, v174, v174 row_mirror row_mask:0xf bank_mask:0xf bound_ctrl:1
	v_fmac_f32_e32 v170, v174, v52
	v_fmac_f32_e32 v171, v174, v53
	v_fmac_f32_e32 v172, v174, v54
	v_fmac_f32_e32 v173, v174, v55
	s_mov_b64 exec, s[6:7]
	ds_write_b32 v149, v175 offset:13312
	s_mov_b64 exec, -1
	ds_read_b128 v[48:51], v142 offset:15616
	ds_read_b128 v[52:55], v142 offset:23808
	ds_read_b128 v[56:59], v142 offset:32000
	ds_read_b128 v[60:63], v142 offset:40192
	ds_read_b32 v65, v148 offset:56576
	s_waitcnt lgkmcnt(12)
	v_mul_f32_e32 v174, v170, v8
	v_mul_f32_e32 v175, v170, v20
	v_fmac_f32_e32 v174, v171, v9
	v_fmac_f32_e32 v175, v171, v21
	v_fmac_f32_e32 v174, v172, v10
	v_fmac_f32_e32 v175, v172, v22
	v_fmac_f32_e32 v174, v173, v11
	v_fmac_f32_e32 v175, v173, v23
	v_fmac_f32_e32 v170, v122, v16
	v_add_f32_dpp v174, v174, v174 quad_perm:[1,0,3,2] row_mask:0xf bank_mask:0xf bound_ctrl:1
	v_add_f32_dpp v175, v175, v175 quad_perm:[1,0,3,2] row_mask:0xf bank_mask:0xf bound_ctrl:1
	v_fmac_f32_e32 v171, v122, v17
	v_add_f32_dpp v174, v174, v174 quad_perm:[2,3,0,1] row_mask:0xf bank_mask:0xf bound_ctrl:1
	v_add_f32_dpp v175, v175, v175 quad_perm:[2,3,0,1] row_mask:0xf bank_mask:0xf bound_ctrl:1
	v_fmac_f32_e32 v172, v122, v18
	v_add_f32_dpp v174, v174, v174 row_half_mirror row_mask:0xf bank_mask:0xf bound_ctrl:1
	v_add_f32_dpp v175, v175, v175 row_half_mirror row_mask:0xf bank_mask:0xf bound_ctrl:1
	v_fmac_f32_e32 v173, v122, v19
	v_add_f32_dpp v174, v174, v174 row_mirror row_mask:0xf bank_mask:0xf bound_ctrl:1
	v_fmac_f32_e32 v170, v174, v12
	v_fmac_f32_e32 v171, v174, v13
	v_fmac_f32_e32 v172, v174, v14
	v_fmac_f32_e32 v173, v174, v15
	s_mov_b64 exec, s[6:7]
	ds_write_b32 v149, v175 offset:13824
	s_mov_b64 exec, -1
	ds_read_b128 v[8:11], v142 offset:15872
	ds_read_b128 v[12:15], v142 offset:24064
	ds_read_b128 v[16:19], v142 offset:32256
	ds_read_b128 v[20:23], v142 offset:40448
	ds_read_b32 v122, v148 offset:56832
	s_waitcnt lgkmcnt(12)
	v_mul_f32_e32 v174, v170, v28
	v_mul_f32_e32 v175, v170, v40
	v_fmac_f32_e32 v174, v171, v29
	v_fmac_f32_e32 v175, v171, v41
	v_fmac_f32_e32 v174, v172, v30
	v_fmac_f32_e32 v175, v172, v42
	v_fmac_f32_e32 v174, v173, v31
	v_fmac_f32_e32 v175, v173, v43
	v_fmac_f32_e32 v170, v123, v36
	v_add_f32_dpp v174, v174, v174 quad_perm:[1,0,3,2] row_mask:0xf bank_mask:0xf bound_ctrl:1
	v_add_f32_dpp v175, v175, v175 quad_perm:[1,0,3,2] row_mask:0xf bank_mask:0xf bound_ctrl:1
	v_fmac_f32_e32 v171, v123, v37
	v_add_f32_dpp v174, v174, v174 quad_perm:[2,3,0,1] row_mask:0xf bank_mask:0xf bound_ctrl:1
	v_add_f32_dpp v175, v175, v175 quad_perm:[2,3,0,1] row_mask:0xf bank_mask:0xf bound_ctrl:1
	v_fmac_f32_e32 v172, v123, v38
	v_add_f32_dpp v174, v174, v174 row_half_mirror row_mask:0xf bank_mask:0xf bound_ctrl:1
	v_add_f32_dpp v175, v175, v175 row_half_mirror row_mask:0xf bank_mask:0xf bound_ctrl:1
	v_fmac_f32_e32 v173, v123, v39
	v_add_f32_dpp v174, v174, v174 row_mirror row_mask:0xf bank_mask:0xf bound_ctrl:1
	v_fmac_f32_e32 v170, v174, v32
	v_fmac_f32_e32 v171, v174, v33
	v_fmac_f32_e32 v172, v174, v34
	v_fmac_f32_e32 v173, v174, v35
	s_mov_b64 exec, s[6:7]
	ds_write_b32 v149, v175 offset:14336
	s_mov_b64 exec, -1
	ds_read_b128 v[28:31], v142 offset:16128
	ds_read_b128 v[32:35], v142 offset:24320
	ds_read_b128 v[36:39], v142 offset:32512
	ds_read_b128 v[40:43], v142 offset:40704
	ds_read_b32 v123, v148 offset:57088
	s_waitcnt lgkmcnt(12)
	v_mul_f32_e32 v174, v170, v48
	v_mul_f32_e32 v175, v170, v60
	v_fmac_f32_e32 v174, v171, v49
	v_fmac_f32_e32 v175, v171, v61
	v_fmac_f32_e32 v174, v172, v50
	v_fmac_f32_e32 v175, v172, v62
	v_fmac_f32_e32 v174, v173, v51
	v_fmac_f32_e32 v175, v173, v63
	v_fmac_f32_e32 v170, v65, v56
	v_add_f32_dpp v174, v174, v174 quad_perm:[1,0,3,2] row_mask:0xf bank_mask:0xf bound_ctrl:1
	v_add_f32_dpp v175, v175, v175 quad_perm:[1,0,3,2] row_mask:0xf bank_mask:0xf bound_ctrl:1
	v_fmac_f32_e32 v171, v65, v57
	v_add_f32_dpp v174, v174, v174 quad_perm:[2,3,0,1] row_mask:0xf bank_mask:0xf bound_ctrl:1
	v_add_f32_dpp v175, v175, v175 quad_perm:[2,3,0,1] row_mask:0xf bank_mask:0xf bound_ctrl:1
	v_fmac_f32_e32 v172, v65, v58
	v_add_f32_dpp v174, v174, v174 row_half_mirror row_mask:0xf bank_mask:0xf bound_ctrl:1
	v_add_f32_dpp v175, v175, v175 row_half_mirror row_mask:0xf bank_mask:0xf bound_ctrl:1
	v_fmac_f32_e32 v173, v65, v59
	v_add_f32_dpp v174, v174, v174 row_mirror row_mask:0xf bank_mask:0xf bound_ctrl:1
	v_fmac_f32_e32 v170, v174, v52
	v_fmac_f32_e32 v171, v174, v53
	v_fmac_f32_e32 v172, v174, v54
	v_fmac_f32_e32 v173, v174, v55
	s_mov_b64 exec, s[6:7]
	ds_write_b32 v149, v175 offset:14848
	s_mov_b64 exec, -1
	s_waitcnt lgkmcnt(7)
	v_mul_f32_e32 v174, v170, v8
	v_mul_f32_e32 v175, v170, v20
	v_fmac_f32_e32 v174, v171, v9
	v_fmac_f32_e32 v175, v171, v21
	v_fmac_f32_e32 v174, v172, v10
	v_fmac_f32_e32 v175, v172, v22
	v_fmac_f32_e32 v174, v173, v11
	v_fmac_f32_e32 v175, v173, v23
	v_fmac_f32_e32 v170, v122, v16
	v_add_f32_dpp v174, v174, v174 quad_perm:[1,0,3,2] row_mask:0xf bank_mask:0xf bound_ctrl:1
	v_add_f32_dpp v175, v175, v175 quad_perm:[1,0,3,2] row_mask:0xf bank_mask:0xf bound_ctrl:1
	v_fmac_f32_e32 v171, v122, v17
	v_add_f32_dpp v174, v174, v174 quad_perm:[2,3,0,1] row_mask:0xf bank_mask:0xf bound_ctrl:1
	v_add_f32_dpp v175, v175, v175 quad_perm:[2,3,0,1] row_mask:0xf bank_mask:0xf bound_ctrl:1
	v_fmac_f32_e32 v172, v122, v18
	v_add_f32_dpp v174, v174, v174 row_half_mirror row_mask:0xf bank_mask:0xf bound_ctrl:1
	v_add_f32_dpp v175, v175, v175 row_half_mirror row_mask:0xf bank_mask:0xf bound_ctrl:1
	v_fmac_f32_e32 v173, v122, v19
	v_add_f32_dpp v174, v174, v174 row_mirror row_mask:0xf bank_mask:0xf bound_ctrl:1
	v_fmac_f32_e32 v170, v174, v12
	v_fmac_f32_e32 v171, v174, v13
	v_fmac_f32_e32 v172, v174, v14
	v_fmac_f32_e32 v173, v174, v15
	s_mov_b64 exec, s[6:7]
	ds_write_b32 v149, v175 offset:15360
	s_mov_b64 exec, -1
	s_waitcnt lgkmcnt(2)
	v_mul_f32_e32 v174, v170, v28
	v_mul_f32_e32 v175, v170, v40
	v_fmac_f32_e32 v174, v171, v29
	v_fmac_f32_e32 v175, v171, v41
	v_fmac_f32_e32 v174, v172, v30
	v_fmac_f32_e32 v175, v172, v42
	v_fmac_f32_e32 v174, v173, v31
	v_fmac_f32_e32 v175, v173, v43
	v_fmac_f32_e32 v170, v123, v36
	v_add_f32_dpp v174, v174, v174 quad_perm:[1,0,3,2] row_mask:0xf bank_mask:0xf bound_ctrl:1
	v_add_f32_dpp v175, v175, v175 quad_perm:[1,0,3,2] row_mask:0xf bank_mask:0xf bound_ctrl:1
	v_fmac_f32_e32 v171, v123, v37
	v_add_f32_dpp v174, v174, v174 quad_perm:[2,3,0,1] row_mask:0xf bank_mask:0xf bound_ctrl:1
	v_add_f32_dpp v175, v175, v175 quad_perm:[2,3,0,1] row_mask:0xf bank_mask:0xf bound_ctrl:1
	v_fmac_f32_e32 v172, v123, v38
	v_add_f32_dpp v174, v174, v174 row_half_mirror row_mask:0xf bank_mask:0xf bound_ctrl:1
	v_add_f32_dpp v175, v175, v175 row_half_mirror row_mask:0xf bank_mask:0xf bound_ctrl:1
	v_fmac_f32_e32 v173, v123, v39
	v_add_f32_dpp v174, v174, v174 row_mirror row_mask:0xf bank_mask:0xf bound_ctrl:1
	v_fmac_f32_e32 v170, v174, v32
	v_fmac_f32_e32 v171, v174, v33
	v_fmac_f32_e32 v172, v174, v34
	v_fmac_f32_e32 v173, v174, v35
	s_mov_b64 exec, s[6:7]
	ds_write_b32 v149, v175 offset:15872
	s_mov_b64 exec, -1
	ds_read_b128 v[4:7], v142 offset:65280
	s_waitcnt lgkmcnt(0)
	v_mul_f32_e32 v170, v170, v4
	v_mul_f32_e32 v171, v171, v5
	v_mul_f32_e32 v172, v172, v6
	v_mul_f32_e32 v173, v173, v7
	s_waitcnt lgkmcnt(0)
	s_barrier
	s_and_saveexec_b64 s[10:11], s[8:9]
	s_cbranch_execz .LBB0_349
	ds_read_b128 v[4:7], v150
	ds_read_b128 v[8:11], v150 offset:256
	s_waitcnt lgkmcnt(0)
	v_pk_add_f32 v[10:11], v[6:7], v[10:11]
	v_pk_add_f32 v[8:9], v[4:5], v[8:9]
	ds_read_b128 v[4:7], v147
	s_waitcnt lgkmcnt(0)
	v_pk_add_f32 v[6:7], v[10:11], v[6:7]
	v_pk_add_f32 v[4:5], v[8:9], v[4:5]
	s_nop 0
	v_cvt_pk_bf16_f32 v4, v4, v5
	v_cvt_pk_bf16_f32 v5, v6, v7
	v_lshlrev_b64 v[6:7], 11, v[120:121]
	v_lshl_add_u64 v[6:7], v[102:103], 0, v[6:7]
	global_store_dwordx2 v[6:7], v[4:5], off
	s_branch .LBB0_349

	.amdhsa_kernel _Z14fwd_megakernel6Params
		.amdhsa_group_segment_fixed_size 0
		.amdhsa_private_segment_fixed_size 0
		.amdhsa_kernarg_size 512
		.amdhsa_user_sgpr_count 2
		.amdhsa_user_sgpr_dispatch_ptr 0
		.amdhsa_user_sgpr_queue_ptr 0
		.amdhsa_user_sgpr_kernarg_segment_ptr 1
		.amdhsa_user_sgpr_dispatch_id 0
		.amdhsa_user_sgpr_kernarg_preload_length 0
		.amdhsa_user_sgpr_kernarg_preload_offset 0
		.amdhsa_user_sgpr_private_segment_size 0
		.amdhsa_uses_dynamic_stack 0
		.amdhsa_enable_private_segment 0
		.amdhsa_system_sgpr_workgroup_id_x 1
		.amdhsa_system_sgpr_workgroup_id_y 0
		.amdhsa_system_sgpr_workgroup_id_z 0
		.amdhsa_system_sgpr_workgroup_info 0
		.amdhsa_system_vgpr_workitem_id 2
		.amdhsa_next_free_vgpr 240
		.amdhsa_next_free_sgpr 98
		.amdhsa_accum_offset 240
		.amdhsa_reserve_vcc 1
		.amdhsa_float_round_mode_32 0
		.amdhsa_float_round_mode_16_64 0
		.amdhsa_float_denorm_mode_32 3
		.amdhsa_float_denorm_mode_16_64 3
		.amdhsa_dx10_clamp 1
		.amdhsa_ieee_mode 1
		.amdhsa_fp16_overflow 0
		.amdhsa_tg_split 0
		.amdhsa_exception_fp_ieee_invalid_op 0
		.amdhsa_exception_fp_denorm_src 0
		.amdhsa_exception_fp_ieee_div_zero 0
		.amdhsa_exception_fp_ieee_overflow 0
		.amdhsa_exception_fp_ieee_underflow 0
		.amdhsa_exception_fp_ieee_inexact 0
		.amdhsa_exception_int_div_zero 0
	.end_amdhsa_kernel

amdhsa.kernels:
  - .agpr_count:     0
    .args:
      - .offset:         0
        .size:           256
        .value_kind:     by_value
      - .offset:         256
        .size:           4
        .value_kind:     hidden_block_count_x
      - .offset:         260
        .size:           4
        .value_kind:     hidden_block_count_y
      - .offset:         264
        .size:           4
        .value_kind:     hidden_block_count_z
      - .offset:         268
        .size:           2
        .value_kind:     hidden_group_size_x
      - .offset:         270
        .size:           2
        .value_kind:     hidden_group_size_y
      - .offset:         272
        .size:           2
        .value_kind:     hidden_group_size_z
      - .offset:         274
        .size:           2
        .value_kind:     hidden_remainder_x
      - .offset:         276
        .size:           2
        .value_kind:     hidden_remainder_y
      - .offset:         278
        .size:           2
        .value_kind:     hidden_remainder_z
      - .offset:         296
        .size:           8
        .value_kind:     hidden_global_offset_x
      - .offset:         304
        .size:           8
        .value_kind:     hidden_global_offset_y
      - .offset:         312
        .size:           8
        .value_kind:     hidden_global_offset_z
      - .offset:         320
        .size:           2
        .value_kind:     hidden_grid_dims
      - .offset:         344
        .size:           8
        .value_kind:     hidden_multigrid_sync_arg
      - .offset:         376
        .size:           4
        .value_kind:     hidden_dynamic_lds_size
    .group_segment_fixed_size: 0
    .kernarg_segment_align: 8
    .kernarg_segment_size: 512
    .language:       OpenCL C
    .language_version:
      - 2
      - 0
    .max_flat_workgroup_size: 512
    .name:           _Z14fwd_megakernel6Params
    .private_segment_fixed_size: 0
    .sgpr_count:     104
    .sgpr_spill_count: 51
    .symbol:         _Z14fwd_megakernel6Params.kd
    .uniform_work_group_size: 1
    .uses_dynamic_stack: false
    .vgpr_count:     240
    .vgpr_spill_count: 0
    .wavefront_size: 64
